# merged 4-phase GEMM loops without per-segment s_setprio flips (otherwise as previous best)
# speedup vs baseline: 1.0027x; 1.0027x over previous
.Lm4ap_31:
	s_waitcnt lgkmcnt(0)
	s_barrier
	v_mfma_f32_16x16x32_bf16 v[124:127], v[128:131], v[162:165], 0
	v_mfma_f32_16x16x32_bf16 v[120:123], v[136:139], v[162:165], 0
	v_mfma_f32_16x16x32_bf16 v[108:111], v[128:131], v[170:173], 0
	v_mfma_f32_16x16x32_bf16 v[104:107], v[136:139], v[170:173], 0
	v_mfma_f32_16x16x32_bf16 v[96:99], v[128:131], v[178:181], 0
	v_mfma_f32_16x16x32_bf16 v[88:91], v[136:139], v[178:181], 0
	v_mfma_f32_16x16x32_bf16 v[84:87], v[128:131], v[194:197], 0
	v_mfma_f32_16x16x32_bf16 v[80:83], v[136:139], v[194:197], 0
	v_mfma_f32_16x16x32_bf16 v[124:127], v[132:135], v[166:169], v[124:127]
	v_mfma_f32_16x16x32_bf16 v[120:123], v[146:149], v[166:169], v[120:123]
	v_mfma_f32_16x16x32_bf16 v[108:111], v[132:135], v[174:177], v[108:111]
	v_mfma_f32_16x16x32_bf16 v[104:107], v[146:149], v[174:177], v[104:107]
	v_mfma_f32_16x16x32_bf16 v[96:99], v[132:135], v[182:185], v[96:99]
	v_mfma_f32_16x16x32_bf16 v[88:91], v[146:149], v[182:185], v[88:91]
	v_mfma_f32_16x16x32_bf16 v[84:87], v[132:135], v[210:213], v[84:87]
	v_mfma_f32_16x16x32_bf16 v[80:83], v[146:149], v[210:213], v[80:83]
	v_mfma_f32_16x16x32_bf16 v[116:119], v[214:217], v[162:165], 0
	v_mfma_f32_16x16x32_bf16 v[112:115], v[222:225], v[162:165], 0
	v_mfma_f32_16x16x32_bf16 v[100:103], v[214:217], v[170:173], 0
	v_mfma_f32_16x16x32_bf16 v[92:95], v[222:225], v[170:173], 0
	v_mfma_f32_16x16x32_bf16 v[76:79], v[214:217], v[178:181], 0
	v_mfma_f32_16x16x32_bf16 v[72:75], v[222:225], v[178:181], 0
	v_mfma_f32_16x16x32_bf16 v[68:71], v[214:217], v[194:197], 0
	v_mfma_f32_16x16x32_bf16 v[64:67], v[222:225], v[194:197], 0
	v_mfma_f32_16x16x32_bf16 v[116:119], v[218:221], v[166:169], v[116:119]
	v_mfma_f32_16x16x32_bf16 v[112:115], v[226:229], v[166:169], v[112:115]
	v_mfma_f32_16x16x32_bf16 v[100:103], v[218:221], v[174:177], v[100:103]
	v_mfma_f32_16x16x32_bf16 v[92:95], v[226:229], v[174:177], v[92:95]
	v_mfma_f32_16x16x32_bf16 v[76:79], v[218:221], v[182:185], v[76:79]
	v_mfma_f32_16x16x32_bf16 v[72:75], v[226:229], v[182:185], v[72:75]
	v_mfma_f32_16x16x32_bf16 v[68:71], v[218:221], v[210:213], v[68:71]
	v_mfma_f32_16x16x32_bf16 v[64:67], v[226:229], v[210:213], v[64:67]
	s_barrier
	s_add_i32 s6, s6, s57
	v_lshl_add_u64 v[230:231], s[48:49], 0, v[140:141]
	s_mov_b32 m0, s6
	s_nop 0
	global_load_lds_dwordx4 v[230:231], off
	v_lshl_add_u64 v[232:233], s[48:49], 0, v[150:151]
	s_add_i32 m0, s6, 0x2000
	s_nop 0
	global_load_lds_dwordx4 v[232:233], off
	s_mov_b32 m0, s58
	v_lshl_add_u64 v[234:235], s[52:53], 0, v[154:155]
	ds_read_b128 v[162:165], v208 offset:16384
	ds_read_b128 v[166:169], v208 offset:17408
	ds_read_b128 v[170:173], v208 offset:18432
	ds_read_b128 v[174:177], v208 offset:19456
	ds_read_b128 v[178:181], v208 offset:20480
	ds_read_b128 v[182:185], v208 offset:21504
	ds_read_b128 v[194:197], v208 offset:22528
	ds_read_b128 v[210:213], v208 offset:23552
	global_load_lds_dwordx4 v[234:235], off
	v_lshl_add_u64 v[236:237], s[52:53], 0, v[152:153]
	s_mov_b32 m0, s59
	s_nop 0
	global_load_lds_dwordx4 v[236:237], off
	s_add_u32 s50, s48, 0xb0000
	s_addc_u32 s51, s49, 0
	s_add_i32 s6, s19, s57
	v_lshl_add_u64 v[250:251], s[50:51], 0, v[140:141]
	s_mov_b32 m0, s6
	s_nop 0
	global_load_lds_dwordx4 v[250:251], off
	v_lshl_add_u64 v[250:251], s[50:51], 0, v[150:151]
	s_add_i32 m0, s6, 0x2000
	s_nop 0
	global_load_lds_dwordx4 v[250:251], off
	s_waitcnt vmcnt(40)
	s_cmp_lg_u32 s100, 0
	s_cbranch_scc1 .Lm4bp_31
	s_waitcnt vmcnt(8)
.Lm4bp_31:
	s_waitcnt lgkmcnt(0)
	s_mov_b32 s100, 0
	s_barrier
	v_mfma_f32_16x16x32_bf16 v[60:63], v[128:131], v[162:165], 0
	v_mfma_f32_16x16x32_bf16 v[56:59], v[136:139], v[162:165], 0
	v_mfma_f32_16x16x32_bf16 v[48:51], v[128:131], v[170:173], 0
	v_mfma_f32_16x16x32_bf16 v[40:43], v[136:139], v[170:173], 0
	v_mfma_f32_16x16x32_bf16 v[32:35], v[128:131], v[178:181], 0
	v_mfma_f32_16x16x32_bf16 v[24:27], v[136:139], v[178:181], 0
	v_mfma_f32_16x16x32_bf16 v[16:19], v[128:131], v[194:197], 0
	v_mfma_f32_16x16x32_bf16 v[8:11], v[136:139], v[194:197], 0
	v_mfma_f32_16x16x32_bf16 v[60:63], v[132:135], v[166:169], v[60:63]
	v_mfma_f32_16x16x32_bf16 v[56:59], v[146:149], v[166:169], v[56:59]
	v_mfma_f32_16x16x32_bf16 v[48:51], v[132:135], v[174:177], v[48:51]
	v_mfma_f32_16x16x32_bf16 v[40:43], v[146:149], v[174:177], v[40:43]
	v_mfma_f32_16x16x32_bf16 v[32:35], v[132:135], v[182:185], v[32:35]
	v_mfma_f32_16x16x32_bf16 v[24:27], v[146:149], v[182:185], v[24:27]
	v_mfma_f32_16x16x32_bf16 v[16:19], v[132:135], v[210:213], v[16:19]
	v_mfma_f32_16x16x32_bf16 v[8:11], v[146:149], v[210:213], v[8:11]
	v_mfma_f32_16x16x32_bf16 v[52:55], v[214:217], v[162:165], 0
	v_mfma_f32_16x16x32_bf16 v[44:47], v[222:225], v[162:165], 0
	v_mfma_f32_16x16x32_bf16 v[36:39], v[214:217], v[170:173], 0
	v_mfma_f32_16x16x32_bf16 v[28:31], v[222:225], v[170:173], 0
	v_mfma_f32_16x16x32_bf16 v[20:23], v[214:217], v[178:181], 0
	v_mfma_f32_16x16x32_bf16 v[12:15], v[222:225], v[178:181], 0
	v_mfma_f32_16x16x32_bf16 v[4:7], v[214:217], v[194:197], 0
	v_mfma_f32_16x16x32_bf16 v[0:3], v[222:225], v[194:197], 0
	v_mfma_f32_16x16x32_bf16 v[52:55], v[218:221], v[166:169], v[52:55]
	v_mfma_f32_16x16x32_bf16 v[44:47], v[226:229], v[166:169], v[44:47]
	v_mfma_f32_16x16x32_bf16 v[36:39], v[218:221], v[174:177], v[36:39]
	v_mfma_f32_16x16x32_bf16 v[28:31], v[226:229], v[174:177], v[28:31]
	v_mfma_f32_16x16x32_bf16 v[20:23], v[218:221], v[182:185], v[20:23]
	v_mfma_f32_16x16x32_bf16 v[12:15], v[226:229], v[182:185], v[12:15]
	v_mfma_f32_16x16x32_bf16 v[4:7], v[218:221], v[210:213], v[4:7]
	v_mfma_f32_16x16x32_bf16 v[0:3], v[226:229], v[210:213], v[0:3]
	s_barrier
	s_add_i32 s6, 0, 0x18000
	v_add_u32_e32 v146, s6, v206
	ds_read_b128 v[128:131], v146
	ds_read_b128 v[132:135], v146 offset:1024
	ds_read_b128 v[136:139], v146 offset:2048
	ds_read_b128 v[146:149], v146 offset:3072
	s_add_u32 s50, s52, 0xb0000
	s_addc_u32 s51, s53, 0
	s_mov_b32 m0, s68
	v_lshl_add_u64 v[214:215], s[50:51], 0, v[154:155]
	ds_read_b128 v[162:165], v208 offset:32768
	ds_read_b128 v[166:169], v208 offset:33792
	ds_read_b128 v[170:173], v208 offset:34816
	ds_read_b128 v[174:177], v208 offset:35840
	ds_read_b128 v[178:181], v208 offset:36864
	ds_read_b128 v[182:185], v208 offset:37888
	ds_read_b128 v[194:197], v208 offset:38912
	ds_read_b128 v[210:213], v208 offset:39936
	global_load_lds_dwordx4 v[214:215], off
	v_lshl_add_u64 v[214:215], s[50:51], 0, v[152:153]
	s_mov_b32 m0, s69
	s_nop 0
	global_load_lds_dwordx4 v[214:215], off
	s_add_i32 s19, 0, 0x1c000
	v_add_u32_e32 v192, s19, v206
	ds_read_b128 v[214:217], v192
	ds_read_b128 v[218:221], v192 offset:1024
	ds_read_b128 v[222:225], v192 offset:2048
	ds_read_b128 v[226:229], v192 offset:3072
	s_waitcnt vmcnt(8)
	s_waitcnt lgkmcnt(0)
	s_barrier
	v_mfma_f32_16x16x32_bf16 v[124:127], v[128:131], v[162:165], v[124:127]
	v_mfma_f32_16x16x32_bf16 v[120:123], v[136:139], v[162:165], v[120:123]
	v_mfma_f32_16x16x32_bf16 v[108:111], v[128:131], v[170:173], v[108:111]
	v_mfma_f32_16x16x32_bf16 v[104:107], v[136:139], v[170:173], v[104:107]
	v_mfma_f32_16x16x32_bf16 v[96:99], v[128:131], v[178:181], v[96:99]
	v_mfma_f32_16x16x32_bf16 v[88:91], v[136:139], v[178:181], v[88:91]
	v_mfma_f32_16x16x32_bf16 v[84:87], v[128:131], v[194:197], v[84:87]
	v_mfma_f32_16x16x32_bf16 v[80:83], v[136:139], v[194:197], v[80:83]
	v_mfma_f32_16x16x32_bf16 v[124:127], v[132:135], v[166:169], v[124:127]
	v_mfma_f32_16x16x32_bf16 v[120:123], v[146:149], v[166:169], v[120:123]
	v_mfma_f32_16x16x32_bf16 v[108:111], v[132:135], v[174:177], v[108:111]
	v_mfma_f32_16x16x32_bf16 v[104:107], v[146:149], v[174:177], v[104:107]
	v_mfma_f32_16x16x32_bf16 v[96:99], v[132:135], v[182:185], v[96:99]
	v_mfma_f32_16x16x32_bf16 v[88:91], v[146:149], v[182:185], v[88:91]
	v_mfma_f32_16x16x32_bf16 v[84:87], v[132:135], v[210:213], v[84:87]
	v_mfma_f32_16x16x32_bf16 v[80:83], v[146:149], v[210:213], v[80:83]
	v_mfma_f32_16x16x32_bf16 v[116:119], v[214:217], v[162:165], v[116:119]
	v_mfma_f32_16x16x32_bf16 v[112:115], v[222:225], v[162:165], v[112:115]
	v_mfma_f32_16x16x32_bf16 v[100:103], v[214:217], v[170:173], v[100:103]
	v_mfma_f32_16x16x32_bf16 v[92:95], v[222:225], v[170:173], v[92:95]
	v_mfma_f32_16x16x32_bf16 v[76:79], v[214:217], v[178:181], v[76:79]
	v_mfma_f32_16x16x32_bf16 v[72:75], v[222:225], v[178:181], v[72:75]
	v_mfma_f32_16x16x32_bf16 v[68:71], v[214:217], v[194:197], v[68:71]
	v_mfma_f32_16x16x32_bf16 v[64:67], v[222:225], v[194:197], v[64:67]
	v_mfma_f32_16x16x32_bf16 v[116:119], v[218:221], v[166:169], v[116:119]
	v_mfma_f32_16x16x32_bf16 v[112:115], v[226:229], v[166:169], v[112:115]
	v_mfma_f32_16x16x32_bf16 v[100:103], v[218:221], v[174:177], v[100:103]
	v_mfma_f32_16x16x32_bf16 v[92:95], v[226:229], v[174:177], v[92:95]
	v_mfma_f32_16x16x32_bf16 v[76:79], v[218:221], v[182:185], v[76:79]
	v_mfma_f32_16x16x32_bf16 v[72:75], v[226:229], v[182:185], v[72:75]
	v_mfma_f32_16x16x32_bf16 v[68:71], v[218:221], v[210:213], v[68:71]
	v_mfma_f32_16x16x32_bf16 v[64:67], v[226:229], v[210:213], v[64:67]
	s_barrier
	s_add_i32 s6, s6, s57
	v_lshl_add_u64 v[230:231], v[230:231], 0, s[36:37]
	s_mov_b32 m0, s6
	s_nop 0
	global_load_lds_dwordx4 v[230:231], off
	v_lshl_add_u64 v[230:231], v[232:233], 0, s[36:37]
	s_add_i32 m0, s6, 0x2000
	s_nop 0
	global_load_lds_dwordx4 v[230:231], off
	s_mov_b32 m0, s70
	v_lshl_add_u64 v[230:231], v[234:235], 0, s[36:37]
	ds_read_b128 v[162:165], v208 offset:49152
	ds_read_b128 v[166:169], v208 offset:50176
	ds_read_b128 v[170:173], v208 offset:51200
	ds_read_b128 v[174:177], v208 offset:52224
	ds_read_b128 v[178:181], v208 offset:53248
	ds_read_b128 v[182:185], v208 offset:54272
	ds_read_b128 v[194:197], v208 offset:55296
	ds_read_b128 v[210:213], v208 offset:56320
	global_load_lds_dwordx4 v[230:231], off
	v_lshl_add_u64 v[230:231], v[236:237], 0, s[36:37]
	s_mov_b32 m0, s71
	s_nop 0
	global_load_lds_dwordx4 v[230:231], off
	s_add_u32 s48, s48, 0xb0080
	s_addc_u32 s49, s49, 0
	s_add_i32 s6, s19, s57
	v_lshl_add_u64 v[250:251], s[48:49], 0, v[140:141]
	s_mov_b32 m0, s6
	s_nop 0
	global_load_lds_dwordx4 v[250:251], off
	v_lshl_add_u64 v[250:251], s[48:49], 0, v[150:151]
	s_add_i32 m0, s6, 0x2000
	s_nop 0
	global_load_lds_dwordx4 v[250:251], off
	s_waitcnt vmcnt(8)
	s_waitcnt lgkmcnt(0)
	s_barrier
	v_mfma_f32_16x16x32_bf16 v[60:63], v[128:131], v[162:165], v[60:63]
	v_mfma_f32_16x16x32_bf16 v[56:59], v[136:139], v[162:165], v[56:59]
	v_mfma_f32_16x16x32_bf16 v[48:51], v[128:131], v[170:173], v[48:51]
	v_mfma_f32_16x16x32_bf16 v[40:43], v[136:139], v[170:173], v[40:43]
	v_mfma_f32_16x16x32_bf16 v[32:35], v[128:131], v[178:181], v[32:35]
	v_mfma_f32_16x16x32_bf16 v[24:27], v[136:139], v[178:181], v[24:27]
	v_mfma_f32_16x16x32_bf16 v[16:19], v[128:131], v[194:197], v[16:19]
	v_mfma_f32_16x16x32_bf16 v[8:11], v[136:139], v[194:197], v[8:11]
	v_mfma_f32_16x16x32_bf16 v[60:63], v[132:135], v[166:169], v[60:63]
	v_mfma_f32_16x16x32_bf16 v[56:59], v[146:149], v[166:169], v[56:59]
	v_mfma_f32_16x16x32_bf16 v[48:51], v[132:135], v[174:177], v[48:51]
	v_mfma_f32_16x16x32_bf16 v[40:43], v[146:149], v[174:177], v[40:43]
	v_mfma_f32_16x16x32_bf16 v[32:35], v[132:135], v[182:185], v[32:35]
	v_mfma_f32_16x16x32_bf16 v[24:27], v[146:149], v[182:185], v[24:27]
	v_mfma_f32_16x16x32_bf16 v[16:19], v[132:135], v[210:213], v[16:19]
	v_mfma_f32_16x16x32_bf16 v[8:11], v[146:149], v[210:213], v[8:11]
	v_mfma_f32_16x16x32_bf16 v[52:55], v[214:217], v[162:165], v[52:55]
	v_mfma_f32_16x16x32_bf16 v[44:47], v[222:225], v[162:165], v[44:47]
	v_mfma_f32_16x16x32_bf16 v[36:39], v[214:217], v[170:173], v[36:39]
	v_mfma_f32_16x16x32_bf16 v[28:31], v[222:225], v[170:173], v[28:31]
	v_mfma_f32_16x16x32_bf16 v[20:23], v[214:217], v[178:181], v[20:23]
	v_mfma_f32_16x16x32_bf16 v[12:15], v[222:225], v[178:181], v[12:15]
	v_mfma_f32_16x16x32_bf16 v[4:7], v[214:217], v[194:197], v[4:7]
	v_mfma_f32_16x16x32_bf16 v[0:3], v[222:225], v[194:197], v[0:3]
	v_mfma_f32_16x16x32_bf16 v[52:55], v[218:221], v[166:169], v[52:55]
	v_mfma_f32_16x16x32_bf16 v[44:47], v[226:229], v[166:169], v[44:47]
	v_mfma_f32_16x16x32_bf16 v[36:39], v[218:221], v[174:177], v[36:39]
	v_mfma_f32_16x16x32_bf16 v[28:31], v[226:229], v[174:177], v[28:31]
	v_mfma_f32_16x16x32_bf16 v[20:23], v[218:221], v[182:185], v[20:23]
	v_mfma_f32_16x16x32_bf16 v[12:15], v[226:229], v[182:185], v[12:15]
	v_mfma_f32_16x16x32_bf16 v[4:7], v[218:221], v[210:213], v[4:7]
	v_mfma_f32_16x16x32_bf16 v[0:3], v[226:229], v[210:213], v[0:3]
	s_add_i32 s12, s12, 2
	s_add_u32 s10, s10, 0x100
	s_addc_u32 s11, s11, 0
	s_cmp_gt_u32 s12, 41
	s_mov_b64 s[50:51], s[46:47]
	s_barrier
.LBB0_31:
	s_add_u32 s46, s50, 0x100
	s_addc_u32 s47, s51, 0
	s_add_i32 s6, 0, 0x10000
	v_add_u32_e32 v146, s6, v206
	ds_read_b128 v[128:131], v146
	ds_read_b128 v[132:135], v146 offset:1024
	ds_read_b128 v[136:139], v146 offset:2048
	ds_read_b128 v[146:149], v146 offset:3072
	s_cmp_eq_u32 s12, 40
	s_cselect_b32 s53, s31, s47
	s_cselect_b32 s52, s30, s46
	s_cselect_b32 s49, s35, s11
	s_cselect_b32 s48, s34, s10
	v_lshl_add_u64 v[214:215], s[50:51], 0, v[158:159]
	s_add_i32 m0, s58, 0xc000
	ds_read_b128 v[162:165], v208
	ds_read_b128 v[166:169], v208 offset:1024
	ds_read_b128 v[170:173], v208 offset:2048
	ds_read_b128 v[174:177], v208 offset:3072
	ds_read_b128 v[178:181], v208 offset:4096
	ds_read_b128 v[182:185], v208 offset:5120
	ds_read_b128 v[194:197], v208 offset:6144
	ds_read_b128 v[210:213], v208 offset:7168
	global_load_lds_dwordx4 v[214:215], off
	v_lshl_add_u64 v[214:215], s[50:51], 0, v[160:161]
	s_add_i32 m0, s58, 0xe000
	s_nop 0
	global_load_lds_dwordx4 v[214:215], off
	s_add_i32 s19, 0, 0x14000
	v_add_u32_e32 v192, s19, v206
	ds_read_b128 v[214:217], v192
	ds_read_b128 v[218:221], v192 offset:1024
	ds_read_b128 v[222:225], v192 offset:2048
	ds_read_b128 v[226:229], v192 offset:3072
	s_waitcnt vmcnt(8)
	s_waitcnt lgkmcnt(0)
	s_barrier
	v_mfma_f32_16x16x32_bf16 v[124:127], v[128:131], v[162:165], v[124:127]
	v_mfma_f32_16x16x32_bf16 v[120:123], v[136:139], v[162:165], v[120:123]
	v_mfma_f32_16x16x32_bf16 v[108:111], v[128:131], v[170:173], v[108:111]
	v_mfma_f32_16x16x32_bf16 v[104:107], v[136:139], v[170:173], v[104:107]
	v_mfma_f32_16x16x32_bf16 v[96:99], v[128:131], v[178:181], v[96:99]
	v_mfma_f32_16x16x32_bf16 v[88:91], v[136:139], v[178:181], v[88:91]
	v_mfma_f32_16x16x32_bf16 v[84:87], v[128:131], v[194:197], v[84:87]
	v_mfma_f32_16x16x32_bf16 v[80:83], v[136:139], v[194:197], v[80:83]
	v_mfma_f32_16x16x32_bf16 v[124:127], v[132:135], v[166:169], v[124:127]
	v_mfma_f32_16x16x32_bf16 v[120:123], v[146:149], v[166:169], v[120:123]
	v_mfma_f32_16x16x32_bf16 v[108:111], v[132:135], v[174:177], v[108:111]
	v_mfma_f32_16x16x32_bf16 v[104:107], v[146:149], v[174:177], v[104:107]
	v_mfma_f32_16x16x32_bf16 v[96:99], v[132:135], v[182:185], v[96:99]
	v_mfma_f32_16x16x32_bf16 v[88:91], v[146:149], v[182:185], v[88:91]
	v_mfma_f32_16x16x32_bf16 v[84:87], v[132:135], v[210:213], v[84:87]
	v_mfma_f32_16x16x32_bf16 v[80:83], v[146:149], v[210:213], v[80:83]
	v_mfma_f32_16x16x32_bf16 v[116:119], v[214:217], v[162:165], v[116:119]
	v_mfma_f32_16x16x32_bf16 v[112:115], v[222:225], v[162:165], v[112:115]
	v_mfma_f32_16x16x32_bf16 v[100:103], v[214:217], v[170:173], v[100:103]
	v_mfma_f32_16x16x32_bf16 v[92:95], v[222:225], v[170:173], v[92:95]
	v_mfma_f32_16x16x32_bf16 v[76:79], v[214:217], v[178:181], v[76:79]
	v_mfma_f32_16x16x32_bf16 v[72:75], v[222:225], v[178:181], v[72:75]
	v_mfma_f32_16x16x32_bf16 v[68:71], v[214:217], v[194:197], v[68:71]
	v_mfma_f32_16x16x32_bf16 v[64:67], v[222:225], v[194:197], v[64:67]
	v_mfma_f32_16x16x32_bf16 v[116:119], v[218:221], v[166:169], v[116:119]
	v_mfma_f32_16x16x32_bf16 v[112:115], v[226:229], v[166:169], v[112:115]
	v_mfma_f32_16x16x32_bf16 v[100:103], v[218:221], v[174:177], v[100:103]
	v_mfma_f32_16x16x32_bf16 v[92:95], v[226:229], v[174:177], v[92:95]
	v_mfma_f32_16x16x32_bf16 v[76:79], v[218:221], v[182:185], v[76:79]
	v_mfma_f32_16x16x32_bf16 v[72:75], v[226:229], v[182:185], v[72:75]
	v_mfma_f32_16x16x32_bf16 v[68:71], v[218:221], v[210:213], v[68:71]
	v_mfma_f32_16x16x32_bf16 v[64:67], v[226:229], v[210:213], v[64:67]
	s_barrier
	s_add_i32 s6, s6, s57
	v_lshl_add_u64 v[230:231], s[48:49], 0, v[140:141]
	s_mov_b32 m0, s6
	s_nop 0
	global_load_lds_dwordx4 v[230:231], off
	v_lshl_add_u64 v[232:233], s[48:49], 0, v[150:151]
	s_add_i32 m0, s6, 0x2000
	s_nop 0
	global_load_lds_dwordx4 v[232:233], off
	s_mov_b32 m0, s58
	v_lshl_add_u64 v[234:235], s[52:53], 0, v[154:155]
	ds_read_b128 v[162:165], v208 offset:16384
	ds_read_b128 v[166:169], v208 offset:17408
	ds_read_b128 v[170:173], v208 offset:18432
	ds_read_b128 v[174:177], v208 offset:19456
	ds_read_b128 v[178:181], v208 offset:20480
	ds_read_b128 v[182:185], v208 offset:21504
	ds_read_b128 v[194:197], v208 offset:22528
	ds_read_b128 v[210:213], v208 offset:23552
	global_load_lds_dwordx4 v[234:235], off
	v_lshl_add_u64 v[236:237], s[52:53], 0, v[152:153]
	s_mov_b32 m0, s59
	s_nop 0
	global_load_lds_dwordx4 v[236:237], off
	s_add_u32 s50, s48, 0xb0000
	s_addc_u32 s51, s49, 0
	s_add_i32 s6, s19, s57
	v_lshl_add_u64 v[250:251], s[50:51], 0, v[140:141]
	s_mov_b32 m0, s6
	s_nop 0
	global_load_lds_dwordx4 v[250:251], off
	v_lshl_add_u64 v[250:251], s[50:51], 0, v[150:151]
	s_add_i32 m0, s6, 0x2000
	s_nop 0
	global_load_lds_dwordx4 v[250:251], off
	s_waitcnt vmcnt(8)
	s_waitcnt lgkmcnt(0)
	s_barrier
	v_mfma_f32_16x16x32_bf16 v[60:63], v[128:131], v[162:165], v[60:63]
	v_mfma_f32_16x16x32_bf16 v[56:59], v[136:139], v[162:165], v[56:59]
	v_mfma_f32_16x16x32_bf16 v[48:51], v[128:131], v[170:173], v[48:51]
	v_mfma_f32_16x16x32_bf16 v[40:43], v[136:139], v[170:173], v[40:43]
	v_mfma_f32_16x16x32_bf16 v[32:35], v[128:131], v[178:181], v[32:35]
	v_mfma_f32_16x16x32_bf16 v[24:27], v[136:139], v[178:181], v[24:27]
	v_mfma_f32_16x16x32_bf16 v[16:19], v[128:131], v[194:197], v[16:19]
	v_mfma_f32_16x16x32_bf16 v[8:11], v[136:139], v[194:197], v[8:11]
	v_mfma_f32_16x16x32_bf16 v[60:63], v[132:135], v[166:169], v[60:63]
	v_mfma_f32_16x16x32_bf16 v[56:59], v[146:149], v[166:169], v[56:59]
	v_mfma_f32_16x16x32_bf16 v[48:51], v[132:135], v[174:177], v[48:51]
	v_mfma_f32_16x16x32_bf16 v[40:43], v[146:149], v[174:177], v[40:43]
	v_mfma_f32_16x16x32_bf16 v[32:35], v[132:135], v[182:185], v[32:35]
	v_mfma_f32_16x16x32_bf16 v[24:27], v[146:149], v[182:185], v[24:27]
	v_mfma_f32_16x16x32_bf16 v[16:19], v[132:135], v[210:213], v[16:19]
	v_mfma_f32_16x16x32_bf16 v[8:11], v[146:149], v[210:213], v[8:11]
	v_mfma_f32_16x16x32_bf16 v[52:55], v[214:217], v[162:165], v[52:55]
	v_mfma_f32_16x16x32_bf16 v[44:47], v[222:225], v[162:165], v[44:47]
	v_mfma_f32_16x16x32_bf16 v[36:39], v[214:217], v[170:173], v[36:39]
	v_mfma_f32_16x16x32_bf16 v[28:31], v[222:225], v[170:173], v[28:31]
	v_mfma_f32_16x16x32_bf16 v[20:23], v[214:217], v[178:181], v[20:23]
	v_mfma_f32_16x16x32_bf16 v[12:15], v[222:225], v[178:181], v[12:15]
	v_mfma_f32_16x16x32_bf16 v[4:7], v[214:217], v[194:197], v[4:7]
	v_mfma_f32_16x16x32_bf16 v[0:3], v[222:225], v[194:197], v[0:3]
	v_mfma_f32_16x16x32_bf16 v[52:55], v[218:221], v[166:169], v[52:55]
	v_mfma_f32_16x16x32_bf16 v[44:47], v[226:229], v[166:169], v[44:47]
	v_mfma_f32_16x16x32_bf16 v[36:39], v[218:221], v[174:177], v[36:39]
	v_mfma_f32_16x16x32_bf16 v[28:31], v[226:229], v[174:177], v[28:31]
	v_mfma_f32_16x16x32_bf16 v[20:23], v[218:221], v[182:185], v[20:23]
	v_mfma_f32_16x16x32_bf16 v[12:15], v[226:229], v[182:185], v[12:15]
	v_mfma_f32_16x16x32_bf16 v[4:7], v[218:221], v[210:213], v[4:7]
	v_mfma_f32_16x16x32_bf16 v[0:3], v[226:229], v[210:213], v[0:3]
	s_barrier
	s_add_i32 s6, 0, 0x18000
	v_add_u32_e32 v146, s6, v206
	ds_read_b128 v[128:131], v146
	ds_read_b128 v[132:135], v146 offset:1024
	ds_read_b128 v[136:139], v146 offset:2048
	ds_read_b128 v[146:149], v146 offset:3072
	s_add_u32 s50, s52, 0xb0000
	s_addc_u32 s51, s53, 0
	s_mov_b32 m0, s68
	v_lshl_add_u64 v[214:215], s[50:51], 0, v[154:155]
	ds_read_b128 v[162:165], v208 offset:32768
	ds_read_b128 v[166:169], v208 offset:33792
	ds_read_b128 v[170:173], v208 offset:34816
	ds_read_b128 v[174:177], v208 offset:35840
	ds_read_b128 v[178:181], v208 offset:36864
	ds_read_b128 v[182:185], v208 offset:37888
	ds_read_b128 v[194:197], v208 offset:38912
	ds_read_b128 v[210:213], v208 offset:39936
	global_load_lds_dwordx4 v[214:215], off
	v_lshl_add_u64 v[214:215], s[50:51], 0, v[152:153]
	s_mov_b32 m0, s69
	s_nop 0
	global_load_lds_dwordx4 v[214:215], off
	s_add_i32 s19, 0, 0x1c000
	v_add_u32_e32 v192, s19, v206
	ds_read_b128 v[214:217], v192
	ds_read_b128 v[218:221], v192 offset:1024
	ds_read_b128 v[222:225], v192 offset:2048
	ds_read_b128 v[226:229], v192 offset:3072
	s_waitcnt vmcnt(8)
	s_waitcnt lgkmcnt(0)
	s_barrier
	v_mfma_f32_16x16x32_bf16 v[124:127], v[128:131], v[162:165], v[124:127]
	v_mfma_f32_16x16x32_bf16 v[120:123], v[136:139], v[162:165], v[120:123]
	v_mfma_f32_16x16x32_bf16 v[108:111], v[128:131], v[170:173], v[108:111]
	v_mfma_f32_16x16x32_bf16 v[104:107], v[136:139], v[170:173], v[104:107]
	v_mfma_f32_16x16x32_bf16 v[96:99], v[128:131], v[178:181], v[96:99]
	v_mfma_f32_16x16x32_bf16 v[88:91], v[136:139], v[178:181], v[88:91]
	v_mfma_f32_16x16x32_bf16 v[84:87], v[128:131], v[194:197], v[84:87]
	v_mfma_f32_16x16x32_bf16 v[80:83], v[136:139], v[194:197], v[80:83]
	v_mfma_f32_16x16x32_bf16 v[124:127], v[132:135], v[166:169], v[124:127]
	v_mfma_f32_16x16x32_bf16 v[120:123], v[146:149], v[166:169], v[120:123]
	v_mfma_f32_16x16x32_bf16 v[108:111], v[132:135], v[174:177], v[108:111]
	v_mfma_f32_16x16x32_bf16 v[104:107], v[146:149], v[174:177], v[104:107]
	v_mfma_f32_16x16x32_bf16 v[96:99], v[132:135], v[182:185], v[96:99]
	v_mfma_f32_16x16x32_bf16 v[88:91], v[146:149], v[182:185], v[88:91]
	v_mfma_f32_16x16x32_bf16 v[84:87], v[132:135], v[210:213], v[84:87]
	v_mfma_f32_16x16x32_bf16 v[80:83], v[146:149], v[210:213], v[80:83]
	v_mfma_f32_16x16x32_bf16 v[116:119], v[214:217], v[162:165], v[116:119]
	v_mfma_f32_16x16x32_bf16 v[112:115], v[222:225], v[162:165], v[112:115]
	v_mfma_f32_16x16x32_bf16 v[100:103], v[214:217], v[170:173], v[100:103]
	v_mfma_f32_16x16x32_bf16 v[92:95], v[222:225], v[170:173], v[92:95]
	v_mfma_f32_16x16x32_bf16 v[76:79], v[214:217], v[178:181], v[76:79]
	v_mfma_f32_16x16x32_bf16 v[72:75], v[222:225], v[178:181], v[72:75]
	v_mfma_f32_16x16x32_bf16 v[68:71], v[214:217], v[194:197], v[68:71]
	v_mfma_f32_16x16x32_bf16 v[64:67], v[222:225], v[194:197], v[64:67]
	v_mfma_f32_16x16x32_bf16 v[116:119], v[218:221], v[166:169], v[116:119]
	v_mfma_f32_16x16x32_bf16 v[112:115], v[226:229], v[166:169], v[112:115]
	v_mfma_f32_16x16x32_bf16 v[100:103], v[218:221], v[174:177], v[100:103]
	v_mfma_f32_16x16x32_bf16 v[92:95], v[226:229], v[174:177], v[92:95]
	v_mfma_f32_16x16x32_bf16 v[76:79], v[218:221], v[182:185], v[76:79]
	v_mfma_f32_16x16x32_bf16 v[72:75], v[226:229], v[182:185], v[72:75]
	v_mfma_f32_16x16x32_bf16 v[68:71], v[218:221], v[210:213], v[68:71]
	v_mfma_f32_16x16x32_bf16 v[64:67], v[226:229], v[210:213], v[64:67]
	s_barrier
	s_add_i32 s6, s6, s57
	v_lshl_add_u64 v[230:231], v[230:231], 0, s[36:37]
	s_mov_b32 m0, s6
	s_nop 0
	global_load_lds_dwordx4 v[230:231], off
	v_lshl_add_u64 v[230:231], v[232:233], 0, s[36:37]
	s_add_i32 m0, s6, 0x2000
	s_nop 0
	global_load_lds_dwordx4 v[230:231], off
	s_mov_b32 m0, s70
	v_lshl_add_u64 v[230:231], v[234:235], 0, s[36:37]
	ds_read_b128 v[162:165], v208 offset:49152
	ds_read_b128 v[166:169], v208 offset:50176
	ds_read_b128 v[170:173], v208 offset:51200
	ds_read_b128 v[174:177], v208 offset:52224
	ds_read_b128 v[178:181], v208 offset:53248
	ds_read_b128 v[182:185], v208 offset:54272
	ds_read_b128 v[194:197], v208 offset:55296
	ds_read_b128 v[210:213], v208 offset:56320
	global_load_lds_dwordx4 v[230:231], off
	v_lshl_add_u64 v[230:231], v[236:237], 0, s[36:37]
	s_mov_b32 m0, s71
	s_nop 0
	global_load_lds_dwordx4 v[230:231], off
	s_add_u32 s48, s48, 0xb0080
	s_addc_u32 s49, s49, 0
	s_add_i32 s6, s19, s57
	v_lshl_add_u64 v[250:251], s[48:49], 0, v[140:141]
	s_mov_b32 m0, s6
	s_nop 0
	global_load_lds_dwordx4 v[250:251], off
	v_lshl_add_u64 v[250:251], s[48:49], 0, v[150:151]
	s_add_i32 m0, s6, 0x2000
	s_nop 0
	global_load_lds_dwordx4 v[250:251], off
	s_waitcnt vmcnt(8)
	s_waitcnt lgkmcnt(0)
	s_barrier
	v_mfma_f32_16x16x32_bf16 v[60:63], v[128:131], v[162:165], v[60:63]
	v_mfma_f32_16x16x32_bf16 v[56:59], v[136:139], v[162:165], v[56:59]
	v_mfma_f32_16x16x32_bf16 v[48:51], v[128:131], v[170:173], v[48:51]
	v_mfma_f32_16x16x32_bf16 v[40:43], v[136:139], v[170:173], v[40:43]
	v_mfma_f32_16x16x32_bf16 v[32:35], v[128:131], v[178:181], v[32:35]
	v_mfma_f32_16x16x32_bf16 v[24:27], v[136:139], v[178:181], v[24:27]
	v_mfma_f32_16x16x32_bf16 v[16:19], v[128:131], v[194:197], v[16:19]
	v_mfma_f32_16x16x32_bf16 v[8:11], v[136:139], v[194:197], v[8:11]
	v_mfma_f32_16x16x32_bf16 v[60:63], v[132:135], v[166:169], v[60:63]
	v_mfma_f32_16x16x32_bf16 v[56:59], v[146:149], v[166:169], v[56:59]
	v_mfma_f32_16x16x32_bf16 v[48:51], v[132:135], v[174:177], v[48:51]
	v_mfma_f32_16x16x32_bf16 v[40:43], v[146:149], v[174:177], v[40:43]
	v_mfma_f32_16x16x32_bf16 v[32:35], v[132:135], v[182:185], v[32:35]
	v_mfma_f32_16x16x32_bf16 v[24:27], v[146:149], v[182:185], v[24:27]
	v_mfma_f32_16x16x32_bf16 v[16:19], v[132:135], v[210:213], v[16:19]
	v_mfma_f32_16x16x32_bf16 v[8:11], v[146:149], v[210:213], v[8:11]
	v_mfma_f32_16x16x32_bf16 v[52:55], v[214:217], v[162:165], v[52:55]
	v_mfma_f32_16x16x32_bf16 v[44:47], v[222:225], v[162:165], v[44:47]
	v_mfma_f32_16x16x32_bf16 v[36:39], v[214:217], v[170:173], v[36:39]
	v_mfma_f32_16x16x32_bf16 v[28:31], v[222:225], v[170:173], v[28:31]
	v_mfma_f32_16x16x32_bf16 v[20:23], v[214:217], v[178:181], v[20:23]
	v_mfma_f32_16x16x32_bf16 v[12:15], v[222:225], v[178:181], v[12:15]
	v_mfma_f32_16x16x32_bf16 v[4:7], v[214:217], v[194:197], v[4:7]
	v_mfma_f32_16x16x32_bf16 v[0:3], v[222:225], v[194:197], v[0:3]
	v_mfma_f32_16x16x32_bf16 v[52:55], v[218:221], v[166:169], v[52:55]
	v_mfma_f32_16x16x32_bf16 v[44:47], v[226:229], v[166:169], v[44:47]
	v_mfma_f32_16x16x32_bf16 v[36:39], v[218:221], v[174:177], v[36:39]
	v_mfma_f32_16x16x32_bf16 v[28:31], v[226:229], v[174:177], v[28:31]
	v_mfma_f32_16x16x32_bf16 v[20:23], v[218:221], v[182:185], v[20:23]
	v_mfma_f32_16x16x32_bf16 v[12:15], v[226:229], v[182:185], v[12:15]
	v_mfma_f32_16x16x32_bf16 v[4:7], v[218:221], v[210:213], v[4:7]
	v_mfma_f32_16x16x32_bf16 v[0:3], v[226:229], v[210:213], v[0:3]
	s_add_i32 s12, s12, 2
	s_add_u32 s10, s10, 0x100
	s_addc_u32 s11, s11, 0
	s_cmp_gt_u32 s12, 41
	s_mov_b64 s[50:51], s[46:47]
	s_barrier
	s_cbranch_scc0 .LBB0_31
	s_mov_b32 s100, 1
	s_ashr_i32 s39, s38, 31
	v_lshl_or_b32 v128, s81, 8, v207
	s_lshl_b64 s[10:11], s[38:39], 8
	v_ashrrev_i32_e32 v129, 31, v128
	v_lshl_add_u64 v[168:169], s[10:11], 0, v[156:157]
	v_lshlrev_b64 v[170:171], 1, v[128:129]
	v_lshl_add_u64 v[174:175], s[4:5], 0, v[170:171]
	v_lshlrev_b64 v[172:173], 11, v[168:169]
	v_lshl_add_u64 v[128:129], v[174:175], 0, v[172:173]
	global_load_dwordx4 v[146:149], v[128:129], off
	global_load_dwordx4 v[182:185], v[128:129], off offset:256
	v_or_b32_e32 v166, 16, v168
	v_mov_b32_e32 v167, v169
	v_lshlrev_b64 v[176:177], 11, v[166:167]
	v_lshl_add_u64 v[128:129], v[174:175], 0, v[176:177]
	global_load_dwordx4 v[194:197], v[128:129], off
	global_load_dwordx4 v[210:213], v[128:129], off offset:256
	v_or_b32_e32 v164, 32, v168
	v_mov_b32_e32 v165, v169
	v_or_b32_e32 v162, 48, v168
	v_mov_b32_e32 v163, v169
	v_lshlrev_b64 v[180:181], 11, v[164:165]
	v_lshlrev_b64 v[178:179], 11, v[162:163]
	v_lshl_add_u64 v[128:129], v[174:175], 0, v[180:181]
	v_lshl_add_u64 v[130:131], v[174:175], 0, v[178:179]
	global_load_dwordx4 v[214:217], v[128:129], off
	global_load_dwordx4 v[136:139], v[128:129], off offset:256
	global_load_dwordx4 v[132:135], v[130:131], off
	s_nop 0
	global_load_dwordx4 v[128:131], v[130:131], off offset:256
	s_mov_b64 s[10:11], 0x90
	v_lshl_add_u64 v[172:173], s[28:29], 0, v[172:173]
	v_lshl_add_u64 v[172:173], v[172:173], 0, v[170:171]
	s_waitcnt vmcnt(0)
	v_lshlrev_b32_e32 v218, 16, v146
	v_and_b32_e32 v219, 0xffff0000, v146
	v_lshlrev_b32_e32 v220, 16, v148
	v_and_b32_e32 v221, 0xffff0000, v148
	v_lshlrev_b32_e32 v146, 16, v147
	v_and_b32_e32 v147, 0xffff0000, v147
	v_lshlrev_b32_e32 v222, 16, v182
	v_and_b32_e32 v223, 0xffff0000, v182
	v_lshlrev_b32_e32 v224, 16, v184
	v_and_b32_e32 v225, 0xffff0000, v184
	v_lshlrev_b32_e32 v182, 16, v183
	v_and_b32_e32 v183, 0xffff0000, v183
	v_pk_fma_f32 v[124:125], v[124:125], 0.5, v[218:219] op_sel_hi:[1,0,1]
	v_pk_fma_f32 v[120:121], v[120:121], 0.5, v[220:221] op_sel_hi:[1,0,1]
	v_pk_fma_f32 v[126:127], v[126:127], 0.5, v[146:147] op_sel_hi:[1,0,1]
	v_pk_fma_f32 v[116:117], v[116:117], 0.5, v[222:223] op_sel_hi:[1,0,1]
	v_pk_fma_f32 v[146:147], v[112:113], 0.5, v[224:225] op_sel_hi:[1,0,1]
	v_pk_fma_f32 v[118:119], v[118:119], 0.5, v[182:183] op_sel_hi:[1,0,1]
	v_pk_mul_f32 v[220:221], v[124:125], v[124:125]
	v_pk_mul_f32 v[222:223], v[126:127], v[126:127]
	v_cvt_pk_bf16_f32 v112, v124, v125
	v_cvt_pk_bf16_f32 v113, v126, v127
	v_pk_mul_f32 v[124:125], v[116:117], v[116:117]
	v_pk_mul_f32 v[126:127], v[118:119], v[118:119]
	v_pk_mul_f32 v[228:229], v[146:147], v[146:147]
	v_cvt_pk_bf16_f32 v116, v116, v117
	v_cvt_pk_bf16_f32 v117, v118, v119
	v_cvt_pk_bf16_f32 v118, v146, v147
	v_add_f32_e32 v146, v220, v221
	v_add_f32_e32 v146, v222, v146
	v_lshlrev_b32_e32 v148, 16, v149
	v_and_b32_e32 v149, 0xffff0000, v149
	v_pk_mul_f32 v[224:225], v[120:121], v[120:121]
	v_add_f32_e32 v146, v223, v146
	v_pk_fma_f32 v[122:123], v[122:123], 0.5, v[148:149] op_sel_hi:[1,0,1]
	v_add_f32_e32 v146, v224, v146
	v_pk_mul_f32 v[226:227], v[122:123], v[122:123]
	v_add_f32_e32 v146, v225, v146
	v_add_f32_e32 v146, v226, v146
	v_add_f32_e32 v146, v227, v146
	v_add_f32_e32 v124, v124, v146
	v_add_f32_e32 v124, v125, v124
	v_add_f32_e32 v124, v126, v124
	v_lshlrev_b32_e32 v184, 16, v185
	v_and_b32_e32 v185, 0xffff0000, v185
	v_add_f32_e32 v124, v127, v124
	v_pk_fma_f32 v[148:149], v[114:115], 0.5, v[184:185] op_sel_hi:[1,0,1]
	v_add_f32_e32 v124, v228, v124
	v_pk_mul_f32 v[230:231], v[148:149], v[148:149]
	v_add_f32_e32 v124, v229, v124
	v_add_f32_e32 v124, v230, v124
	v_add_f32_e32 v209, v231, v124
	v_lshlrev_b32_e32 v124, 16, v212
	v_and_b32_e32 v125, 0xffff0000, v212
	v_pk_fma_f32 v[124:125], v[92:93], 0.5, v[124:125] op_sel_hi:[1,0,1]
	v_lshlrev_b32_e32 v92, 16, v211
	v_and_b32_e32 v93, 0xffff0000, v211
	v_pk_fma_f32 v[102:103], v[102:103], 0.5, v[92:93] op_sel_hi:[1,0,1]
	v_lshlrev_b32_e32 v92, 16, v213
	v_and_b32_e32 v93, 0xffff0000, v213
	v_pk_fma_f32 v[126:127], v[94:95], 0.5, v[92:93] op_sel_hi:[1,0,1]
	v_lshlrev_b32_e32 v92, 16, v214
	v_and_b32_e32 v93, 0xffff0000, v214
	v_pk_fma_f32 v[92:93], v[96:97], 0.5, v[92:93] op_sel_hi:[1,0,1]
	v_lshlrev_b32_e32 v96, 16, v217
	v_and_b32_e32 v97, 0xffff0000, v217
	v_lshlrev_b32_e32 v94, 16, v216
	v_and_b32_e32 v95, 0xffff0000, v216
	v_pk_fma_f32 v[90:91], v[90:91], 0.5, v[96:97] op_sel_hi:[1,0,1]
	v_lshlrev_b32_e32 v96, 16, v136
	v_and_b32_e32 v97, 0xffff0000, v136
	v_lshlrev_b32_e32 v182, 16, v194
	v_and_b32_e32 v183, 0xffff0000, v194
	v_pk_fma_f32 v[88:89], v[88:89], 0.5, v[94:95] op_sel_hi:[1,0,1]
	v_lshlrev_b32_e32 v94, 16, v215
	v_and_b32_e32 v95, 0xffff0000, v215
	v_pk_fma_f32 v[96:97], v[76:77], 0.5, v[96:97] op_sel_hi:[1,0,1]
	v_lshl_add_u64 v[76:77], v[168:169], 0, s[36:37]
	v_lshlrev_b32_e32 v184, 16, v196
	v_and_b32_e32 v185, 0xffff0000, v196
	v_cvt_pk_bf16_f32 v114, v120, v121
	v_pk_fma_f32 v[120:121], v[108:109], 0.5, v[182:183] op_sel_hi:[1,0,1]
	v_pk_fma_f32 v[94:95], v[98:99], 0.5, v[94:95] op_sel_hi:[1,0,1]
	v_lshlrev_b64 v[182:183], 11, v[76:77]
	v_lshlrev_b32_e32 v98, 16, v138
	v_and_b32_e32 v99, 0xffff0000, v138
	v_pk_fma_f32 v[108:109], v[104:105], 0.5, v[184:185] op_sel_hi:[1,0,1]
	v_lshl_add_u64 v[184:185], v[174:175], 0, v[182:183]
	v_pk_fma_f32 v[98:99], v[72:73], 0.5, v[98:99] op_sel_hi:[1,0,1]
	v_lshlrev_b32_e32 v72, 16, v137
	v_and_b32_e32 v73, 0xffff0000, v137
	v_lshlrev_b32_e32 v218, 16, v210
	v_and_b32_e32 v219, 0xffff0000, v210
	global_load_dwordx4 v[210:213], v[184:185], off
	v_pk_fma_f32 v[136:137], v[78:79], 0.5, v[72:73] op_sel_hi:[1,0,1]
	v_lshlrev_b32_e32 v72, 16, v139
	v_and_b32_e32 v73, 0xffff0000, v139
	v_pk_fma_f32 v[138:139], v[74:75], 0.5, v[72:73] op_sel_hi:[1,0,1]
	v_lshlrev_b32_e32 v72, 16, v132
	v_and_b32_e32 v73, 0xffff0000, v132
	v_pk_fma_f32 v[74:75], v[84:85], 0.5, v[72:73] op_sel_hi:[1,0,1]
	v_lshlrev_b32_e32 v72, 16, v134
	v_and_b32_e32 v73, 0xffff0000, v134
	v_pk_fma_f32 v[78:79], v[80:81], 0.5, v[72:73] op_sel_hi:[1,0,1]
	v_lshlrev_b32_e32 v72, 16, v133
	v_and_b32_e32 v73, 0xffff0000, v133
	v_pk_fma_f32 v[100:101], v[100:101], 0.5, v[218:219] op_sel_hi:[1,0,1]
	global_load_dwordx4 v[218:221], v[184:185], off offset:256
	v_pk_fma_f32 v[80:81], v[86:87], 0.5, v[72:73] op_sel_hi:[1,0,1]
	v_lshlrev_b32_e32 v72, 16, v135
	v_and_b32_e32 v73, 0xffff0000, v135
	v_pk_fma_f32 v[82:83], v[82:83], 0.5, v[72:73] op_sel_hi:[1,0,1]
	v_lshl_add_u64 v[72:73], v[168:169], 0, s[10:11]
	v_lshlrev_b64 v[132:133], 11, v[72:73]
	v_lshl_add_u64 v[134:135], v[174:175], 0, v[132:133]
	v_lshlrev_b32_e32 v84, 16, v128
	v_and_b32_e32 v85, 0xffff0000, v128
	global_load_dwordx4 v[226:229], v[134:135], off
	global_load_dwordx4 v[234:237], v[134:135], off offset:256
	v_pk_fma_f32 v[84:85], v[68:69], 0.5, v[84:85] op_sel_hi:[1,0,1]
	v_lshlrev_b32_e32 v68, 16, v130
	v_and_b32_e32 v69, 0xffff0000, v130
	v_pk_fma_f32 v[86:87], v[64:65], 0.5, v[68:69] op_sel_hi:[1,0,1]
	v_lshlrev_b32_e32 v64, 16, v129
	v_and_b32_e32 v65, 0xffff0000, v129
	s_mov_b64 s[10:11], 0xa0
	v_pk_fma_f32 v[128:129], v[70:71], 0.5, v[64:65] op_sel_hi:[1,0,1]
	v_lshl_add_u64 v[70:71], v[168:169], 0, s[10:11]
	s_mov_b64 s[10:11], 0xb0
	v_lshlrev_b32_e32 v64, 16, v131
	v_and_b32_e32 v65, 0xffff0000, v131
	v_lshlrev_b64 v[134:135], 11, v[70:71]
	v_lshl_add_u64 v[68:69], v[168:169], 0, s[10:11]
	v_pk_fma_f32 v[130:131], v[66:67], 0.5, v[64:65] op_sel_hi:[1,0,1]
	v_lshl_add_u64 v[64:65], v[174:175], 0, v[134:135]
	v_lshlrev_b64 v[184:185], 11, v[68:69]
	global_load_dwordx4 v[238:241], v[64:65], off
	global_load_dwordx4 v[242:245], v[64:65], off offset:256
	v_lshl_add_u64 v[64:65], v[174:175], 0, v[184:185]
	global_load_dwordx4 v[246:249], v[64:65], off
	s_nop 0
	global_load_dwordx4 v[64:67], v[64:65], off offset:256
	v_lshlrev_b32_e32 v194, 16, v195
	v_and_b32_e32 v195, 0xffff0000, v195
	v_lshlrev_b32_e32 v196, 16, v197
	v_and_b32_e32 v197, 0xffff0000, v197
	v_cvt_pk_bf16_f32 v115, v122, v123
	v_cvt_pk_bf16_f32 v119, v148, v149
	v_pk_fma_f32 v[122:123], v[110:111], 0.5, v[194:195] op_sel_hi:[1,0,1]
	v_pk_fma_f32 v[110:111], v[106:107], 0.5, v[196:197] op_sel_hi:[1,0,1]
	global_store_dwordx4 v[172:173], v[112:115], off
	global_store_dwordx4 v[172:173], v[116:119], off offset:256
	v_cvt_pk_bf16_f32 v104, v120, v121
	v_lshl_add_u64 v[112:113], s[28:29], 0, v[176:177]
	v_cvt_pk_bf16_f32 v105, v122, v123
	v_cvt_pk_bf16_f32 v106, v108, v109
	v_cvt_pk_bf16_f32 v107, v110, v111
	v_lshl_add_u64 v[112:113], v[112:113], 0, v[170:171]
	v_cvt_pk_bf16_f32 v146, v100, v101
	v_cvt_pk_bf16_f32 v147, v102, v103
	v_cvt_pk_bf16_f32 v148, v124, v125
	v_cvt_pk_bf16_f32 v149, v126, v127
	global_store_dwordx4 v[112:113], v[104:107], off
	global_store_dwordx4 v[112:113], v[146:149], off offset:256
	v_cvt_pk_bf16_f32 v194, v92, v93
	v_lshl_add_u64 v[104:105], s[28:29], 0, v[180:181]
	v_cvt_pk_bf16_f32 v195, v94, v95
	v_cvt_pk_bf16_f32 v196, v88, v89
	v_cvt_pk_bf16_f32 v197, v90, v91
	v_lshl_add_u64 v[104:105], v[104:105], 0, v[170:171]
	v_cvt_pk_bf16_f32 v214, v96, v97
	v_cvt_pk_bf16_f32 v215, v136, v137
	v_cvt_pk_bf16_f32 v216, v98, v99
	v_cvt_pk_bf16_f32 v217, v138, v139
	global_store_dwordx4 v[104:105], v[194:197], off
	global_store_dwordx4 v[104:105], v[214:217], off offset:256
	v_lshl_add_u64 v[104:105], s[28:29], 0, v[178:179]
	v_cvt_pk_bf16_f32 v222, v74, v75
	v_cvt_pk_bf16_f32 v223, v80, v81
	v_cvt_pk_bf16_f32 v224, v78, v79
	v_cvt_pk_bf16_f32 v225, v82, v83
	v_lshl_add_u64 v[104:105], v[104:105], 0, v[170:171]
	v_cvt_pk_bf16_f32 v230, v84, v85
	v_cvt_pk_bf16_f32 v231, v128, v129
	v_cvt_pk_bf16_f32 v232, v86, v87
	v_cvt_pk_bf16_f32 v233, v130, v131
	global_store_dwordx4 v[104:105], v[222:225], off
	global_store_dwordx4 v[104:105], v[230:233], off offset:256
	s_waitcnt vmcnt(0)
	v_lshlrev_b32_e32 v104, 16, v210
	v_and_b32_e32 v105, 0xffff0000, v210
	v_pk_fma_f32 v[60:61], v[60:61], 0.5, v[104:105] op_sel_hi:[1,0,1]
	v_lshlrev_b32_e32 v104, 16, v212
	v_and_b32_e32 v105, 0xffff0000, v212
	v_pk_fma_f32 v[56:57], v[56:57], 0.5, v[104:105] op_sel_hi:[1,0,1]
	v_lshlrev_b32_e32 v104, 16, v211
	v_and_b32_e32 v105, 0xffff0000, v211
	v_pk_fma_f32 v[62:63], v[62:63], 0.5, v[104:105] op_sel_hi:[1,0,1]
	v_lshlrev_b32_e32 v104, 16, v213
	v_and_b32_e32 v105, 0xffff0000, v213
	v_pk_fma_f32 v[58:59], v[58:59], 0.5, v[104:105] op_sel_hi:[1,0,1]
	v_lshlrev_b32_e32 v104, 16, v218
	v_and_b32_e32 v105, 0xffff0000, v218
	v_pk_fma_f32 v[52:53], v[52:53], 0.5, v[104:105] op_sel_hi:[1,0,1]
	v_lshlrev_b32_e32 v104, 16, v220
	v_and_b32_e32 v105, 0xffff0000, v220
	v_pk_fma_f32 v[104:105], v[44:45], 0.5, v[104:105] op_sel_hi:[1,0,1]
	v_lshlrev_b32_e32 v44, 16, v219
	v_and_b32_e32 v45, 0xffff0000, v219
	v_pk_fma_f32 v[54:55], v[54:55], 0.5, v[44:45] op_sel_hi:[1,0,1]
	v_lshlrev_b32_e32 v44, 16, v221
	v_and_b32_e32 v45, 0xffff0000, v221
	v_pk_fma_f32 v[106:107], v[46:47], 0.5, v[44:45] op_sel_hi:[1,0,1]
	v_lshlrev_b32_e32 v44, 16, v226
	v_and_b32_e32 v45, 0xffff0000, v226
	v_pk_fma_f32 v[44:45], v[48:49], 0.5, v[44:45] op_sel_hi:[1,0,1]
	v_lshlrev_b32_e32 v48, 16, v229
	v_and_b32_e32 v49, 0xffff0000, v229
	v_pk_fma_f32 v[42:43], v[42:43], 0.5, v[48:49] op_sel_hi:[1,0,1]
	v_lshlrev_b32_e32 v48, 16, v234
	v_and_b32_e32 v49, 0xffff0000, v234
	v_pk_fma_f32 v[36:37], v[36:37], 0.5, v[48:49] op_sel_hi:[1,0,1]
	v_lshlrev_b32_e32 v48, 16, v236
	v_and_b32_e32 v49, 0xffff0000, v236
	v_lshlrev_b32_e32 v46, 16, v228
	v_and_b32_e32 v47, 0xffff0000, v228
	v_pk_fma_f32 v[48:49], v[28:29], 0.5, v[48:49] op_sel_hi:[1,0,1]
	v_lshlrev_b32_e32 v28, 16, v235
	v_and_b32_e32 v29, 0xffff0000, v235
	v_pk_fma_f32 v[40:41], v[40:41], 0.5, v[46:47] op_sel_hi:[1,0,1]
	v_lshlrev_b32_e32 v46, 16, v227
	v_and_b32_e32 v47, 0xffff0000, v227
	v_pk_fma_f32 v[38:39], v[38:39], 0.5, v[28:29] op_sel_hi:[1,0,1]
	v_lshlrev_b32_e32 v28, 16, v237
	v_and_b32_e32 v29, 0xffff0000, v237
	v_pk_fma_f32 v[46:47], v[50:51], 0.5, v[46:47] op_sel_hi:[1,0,1]
	v_pk_fma_f32 v[50:51], v[30:31], 0.5, v[28:29] op_sel_hi:[1,0,1]
	v_lshlrev_b32_e32 v28, 16, v238
	v_and_b32_e32 v29, 0xffff0000, v238
	v_lshlrev_b32_e32 v180, 16, v64
	v_and_b32_e32 v181, 0xffff0000, v64
	v_pk_fma_f32 v[28:29], v[32:33], 0.5, v[28:29] op_sel_hi:[1,0,1]
	v_lshlrev_b32_e32 v32, 16, v241
	v_and_b32_e32 v33, 0xffff0000, v241
	v_pk_fma_f32 v[4:5], v[4:5], 0.5, v[180:181] op_sel_hi:[1,0,1]
	v_lshlrev_b32_e32 v180, 16, v66
	v_and_b32_e32 v181, 0xffff0000, v66
	v_pk_fma_f32 v[26:27], v[26:27], 0.5, v[32:33] op_sel_hi:[1,0,1]
	v_lshlrev_b32_e32 v32, 16, v242
	v_and_b32_e32 v33, 0xffff0000, v242
	v_pk_fma_f32 v[0:1], v[0:1], 0.5, v[180:181] op_sel_hi:[1,0,1]
	v_lshl_add_u64 v[180:181], s[28:29], 0, v[182:183]
	v_cvt_pk_bf16_f32 v112, v60, v61
	v_cvt_pk_bf16_f32 v113, v62, v63
	v_cvt_pk_bf16_f32 v114, v56, v57
	v_cvt_pk_bf16_f32 v115, v58, v59
	v_pk_fma_f32 v[20:21], v[20:21], 0.5, v[32:33] op_sel_hi:[1,0,1]
	v_lshlrev_b32_e32 v32, 16, v244
	v_and_b32_e32 v33, 0xffff0000, v244
	v_lshl_add_u64 v[180:181], v[180:181], 0, v[170:171]
	v_cvt_pk_bf16_f32 v116, v52, v53
	v_cvt_pk_bf16_f32 v117, v54, v55
	v_cvt_pk_bf16_f32 v118, v104, v105
	v_cvt_pk_bf16_f32 v119, v106, v107
	v_lshlrev_b32_e32 v30, 16, v240
	v_and_b32_e32 v31, 0xffff0000, v240
	v_pk_fma_f32 v[32:33], v[12:13], 0.5, v[32:33] op_sel_hi:[1,0,1]
	v_lshlrev_b32_e32 v12, 16, v243
	v_and_b32_e32 v13, 0xffff0000, v243
	global_store_dwordx4 v[180:181], v[112:115], off
	global_store_dwordx4 v[180:181], v[116:119], off offset:256
	v_cvt_pk_bf16_f32 v146, v44, v45
	v_lshl_add_u64 v[112:113], s[28:29], 0, v[132:133]
	v_cvt_pk_bf16_f32 v147, v46, v47
	v_cvt_pk_bf16_f32 v148, v40, v41
	v_cvt_pk_bf16_f32 v149, v42, v43
	v_pk_fma_f32 v[24:25], v[24:25], 0.5, v[30:31] op_sel_hi:[1,0,1]
	v_lshlrev_b32_e32 v30, 16, v239
	v_and_b32_e32 v31, 0xffff0000, v239
	v_pk_fma_f32 v[22:23], v[22:23], 0.5, v[12:13] op_sel_hi:[1,0,1]
	v_lshlrev_b32_e32 v12, 16, v245
	v_and_b32_e32 v13, 0xffff0000, v245
	v_lshl_add_u64 v[112:113], v[112:113], 0, v[170:171]
	v_cvt_pk_bf16_f32 v172, v36, v37
	v_cvt_pk_bf16_f32 v173, v38, v39
	v_cvt_pk_bf16_f32 v174, v48, v49
	v_cvt_pk_bf16_f32 v175, v50, v51
	v_pk_fma_f32 v[30:31], v[34:35], 0.5, v[30:31] op_sel_hi:[1,0,1]
	v_pk_fma_f32 v[34:35], v[14:15], 0.5, v[12:13] op_sel_hi:[1,0,1]
	v_lshlrev_b32_e32 v12, 16, v246
	v_and_b32_e32 v13, 0xffff0000, v246
	v_lshlrev_b32_e32 v14, 16, v248
	v_and_b32_e32 v15, 0xffff0000, v248
	global_store_dwordx4 v[112:113], v[146:149], off
	global_store_dwordx4 v[112:113], v[172:175], off offset:256
	v_lshl_add_u64 v[112:113], s[28:29], 0, v[134:135]
	v_cvt_pk_bf16_f32 v176, v28, v29
	v_cvt_pk_bf16_f32 v177, v30, v31
	v_cvt_pk_bf16_f32 v178, v24, v25
	v_cvt_pk_bf16_f32 v179, v26, v27
	v_pk_fma_f32 v[12:13], v[16:17], 0.5, v[12:13] op_sel_hi:[1,0,1]
	v_pk_fma_f32 v[8:9], v[8:9], 0.5, v[14:15] op_sel_hi:[1,0,1]
	v_lshlrev_b32_e32 v14, 16, v247
	v_and_b32_e32 v15, 0xffff0000, v247
	v_lshlrev_b32_e32 v16, 16, v249
	v_and_b32_e32 v17, 0xffff0000, v249
	v_lshlrev_b32_e32 v64, 16, v65
	v_and_b32_e32 v65, 0xffff0000, v65
	v_lshl_add_u64 v[112:113], v[112:113], 0, v[170:171]
	v_cvt_pk_bf16_f32 v194, v20, v21
	v_cvt_pk_bf16_f32 v195, v22, v23
	v_cvt_pk_bf16_f32 v196, v32, v33
	v_cvt_pk_bf16_f32 v197, v34, v35
	v_pk_fma_f32 v[14:15], v[18:19], 0.5, v[14:15] op_sel_hi:[1,0,1]
	v_pk_fma_f32 v[10:11], v[10:11], 0.5, v[16:17] op_sel_hi:[1,0,1]
	v_pk_fma_f32 v[6:7], v[6:7], 0.5, v[64:65] op_sel_hi:[1,0,1]
	v_lshlrev_b32_e32 v64, 16, v67
	v_and_b32_e32 v65, 0xffff0000, v67
	global_store_dwordx4 v[112:113], v[176:179], off
	global_store_dwordx4 v[112:113], v[194:197], off offset:256
	v_lshl_add_u64 v[112:113], s[28:29], 0, v[184:185]
	v_cvt_pk_bf16_f32 v16, v12, v13
	v_cvt_pk_bf16_f32 v17, v14, v15
	v_cvt_pk_bf16_f32 v18, v8, v9
	v_cvt_pk_bf16_f32 v19, v10, v11
	v_pk_fma_f32 v[2:3], v[2:3], 0.5, v[64:65] op_sel_hi:[1,0,1]
	v_lshl_add_u64 v[112:113], v[112:113], 0, v[170:171]
	v_cvt_pk_bf16_f32 v64, v4, v5
	v_cvt_pk_bf16_f32 v65, v6, v7
	v_cvt_pk_bf16_f32 v66, v0, v1
	v_cvt_pk_bf16_f32 v67, v2, v3
	global_store_dwordx4 v[112:113], v[16:19], off
	global_store_dwordx4 v[112:113], v[64:67], off offset:256
	s_lshl_b32 s10, s81, 2
	v_and_b32_e32 v17, 64, v188
	v_xor_b32_e32 v16, 16, v188
	v_add_u32_e32 v17, 64, v17
	v_cmp_lt_i32_e32 vcc, v16, v17
	v_xor_b32_e32 v18, 32, v188
	s_ashr_i32 s11, s10, 31
	v_cndmask_b32_e32 v16, v188, v16, vcc
	v_lshlrev_b32_e32 v16, 2, v16
	ds_bpermute_b32 v19, v16, v209
	v_cmp_lt_i32_e32 vcc, v18, v17
	s_lshl_b64 s[10:11], s[10:11], 2
	s_add_u32 s38, s73, s10
	v_cndmask_b32_e32 v17, v188, v18, vcc
	v_lshlrev_b32_e32 v17, 2, v17
	s_waitcnt lgkmcnt(0)
	v_add_f32_e32 v18, v209, v19
	ds_bpermute_b32 v19, v17, v18
	s_addc_u32 s39, s74, s11
	s_and_saveexec_b64 s[46:47], s[42:43]
	s_cbranch_execz .LBB0_34
	s_waitcnt lgkmcnt(0)
	v_add_f32_e32 v64, v18, v19
	v_lshlrev_b64 v[18:19], 6, v[168:169]
	v_lshl_add_u64 v[18:19], s[38:39], 0, v[18:19]
	global_store_dword v[18:19], v64, off

.Lm4ap_77:
	s_waitcnt lgkmcnt(0)
	s_barrier
	v_mfma_f32_16x16x32_bf16 v[124:127], v[158:161], v[174:177], 0
	v_mfma_f32_16x16x32_bf16 v[120:123], v[166:169], v[174:177], 0
	v_mfma_f32_16x16x32_bf16 v[116:119], v[158:161], v[182:185], 0
	v_mfma_f32_16x16x32_bf16 v[112:115], v[166:169], v[182:185], 0
	v_mfma_f32_16x16x32_bf16 v[108:111], v[158:161], v[210:213], 0
	v_mfma_f32_16x16x32_bf16 v[104:107], v[166:169], v[210:213], 0
	v_mfma_f32_16x16x32_bf16 v[100:103], v[158:161], v[218:221], 0
	v_mfma_f32_16x16x32_bf16 v[96:99], v[166:169], v[218:221], 0
	v_mfma_f32_16x16x32_bf16 v[124:127], v[162:165], v[178:181], v[124:127]
	v_mfma_f32_16x16x32_bf16 v[120:123], v[170:173], v[178:181], v[120:123]
	v_mfma_f32_16x16x32_bf16 v[116:119], v[162:165], v[206:209], v[116:119]
	v_mfma_f32_16x16x32_bf16 v[112:115], v[170:173], v[206:209], v[112:115]
	v_mfma_f32_16x16x32_bf16 v[108:111], v[162:165], v[214:217], v[108:111]
	v_mfma_f32_16x16x32_bf16 v[104:107], v[170:173], v[214:217], v[104:107]
	v_mfma_f32_16x16x32_bf16 v[100:103], v[162:165], v[222:225], v[100:103]
	v_mfma_f32_16x16x32_bf16 v[96:99], v[170:173], v[222:225], v[96:99]
	v_mfma_f32_16x16x32_bf16 v[92:95], v[226:229], v[174:177], 0
	v_mfma_f32_16x16x32_bf16 v[88:91], v[234:237], v[174:177], 0
	v_mfma_f32_16x16x32_bf16 v[84:87], v[226:229], v[182:185], 0
	v_mfma_f32_16x16x32_bf16 v[80:83], v[234:237], v[182:185], 0
	v_mfma_f32_16x16x32_bf16 v[76:79], v[226:229], v[210:213], 0
	v_mfma_f32_16x16x32_bf16 v[72:75], v[234:237], v[210:213], 0
	v_mfma_f32_16x16x32_bf16 v[68:71], v[226:229], v[218:221], 0
	v_mfma_f32_16x16x32_bf16 v[64:67], v[234:237], v[218:221], 0
	v_mfma_f32_16x16x32_bf16 v[92:95], v[230:233], v[178:181], v[92:95]
	v_mfma_f32_16x16x32_bf16 v[88:91], v[238:241], v[178:181], v[88:91]
	v_mfma_f32_16x16x32_bf16 v[84:87], v[230:233], v[206:209], v[84:87]
	v_mfma_f32_16x16x32_bf16 v[80:83], v[238:241], v[206:209], v[80:83]
	v_mfma_f32_16x16x32_bf16 v[76:79], v[230:233], v[214:217], v[76:79]
	v_mfma_f32_16x16x32_bf16 v[72:75], v[238:241], v[214:217], v[72:75]
	v_mfma_f32_16x16x32_bf16 v[68:71], v[230:233], v[222:225], v[68:71]
	v_mfma_f32_16x16x32_bf16 v[64:67], v[238:241], v[222:225], v[64:67]
	s_barrier
	s_add_i32 s19, s82, s59
	v_lshl_add_u64 v[146:147], s[52:53], 0, v[140:141]
	s_mov_b32 m0, s19
	v_lshl_add_u64 v[148:149], s[52:53], 0, v[132:133]
	global_load_lds_dwordx4 v[146:147], off
	s_add_i32 m0, s19, 0x2000
	s_nop 0
	global_load_lds_dwordx4 v[148:149], off
	s_mov_b32 m0, s68
	v_lshl_add_u64 v[194:195], s[54:55], 0, v[128:129]
	ds_read_b128 v[174:177], v157 offset:16384
	ds_read_b128 v[178:181], v157 offset:17408
	ds_read_b128 v[182:185], v157 offset:18432
	ds_read_b128 v[206:209], v157 offset:19456
	ds_read_b128 v[210:213], v157 offset:20480
	ds_read_b128 v[214:217], v157 offset:21504
	ds_read_b128 v[218:221], v157 offset:22528
	ds_read_b128 v[222:225], v157 offset:23552
	global_load_lds_dwordx4 v[194:195], off
	v_lshl_add_u64 v[196:197], s[54:55], 0, v[130:131]
	s_mov_b32 m0, s69
	s_nop 0
	global_load_lds_dwordx4 v[196:197], off
	s_add_u32 s82, s52, 0x40000
	s_addc_u32 s83, s53, 0
	s_add_i32 s6, s6, s59
	v_lshl_add_u64 v[250:251], s[82:83], 0, v[140:141]
	s_mov_b32 m0, s6
	s_nop 0
	global_load_lds_dwordx4 v[250:251], off
	v_lshl_add_u64 v[250:251], s[82:83], 0, v[132:133]
	s_add_i32 m0, s6, 0x2000
	s_nop 0
	global_load_lds_dwordx4 v[250:251], off
	s_waitcnt vmcnt(16)
	s_cmp_lg_u32 s100, 0
	s_cbranch_scc1 .Lm4bp_77
	s_waitcnt vmcnt(8)
.Lm4bp_77:
	s_waitcnt lgkmcnt(0)
	s_mov_b32 s100, 0
	s_barrier
	v_mfma_f32_16x16x32_bf16 v[60:63], v[158:161], v[174:177], 0
	v_mfma_f32_16x16x32_bf16 v[56:59], v[166:169], v[174:177], 0
	v_mfma_f32_16x16x32_bf16 v[52:55], v[158:161], v[182:185], 0
	v_mfma_f32_16x16x32_bf16 v[48:51], v[166:169], v[182:185], 0
	v_mfma_f32_16x16x32_bf16 v[44:47], v[158:161], v[210:213], 0
	v_mfma_f32_16x16x32_bf16 v[40:43], v[166:169], v[210:213], 0
	v_mfma_f32_16x16x32_bf16 v[36:39], v[158:161], v[218:221], 0
	v_mfma_f32_16x16x32_bf16 v[32:35], v[166:169], v[218:221], 0
	v_mfma_f32_16x16x32_bf16 v[60:63], v[162:165], v[178:181], v[60:63]
	v_mfma_f32_16x16x32_bf16 v[56:59], v[170:173], v[178:181], v[56:59]
	v_mfma_f32_16x16x32_bf16 v[52:55], v[162:165], v[206:209], v[52:55]
	v_mfma_f32_16x16x32_bf16 v[48:51], v[170:173], v[206:209], v[48:51]
	v_mfma_f32_16x16x32_bf16 v[44:47], v[162:165], v[214:217], v[44:47]
	v_mfma_f32_16x16x32_bf16 v[40:43], v[170:173], v[214:217], v[40:43]
	v_mfma_f32_16x16x32_bf16 v[36:39], v[162:165], v[222:225], v[36:39]
	v_mfma_f32_16x16x32_bf16 v[32:35], v[170:173], v[222:225], v[32:35]
	v_mfma_f32_16x16x32_bf16 v[28:31], v[226:229], v[174:177], 0
	v_mfma_f32_16x16x32_bf16 v[24:27], v[234:237], v[174:177], 0
	v_mfma_f32_16x16x32_bf16 v[20:23], v[226:229], v[182:185], 0
	v_mfma_f32_16x16x32_bf16 v[16:19], v[234:237], v[182:185], 0
	v_mfma_f32_16x16x32_bf16 v[12:15], v[226:229], v[210:213], 0
	v_mfma_f32_16x16x32_bf16 v[8:11], v[234:237], v[210:213], 0
	v_mfma_f32_16x16x32_bf16 v[4:7], v[226:229], v[218:221], 0
	v_mfma_f32_16x16x32_bf16 v[0:3], v[234:237], v[218:221], 0
	v_mfma_f32_16x16x32_bf16 v[28:31], v[230:233], v[178:181], v[28:31]
	v_mfma_f32_16x16x32_bf16 v[24:27], v[238:241], v[178:181], v[24:27]
	v_mfma_f32_16x16x32_bf16 v[20:23], v[230:233], v[206:209], v[20:23]
	v_mfma_f32_16x16x32_bf16 v[16:19], v[238:241], v[206:209], v[16:19]
	v_mfma_f32_16x16x32_bf16 v[12:15], v[230:233], v[214:217], v[12:15]
	v_mfma_f32_16x16x32_bf16 v[8:11], v[238:241], v[214:217], v[8:11]
	v_mfma_f32_16x16x32_bf16 v[4:7], v[230:233], v[222:225], v[4:7]
	v_mfma_f32_16x16x32_bf16 v[0:3], v[238:241], v[222:225], v[0:3]
	s_barrier
	s_add_i32 s6, 0, 0x18000
	v_add_u32_e32 v170, s6, v154
	ds_read_b128 v[158:161], v170
	ds_read_b128 v[162:165], v170 offset:1024
	ds_read_b128 v[166:169], v170 offset:2048
	ds_read_b128 v[170:173], v170 offset:3072
	s_add_u32 s54, s54, 0x40000
	s_addc_u32 s55, s55, 0
	s_mov_b32 m0, s70
	v_lshl_add_u64 v[226:227], s[54:55], 0, v[128:129]
	ds_read_b128 v[174:177], v157 offset:32768
	ds_read_b128 v[178:181], v157 offset:33792
	ds_read_b128 v[182:185], v157 offset:34816
	ds_read_b128 v[206:209], v157 offset:35840
	ds_read_b128 v[210:213], v157 offset:36864
	ds_read_b128 v[214:217], v157 offset:37888
	ds_read_b128 v[218:221], v157 offset:38912
	ds_read_b128 v[222:225], v157 offset:39936
	global_load_lds_dwordx4 v[226:227], off
	v_lshl_add_u64 v[226:227], s[54:55], 0, v[130:131]
	s_mov_b32 m0, s71
	s_nop 0
	global_load_lds_dwordx4 v[226:227], off
	s_add_i32 s19, 0, 0x1c000
	v_add_u32_e32 v192, s19, v154
	ds_read_b128 v[226:229], v192
	ds_read_b128 v[230:233], v192 offset:1024
	ds_read_b128 v[234:237], v192 offset:2048
	ds_read_b128 v[238:241], v192 offset:3072
	s_waitcnt vmcnt(8)
	s_waitcnt lgkmcnt(0)
	s_barrier
	v_mfma_f32_16x16x32_bf16 v[124:127], v[158:161], v[174:177], v[124:127]
	v_mfma_f32_16x16x32_bf16 v[120:123], v[166:169], v[174:177], v[120:123]
	v_mfma_f32_16x16x32_bf16 v[116:119], v[158:161], v[182:185], v[116:119]
	v_mfma_f32_16x16x32_bf16 v[112:115], v[166:169], v[182:185], v[112:115]
	v_mfma_f32_16x16x32_bf16 v[108:111], v[158:161], v[210:213], v[108:111]
	v_mfma_f32_16x16x32_bf16 v[104:107], v[166:169], v[210:213], v[104:107]
	v_mfma_f32_16x16x32_bf16 v[100:103], v[158:161], v[218:221], v[100:103]
	v_mfma_f32_16x16x32_bf16 v[96:99], v[166:169], v[218:221], v[96:99]
	v_mfma_f32_16x16x32_bf16 v[124:127], v[162:165], v[178:181], v[124:127]
	v_mfma_f32_16x16x32_bf16 v[120:123], v[170:173], v[178:181], v[120:123]
	v_mfma_f32_16x16x32_bf16 v[116:119], v[162:165], v[206:209], v[116:119]
	v_mfma_f32_16x16x32_bf16 v[112:115], v[170:173], v[206:209], v[112:115]
	v_mfma_f32_16x16x32_bf16 v[108:111], v[162:165], v[214:217], v[108:111]
	v_mfma_f32_16x16x32_bf16 v[104:107], v[170:173], v[214:217], v[104:107]
	v_mfma_f32_16x16x32_bf16 v[100:103], v[162:165], v[222:225], v[100:103]
	v_mfma_f32_16x16x32_bf16 v[96:99], v[170:173], v[222:225], v[96:99]
	v_mfma_f32_16x16x32_bf16 v[92:95], v[226:229], v[174:177], v[92:95]
	v_mfma_f32_16x16x32_bf16 v[88:91], v[234:237], v[174:177], v[88:91]
	v_mfma_f32_16x16x32_bf16 v[84:87], v[226:229], v[182:185], v[84:87]
	v_mfma_f32_16x16x32_bf16 v[80:83], v[234:237], v[182:185], v[80:83]
	v_mfma_f32_16x16x32_bf16 v[76:79], v[226:229], v[210:213], v[76:79]
	v_mfma_f32_16x16x32_bf16 v[72:75], v[234:237], v[210:213], v[72:75]
	v_mfma_f32_16x16x32_bf16 v[68:71], v[226:229], v[218:221], v[68:71]
	v_mfma_f32_16x16x32_bf16 v[64:67], v[234:237], v[218:221], v[64:67]
	v_mfma_f32_16x16x32_bf16 v[92:95], v[230:233], v[178:181], v[92:95]
	v_mfma_f32_16x16x32_bf16 v[88:91], v[238:241], v[178:181], v[88:91]
	v_mfma_f32_16x16x32_bf16 v[84:87], v[230:233], v[206:209], v[84:87]
	v_mfma_f32_16x16x32_bf16 v[80:83], v[238:241], v[206:209], v[80:83]
	v_mfma_f32_16x16x32_bf16 v[76:79], v[230:233], v[214:217], v[76:79]
	v_mfma_f32_16x16x32_bf16 v[72:75], v[238:241], v[214:217], v[72:75]
	v_mfma_f32_16x16x32_bf16 v[68:71], v[230:233], v[222:225], v[68:71]
	v_mfma_f32_16x16x32_bf16 v[64:67], v[238:241], v[222:225], v[64:67]
	s_barrier
	s_add_i32 s6, s6, s59
	v_lshl_add_u64 v[146:147], v[146:147], 0, s[36:37]
	s_mov_b32 m0, s6
	s_nop 0
	global_load_lds_dwordx4 v[146:147], off
	v_lshl_add_u64 v[146:147], v[148:149], 0, s[36:37]
	s_add_i32 m0, s6, 0x2000
	s_nop 0
	global_load_lds_dwordx4 v[146:147], off
	s_mov_b32 m0, s72
	v_lshl_add_u64 v[146:147], v[194:195], 0, s[36:37]
	ds_read_b128 v[174:177], v157 offset:49152
	ds_read_b128 v[178:181], v157 offset:50176
	ds_read_b128 v[182:185], v157 offset:51200
	ds_read_b128 v[206:209], v157 offset:52224
	ds_read_b128 v[210:213], v157 offset:53248
	ds_read_b128 v[214:217], v157 offset:54272
	ds_read_b128 v[218:221], v157 offset:55296
	ds_read_b128 v[222:225], v157 offset:56320
	global_load_lds_dwordx4 v[146:147], off
	v_lshl_add_u64 v[146:147], v[196:197], 0, s[36:37]
	s_mov_b32 m0, s73
	s_nop 0
	global_load_lds_dwordx4 v[146:147], off
	s_add_u32 s52, s52, 0x40080
	s_addc_u32 s53, s53, 0
	s_add_i32 s6, s19, s59
	v_lshl_add_u64 v[146:147], s[52:53], 0, v[140:141]
	s_mov_b32 m0, s6
	s_nop 0
	global_load_lds_dwordx4 v[146:147], off
	v_lshl_add_u64 v[146:147], s[52:53], 0, v[132:133]
	s_add_i32 m0, s6, 0x2000
	s_nop 0
	global_load_lds_dwordx4 v[146:147], off
	s_waitcnt vmcnt(8)
	s_waitcnt lgkmcnt(0)
	s_barrier
	v_mfma_f32_16x16x32_bf16 v[60:63], v[158:161], v[174:177], v[60:63]
	v_mfma_f32_16x16x32_bf16 v[56:59], v[166:169], v[174:177], v[56:59]
	v_mfma_f32_16x16x32_bf16 v[52:55], v[158:161], v[182:185], v[52:55]
	v_mfma_f32_16x16x32_bf16 v[48:51], v[166:169], v[182:185], v[48:51]
	v_mfma_f32_16x16x32_bf16 v[44:47], v[158:161], v[210:213], v[44:47]
	v_mfma_f32_16x16x32_bf16 v[40:43], v[166:169], v[210:213], v[40:43]
	v_mfma_f32_16x16x32_bf16 v[36:39], v[158:161], v[218:221], v[36:39]
	v_mfma_f32_16x16x32_bf16 v[32:35], v[166:169], v[218:221], v[32:35]
	v_mfma_f32_16x16x32_bf16 v[60:63], v[162:165], v[178:181], v[60:63]
	v_mfma_f32_16x16x32_bf16 v[56:59], v[170:173], v[178:181], v[56:59]
	v_mfma_f32_16x16x32_bf16 v[52:55], v[162:165], v[206:209], v[52:55]
	v_mfma_f32_16x16x32_bf16 v[48:51], v[170:173], v[206:209], v[48:51]
	v_mfma_f32_16x16x32_bf16 v[44:47], v[162:165], v[214:217], v[44:47]
	v_mfma_f32_16x16x32_bf16 v[40:43], v[170:173], v[214:217], v[40:43]
	v_mfma_f32_16x16x32_bf16 v[36:39], v[162:165], v[222:225], v[36:39]
	v_mfma_f32_16x16x32_bf16 v[32:35], v[170:173], v[222:225], v[32:35]
	v_mfma_f32_16x16x32_bf16 v[28:31], v[226:229], v[174:177], v[28:31]
	v_mfma_f32_16x16x32_bf16 v[24:27], v[234:237], v[174:177], v[24:27]
	v_mfma_f32_16x16x32_bf16 v[20:23], v[226:229], v[182:185], v[20:23]
	v_mfma_f32_16x16x32_bf16 v[16:19], v[234:237], v[182:185], v[16:19]
	v_mfma_f32_16x16x32_bf16 v[12:15], v[226:229], v[210:213], v[12:15]
	v_mfma_f32_16x16x32_bf16 v[8:11], v[234:237], v[210:213], v[8:11]
	v_mfma_f32_16x16x32_bf16 v[4:7], v[226:229], v[218:221], v[4:7]
	v_mfma_f32_16x16x32_bf16 v[0:3], v[234:237], v[218:221], v[0:3]
	v_mfma_f32_16x16x32_bf16 v[28:31], v[230:233], v[178:181], v[28:31]
	v_mfma_f32_16x16x32_bf16 v[24:27], v[238:241], v[178:181], v[24:27]
	v_mfma_f32_16x16x32_bf16 v[20:23], v[230:233], v[206:209], v[20:23]
	v_mfma_f32_16x16x32_bf16 v[16:19], v[238:241], v[206:209], v[16:19]
	v_mfma_f32_16x16x32_bf16 v[12:15], v[230:233], v[214:217], v[12:15]
	v_mfma_f32_16x16x32_bf16 v[8:11], v[238:241], v[214:217], v[8:11]
	v_mfma_f32_16x16x32_bf16 v[4:7], v[230:233], v[222:225], v[4:7]
	v_mfma_f32_16x16x32_bf16 v[0:3], v[238:241], v[222:225], v[0:3]
	s_add_i32 s81, s81, 2
	s_add_u32 s50, s50, 0x100
	s_addc_u32 s51, s51, 0
	s_cmp_gt_u32 s81, 13
	s_barrier
.LBB0_77:
	s_add_u32 s6, s26, s50
	s_addc_u32 s19, s27, s51
	s_add_u32 s6, s6, 0x100
	s_addc_u32 s19, s19, 0
	s_add_u32 s23, s10, s50
	s_addc_u32 s52, s11, s51
	s_add_i32 s82, 0, 0x10000
	v_add_u32_e32 v146, s82, v154
	ds_read_b128 v[158:161], v146
	ds_read_b128 v[162:165], v146 offset:1024
	ds_read_b128 v[166:169], v146 offset:2048
	ds_read_b128 v[170:173], v146 offset:3072
	s_cmpk_eq_i32 s50, 0x700
	s_cselect_b32 s55, s12, s19
	s_cselect_b32 s54, s31, s6
	s_cselect_b32 s53, s35, s52
	s_cselect_b32 s52, s39, s23
	v_lshl_add_u64 v[146:147], v[150:151], 0, s[50:51]
	s_add_i32 m0, s68, 0xc000
	ds_read_b128 v[174:177], v157
	ds_read_b128 v[178:181], v157 offset:1024
	ds_read_b128 v[182:185], v157 offset:2048
	ds_read_b128 v[206:209], v157 offset:3072
	ds_read_b128 v[210:213], v157 offset:4096
	ds_read_b128 v[214:217], v157 offset:5120
	ds_read_b128 v[218:221], v157 offset:6144
	ds_read_b128 v[222:225], v157 offset:7168
	global_load_lds_dwordx4 v[146:147], off
	v_lshl_add_u64 v[146:147], v[152:153], 0, s[50:51]
	s_add_i32 m0, s68, 0xe000
	s_nop 0
	global_load_lds_dwordx4 v[146:147], off
	s_add_i32 s6, 0, 0x14000
	v_add_u32_e32 v146, s6, v154
	ds_read_b128 v[226:229], v146
	ds_read_b128 v[230:233], v146 offset:1024
	ds_read_b128 v[234:237], v146 offset:2048
	ds_read_b128 v[238:241], v146 offset:3072
	s_waitcnt vmcnt(8)
	s_waitcnt lgkmcnt(0)
	s_barrier
	v_mfma_f32_16x16x32_bf16 v[124:127], v[158:161], v[174:177], v[124:127]
	v_mfma_f32_16x16x32_bf16 v[120:123], v[166:169], v[174:177], v[120:123]
	v_mfma_f32_16x16x32_bf16 v[116:119], v[158:161], v[182:185], v[116:119]
	v_mfma_f32_16x16x32_bf16 v[112:115], v[166:169], v[182:185], v[112:115]
	v_mfma_f32_16x16x32_bf16 v[108:111], v[158:161], v[210:213], v[108:111]
	v_mfma_f32_16x16x32_bf16 v[104:107], v[166:169], v[210:213], v[104:107]
	v_mfma_f32_16x16x32_bf16 v[100:103], v[158:161], v[218:221], v[100:103]
	v_mfma_f32_16x16x32_bf16 v[96:99], v[166:169], v[218:221], v[96:99]
	v_mfma_f32_16x16x32_bf16 v[124:127], v[162:165], v[178:181], v[124:127]
	v_mfma_f32_16x16x32_bf16 v[120:123], v[170:173], v[178:181], v[120:123]
	v_mfma_f32_16x16x32_bf16 v[116:119], v[162:165], v[206:209], v[116:119]
	v_mfma_f32_16x16x32_bf16 v[112:115], v[170:173], v[206:209], v[112:115]
	v_mfma_f32_16x16x32_bf16 v[108:111], v[162:165], v[214:217], v[108:111]
	v_mfma_f32_16x16x32_bf16 v[104:107], v[170:173], v[214:217], v[104:107]
	v_mfma_f32_16x16x32_bf16 v[100:103], v[162:165], v[222:225], v[100:103]
	v_mfma_f32_16x16x32_bf16 v[96:99], v[170:173], v[222:225], v[96:99]
	v_mfma_f32_16x16x32_bf16 v[92:95], v[226:229], v[174:177], v[92:95]
	v_mfma_f32_16x16x32_bf16 v[88:91], v[234:237], v[174:177], v[88:91]
	v_mfma_f32_16x16x32_bf16 v[84:87], v[226:229], v[182:185], v[84:87]
	v_mfma_f32_16x16x32_bf16 v[80:83], v[234:237], v[182:185], v[80:83]
	v_mfma_f32_16x16x32_bf16 v[76:79], v[226:229], v[210:213], v[76:79]
	v_mfma_f32_16x16x32_bf16 v[72:75], v[234:237], v[210:213], v[72:75]
	v_mfma_f32_16x16x32_bf16 v[68:71], v[226:229], v[218:221], v[68:71]
	v_mfma_f32_16x16x32_bf16 v[64:67], v[234:237], v[218:221], v[64:67]
	v_mfma_f32_16x16x32_bf16 v[92:95], v[230:233], v[178:181], v[92:95]
	v_mfma_f32_16x16x32_bf16 v[88:91], v[238:241], v[178:181], v[88:91]
	v_mfma_f32_16x16x32_bf16 v[84:87], v[230:233], v[206:209], v[84:87]
	v_mfma_f32_16x16x32_bf16 v[80:83], v[238:241], v[206:209], v[80:83]
	v_mfma_f32_16x16x32_bf16 v[76:79], v[230:233], v[214:217], v[76:79]
	v_mfma_f32_16x16x32_bf16 v[72:75], v[238:241], v[214:217], v[72:75]
	v_mfma_f32_16x16x32_bf16 v[68:71], v[230:233], v[222:225], v[68:71]
	v_mfma_f32_16x16x32_bf16 v[64:67], v[238:241], v[222:225], v[64:67]
	s_barrier
	s_add_i32 s19, s82, s59
	v_lshl_add_u64 v[146:147], s[52:53], 0, v[140:141]
	s_mov_b32 m0, s19
	v_lshl_add_u64 v[148:149], s[52:53], 0, v[132:133]
	global_load_lds_dwordx4 v[146:147], off
	s_add_i32 m0, s19, 0x2000
	s_nop 0
	global_load_lds_dwordx4 v[148:149], off
	s_mov_b32 m0, s68
	v_lshl_add_u64 v[194:195], s[54:55], 0, v[128:129]
	ds_read_b128 v[174:177], v157 offset:16384
	ds_read_b128 v[178:181], v157 offset:17408
	ds_read_b128 v[182:185], v157 offset:18432
	ds_read_b128 v[206:209], v157 offset:19456
	ds_read_b128 v[210:213], v157 offset:20480
	ds_read_b128 v[214:217], v157 offset:21504
	ds_read_b128 v[218:221], v157 offset:22528
	ds_read_b128 v[222:225], v157 offset:23552
	global_load_lds_dwordx4 v[194:195], off
	v_lshl_add_u64 v[196:197], s[54:55], 0, v[130:131]
	s_mov_b32 m0, s69
	s_nop 0
	global_load_lds_dwordx4 v[196:197], off
	s_add_u32 s82, s52, 0x40000
	s_addc_u32 s83, s53, 0
	s_add_i32 s6, s6, s59
	v_lshl_add_u64 v[250:251], s[82:83], 0, v[140:141]
	s_mov_b32 m0, s6
	s_nop 0
	global_load_lds_dwordx4 v[250:251], off
	v_lshl_add_u64 v[250:251], s[82:83], 0, v[132:133]
	s_add_i32 m0, s6, 0x2000
	s_nop 0
	global_load_lds_dwordx4 v[250:251], off
	s_waitcnt vmcnt(8)
	s_waitcnt lgkmcnt(0)
	s_barrier
	v_mfma_f32_16x16x32_bf16 v[60:63], v[158:161], v[174:177], v[60:63]
	v_mfma_f32_16x16x32_bf16 v[56:59], v[166:169], v[174:177], v[56:59]
	v_mfma_f32_16x16x32_bf16 v[52:55], v[158:161], v[182:185], v[52:55]
	v_mfma_f32_16x16x32_bf16 v[48:51], v[166:169], v[182:185], v[48:51]
	v_mfma_f32_16x16x32_bf16 v[44:47], v[158:161], v[210:213], v[44:47]
	v_mfma_f32_16x16x32_bf16 v[40:43], v[166:169], v[210:213], v[40:43]
	v_mfma_f32_16x16x32_bf16 v[36:39], v[158:161], v[218:221], v[36:39]
	v_mfma_f32_16x16x32_bf16 v[32:35], v[166:169], v[218:221], v[32:35]
	v_mfma_f32_16x16x32_bf16 v[60:63], v[162:165], v[178:181], v[60:63]
	v_mfma_f32_16x16x32_bf16 v[56:59], v[170:173], v[178:181], v[56:59]
	v_mfma_f32_16x16x32_bf16 v[52:55], v[162:165], v[206:209], v[52:55]
	v_mfma_f32_16x16x32_bf16 v[48:51], v[170:173], v[206:209], v[48:51]
	v_mfma_f32_16x16x32_bf16 v[44:47], v[162:165], v[214:217], v[44:47]
	v_mfma_f32_16x16x32_bf16 v[40:43], v[170:173], v[214:217], v[40:43]
	v_mfma_f32_16x16x32_bf16 v[36:39], v[162:165], v[222:225], v[36:39]
	v_mfma_f32_16x16x32_bf16 v[32:35], v[170:173], v[222:225], v[32:35]
	v_mfma_f32_16x16x32_bf16 v[28:31], v[226:229], v[174:177], v[28:31]
	v_mfma_f32_16x16x32_bf16 v[24:27], v[234:237], v[174:177], v[24:27]
	v_mfma_f32_16x16x32_bf16 v[20:23], v[226:229], v[182:185], v[20:23]
	v_mfma_f32_16x16x32_bf16 v[16:19], v[234:237], v[182:185], v[16:19]
	v_mfma_f32_16x16x32_bf16 v[12:15], v[226:229], v[210:213], v[12:15]
	v_mfma_f32_16x16x32_bf16 v[8:11], v[234:237], v[210:213], v[8:11]
	v_mfma_f32_16x16x32_bf16 v[4:7], v[226:229], v[218:221], v[4:7]
	v_mfma_f32_16x16x32_bf16 v[0:3], v[234:237], v[218:221], v[0:3]
	v_mfma_f32_16x16x32_bf16 v[28:31], v[230:233], v[178:181], v[28:31]
	v_mfma_f32_16x16x32_bf16 v[24:27], v[238:241], v[178:181], v[24:27]
	v_mfma_f32_16x16x32_bf16 v[20:23], v[230:233], v[206:209], v[20:23]
	v_mfma_f32_16x16x32_bf16 v[16:19], v[238:241], v[206:209], v[16:19]
	v_mfma_f32_16x16x32_bf16 v[12:15], v[230:233], v[214:217], v[12:15]
	v_mfma_f32_16x16x32_bf16 v[8:11], v[238:241], v[214:217], v[8:11]
	v_mfma_f32_16x16x32_bf16 v[4:7], v[230:233], v[222:225], v[4:7]
	v_mfma_f32_16x16x32_bf16 v[0:3], v[238:241], v[222:225], v[0:3]
	s_barrier
	s_add_i32 s6, 0, 0x18000
	v_add_u32_e32 v170, s6, v154
	ds_read_b128 v[158:161], v170
	ds_read_b128 v[162:165], v170 offset:1024
	ds_read_b128 v[166:169], v170 offset:2048
	ds_read_b128 v[170:173], v170 offset:3072
	s_add_u32 s54, s54, 0x40000
	s_addc_u32 s55, s55, 0
	s_mov_b32 m0, s70
	v_lshl_add_u64 v[226:227], s[54:55], 0, v[128:129]
	ds_read_b128 v[174:177], v157 offset:32768
	ds_read_b128 v[178:181], v157 offset:33792
	ds_read_b128 v[182:185], v157 offset:34816
	ds_read_b128 v[206:209], v157 offset:35840
	ds_read_b128 v[210:213], v157 offset:36864
	ds_read_b128 v[214:217], v157 offset:37888
	ds_read_b128 v[218:221], v157 offset:38912
	ds_read_b128 v[222:225], v157 offset:39936
	global_load_lds_dwordx4 v[226:227], off
	v_lshl_add_u64 v[226:227], s[54:55], 0, v[130:131]
	s_mov_b32 m0, s71
	s_nop 0
	global_load_lds_dwordx4 v[226:227], off
	s_add_i32 s19, 0, 0x1c000
	v_add_u32_e32 v192, s19, v154
	ds_read_b128 v[226:229], v192
	ds_read_b128 v[230:233], v192 offset:1024
	ds_read_b128 v[234:237], v192 offset:2048
	ds_read_b128 v[238:241], v192 offset:3072
	s_waitcnt vmcnt(8)
	s_waitcnt lgkmcnt(0)
	s_barrier
	v_mfma_f32_16x16x32_bf16 v[124:127], v[158:161], v[174:177], v[124:127]
	v_mfma_f32_16x16x32_bf16 v[120:123], v[166:169], v[174:177], v[120:123]
	v_mfma_f32_16x16x32_bf16 v[116:119], v[158:161], v[182:185], v[116:119]
	v_mfma_f32_16x16x32_bf16 v[112:115], v[166:169], v[182:185], v[112:115]
	v_mfma_f32_16x16x32_bf16 v[108:111], v[158:161], v[210:213], v[108:111]
	v_mfma_f32_16x16x32_bf16 v[104:107], v[166:169], v[210:213], v[104:107]
	v_mfma_f32_16x16x32_bf16 v[100:103], v[158:161], v[218:221], v[100:103]
	v_mfma_f32_16x16x32_bf16 v[96:99], v[166:169], v[218:221], v[96:99]
	v_mfma_f32_16x16x32_bf16 v[124:127], v[162:165], v[178:181], v[124:127]
	v_mfma_f32_16x16x32_bf16 v[120:123], v[170:173], v[178:181], v[120:123]
	v_mfma_f32_16x16x32_bf16 v[116:119], v[162:165], v[206:209], v[116:119]
	v_mfma_f32_16x16x32_bf16 v[112:115], v[170:173], v[206:209], v[112:115]
	v_mfma_f32_16x16x32_bf16 v[108:111], v[162:165], v[214:217], v[108:111]
	v_mfma_f32_16x16x32_bf16 v[104:107], v[170:173], v[214:217], v[104:107]
	v_mfma_f32_16x16x32_bf16 v[100:103], v[162:165], v[222:225], v[100:103]
	v_mfma_f32_16x16x32_bf16 v[96:99], v[170:173], v[222:225], v[96:99]
	v_mfma_f32_16x16x32_bf16 v[92:95], v[226:229], v[174:177], v[92:95]
	v_mfma_f32_16x16x32_bf16 v[88:91], v[234:237], v[174:177], v[88:91]
	v_mfma_f32_16x16x32_bf16 v[84:87], v[226:229], v[182:185], v[84:87]
	v_mfma_f32_16x16x32_bf16 v[80:83], v[234:237], v[182:185], v[80:83]
	v_mfma_f32_16x16x32_bf16 v[76:79], v[226:229], v[210:213], v[76:79]
	v_mfma_f32_16x16x32_bf16 v[72:75], v[234:237], v[210:213], v[72:75]
	v_mfma_f32_16x16x32_bf16 v[68:71], v[226:229], v[218:221], v[68:71]
	v_mfma_f32_16x16x32_bf16 v[64:67], v[234:237], v[218:221], v[64:67]
	v_mfma_f32_16x16x32_bf16 v[92:95], v[230:233], v[178:181], v[92:95]
	v_mfma_f32_16x16x32_bf16 v[88:91], v[238:241], v[178:181], v[88:91]
	v_mfma_f32_16x16x32_bf16 v[84:87], v[230:233], v[206:209], v[84:87]
	v_mfma_f32_16x16x32_bf16 v[80:83], v[238:241], v[206:209], v[80:83]
	v_mfma_f32_16x16x32_bf16 v[76:79], v[230:233], v[214:217], v[76:79]
	v_mfma_f32_16x16x32_bf16 v[72:75], v[238:241], v[214:217], v[72:75]
	v_mfma_f32_16x16x32_bf16 v[68:71], v[230:233], v[222:225], v[68:71]
	v_mfma_f32_16x16x32_bf16 v[64:67], v[238:241], v[222:225], v[64:67]
	s_barrier
	s_add_i32 s6, s6, s59
	v_lshl_add_u64 v[146:147], v[146:147], 0, s[36:37]
	s_mov_b32 m0, s6
	s_nop 0
	global_load_lds_dwordx4 v[146:147], off
	v_lshl_add_u64 v[146:147], v[148:149], 0, s[36:37]
	s_add_i32 m0, s6, 0x2000
	s_nop 0
	global_load_lds_dwordx4 v[146:147], off
	s_mov_b32 m0, s72
	v_lshl_add_u64 v[146:147], v[194:195], 0, s[36:37]
	ds_read_b128 v[174:177], v157 offset:49152
	ds_read_b128 v[178:181], v157 offset:50176
	ds_read_b128 v[182:185], v157 offset:51200
	ds_read_b128 v[206:209], v157 offset:52224
	ds_read_b128 v[210:213], v157 offset:53248
	ds_read_b128 v[214:217], v157 offset:54272
	ds_read_b128 v[218:221], v157 offset:55296
	ds_read_b128 v[222:225], v157 offset:56320
	global_load_lds_dwordx4 v[146:147], off
	v_lshl_add_u64 v[146:147], v[196:197], 0, s[36:37]
	s_mov_b32 m0, s73
	s_nop 0
	global_load_lds_dwordx4 v[146:147], off
	s_add_u32 s52, s52, 0x40080
	s_addc_u32 s53, s53, 0
	s_add_i32 s6, s19, s59
	v_lshl_add_u64 v[146:147], s[52:53], 0, v[140:141]
	s_mov_b32 m0, s6
	s_nop 0
	global_load_lds_dwordx4 v[146:147], off
	v_lshl_add_u64 v[146:147], s[52:53], 0, v[132:133]
	s_add_i32 m0, s6, 0x2000
	s_nop 0
	global_load_lds_dwordx4 v[146:147], off
	s_waitcnt vmcnt(8)
	s_waitcnt lgkmcnt(0)
	s_barrier
	v_mfma_f32_16x16x32_bf16 v[60:63], v[158:161], v[174:177], v[60:63]
	v_mfma_f32_16x16x32_bf16 v[56:59], v[166:169], v[174:177], v[56:59]
	v_mfma_f32_16x16x32_bf16 v[52:55], v[158:161], v[182:185], v[52:55]
	v_mfma_f32_16x16x32_bf16 v[48:51], v[166:169], v[182:185], v[48:51]
	v_mfma_f32_16x16x32_bf16 v[44:47], v[158:161], v[210:213], v[44:47]
	v_mfma_f32_16x16x32_bf16 v[40:43], v[166:169], v[210:213], v[40:43]
	v_mfma_f32_16x16x32_bf16 v[36:39], v[158:161], v[218:221], v[36:39]
	v_mfma_f32_16x16x32_bf16 v[32:35], v[166:169], v[218:221], v[32:35]
	v_mfma_f32_16x16x32_bf16 v[60:63], v[162:165], v[178:181], v[60:63]
	v_mfma_f32_16x16x32_bf16 v[56:59], v[170:173], v[178:181], v[56:59]
	v_mfma_f32_16x16x32_bf16 v[52:55], v[162:165], v[206:209], v[52:55]
	v_mfma_f32_16x16x32_bf16 v[48:51], v[170:173], v[206:209], v[48:51]
	v_mfma_f32_16x16x32_bf16 v[44:47], v[162:165], v[214:217], v[44:47]
	v_mfma_f32_16x16x32_bf16 v[40:43], v[170:173], v[214:217], v[40:43]
	v_mfma_f32_16x16x32_bf16 v[36:39], v[162:165], v[222:225], v[36:39]
	v_mfma_f32_16x16x32_bf16 v[32:35], v[170:173], v[222:225], v[32:35]
	v_mfma_f32_16x16x32_bf16 v[28:31], v[226:229], v[174:177], v[28:31]
	v_mfma_f32_16x16x32_bf16 v[24:27], v[234:237], v[174:177], v[24:27]
	v_mfma_f32_16x16x32_bf16 v[20:23], v[226:229], v[182:185], v[20:23]
	v_mfma_f32_16x16x32_bf16 v[16:19], v[234:237], v[182:185], v[16:19]
	v_mfma_f32_16x16x32_bf16 v[12:15], v[226:229], v[210:213], v[12:15]
	v_mfma_f32_16x16x32_bf16 v[8:11], v[234:237], v[210:213], v[8:11]
	v_mfma_f32_16x16x32_bf16 v[4:7], v[226:229], v[218:221], v[4:7]
	v_mfma_f32_16x16x32_bf16 v[0:3], v[234:237], v[218:221], v[0:3]
	v_mfma_f32_16x16x32_bf16 v[28:31], v[230:233], v[178:181], v[28:31]
	v_mfma_f32_16x16x32_bf16 v[24:27], v[238:241], v[178:181], v[24:27]
	v_mfma_f32_16x16x32_bf16 v[20:23], v[230:233], v[206:209], v[20:23]
	v_mfma_f32_16x16x32_bf16 v[16:19], v[238:241], v[206:209], v[16:19]
	v_mfma_f32_16x16x32_bf16 v[12:15], v[230:233], v[214:217], v[12:15]
	v_mfma_f32_16x16x32_bf16 v[8:11], v[238:241], v[214:217], v[8:11]
	v_mfma_f32_16x16x32_bf16 v[4:7], v[230:233], v[222:225], v[4:7]
	v_mfma_f32_16x16x32_bf16 v[0:3], v[238:241], v[222:225], v[0:3]
	s_add_i32 s81, s81, 2
	s_add_u32 s50, s50, 0x100
	s_addc_u32 s51, s51, 0
	s_cmp_gt_u32 s81, 13
	s_barrier
	s_cbranch_scc0 .LBB0_77
	s_mov_b32 s100, 1
	v_lshl_add_u32 v158, s75, 10, v155
	ds_read2_b32 v[146:147], v158 offset1:16
	s_add_u32 s50, s10, 0xffffff00
	s_addc_u32 s51, s11, -1
	s_ashr_i32 s31, s30, 31
	s_lshl_b64 s[10:11], s[30:31], 8
	s_waitcnt lgkmcnt(0)
	v_mul_f32_e32 v184, 0xbfb8aa3b, v146
	v_mul_f32_e32 v206, v146, v146
	v_pk_mul_f32 v[168:169], v[124:125], v[184:185] op_sel_hi:[1,0]
	v_pk_mul_f32 v[170:171], v[126:127], v[184:185] op_sel_hi:[1,0]
	v_pk_mul_f32 v[172:173], v[120:121], v[184:185] op_sel_hi:[1,0]
	v_pk_mul_f32 v[174:175], v[122:123], v[184:185] op_sel_hi:[1,0]
	v_exp_f32_e32 v168, v168
	v_exp_f32_e32 v169, v169
	v_exp_f32_e32 v170, v170
	v_exp_f32_e32 v171, v171
	v_exp_f32_e32 v172, v172
	v_exp_f32_e32 v173, v173
	v_exp_f32_e32 v174, v174
	v_exp_f32_e32 v175, v175
	v_pk_mul_f32 v[176:177], v[124:125], v[92:93]
	v_pk_mul_f32 v[178:179], v[126:127], v[94:95]
	v_pk_mul_f32 v[180:181], v[120:121], v[88:89]
	v_pk_mul_f32 v[182:183], v[122:123], v[90:91]
	v_pk_add_f32 v[168:169], v[168:169], 1.0 op_sel_hi:[1,0]
	v_pk_add_f32 v[170:171], v[170:171], 1.0 op_sel_hi:[1,0]
	v_pk_add_f32 v[172:173], v[172:173], 1.0 op_sel_hi:[1,0]
	v_pk_add_f32 v[174:175], v[174:175], 1.0 op_sel_hi:[1,0]
	v_rcp_f32_e32 v168, v168
	v_rcp_f32_e32 v169, v169
	v_rcp_f32_e32 v170, v170
	v_rcp_f32_e32 v171, v171
	v_rcp_f32_e32 v172, v172
	v_rcp_f32_e32 v173, v173
	v_rcp_f32_e32 v174, v174
	v_rcp_f32_e32 v175, v175
	v_pk_mul_f32 v[176:177], v[176:177], v[206:207] op_sel_hi:[1,0]
	v_pk_mul_f32 v[178:179], v[178:179], v[206:207] op_sel_hi:[1,0]
	v_pk_mul_f32 v[180:181], v[180:181], v[206:207] op_sel_hi:[1,0]
	v_pk_mul_f32 v[182:183], v[182:183], v[206:207] op_sel_hi:[1,0]
	v_pk_mul_f32 v[176:177], v[176:177], v[168:169]
	v_pk_mul_f32 v[178:179], v[178:179], v[170:171]
	v_pk_mul_f32 v[180:181], v[180:181], v[172:173]
	v_pk_mul_f32 v[182:183], v[182:183], v[174:175]
	v_cvt_pk_bf16_f32 v160, v176, v177
	v_cvt_pk_bf16_f32 v161, v178, v179
	v_cvt_pk_bf16_f32 v162, v180, v181
	v_cvt_pk_bf16_f32 v163, v182, v183
	v_lshl_add_u64 v[152:153], v[134:135], 0, s[10:11]
	s_movk_i32 s6, 0x1600
	v_lshl_or_b32 v150, s74, 7, v156
	v_ashrrev_i32_e32 v151, 31, v150
	s_nop 1
	v_mov_b64_e32 v[148:149], s[28:29]
	v_mad_u64_u32 v[148:149], s[10:11], v152, s6, v[148:149]
	v_mov_b32_e32 v146, v149
	v_mad_u64_u32 v[152:153], s[10:11], v153, s6, v[146:147]
	v_mov_b32_e32 v149, v152
	v_mov_b32_e32 v146, v147
	v_lshl_add_u64 v[150:151], v[150:151], 1, v[148:149]
	global_store_dwordx4 v[150:151], v[160:163], off
	v_mul_f32_e32 v184, 0xbfb8aa3b, v146
	v_mul_f32_e32 v206, v146, v146
	v_pk_mul_f32 v[168:169], v[116:117], v[184:185] op_sel_hi:[1,0]
	v_pk_mul_f32 v[170:171], v[118:119], v[184:185] op_sel_hi:[1,0]
	v_pk_mul_f32 v[172:173], v[112:113], v[184:185] op_sel_hi:[1,0]
	v_pk_mul_f32 v[174:175], v[114:115], v[184:185] op_sel_hi:[1,0]
	v_exp_f32_e32 v168, v168
	v_exp_f32_e32 v169, v169
	v_exp_f32_e32 v170, v170
	v_exp_f32_e32 v171, v171
	v_exp_f32_e32 v172, v172
	v_exp_f32_e32 v173, v173
	v_exp_f32_e32 v174, v174
	v_exp_f32_e32 v175, v175
	v_pk_mul_f32 v[176:177], v[116:117], v[84:85]
	v_pk_mul_f32 v[178:179], v[118:119], v[86:87]
	v_pk_mul_f32 v[180:181], v[112:113], v[80:81]
	v_pk_mul_f32 v[182:183], v[114:115], v[82:83]
	v_pk_add_f32 v[168:169], v[168:169], 1.0 op_sel_hi:[1,0]
	v_pk_add_f32 v[170:171], v[170:171], 1.0 op_sel_hi:[1,0]
	v_pk_add_f32 v[172:173], v[172:173], 1.0 op_sel_hi:[1,0]
	v_pk_add_f32 v[174:175], v[174:175], 1.0 op_sel_hi:[1,0]
	v_rcp_f32_e32 v168, v168
	v_rcp_f32_e32 v169, v169
	v_rcp_f32_e32 v170, v170
	v_rcp_f32_e32 v171, v171
	v_rcp_f32_e32 v172, v172
	v_rcp_f32_e32 v173, v173
	v_rcp_f32_e32 v174, v174
	v_rcp_f32_e32 v175, v175
	v_pk_mul_f32 v[176:177], v[176:177], v[206:207] op_sel_hi:[1,0]
	v_pk_mul_f32 v[178:179], v[178:179], v[206:207] op_sel_hi:[1,0]
	v_pk_mul_f32 v[180:181], v[180:181], v[206:207] op_sel_hi:[1,0]
	v_pk_mul_f32 v[182:183], v[182:183], v[206:207] op_sel_hi:[1,0]
	v_pk_mul_f32 v[176:177], v[176:177], v[168:169]
	v_pk_mul_f32 v[178:179], v[178:179], v[170:171]
	v_pk_mul_f32 v[180:181], v[180:181], v[172:173]
	v_pk_mul_f32 v[182:183], v[182:183], v[174:175]
	v_cvt_pk_bf16_f32 v160, v176, v177
	v_cvt_pk_bf16_f32 v161, v178, v179
	v_cvt_pk_bf16_f32 v162, v180, v181
	v_cvt_pk_bf16_f32 v163, v182, v183
	s_mov_b32 s6, 0x16000
	s_nop 1
	v_add_co_u32_e32 v146, vcc, s6, v150
	s_nop 0
	v_addc_co_u32_e32 v147, vcc, 0, v151, vcc
	global_store_dwordx4 v[146:147], v[160:163], off
	ds_read2_b32 v[146:147], v158 offset0:32 offset1:48
	s_mov_b32 s6, 0x2c000
	s_waitcnt lgkmcnt(0)
	v_mul_f32_e32 v184, 0xbfb8aa3b, v146
	v_mul_f32_e32 v206, v146, v146
	v_pk_mul_f32 v[168:169], v[108:109], v[184:185] op_sel_hi:[1,0]
	v_pk_mul_f32 v[170:171], v[110:111], v[184:185] op_sel_hi:[1,0]
	v_pk_mul_f32 v[172:173], v[104:105], v[184:185] op_sel_hi:[1,0]
	v_pk_mul_f32 v[174:175], v[106:107], v[184:185] op_sel_hi:[1,0]
	v_exp_f32_e32 v168, v168
	v_exp_f32_e32 v169, v169
	v_exp_f32_e32 v170, v170
	v_exp_f32_e32 v171, v171
	v_exp_f32_e32 v172, v172
	v_exp_f32_e32 v173, v173
	v_exp_f32_e32 v174, v174
	v_exp_f32_e32 v175, v175
	v_pk_mul_f32 v[176:177], v[108:109], v[76:77]
	v_pk_mul_f32 v[178:179], v[110:111], v[78:79]
	v_pk_mul_f32 v[180:181], v[104:105], v[72:73]
	v_pk_mul_f32 v[182:183], v[106:107], v[74:75]
	v_pk_add_f32 v[168:169], v[168:169], 1.0 op_sel_hi:[1,0]
	v_pk_add_f32 v[170:171], v[170:171], 1.0 op_sel_hi:[1,0]
	v_pk_add_f32 v[172:173], v[172:173], 1.0 op_sel_hi:[1,0]
	v_pk_add_f32 v[174:175], v[174:175], 1.0 op_sel_hi:[1,0]
	v_rcp_f32_e32 v168, v168
	v_rcp_f32_e32 v169, v169
	v_rcp_f32_e32 v170, v170
	v_rcp_f32_e32 v171, v171
	v_rcp_f32_e32 v172, v172
	v_rcp_f32_e32 v173, v173
	v_rcp_f32_e32 v174, v174
	v_rcp_f32_e32 v175, v175
	v_pk_mul_f32 v[176:177], v[176:177], v[206:207] op_sel_hi:[1,0]
	v_pk_mul_f32 v[178:179], v[178:179], v[206:207] op_sel_hi:[1,0]
	v_pk_mul_f32 v[180:181], v[180:181], v[206:207] op_sel_hi:[1,0]
	v_pk_mul_f32 v[182:183], v[182:183], v[206:207] op_sel_hi:[1,0]
	v_pk_mul_f32 v[176:177], v[176:177], v[168:169]
	v_pk_mul_f32 v[178:179], v[178:179], v[170:171]
	v_pk_mul_f32 v[180:181], v[180:181], v[172:173]
	v_pk_mul_f32 v[182:183], v[182:183], v[174:175]
	v_cvt_pk_bf16_f32 v160, v176, v177
	v_cvt_pk_bf16_f32 v161, v178, v179
	v_cvt_pk_bf16_f32 v162, v180, v181
	v_cvt_pk_bf16_f32 v163, v182, v183
	s_nop 1
	v_mov_b32_e32 v146, v147
	v_add_co_u32_e32 v148, vcc, s6, v150
	v_addc_co_u32_e32 v149, vcc, 0, v151, vcc
	global_store_dwordx4 v[148:149], v[160:163], off
	v_mul_f32_e32 v184, 0xbfb8aa3b, v146
	v_mul_f32_e32 v206, v146, v146
	v_pk_mul_f32 v[168:169], v[100:101], v[184:185] op_sel_hi:[1,0]
	v_pk_mul_f32 v[170:171], v[102:103], v[184:185] op_sel_hi:[1,0]
	v_pk_mul_f32 v[172:173], v[96:97], v[184:185] op_sel_hi:[1,0]
	v_pk_mul_f32 v[174:175], v[98:99], v[184:185] op_sel_hi:[1,0]
	v_exp_f32_e32 v168, v168
	v_exp_f32_e32 v169, v169
	v_exp_f32_e32 v170, v170
	v_exp_f32_e32 v171, v171
	v_exp_f32_e32 v172, v172
	v_exp_f32_e32 v173, v173
	v_exp_f32_e32 v174, v174
	v_exp_f32_e32 v175, v175
	v_pk_mul_f32 v[176:177], v[100:101], v[68:69]
	v_pk_mul_f32 v[178:179], v[102:103], v[70:71]
	v_pk_mul_f32 v[180:181], v[96:97], v[64:65]
	v_pk_mul_f32 v[182:183], v[98:99], v[66:67]
	v_pk_add_f32 v[168:169], v[168:169], 1.0 op_sel_hi:[1,0]
	v_pk_add_f32 v[170:171], v[170:171], 1.0 op_sel_hi:[1,0]
	v_pk_add_f32 v[172:173], v[172:173], 1.0 op_sel_hi:[1,0]
	v_pk_add_f32 v[174:175], v[174:175], 1.0 op_sel_hi:[1,0]
	v_rcp_f32_e32 v168, v168
	v_rcp_f32_e32 v169, v169
	v_rcp_f32_e32 v170, v170
	v_rcp_f32_e32 v171, v171
	v_rcp_f32_e32 v172, v172
	v_rcp_f32_e32 v173, v173
	v_rcp_f32_e32 v174, v174
	v_rcp_f32_e32 v175, v175
	v_pk_mul_f32 v[176:177], v[176:177], v[206:207] op_sel_hi:[1,0]
	v_pk_mul_f32 v[178:179], v[178:179], v[206:207] op_sel_hi:[1,0]
	v_pk_mul_f32 v[180:181], v[180:181], v[206:207] op_sel_hi:[1,0]
	v_pk_mul_f32 v[182:183], v[182:183], v[206:207] op_sel_hi:[1,0]
	v_pk_mul_f32 v[176:177], v[176:177], v[168:169]
	v_pk_mul_f32 v[178:179], v[178:179], v[170:171]
	v_pk_mul_f32 v[180:181], v[180:181], v[172:173]
	v_pk_mul_f32 v[182:183], v[182:183], v[174:175]
	v_cvt_pk_bf16_f32 v160, v176, v177
	v_cvt_pk_bf16_f32 v161, v178, v179
	v_cvt_pk_bf16_f32 v162, v180, v181
	v_cvt_pk_bf16_f32 v163, v182, v183
	s_mov_b32 s6, 0x42000
	s_nop 1
	v_add_co_u32_e32 v146, vcc, s6, v150
	s_nop 0
	v_addc_co_u32_e32 v147, vcc, 0, v151, vcc
	global_store_dwordx4 v[146:147], v[160:163], off
	ds_read2_b32 v[146:147], v158 offset0:128 offset1:144
	s_mov_b32 s6, 0xb0000
	s_waitcnt lgkmcnt(0)
	v_mul_f32_e32 v184, 0xbfb8aa3b, v146
	v_mul_f32_e32 v206, v146, v146
	v_pk_mul_f32 v[168:169], v[60:61], v[184:185] op_sel_hi:[1,0]
	v_pk_mul_f32 v[170:171], v[62:63], v[184:185] op_sel_hi:[1,0]
	v_pk_mul_f32 v[172:173], v[56:57], v[184:185] op_sel_hi:[1,0]
	v_pk_mul_f32 v[174:175], v[58:59], v[184:185] op_sel_hi:[1,0]
	v_exp_f32_e32 v168, v168
	v_exp_f32_e32 v169, v169
	v_exp_f32_e32 v170, v170
	v_exp_f32_e32 v171, v171
	v_exp_f32_e32 v172, v172
	v_exp_f32_e32 v173, v173
	v_exp_f32_e32 v174, v174
	v_exp_f32_e32 v175, v175
	v_pk_mul_f32 v[176:177], v[60:61], v[28:29]
	v_pk_mul_f32 v[178:179], v[62:63], v[30:31]
	v_pk_mul_f32 v[180:181], v[56:57], v[24:25]
	v_pk_mul_f32 v[182:183], v[58:59], v[26:27]
	v_pk_add_f32 v[168:169], v[168:169], 1.0 op_sel_hi:[1,0]
	v_pk_add_f32 v[170:171], v[170:171], 1.0 op_sel_hi:[1,0]
	v_pk_add_f32 v[172:173], v[172:173], 1.0 op_sel_hi:[1,0]
	v_pk_add_f32 v[174:175], v[174:175], 1.0 op_sel_hi:[1,0]
	v_rcp_f32_e32 v168, v168
	v_rcp_f32_e32 v169, v169
	v_rcp_f32_e32 v170, v170
	v_rcp_f32_e32 v171, v171
	v_rcp_f32_e32 v172, v172
	v_rcp_f32_e32 v173, v173
	v_rcp_f32_e32 v174, v174
	v_rcp_f32_e32 v175, v175
	v_pk_mul_f32 v[176:177], v[176:177], v[206:207] op_sel_hi:[1,0]
	v_pk_mul_f32 v[178:179], v[178:179], v[206:207] op_sel_hi:[1,0]
	v_pk_mul_f32 v[180:181], v[180:181], v[206:207] op_sel_hi:[1,0]
	v_pk_mul_f32 v[182:183], v[182:183], v[206:207] op_sel_hi:[1,0]
	v_pk_mul_f32 v[176:177], v[176:177], v[168:169]
	v_pk_mul_f32 v[178:179], v[178:179], v[170:171]
	v_pk_mul_f32 v[180:181], v[180:181], v[172:173]
	v_pk_mul_f32 v[182:183], v[182:183], v[174:175]
	v_cvt_pk_bf16_f32 v160, v176, v177
	v_cvt_pk_bf16_f32 v161, v178, v179
	v_cvt_pk_bf16_f32 v162, v180, v181
	v_cvt_pk_bf16_f32 v163, v182, v183
	s_nop 1
	v_mov_b32_e32 v146, v147
	v_add_co_u32_e32 v148, vcc, s6, v150
	v_addc_co_u32_e32 v149, vcc, 0, v151, vcc
	global_store_dwordx4 v[148:149], v[160:163], off
	v_mul_f32_e32 v184, 0xbfb8aa3b, v146
	v_mul_f32_e32 v206, v146, v146
	v_pk_mul_f32 v[168:169], v[52:53], v[184:185] op_sel_hi:[1,0]
	v_pk_mul_f32 v[170:171], v[54:55], v[184:185] op_sel_hi:[1,0]
	v_pk_mul_f32 v[172:173], v[48:49], v[184:185] op_sel_hi:[1,0]
	v_pk_mul_f32 v[174:175], v[50:51], v[184:185] op_sel_hi:[1,0]
	v_exp_f32_e32 v168, v168
	v_exp_f32_e32 v169, v169
	v_exp_f32_e32 v170, v170
	v_exp_f32_e32 v171, v171
	v_exp_f32_e32 v172, v172
	v_exp_f32_e32 v173, v173
	v_exp_f32_e32 v174, v174
	v_exp_f32_e32 v175, v175
	v_pk_mul_f32 v[176:177], v[52:53], v[20:21]
	v_pk_mul_f32 v[178:179], v[54:55], v[22:23]
	v_pk_mul_f32 v[180:181], v[48:49], v[16:17]
	v_pk_mul_f32 v[182:183], v[50:51], v[18:19]
	v_pk_add_f32 v[168:169], v[168:169], 1.0 op_sel_hi:[1,0]
	v_pk_add_f32 v[170:171], v[170:171], 1.0 op_sel_hi:[1,0]
	v_pk_add_f32 v[172:173], v[172:173], 1.0 op_sel_hi:[1,0]
	v_pk_add_f32 v[174:175], v[174:175], 1.0 op_sel_hi:[1,0]
	v_rcp_f32_e32 v168, v168
	v_rcp_f32_e32 v169, v169
	v_rcp_f32_e32 v170, v170
	v_rcp_f32_e32 v171, v171
	v_rcp_f32_e32 v172, v172
	v_rcp_f32_e32 v173, v173
	v_rcp_f32_e32 v174, v174
	v_rcp_f32_e32 v175, v175
	v_pk_mul_f32 v[176:177], v[176:177], v[206:207] op_sel_hi:[1,0]
	v_pk_mul_f32 v[178:179], v[178:179], v[206:207] op_sel_hi:[1,0]
	v_pk_mul_f32 v[180:181], v[180:181], v[206:207] op_sel_hi:[1,0]
	v_pk_mul_f32 v[182:183], v[182:183], v[206:207] op_sel_hi:[1,0]
	v_pk_mul_f32 v[176:177], v[176:177], v[168:169]
	v_pk_mul_f32 v[178:179], v[178:179], v[170:171]
	v_pk_mul_f32 v[180:181], v[180:181], v[172:173]
	v_pk_mul_f32 v[182:183], v[182:183], v[174:175]
	v_cvt_pk_bf16_f32 v160, v176, v177
	v_cvt_pk_bf16_f32 v161, v178, v179
	v_cvt_pk_bf16_f32 v162, v180, v181
	v_cvt_pk_bf16_f32 v163, v182, v183
	s_mov_b32 s6, 0xc6000
	s_nop 1
	v_add_co_u32_e32 v146, vcc, s6, v150
	s_nop 0
	v_addc_co_u32_e32 v147, vcc, 0, v151, vcc
	global_store_dwordx4 v[146:147], v[160:163], off
	ds_read2_b32 v[146:147], v158 offset0:160 offset1:176
	s_mov_b32 s6, 0xdc000
	s_waitcnt lgkmcnt(0)
	v_mul_f32_e32 v184, 0xbfb8aa3b, v146
	v_mul_f32_e32 v206, v146, v146
	v_pk_mul_f32 v[168:169], v[44:45], v[184:185] op_sel_hi:[1,0]
	v_pk_mul_f32 v[170:171], v[46:47], v[184:185] op_sel_hi:[1,0]
	v_pk_mul_f32 v[172:173], v[40:41], v[184:185] op_sel_hi:[1,0]
	v_pk_mul_f32 v[174:175], v[42:43], v[184:185] op_sel_hi:[1,0]
	v_exp_f32_e32 v168, v168
	v_exp_f32_e32 v169, v169
	v_exp_f32_e32 v170, v170
	v_exp_f32_e32 v171, v171
	v_exp_f32_e32 v172, v172
	v_exp_f32_e32 v173, v173
	v_exp_f32_e32 v174, v174
	v_exp_f32_e32 v175, v175
	v_pk_mul_f32 v[176:177], v[44:45], v[12:13]
	v_pk_mul_f32 v[178:179], v[46:47], v[14:15]
	v_pk_mul_f32 v[180:181], v[40:41], v[8:9]
	v_pk_mul_f32 v[182:183], v[42:43], v[10:11]
	v_pk_add_f32 v[168:169], v[168:169], 1.0 op_sel_hi:[1,0]
	v_pk_add_f32 v[170:171], v[170:171], 1.0 op_sel_hi:[1,0]
	v_pk_add_f32 v[172:173], v[172:173], 1.0 op_sel_hi:[1,0]
	v_pk_add_f32 v[174:175], v[174:175], 1.0 op_sel_hi:[1,0]
	v_rcp_f32_e32 v168, v168
	v_rcp_f32_e32 v169, v169
	v_rcp_f32_e32 v170, v170
	v_rcp_f32_e32 v171, v171
	v_rcp_f32_e32 v172, v172
	v_rcp_f32_e32 v173, v173
	v_rcp_f32_e32 v174, v174
	v_rcp_f32_e32 v175, v175
	v_pk_mul_f32 v[176:177], v[176:177], v[206:207] op_sel_hi:[1,0]
	v_pk_mul_f32 v[178:179], v[178:179], v[206:207] op_sel_hi:[1,0]
	v_pk_mul_f32 v[180:181], v[180:181], v[206:207] op_sel_hi:[1,0]
	v_pk_mul_f32 v[182:183], v[182:183], v[206:207] op_sel_hi:[1,0]
	v_pk_mul_f32 v[176:177], v[176:177], v[168:169]
	v_pk_mul_f32 v[178:179], v[178:179], v[170:171]
	v_pk_mul_f32 v[180:181], v[180:181], v[172:173]
	v_pk_mul_f32 v[182:183], v[182:183], v[174:175]
	v_cvt_pk_bf16_f32 v158, v176, v177
	v_cvt_pk_bf16_f32 v159, v178, v179
	v_cvt_pk_bf16_f32 v160, v180, v181
	v_cvt_pk_bf16_f32 v161, v182, v183
	s_nop 1
	v_mov_b32_e32 v146, v147
	v_add_co_u32_e32 v148, vcc, s6, v150
	v_addc_co_u32_e32 v149, vcc, 0, v151, vcc
	global_store_dwordx4 v[148:149], v[158:161], off
	v_mul_f32_e32 v184, 0xbfb8aa3b, v146
	v_mul_f32_e32 v206, v146, v146
	v_pk_mul_f32 v[168:169], v[36:37], v[184:185] op_sel_hi:[1,0]
	v_pk_mul_f32 v[170:171], v[38:39], v[184:185] op_sel_hi:[1,0]
	v_pk_mul_f32 v[172:173], v[32:33], v[184:185] op_sel_hi:[1,0]
	v_pk_mul_f32 v[174:175], v[34:35], v[184:185] op_sel_hi:[1,0]
	v_exp_f32_e32 v168, v168
	v_exp_f32_e32 v169, v169
	v_exp_f32_e32 v170, v170
	v_exp_f32_e32 v171, v171
	v_exp_f32_e32 v172, v172
	v_exp_f32_e32 v173, v173
	v_exp_f32_e32 v174, v174
	v_exp_f32_e32 v175, v175
	v_pk_mul_f32 v[176:177], v[36:37], v[4:5]
	v_pk_mul_f32 v[178:179], v[38:39], v[6:7]
	v_pk_mul_f32 v[180:181], v[32:33], v[0:1]
	v_pk_mul_f32 v[182:183], v[34:35], v[2:3]
	v_pk_add_f32 v[168:169], v[168:169], 1.0 op_sel_hi:[1,0]
	v_pk_add_f32 v[170:171], v[170:171], 1.0 op_sel_hi:[1,0]
	v_pk_add_f32 v[172:173], v[172:173], 1.0 op_sel_hi:[1,0]
	v_pk_add_f32 v[174:175], v[174:175], 1.0 op_sel_hi:[1,0]
	v_rcp_f32_e32 v168, v168
	v_rcp_f32_e32 v169, v169
	v_rcp_f32_e32 v170, v170
	v_rcp_f32_e32 v171, v171
	v_rcp_f32_e32 v172, v172
	v_rcp_f32_e32 v173, v173
	v_rcp_f32_e32 v174, v174
	v_rcp_f32_e32 v175, v175
	v_pk_mul_f32 v[176:177], v[176:177], v[206:207] op_sel_hi:[1,0]
	v_pk_mul_f32 v[178:179], v[178:179], v[206:207] op_sel_hi:[1,0]
	v_pk_mul_f32 v[180:181], v[180:181], v[206:207] op_sel_hi:[1,0]
	v_pk_mul_f32 v[182:183], v[182:183], v[206:207] op_sel_hi:[1,0]
	v_pk_mul_f32 v[176:177], v[176:177], v[168:169]
	v_pk_mul_f32 v[178:179], v[178:179], v[170:171]
	v_pk_mul_f32 v[180:181], v[180:181], v[172:173]
	v_pk_mul_f32 v[182:183], v[182:183], v[174:175]
	v_cvt_pk_bf16_f32 v158, v176, v177
	v_cvt_pk_bf16_f32 v159, v178, v179
	v_cvt_pk_bf16_f32 v160, v180, v181
	v_cvt_pk_bf16_f32 v161, v182, v183
	s_nop 1
	v_add_co_u32_e32 v146, vcc, 0xf2000, v150
	s_nop 0
	v_addc_co_u32_e32 v147, vcc, 0, v151, vcc
	s_andn2_b64 vcc, exec, s[44:45]
	global_store_dwordx4 v[146:147], v[158:161], off
	s_cbranch_vccz .LBB0_73
	s_mov_b64 s[46:47], s[50:51]
	s_andn2_b64 vcc, exec, s[42:43]
	s_mov_b64 s[50:51], s[46:47]
	s_cbranch_vccnz .LBB0_74

.Lm4ap_103:
	s_waitcnt lgkmcnt(0)
	s_barrier
	v_mfma_f32_16x16x32_bf16 v[124:127], v[128:131], v[162:165], 0
	v_mfma_f32_16x16x32_bf16 v[120:123], v[136:139], v[162:165], 0
	v_mfma_f32_16x16x32_bf16 v[108:111], v[128:131], v[170:173], 0
	v_mfma_f32_16x16x32_bf16 v[104:107], v[136:139], v[170:173], 0
	v_mfma_f32_16x16x32_bf16 v[96:99], v[128:131], v[178:181], 0
	v_mfma_f32_16x16x32_bf16 v[88:91], v[136:139], v[178:181], 0
	v_mfma_f32_16x16x32_bf16 v[84:87], v[128:131], v[194:197], 0
	v_mfma_f32_16x16x32_bf16 v[80:83], v[136:139], v[194:197], 0
	v_mfma_f32_16x16x32_bf16 v[124:127], v[132:135], v[166:169], v[124:127]
	v_mfma_f32_16x16x32_bf16 v[120:123], v[146:149], v[166:169], v[120:123]
	v_mfma_f32_16x16x32_bf16 v[108:111], v[132:135], v[174:177], v[108:111]
	v_mfma_f32_16x16x32_bf16 v[104:107], v[146:149], v[174:177], v[104:107]
	v_mfma_f32_16x16x32_bf16 v[96:99], v[132:135], v[182:185], v[96:99]
	v_mfma_f32_16x16x32_bf16 v[88:91], v[146:149], v[182:185], v[88:91]
	v_mfma_f32_16x16x32_bf16 v[84:87], v[132:135], v[210:213], v[84:87]
	v_mfma_f32_16x16x32_bf16 v[80:83], v[146:149], v[210:213], v[80:83]
	v_mfma_f32_16x16x32_bf16 v[116:119], v[214:217], v[162:165], 0
	v_mfma_f32_16x16x32_bf16 v[112:115], v[222:225], v[162:165], 0
	v_mfma_f32_16x16x32_bf16 v[100:103], v[214:217], v[170:173], 0
	v_mfma_f32_16x16x32_bf16 v[92:95], v[222:225], v[170:173], 0
	v_mfma_f32_16x16x32_bf16 v[76:79], v[214:217], v[178:181], 0
	v_mfma_f32_16x16x32_bf16 v[72:75], v[222:225], v[178:181], 0
	v_mfma_f32_16x16x32_bf16 v[68:71], v[214:217], v[194:197], 0
	v_mfma_f32_16x16x32_bf16 v[64:67], v[222:225], v[194:197], 0
	v_mfma_f32_16x16x32_bf16 v[116:119], v[218:221], v[166:169], v[116:119]
	v_mfma_f32_16x16x32_bf16 v[112:115], v[226:229], v[166:169], v[112:115]
	v_mfma_f32_16x16x32_bf16 v[100:103], v[218:221], v[174:177], v[100:103]
	v_mfma_f32_16x16x32_bf16 v[92:95], v[226:229], v[174:177], v[92:95]
	v_mfma_f32_16x16x32_bf16 v[76:79], v[218:221], v[182:185], v[76:79]
	v_mfma_f32_16x16x32_bf16 v[72:75], v[226:229], v[182:185], v[72:75]
	v_mfma_f32_16x16x32_bf16 v[68:71], v[218:221], v[210:213], v[68:71]
	v_mfma_f32_16x16x32_bf16 v[64:67], v[226:229], v[210:213], v[64:67]
	s_barrier
	s_add_i32 s19, s23, s71
	v_lshl_add_u64 v[192:193], s[58:59], 0, v[140:141]
	s_mov_b32 m0, s19
	v_lshl_add_u64 v[230:231], s[58:59], 0, v[150:151]
	global_load_lds_dwordx4 v[192:193], off
	s_add_i32 m0, s19, 0x2000
	s_nop 0
	global_load_lds_dwordx4 v[230:231], off
	s_mov_b32 m0, s72
	v_lshl_add_u64 v[232:233], s[68:69], 0, v[154:155]
	ds_read_b128 v[162:165], v208 offset:16384
	ds_read_b128 v[166:169], v208 offset:17408
	ds_read_b128 v[170:173], v208 offset:18432
	ds_read_b128 v[174:177], v208 offset:19456
	ds_read_b128 v[178:181], v208 offset:20480
	ds_read_b128 v[182:185], v208 offset:21504
	ds_read_b128 v[194:197], v208 offset:22528
	ds_read_b128 v[210:213], v208 offset:23552
	global_load_lds_dwordx4 v[232:233], off
	v_lshl_add_u64 v[234:235], s[68:69], 0, v[152:153]
	s_mov_b32 m0, s73
	s_nop 0
	global_load_lds_dwordx4 v[234:235], off
	s_add_u32 s86, s58, 0x40000
	s_addc_u32 s87, s59, 0
	s_add_i32 s6, s6, s71
	v_lshl_add_u64 v[250:251], s[86:87], 0, v[140:141]
	s_mov_b32 m0, s6
	s_nop 0
	global_load_lds_dwordx4 v[250:251], off
	v_lshl_add_u64 v[250:251], s[86:87], 0, v[150:151]
	s_add_i32 m0, s6, 0x2000
	s_nop 0
	global_load_lds_dwordx4 v[250:251], off
	s_waitcnt vmcnt(40)
	s_cmp_lg_u32 s100, 0
	s_cbranch_scc1 .Lm4bp_103
	s_waitcnt vmcnt(8)
.Lm4bp_103:
	s_waitcnt lgkmcnt(0)
	s_mov_b32 s100, 0
	s_barrier
	v_mfma_f32_16x16x32_bf16 v[60:63], v[128:131], v[162:165], 0
	v_mfma_f32_16x16x32_bf16 v[56:59], v[136:139], v[162:165], 0
	v_mfma_f32_16x16x32_bf16 v[48:51], v[128:131], v[170:173], 0
	v_mfma_f32_16x16x32_bf16 v[40:43], v[136:139], v[170:173], 0
	v_mfma_f32_16x16x32_bf16 v[32:35], v[128:131], v[178:181], 0
	v_mfma_f32_16x16x32_bf16 v[24:27], v[136:139], v[178:181], 0
	v_mfma_f32_16x16x32_bf16 v[16:19], v[128:131], v[194:197], 0
	v_mfma_f32_16x16x32_bf16 v[8:11], v[136:139], v[194:197], 0
	v_mfma_f32_16x16x32_bf16 v[60:63], v[132:135], v[166:169], v[60:63]
	v_mfma_f32_16x16x32_bf16 v[56:59], v[146:149], v[166:169], v[56:59]
	v_mfma_f32_16x16x32_bf16 v[48:51], v[132:135], v[174:177], v[48:51]
	v_mfma_f32_16x16x32_bf16 v[40:43], v[146:149], v[174:177], v[40:43]
	v_mfma_f32_16x16x32_bf16 v[32:35], v[132:135], v[182:185], v[32:35]
	v_mfma_f32_16x16x32_bf16 v[24:27], v[146:149], v[182:185], v[24:27]
	v_mfma_f32_16x16x32_bf16 v[16:19], v[132:135], v[210:213], v[16:19]
	v_mfma_f32_16x16x32_bf16 v[8:11], v[146:149], v[210:213], v[8:11]
	v_mfma_f32_16x16x32_bf16 v[52:55], v[214:217], v[162:165], 0
	v_mfma_f32_16x16x32_bf16 v[44:47], v[222:225], v[162:165], 0
	v_mfma_f32_16x16x32_bf16 v[36:39], v[214:217], v[170:173], 0
	v_mfma_f32_16x16x32_bf16 v[28:31], v[222:225], v[170:173], 0
	v_mfma_f32_16x16x32_bf16 v[20:23], v[214:217], v[178:181], 0
	v_mfma_f32_16x16x32_bf16 v[12:15], v[222:225], v[178:181], 0
	v_mfma_f32_16x16x32_bf16 v[4:7], v[214:217], v[194:197], 0
	v_mfma_f32_16x16x32_bf16 v[0:3], v[222:225], v[194:197], 0
	v_mfma_f32_16x16x32_bf16 v[52:55], v[218:221], v[166:169], v[52:55]
	v_mfma_f32_16x16x32_bf16 v[44:47], v[226:229], v[166:169], v[44:47]
	v_mfma_f32_16x16x32_bf16 v[36:39], v[218:221], v[174:177], v[36:39]
	v_mfma_f32_16x16x32_bf16 v[28:31], v[226:229], v[174:177], v[28:31]
	v_mfma_f32_16x16x32_bf16 v[20:23], v[218:221], v[182:185], v[20:23]
	v_mfma_f32_16x16x32_bf16 v[12:15], v[226:229], v[182:185], v[12:15]
	v_mfma_f32_16x16x32_bf16 v[4:7], v[218:221], v[210:213], v[4:7]
	v_mfma_f32_16x16x32_bf16 v[0:3], v[226:229], v[210:213], v[0:3]
	s_barrier
	s_add_i32 s6, 0, 0x18000
	v_add_u32_e32 v146, s6, v206
	ds_read_b128 v[128:131], v146
	ds_read_b128 v[132:135], v146 offset:1024
	ds_read_b128 v[136:139], v146 offset:2048
	ds_read_b128 v[146:149], v146 offset:3072
	s_add_u32 s68, s68, 0x40000
	s_addc_u32 s69, s69, 0
	s_mov_b32 m0, s74
	v_lshl_add_u64 v[214:215], s[68:69], 0, v[154:155]
	ds_read_b128 v[162:165], v208 offset:32768
	ds_read_b128 v[166:169], v208 offset:33792
	ds_read_b128 v[170:173], v208 offset:34816
	ds_read_b128 v[174:177], v208 offset:35840
	ds_read_b128 v[178:181], v208 offset:36864
	ds_read_b128 v[182:185], v208 offset:37888
	ds_read_b128 v[194:197], v208 offset:38912
	ds_read_b128 v[210:213], v208 offset:39936
	global_load_lds_dwordx4 v[214:215], off
	v_lshl_add_u64 v[214:215], s[68:69], 0, v[152:153]
	s_mov_b32 m0, s75
	s_nop 0
	global_load_lds_dwordx4 v[214:215], off
	s_add_i32 s19, 0, 0x1c000
	v_add_u32_e32 v209, s19, v206
	ds_read_b128 v[214:217], v209
	ds_read_b128 v[218:221], v209 offset:1024
	ds_read_b128 v[222:225], v209 offset:2048
	ds_read_b128 v[226:229], v209 offset:3072
	s_waitcnt vmcnt(8)
	s_waitcnt lgkmcnt(0)
	s_barrier
	v_mfma_f32_16x16x32_bf16 v[124:127], v[128:131], v[162:165], v[124:127]
	v_mfma_f32_16x16x32_bf16 v[120:123], v[136:139], v[162:165], v[120:123]
	v_mfma_f32_16x16x32_bf16 v[108:111], v[128:131], v[170:173], v[108:111]
	v_mfma_f32_16x16x32_bf16 v[104:107], v[136:139], v[170:173], v[104:107]
	v_mfma_f32_16x16x32_bf16 v[96:99], v[128:131], v[178:181], v[96:99]
	v_mfma_f32_16x16x32_bf16 v[88:91], v[136:139], v[178:181], v[88:91]
	v_mfma_f32_16x16x32_bf16 v[84:87], v[128:131], v[194:197], v[84:87]
	v_mfma_f32_16x16x32_bf16 v[80:83], v[136:139], v[194:197], v[80:83]
	v_mfma_f32_16x16x32_bf16 v[124:127], v[132:135], v[166:169], v[124:127]
	v_mfma_f32_16x16x32_bf16 v[120:123], v[146:149], v[166:169], v[120:123]
	v_mfma_f32_16x16x32_bf16 v[108:111], v[132:135], v[174:177], v[108:111]
	v_mfma_f32_16x16x32_bf16 v[104:107], v[146:149], v[174:177], v[104:107]
	v_mfma_f32_16x16x32_bf16 v[96:99], v[132:135], v[182:185], v[96:99]
	v_mfma_f32_16x16x32_bf16 v[88:91], v[146:149], v[182:185], v[88:91]
	v_mfma_f32_16x16x32_bf16 v[84:87], v[132:135], v[210:213], v[84:87]
	v_mfma_f32_16x16x32_bf16 v[80:83], v[146:149], v[210:213], v[80:83]
	v_mfma_f32_16x16x32_bf16 v[116:119], v[214:217], v[162:165], v[116:119]
	v_mfma_f32_16x16x32_bf16 v[112:115], v[222:225], v[162:165], v[112:115]
	v_mfma_f32_16x16x32_bf16 v[100:103], v[214:217], v[170:173], v[100:103]
	v_mfma_f32_16x16x32_bf16 v[92:95], v[222:225], v[170:173], v[92:95]
	v_mfma_f32_16x16x32_bf16 v[76:79], v[214:217], v[178:181], v[76:79]
	v_mfma_f32_16x16x32_bf16 v[72:75], v[222:225], v[178:181], v[72:75]
	v_mfma_f32_16x16x32_bf16 v[68:71], v[214:217], v[194:197], v[68:71]
	v_mfma_f32_16x16x32_bf16 v[64:67], v[222:225], v[194:197], v[64:67]
	v_mfma_f32_16x16x32_bf16 v[116:119], v[218:221], v[166:169], v[116:119]
	v_mfma_f32_16x16x32_bf16 v[112:115], v[226:229], v[166:169], v[112:115]
	v_mfma_f32_16x16x32_bf16 v[100:103], v[218:221], v[174:177], v[100:103]
	v_mfma_f32_16x16x32_bf16 v[92:95], v[226:229], v[174:177], v[92:95]
	v_mfma_f32_16x16x32_bf16 v[76:79], v[218:221], v[182:185], v[76:79]
	v_mfma_f32_16x16x32_bf16 v[72:75], v[226:229], v[182:185], v[72:75]
	v_mfma_f32_16x16x32_bf16 v[68:71], v[218:221], v[210:213], v[68:71]
	v_mfma_f32_16x16x32_bf16 v[64:67], v[226:229], v[210:213], v[64:67]
	s_barrier
	s_add_i32 s6, s6, s71
	v_lshl_add_u64 v[192:193], v[192:193], 0, s[36:37]
	s_mov_b32 m0, s6
	s_nop 0
	global_load_lds_dwordx4 v[192:193], off
	v_lshl_add_u64 v[192:193], v[230:231], 0, s[36:37]
	s_add_i32 m0, s6, 0x2000
	s_nop 0
	global_load_lds_dwordx4 v[192:193], off
	s_mov_b32 m0, s80
	v_lshl_add_u64 v[192:193], v[232:233], 0, s[36:37]
	ds_read_b128 v[162:165], v208 offset:49152
	ds_read_b128 v[166:169], v208 offset:50176
	ds_read_b128 v[170:173], v208 offset:51200
	ds_read_b128 v[174:177], v208 offset:52224
	ds_read_b128 v[178:181], v208 offset:53248
	ds_read_b128 v[182:185], v208 offset:54272
	ds_read_b128 v[194:197], v208 offset:55296
	ds_read_b128 v[210:213], v208 offset:56320
	global_load_lds_dwordx4 v[192:193], off
	v_lshl_add_u64 v[192:193], v[234:235], 0, s[36:37]
	s_mov_b32 m0, s81
	s_nop 0
	global_load_lds_dwordx4 v[192:193], off
	s_add_u32 s58, s58, 0x40080
	s_addc_u32 s59, s59, 0
	s_add_i32 s6, s19, s71
	v_lshl_add_u64 v[250:251], s[58:59], 0, v[140:141]
	s_mov_b32 m0, s6
	s_nop 0
	global_load_lds_dwordx4 v[250:251], off
	v_lshl_add_u64 v[250:251], s[58:59], 0, v[150:151]
	s_add_i32 m0, s6, 0x2000
	s_nop 0
	global_load_lds_dwordx4 v[250:251], off
	s_waitcnt vmcnt(8)
	s_waitcnt lgkmcnt(0)
	s_barrier
	v_mfma_f32_16x16x32_bf16 v[60:63], v[128:131], v[162:165], v[60:63]
	v_mfma_f32_16x16x32_bf16 v[56:59], v[136:139], v[162:165], v[56:59]
	v_mfma_f32_16x16x32_bf16 v[48:51], v[128:131], v[170:173], v[48:51]
	v_mfma_f32_16x16x32_bf16 v[40:43], v[136:139], v[170:173], v[40:43]
	v_mfma_f32_16x16x32_bf16 v[32:35], v[128:131], v[178:181], v[32:35]
	v_mfma_f32_16x16x32_bf16 v[24:27], v[136:139], v[178:181], v[24:27]
	v_mfma_f32_16x16x32_bf16 v[16:19], v[128:131], v[194:197], v[16:19]
	v_mfma_f32_16x16x32_bf16 v[8:11], v[136:139], v[194:197], v[8:11]
	v_mfma_f32_16x16x32_bf16 v[60:63], v[132:135], v[166:169], v[60:63]
	v_mfma_f32_16x16x32_bf16 v[56:59], v[146:149], v[166:169], v[56:59]
	v_mfma_f32_16x16x32_bf16 v[48:51], v[132:135], v[174:177], v[48:51]
	v_mfma_f32_16x16x32_bf16 v[40:43], v[146:149], v[174:177], v[40:43]
	v_mfma_f32_16x16x32_bf16 v[32:35], v[132:135], v[182:185], v[32:35]
	v_mfma_f32_16x16x32_bf16 v[24:27], v[146:149], v[182:185], v[24:27]
	v_mfma_f32_16x16x32_bf16 v[16:19], v[132:135], v[210:213], v[16:19]
	v_mfma_f32_16x16x32_bf16 v[8:11], v[146:149], v[210:213], v[8:11]
	v_mfma_f32_16x16x32_bf16 v[52:55], v[214:217], v[162:165], v[52:55]
	v_mfma_f32_16x16x32_bf16 v[44:47], v[222:225], v[162:165], v[44:47]
	v_mfma_f32_16x16x32_bf16 v[36:39], v[214:217], v[170:173], v[36:39]
	v_mfma_f32_16x16x32_bf16 v[28:31], v[222:225], v[170:173], v[28:31]
	v_mfma_f32_16x16x32_bf16 v[20:23], v[214:217], v[178:181], v[20:23]
	v_mfma_f32_16x16x32_bf16 v[12:15], v[222:225], v[178:181], v[12:15]
	v_mfma_f32_16x16x32_bf16 v[4:7], v[214:217], v[194:197], v[4:7]
	v_mfma_f32_16x16x32_bf16 v[0:3], v[222:225], v[194:197], v[0:3]
	v_mfma_f32_16x16x32_bf16 v[52:55], v[218:221], v[166:169], v[52:55]
	v_mfma_f32_16x16x32_bf16 v[44:47], v[226:229], v[166:169], v[44:47]
	v_mfma_f32_16x16x32_bf16 v[36:39], v[218:221], v[174:177], v[36:39]
	v_mfma_f32_16x16x32_bf16 v[28:31], v[226:229], v[174:177], v[28:31]
	v_mfma_f32_16x16x32_bf16 v[20:23], v[218:221], v[182:185], v[20:23]
	v_mfma_f32_16x16x32_bf16 v[12:15], v[226:229], v[182:185], v[12:15]
	v_mfma_f32_16x16x32_bf16 v[4:7], v[218:221], v[210:213], v[4:7]
	v_mfma_f32_16x16x32_bf16 v[0:3], v[226:229], v[210:213], v[0:3]
	s_add_i32 s12, s12, 2
	s_add_u32 s54, s54, 0x100
	s_addc_u32 s55, s55, 0
	s_add_u32 s10, s10, 0x100
	s_addc_u32 s11, s11, 0
	s_cmp_gt_u32 s12, 13
	s_barrier
.LBB0_103:
	s_add_u32 s6, s54, 0xfffc0080
	s_addc_u32 s19, s55, -1
	s_add_i32 s23, 0, 0x10000
	v_add_u32_e32 v146, s23, v206
	ds_read_b128 v[128:131], v146
	ds_read_b128 v[132:135], v146 offset:1024
	ds_read_b128 v[136:139], v146 offset:2048
	ds_read_b128 v[146:149], v146 offset:3072
	s_cmp_eq_u32 s12, 12
	s_cselect_b32 s69, s47, s19
	s_cselect_b32 s68, s46, s6
	s_cselect_b32 s59, s49, s11
	s_cselect_b32 s58, s48, s10
	v_lshl_add_u64 v[192:193], s[54:55], 0, v[158:159]
	s_add_i32 m0, s72, 0xc000
	ds_read_b128 v[162:165], v208
	ds_read_b128 v[166:169], v208 offset:1024
	ds_read_b128 v[170:173], v208 offset:2048
	ds_read_b128 v[174:177], v208 offset:3072
	ds_read_b128 v[178:181], v208 offset:4096
	ds_read_b128 v[182:185], v208 offset:5120
	ds_read_b128 v[194:197], v208 offset:6144
	ds_read_b128 v[210:213], v208 offset:7168
	global_load_lds_dwordx4 v[192:193], off
	v_lshl_add_u64 v[192:193], s[54:55], 0, v[160:161]
	s_add_i32 m0, s72, 0xe000
	s_nop 0
	global_load_lds_dwordx4 v[192:193], off
	s_add_i32 s6, 0, 0x14000
	v_add_u32_e32 v192, s6, v206
	ds_read_b128 v[214:217], v192
	ds_read_b128 v[218:221], v192 offset:1024
	ds_read_b128 v[222:225], v192 offset:2048
	ds_read_b128 v[226:229], v192 offset:3072
	s_waitcnt vmcnt(8)
	s_waitcnt lgkmcnt(0)
	s_barrier
	v_mfma_f32_16x16x32_bf16 v[124:127], v[128:131], v[162:165], v[124:127]
	v_mfma_f32_16x16x32_bf16 v[120:123], v[136:139], v[162:165], v[120:123]
	v_mfma_f32_16x16x32_bf16 v[108:111], v[128:131], v[170:173], v[108:111]
	v_mfma_f32_16x16x32_bf16 v[104:107], v[136:139], v[170:173], v[104:107]
	v_mfma_f32_16x16x32_bf16 v[96:99], v[128:131], v[178:181], v[96:99]
	v_mfma_f32_16x16x32_bf16 v[88:91], v[136:139], v[178:181], v[88:91]
	v_mfma_f32_16x16x32_bf16 v[84:87], v[128:131], v[194:197], v[84:87]
	v_mfma_f32_16x16x32_bf16 v[80:83], v[136:139], v[194:197], v[80:83]
	v_mfma_f32_16x16x32_bf16 v[124:127], v[132:135], v[166:169], v[124:127]
	v_mfma_f32_16x16x32_bf16 v[120:123], v[146:149], v[166:169], v[120:123]
	v_mfma_f32_16x16x32_bf16 v[108:111], v[132:135], v[174:177], v[108:111]
	v_mfma_f32_16x16x32_bf16 v[104:107], v[146:149], v[174:177], v[104:107]
	v_mfma_f32_16x16x32_bf16 v[96:99], v[132:135], v[182:185], v[96:99]
	v_mfma_f32_16x16x32_bf16 v[88:91], v[146:149], v[182:185], v[88:91]
	v_mfma_f32_16x16x32_bf16 v[84:87], v[132:135], v[210:213], v[84:87]
	v_mfma_f32_16x16x32_bf16 v[80:83], v[146:149], v[210:213], v[80:83]
	v_mfma_f32_16x16x32_bf16 v[116:119], v[214:217], v[162:165], v[116:119]
	v_mfma_f32_16x16x32_bf16 v[112:115], v[222:225], v[162:165], v[112:115]
	v_mfma_f32_16x16x32_bf16 v[100:103], v[214:217], v[170:173], v[100:103]
	v_mfma_f32_16x16x32_bf16 v[92:95], v[222:225], v[170:173], v[92:95]
	v_mfma_f32_16x16x32_bf16 v[76:79], v[214:217], v[178:181], v[76:79]
	v_mfma_f32_16x16x32_bf16 v[72:75], v[222:225], v[178:181], v[72:75]
	v_mfma_f32_16x16x32_bf16 v[68:71], v[214:217], v[194:197], v[68:71]
	v_mfma_f32_16x16x32_bf16 v[64:67], v[222:225], v[194:197], v[64:67]
	v_mfma_f32_16x16x32_bf16 v[116:119], v[218:221], v[166:169], v[116:119]
	v_mfma_f32_16x16x32_bf16 v[112:115], v[226:229], v[166:169], v[112:115]
	v_mfma_f32_16x16x32_bf16 v[100:103], v[218:221], v[174:177], v[100:103]
	v_mfma_f32_16x16x32_bf16 v[92:95], v[226:229], v[174:177], v[92:95]
	v_mfma_f32_16x16x32_bf16 v[76:79], v[218:221], v[182:185], v[76:79]
	v_mfma_f32_16x16x32_bf16 v[72:75], v[226:229], v[182:185], v[72:75]
	v_mfma_f32_16x16x32_bf16 v[68:71], v[218:221], v[210:213], v[68:71]
	v_mfma_f32_16x16x32_bf16 v[64:67], v[226:229], v[210:213], v[64:67]
	s_barrier
	s_add_i32 s19, s23, s71
	v_lshl_add_u64 v[192:193], s[58:59], 0, v[140:141]
	s_mov_b32 m0, s19
	v_lshl_add_u64 v[230:231], s[58:59], 0, v[150:151]
	global_load_lds_dwordx4 v[192:193], off
	s_add_i32 m0, s19, 0x2000
	s_nop 0
	global_load_lds_dwordx4 v[230:231], off
	s_mov_b32 m0, s72
	v_lshl_add_u64 v[232:233], s[68:69], 0, v[154:155]
	ds_read_b128 v[162:165], v208 offset:16384
	ds_read_b128 v[166:169], v208 offset:17408
	ds_read_b128 v[170:173], v208 offset:18432
	ds_read_b128 v[174:177], v208 offset:19456
	ds_read_b128 v[178:181], v208 offset:20480
	ds_read_b128 v[182:185], v208 offset:21504
	ds_read_b128 v[194:197], v208 offset:22528
	ds_read_b128 v[210:213], v208 offset:23552
	global_load_lds_dwordx4 v[232:233], off
	v_lshl_add_u64 v[234:235], s[68:69], 0, v[152:153]
	s_mov_b32 m0, s73
	s_nop 0
	global_load_lds_dwordx4 v[234:235], off
	s_add_u32 s86, s58, 0x40000
	s_addc_u32 s87, s59, 0
	s_add_i32 s6, s6, s71
	v_lshl_add_u64 v[250:251], s[86:87], 0, v[140:141]
	s_mov_b32 m0, s6
	s_nop 0
	global_load_lds_dwordx4 v[250:251], off
	v_lshl_add_u64 v[250:251], s[86:87], 0, v[150:151]
	s_add_i32 m0, s6, 0x2000
	s_nop 0
	global_load_lds_dwordx4 v[250:251], off
	s_waitcnt vmcnt(8)
	s_waitcnt lgkmcnt(0)
	s_barrier
	v_mfma_f32_16x16x32_bf16 v[60:63], v[128:131], v[162:165], v[60:63]
	v_mfma_f32_16x16x32_bf16 v[56:59], v[136:139], v[162:165], v[56:59]
	v_mfma_f32_16x16x32_bf16 v[48:51], v[128:131], v[170:173], v[48:51]
	v_mfma_f32_16x16x32_bf16 v[40:43], v[136:139], v[170:173], v[40:43]
	v_mfma_f32_16x16x32_bf16 v[32:35], v[128:131], v[178:181], v[32:35]
	v_mfma_f32_16x16x32_bf16 v[24:27], v[136:139], v[178:181], v[24:27]
	v_mfma_f32_16x16x32_bf16 v[16:19], v[128:131], v[194:197], v[16:19]
	v_mfma_f32_16x16x32_bf16 v[8:11], v[136:139], v[194:197], v[8:11]
	v_mfma_f32_16x16x32_bf16 v[60:63], v[132:135], v[166:169], v[60:63]
	v_mfma_f32_16x16x32_bf16 v[56:59], v[146:149], v[166:169], v[56:59]
	v_mfma_f32_16x16x32_bf16 v[48:51], v[132:135], v[174:177], v[48:51]
	v_mfma_f32_16x16x32_bf16 v[40:43], v[146:149], v[174:177], v[40:43]
	v_mfma_f32_16x16x32_bf16 v[32:35], v[132:135], v[182:185], v[32:35]
	v_mfma_f32_16x16x32_bf16 v[24:27], v[146:149], v[182:185], v[24:27]
	v_mfma_f32_16x16x32_bf16 v[16:19], v[132:135], v[210:213], v[16:19]
	v_mfma_f32_16x16x32_bf16 v[8:11], v[146:149], v[210:213], v[8:11]
	v_mfma_f32_16x16x32_bf16 v[52:55], v[214:217], v[162:165], v[52:55]
	v_mfma_f32_16x16x32_bf16 v[44:47], v[222:225], v[162:165], v[44:47]
	v_mfma_f32_16x16x32_bf16 v[36:39], v[214:217], v[170:173], v[36:39]
	v_mfma_f32_16x16x32_bf16 v[28:31], v[222:225], v[170:173], v[28:31]
	v_mfma_f32_16x16x32_bf16 v[20:23], v[214:217], v[178:181], v[20:23]
	v_mfma_f32_16x16x32_bf16 v[12:15], v[222:225], v[178:181], v[12:15]
	v_mfma_f32_16x16x32_bf16 v[4:7], v[214:217], v[194:197], v[4:7]
	v_mfma_f32_16x16x32_bf16 v[0:3], v[222:225], v[194:197], v[0:3]
	v_mfma_f32_16x16x32_bf16 v[52:55], v[218:221], v[166:169], v[52:55]
	v_mfma_f32_16x16x32_bf16 v[44:47], v[226:229], v[166:169], v[44:47]
	v_mfma_f32_16x16x32_bf16 v[36:39], v[218:221], v[174:177], v[36:39]
	v_mfma_f32_16x16x32_bf16 v[28:31], v[226:229], v[174:177], v[28:31]
	v_mfma_f32_16x16x32_bf16 v[20:23], v[218:221], v[182:185], v[20:23]
	v_mfma_f32_16x16x32_bf16 v[12:15], v[226:229], v[182:185], v[12:15]
	v_mfma_f32_16x16x32_bf16 v[4:7], v[218:221], v[210:213], v[4:7]
	v_mfma_f32_16x16x32_bf16 v[0:3], v[226:229], v[210:213], v[0:3]
	s_barrier
	s_add_i32 s6, 0, 0x18000
	v_add_u32_e32 v146, s6, v206
	ds_read_b128 v[128:131], v146
	ds_read_b128 v[132:135], v146 offset:1024
	ds_read_b128 v[136:139], v146 offset:2048
	ds_read_b128 v[146:149], v146 offset:3072
	s_add_u32 s68, s68, 0x40000
	s_addc_u32 s69, s69, 0
	s_mov_b32 m0, s74
	v_lshl_add_u64 v[214:215], s[68:69], 0, v[154:155]
	ds_read_b128 v[162:165], v208 offset:32768
	ds_read_b128 v[166:169], v208 offset:33792
	ds_read_b128 v[170:173], v208 offset:34816
	ds_read_b128 v[174:177], v208 offset:35840
	ds_read_b128 v[178:181], v208 offset:36864
	ds_read_b128 v[182:185], v208 offset:37888
	ds_read_b128 v[194:197], v208 offset:38912
	ds_read_b128 v[210:213], v208 offset:39936
	global_load_lds_dwordx4 v[214:215], off
	v_lshl_add_u64 v[214:215], s[68:69], 0, v[152:153]
	s_mov_b32 m0, s75
	s_nop 0
	global_load_lds_dwordx4 v[214:215], off
	s_add_i32 s19, 0, 0x1c000
	v_add_u32_e32 v209, s19, v206
	ds_read_b128 v[214:217], v209
	ds_read_b128 v[218:221], v209 offset:1024
	ds_read_b128 v[222:225], v209 offset:2048
	ds_read_b128 v[226:229], v209 offset:3072
	s_waitcnt vmcnt(8)
	s_waitcnt lgkmcnt(0)
	s_barrier
	v_mfma_f32_16x16x32_bf16 v[124:127], v[128:131], v[162:165], v[124:127]
	v_mfma_f32_16x16x32_bf16 v[120:123], v[136:139], v[162:165], v[120:123]
	v_mfma_f32_16x16x32_bf16 v[108:111], v[128:131], v[170:173], v[108:111]
	v_mfma_f32_16x16x32_bf16 v[104:107], v[136:139], v[170:173], v[104:107]
	v_mfma_f32_16x16x32_bf16 v[96:99], v[128:131], v[178:181], v[96:99]
	v_mfma_f32_16x16x32_bf16 v[88:91], v[136:139], v[178:181], v[88:91]
	v_mfma_f32_16x16x32_bf16 v[84:87], v[128:131], v[194:197], v[84:87]
	v_mfma_f32_16x16x32_bf16 v[80:83], v[136:139], v[194:197], v[80:83]
	v_mfma_f32_16x16x32_bf16 v[124:127], v[132:135], v[166:169], v[124:127]
	v_mfma_f32_16x16x32_bf16 v[120:123], v[146:149], v[166:169], v[120:123]
	v_mfma_f32_16x16x32_bf16 v[108:111], v[132:135], v[174:177], v[108:111]
	v_mfma_f32_16x16x32_bf16 v[104:107], v[146:149], v[174:177], v[104:107]
	v_mfma_f32_16x16x32_bf16 v[96:99], v[132:135], v[182:185], v[96:99]
	v_mfma_f32_16x16x32_bf16 v[88:91], v[146:149], v[182:185], v[88:91]
	v_mfma_f32_16x16x32_bf16 v[84:87], v[132:135], v[210:213], v[84:87]
	v_mfma_f32_16x16x32_bf16 v[80:83], v[146:149], v[210:213], v[80:83]
	v_mfma_f32_16x16x32_bf16 v[116:119], v[214:217], v[162:165], v[116:119]
	v_mfma_f32_16x16x32_bf16 v[112:115], v[222:225], v[162:165], v[112:115]
	v_mfma_f32_16x16x32_bf16 v[100:103], v[214:217], v[170:173], v[100:103]
	v_mfma_f32_16x16x32_bf16 v[92:95], v[222:225], v[170:173], v[92:95]
	v_mfma_f32_16x16x32_bf16 v[76:79], v[214:217], v[178:181], v[76:79]
	v_mfma_f32_16x16x32_bf16 v[72:75], v[222:225], v[178:181], v[72:75]
	v_mfma_f32_16x16x32_bf16 v[68:71], v[214:217], v[194:197], v[68:71]
	v_mfma_f32_16x16x32_bf16 v[64:67], v[222:225], v[194:197], v[64:67]
	v_mfma_f32_16x16x32_bf16 v[116:119], v[218:221], v[166:169], v[116:119]
	v_mfma_f32_16x16x32_bf16 v[112:115], v[226:229], v[166:169], v[112:115]
	v_mfma_f32_16x16x32_bf16 v[100:103], v[218:221], v[174:177], v[100:103]
	v_mfma_f32_16x16x32_bf16 v[92:95], v[226:229], v[174:177], v[92:95]
	v_mfma_f32_16x16x32_bf16 v[76:79], v[218:221], v[182:185], v[76:79]
	v_mfma_f32_16x16x32_bf16 v[72:75], v[226:229], v[182:185], v[72:75]
	v_mfma_f32_16x16x32_bf16 v[68:71], v[218:221], v[210:213], v[68:71]
	v_mfma_f32_16x16x32_bf16 v[64:67], v[226:229], v[210:213], v[64:67]
	s_barrier
	s_add_i32 s6, s6, s71
	v_lshl_add_u64 v[192:193], v[192:193], 0, s[36:37]
	s_mov_b32 m0, s6
	s_nop 0
	global_load_lds_dwordx4 v[192:193], off
	v_lshl_add_u64 v[192:193], v[230:231], 0, s[36:37]
	s_add_i32 m0, s6, 0x2000
	s_nop 0
	global_load_lds_dwordx4 v[192:193], off
	s_mov_b32 m0, s80
	v_lshl_add_u64 v[192:193], v[232:233], 0, s[36:37]
	ds_read_b128 v[162:165], v208 offset:49152
	ds_read_b128 v[166:169], v208 offset:50176
	ds_read_b128 v[170:173], v208 offset:51200
	ds_read_b128 v[174:177], v208 offset:52224
	ds_read_b128 v[178:181], v208 offset:53248
	ds_read_b128 v[182:185], v208 offset:54272
	ds_read_b128 v[194:197], v208 offset:55296
	ds_read_b128 v[210:213], v208 offset:56320
	global_load_lds_dwordx4 v[192:193], off
	v_lshl_add_u64 v[192:193], v[234:235], 0, s[36:37]
	s_mov_b32 m0, s81
	s_nop 0
	global_load_lds_dwordx4 v[192:193], off
	s_add_u32 s58, s58, 0x40080
	s_addc_u32 s59, s59, 0
	s_add_i32 s6, s19, s71
	v_lshl_add_u64 v[250:251], s[58:59], 0, v[140:141]
	s_mov_b32 m0, s6
	s_nop 0
	global_load_lds_dwordx4 v[250:251], off
	v_lshl_add_u64 v[250:251], s[58:59], 0, v[150:151]
	s_add_i32 m0, s6, 0x2000
	s_nop 0
	global_load_lds_dwordx4 v[250:251], off
	s_waitcnt vmcnt(8)
	s_waitcnt lgkmcnt(0)
	s_barrier
	v_mfma_f32_16x16x32_bf16 v[60:63], v[128:131], v[162:165], v[60:63]
	v_mfma_f32_16x16x32_bf16 v[56:59], v[136:139], v[162:165], v[56:59]
	v_mfma_f32_16x16x32_bf16 v[48:51], v[128:131], v[170:173], v[48:51]
	v_mfma_f32_16x16x32_bf16 v[40:43], v[136:139], v[170:173], v[40:43]
	v_mfma_f32_16x16x32_bf16 v[32:35], v[128:131], v[178:181], v[32:35]
	v_mfma_f32_16x16x32_bf16 v[24:27], v[136:139], v[178:181], v[24:27]
	v_mfma_f32_16x16x32_bf16 v[16:19], v[128:131], v[194:197], v[16:19]
	v_mfma_f32_16x16x32_bf16 v[8:11], v[136:139], v[194:197], v[8:11]
	v_mfma_f32_16x16x32_bf16 v[60:63], v[132:135], v[166:169], v[60:63]
	v_mfma_f32_16x16x32_bf16 v[56:59], v[146:149], v[166:169], v[56:59]
	v_mfma_f32_16x16x32_bf16 v[48:51], v[132:135], v[174:177], v[48:51]
	v_mfma_f32_16x16x32_bf16 v[40:43], v[146:149], v[174:177], v[40:43]
	v_mfma_f32_16x16x32_bf16 v[32:35], v[132:135], v[182:185], v[32:35]
	v_mfma_f32_16x16x32_bf16 v[24:27], v[146:149], v[182:185], v[24:27]
	v_mfma_f32_16x16x32_bf16 v[16:19], v[132:135], v[210:213], v[16:19]
	v_mfma_f32_16x16x32_bf16 v[8:11], v[146:149], v[210:213], v[8:11]
	v_mfma_f32_16x16x32_bf16 v[52:55], v[214:217], v[162:165], v[52:55]
	v_mfma_f32_16x16x32_bf16 v[44:47], v[222:225], v[162:165], v[44:47]
	v_mfma_f32_16x16x32_bf16 v[36:39], v[214:217], v[170:173], v[36:39]
	v_mfma_f32_16x16x32_bf16 v[28:31], v[222:225], v[170:173], v[28:31]
	v_mfma_f32_16x16x32_bf16 v[20:23], v[214:217], v[178:181], v[20:23]
	v_mfma_f32_16x16x32_bf16 v[12:15], v[222:225], v[178:181], v[12:15]
	v_mfma_f32_16x16x32_bf16 v[4:7], v[214:217], v[194:197], v[4:7]
	v_mfma_f32_16x16x32_bf16 v[0:3], v[222:225], v[194:197], v[0:3]
	v_mfma_f32_16x16x32_bf16 v[52:55], v[218:221], v[166:169], v[52:55]
	v_mfma_f32_16x16x32_bf16 v[44:47], v[226:229], v[166:169], v[44:47]
	v_mfma_f32_16x16x32_bf16 v[36:39], v[218:221], v[174:177], v[36:39]
	v_mfma_f32_16x16x32_bf16 v[28:31], v[226:229], v[174:177], v[28:31]
	v_mfma_f32_16x16x32_bf16 v[20:23], v[218:221], v[182:185], v[20:23]
	v_mfma_f32_16x16x32_bf16 v[12:15], v[226:229], v[182:185], v[12:15]
	v_mfma_f32_16x16x32_bf16 v[4:7], v[218:221], v[210:213], v[4:7]
	v_mfma_f32_16x16x32_bf16 v[0:3], v[226:229], v[210:213], v[0:3]
	s_add_i32 s12, s12, 2
	s_add_u32 s54, s54, 0x100
	s_addc_u32 s55, s55, 0
	s_add_u32 s10, s10, 0x100
	s_addc_u32 s11, s11, 0
	s_cmp_gt_u32 s12, 13
	s_barrier
	s_cbranch_scc0 .LBB0_103
	s_mov_b32 s100, 1
	s_ashr_i32 s51, s50, 31
	s_ashr_i32 s53, s52, 31
	s_lshl_b64 s[10:11], s[50:51], 13
	s_lshl_b64 s[50:51], s[52:53], 8
	s_add_u32 s10, s50, s10
	v_lshl_or_b32 v128, s85, 8, v207
	s_addc_u32 s11, s51, s11
	v_ashrrev_i32_e32 v129, 31, v128
	v_lshl_add_u64 v[168:169], s[10:11], 0, v[156:157]
	v_lshlrev_b64 v[170:171], 1, v[128:129]
	v_lshl_add_u64 v[174:175], s[26:27], 0, v[170:171]
	v_lshlrev_b64 v[172:173], 11, v[168:169]
	v_or_b32_e32 v166, 16, v168
	v_mov_b32_e32 v167, v169
	v_lshl_add_u64 v[128:129], v[174:175], 0, v[172:173]
	v_lshlrev_b64 v[176:177], 11, v[166:167]
	global_load_dwordx4 v[146:149], v[128:129], off
	global_load_dwordx4 v[182:185], v[128:129], off offset:256
	v_lshl_add_u64 v[128:129], v[174:175], 0, v[176:177]
	global_load_dwordx4 v[194:197], v[128:129], off
	global_load_dwordx4 v[210:213], v[128:129], off offset:256
	v_or_b32_e32 v164, 32, v168
	v_mov_b32_e32 v165, v169
	v_or_b32_e32 v162, 48, v168
	v_mov_b32_e32 v163, v169
	v_lshlrev_b64 v[180:181], 11, v[164:165]
	v_lshlrev_b64 v[178:179], 11, v[162:163]
	v_lshl_add_u64 v[128:129], v[174:175], 0, v[180:181]
	v_lshl_add_u64 v[130:131], v[174:175], 0, v[178:179]
	global_load_dwordx4 v[214:217], v[128:129], off
	global_load_dwordx4 v[136:139], v[128:129], off offset:256
	global_load_dwordx4 v[132:135], v[130:131], off
	s_nop 0
	global_load_dwordx4 v[128:131], v[130:131], off offset:256
	s_mov_b64 s[10:11], 0x90
	v_lshl_add_u64 v[172:173], s[28:29], 0, v[172:173]
	v_lshl_add_u64 v[172:173], v[172:173], 0, v[170:171]
	s_waitcnt vmcnt(0)
	v_lshlrev_b32_e32 v192, 16, v146
	v_and_b32_e32 v193, 0xffff0000, v146
	v_lshlrev_b32_e32 v218, 16, v148
	v_and_b32_e32 v219, 0xffff0000, v148
	v_lshlrev_b32_e32 v146, 16, v147
	v_and_b32_e32 v147, 0xffff0000, v147
	v_lshlrev_b32_e32 v148, 16, v149
	v_and_b32_e32 v149, 0xffff0000, v149
	v_lshlrev_b32_e32 v220, 16, v182
	v_and_b32_e32 v221, 0xffff0000, v182
	v_lshlrev_b32_e32 v222, 16, v184
	v_and_b32_e32 v223, 0xffff0000, v184
	v_lshlrev_b32_e32 v182, 16, v183
	v_and_b32_e32 v183, 0xffff0000, v183
	v_lshlrev_b32_e32 v184, 16, v185
	v_and_b32_e32 v185, 0xffff0000, v185
	v_pk_add_f32 v[124:125], v[124:125], v[192:193]
	v_pk_add_f32 v[126:127], v[126:127], v[146:147]
	v_pk_add_f32 v[122:123], v[122:123], v[148:149]
	v_pk_add_f32 v[116:117], v[116:117], v[220:221]
	v_pk_add_f32 v[146:147], v[112:113], v[222:223]
	v_pk_add_f32 v[118:119], v[118:119], v[182:183]
	v_pk_add_f32 v[148:149], v[114:115], v[184:185]
	v_lshlrev_b32_e32 v182, 16, v194
	v_and_b32_e32 v183, 0xffff0000, v194
	v_lshlrev_b32_e32 v184, 16, v196
	v_and_b32_e32 v185, 0xffff0000, v196
	v_lshlrev_b32_e32 v192, 16, v195
	v_and_b32_e32 v193, 0xffff0000, v195
	v_lshlrev_b32_e32 v194, 16, v197
	v_and_b32_e32 v195, 0xffff0000, v197
	v_pk_mul_f32 v[196:197], v[124:125], v[124:125]
	v_pk_add_f32 v[120:121], v[120:121], v[218:219]
	v_pk_mul_f32 v[218:219], v[126:127], v[126:127]
	v_cvt_pk_bf16_f32 v112, v124, v125
	v_cvt_pk_bf16_f32 v113, v126, v127
	v_pk_mul_f32 v[124:125], v[116:117], v[116:117]
	v_pk_mul_f32 v[126:127], v[118:119], v[118:119]
	v_pk_mul_f32 v[224:225], v[146:147], v[146:147]
	v_cvt_pk_bf16_f32 v116, v116, v117
	v_cvt_pk_bf16_f32 v117, v118, v119
	v_cvt_pk_bf16_f32 v118, v146, v147
	v_add_f32_e32 v146, v196, v197
	v_add_f32_e32 v146, v218, v146
	v_pk_mul_f32 v[220:221], v[120:121], v[120:121]
	v_add_f32_e32 v146, v219, v146
	v_add_f32_e32 v146, v220, v146
	v_pk_mul_f32 v[222:223], v[122:123], v[122:123]
	v_add_f32_e32 v146, v221, v146
	v_add_f32_e32 v146, v222, v146
	v_add_f32_e32 v146, v223, v146
	v_add_f32_e32 v124, v124, v146
	v_add_f32_e32 v124, v125, v124
	v_add_f32_e32 v124, v126, v124
	v_add_f32_e32 v124, v127, v124
	v_add_f32_e32 v124, v224, v124
	v_pk_mul_f32 v[226:227], v[148:149], v[148:149]
	v_add_f32_e32 v124, v225, v124
	v_add_f32_e32 v124, v226, v124
	v_add_f32_e32 v209, v227, v124
	v_lshlrev_b32_e32 v124, 16, v210
	v_and_b32_e32 v125, 0xffff0000, v210
	v_pk_add_f32 v[100:101], v[100:101], v[124:125]
	v_lshlrev_b32_e32 v124, 16, v212
	v_and_b32_e32 v125, 0xffff0000, v212
	v_pk_add_f32 v[124:125], v[92:93], v[124:125]
	v_lshlrev_b32_e32 v92, 16, v211
	v_and_b32_e32 v93, 0xffff0000, v211
	v_pk_add_f32 v[102:103], v[102:103], v[92:93]
	v_lshlrev_b32_e32 v92, 16, v213
	v_and_b32_e32 v93, 0xffff0000, v213
	v_pk_add_f32 v[126:127], v[94:95], v[92:93]
	v_lshlrev_b32_e32 v92, 16, v214
	v_and_b32_e32 v93, 0xffff0000, v214
	v_pk_add_f32 v[92:93], v[96:97], v[92:93]
	v_lshlrev_b32_e32 v96, 16, v217
	v_and_b32_e32 v97, 0xffff0000, v217
	v_lshlrev_b32_e32 v94, 16, v216
	v_and_b32_e32 v95, 0xffff0000, v216
	v_pk_add_f32 v[90:91], v[90:91], v[96:97]
	v_lshlrev_b32_e32 v96, 16, v136
	v_and_b32_e32 v97, 0xffff0000, v136
	v_pk_add_f32 v[88:89], v[88:89], v[94:95]
	v_lshlrev_b32_e32 v94, 16, v215
	v_and_b32_e32 v95, 0xffff0000, v215
	v_pk_add_f32 v[96:97], v[76:77], v[96:97]
	v_lshl_add_u64 v[76:77], v[168:169], 0, s[36:37]
	v_cvt_pk_bf16_f32 v114, v120, v121
	v_pk_add_f32 v[120:121], v[108:109], v[182:183]
	v_pk_add_f32 v[94:95], v[98:99], v[94:95]
	v_lshlrev_b64 v[182:183], 11, v[76:77]
	v_lshlrev_b32_e32 v98, 16, v138
	v_and_b32_e32 v99, 0xffff0000, v138
	v_pk_add_f32 v[108:109], v[104:105], v[184:185]
	v_lshl_add_u64 v[184:185], v[174:175], 0, v[182:183]
	v_pk_add_f32 v[98:99], v[72:73], v[98:99]
	v_lshlrev_b32_e32 v72, 16, v137
	v_and_b32_e32 v73, 0xffff0000, v137
	global_load_dwordx4 v[210:213], v[184:185], off
	global_load_dwordx4 v[218:221], v[184:185], off offset:256
	v_pk_add_f32 v[136:137], v[78:79], v[72:73]
	v_lshlrev_b32_e32 v72, 16, v139
	v_and_b32_e32 v73, 0xffff0000, v139
	v_pk_add_f32 v[138:139], v[74:75], v[72:73]
	v_lshlrev_b32_e32 v72, 16, v132
	v_and_b32_e32 v73, 0xffff0000, v132
	v_pk_add_f32 v[74:75], v[84:85], v[72:73]
	v_lshlrev_b32_e32 v72, 16, v134
	v_and_b32_e32 v73, 0xffff0000, v134
	v_pk_add_f32 v[78:79], v[80:81], v[72:73]
	v_lshlrev_b32_e32 v72, 16, v133
	v_and_b32_e32 v73, 0xffff0000, v133
	v_pk_add_f32 v[80:81], v[86:87], v[72:73]
	v_lshlrev_b32_e32 v72, 16, v135
	v_and_b32_e32 v73, 0xffff0000, v135
	v_pk_add_f32 v[82:83], v[82:83], v[72:73]
	v_lshl_add_u64 v[72:73], v[168:169], 0, s[10:11]
	v_lshlrev_b64 v[132:133], 11, v[72:73]
	v_lshl_add_u64 v[134:135], v[174:175], 0, v[132:133]
	v_lshlrev_b32_e32 v84, 16, v128
	v_and_b32_e32 v85, 0xffff0000, v128
	global_load_dwordx4 v[226:229], v[134:135], off
	global_load_dwordx4 v[234:237], v[134:135], off offset:256
	v_pk_add_f32 v[84:85], v[68:69], v[84:85]
	v_lshlrev_b32_e32 v68, 16, v130
	v_and_b32_e32 v69, 0xffff0000, v130
	v_pk_add_f32 v[86:87], v[64:65], v[68:69]
	v_lshlrev_b32_e32 v64, 16, v129
	v_and_b32_e32 v65, 0xffff0000, v129
	s_mov_b64 s[10:11], 0xa0
	v_pk_add_f32 v[128:129], v[70:71], v[64:65]
	v_lshl_add_u64 v[70:71], v[168:169], 0, s[10:11]
	s_mov_b64 s[10:11], 0xb0
	v_lshlrev_b32_e32 v64, 16, v131
	v_and_b32_e32 v65, 0xffff0000, v131
	v_lshlrev_b64 v[134:135], 11, v[70:71]
	v_lshl_add_u64 v[68:69], v[168:169], 0, s[10:11]
	v_pk_add_f32 v[130:131], v[66:67], v[64:65]
	v_lshl_add_u64 v[64:65], v[174:175], 0, v[134:135]
	v_lshlrev_b64 v[184:185], 11, v[68:69]
	global_load_dwordx4 v[238:241], v[64:65], off
	global_load_dwordx4 v[242:245], v[64:65], off offset:256
	v_lshl_add_u64 v[64:65], v[174:175], 0, v[184:185]
	global_load_dwordx4 v[246:249], v[64:65], off
	s_nop 0
	global_load_dwordx4 v[64:67], v[64:65], off offset:256
	v_cvt_pk_bf16_f32 v115, v122, v123
	v_cvt_pk_bf16_f32 v119, v148, v149
	v_pk_add_f32 v[110:111], v[110:111], v[192:193]
	v_pk_add_f32 v[122:123], v[106:107], v[194:195]
	global_store_dwordx4 v[172:173], v[112:115], off
	global_store_dwordx4 v[172:173], v[116:119], off offset:256
	v_cvt_pk_bf16_f32 v104, v120, v121
	v_lshl_add_u64 v[112:113], s[28:29], 0, v[176:177]
	v_cvt_pk_bf16_f32 v105, v110, v111
	v_cvt_pk_bf16_f32 v106, v108, v109
	v_cvt_pk_bf16_f32 v107, v122, v123
	v_lshl_add_u64 v[112:113], v[112:113], 0, v[170:171]
	v_cvt_pk_bf16_f32 v146, v100, v101
	v_cvt_pk_bf16_f32 v147, v102, v103
	v_cvt_pk_bf16_f32 v148, v124, v125
	v_cvt_pk_bf16_f32 v149, v126, v127
	global_store_dwordx4 v[112:113], v[104:107], off
	global_store_dwordx4 v[112:113], v[146:149], off offset:256
	v_cvt_pk_bf16_f32 v194, v92, v93
	v_lshl_add_u64 v[104:105], s[28:29], 0, v[180:181]
	v_cvt_pk_bf16_f32 v195, v94, v95
	v_cvt_pk_bf16_f32 v196, v88, v89
	v_cvt_pk_bf16_f32 v197, v90, v91
	v_lshl_add_u64 v[104:105], v[104:105], 0, v[170:171]
	v_cvt_pk_bf16_f32 v214, v96, v97
	v_cvt_pk_bf16_f32 v215, v136, v137
	v_cvt_pk_bf16_f32 v216, v98, v99
	v_cvt_pk_bf16_f32 v217, v138, v139
	global_store_dwordx4 v[104:105], v[194:197], off
	global_store_dwordx4 v[104:105], v[214:217], off offset:256
	v_lshl_add_u64 v[104:105], s[28:29], 0, v[178:179]
	v_cvt_pk_bf16_f32 v222, v74, v75
	v_cvt_pk_bf16_f32 v223, v80, v81
	v_cvt_pk_bf16_f32 v224, v78, v79
	v_cvt_pk_bf16_f32 v225, v82, v83
	v_lshl_add_u64 v[104:105], v[104:105], 0, v[170:171]
	v_cvt_pk_bf16_f32 v230, v84, v85
	v_cvt_pk_bf16_f32 v231, v128, v129
	v_cvt_pk_bf16_f32 v232, v86, v87
	v_cvt_pk_bf16_f32 v233, v130, v131
	global_store_dwordx4 v[104:105], v[222:225], off
	global_store_dwordx4 v[104:105], v[230:233], off offset:256
	s_waitcnt vmcnt(0)
	v_lshlrev_b32_e32 v104, 16, v210
	v_and_b32_e32 v105, 0xffff0000, v210
	v_pk_add_f32 v[60:61], v[60:61], v[104:105]
	v_lshlrev_b32_e32 v104, 16, v212
	v_and_b32_e32 v105, 0xffff0000, v212
	v_pk_add_f32 v[56:57], v[56:57], v[104:105]
	v_lshlrev_b32_e32 v104, 16, v211
	v_and_b32_e32 v105, 0xffff0000, v211
	v_pk_add_f32 v[62:63], v[62:63], v[104:105]
	v_lshlrev_b32_e32 v104, 16, v213
	v_and_b32_e32 v105, 0xffff0000, v213
	v_pk_add_f32 v[58:59], v[58:59], v[104:105]
	v_lshlrev_b32_e32 v104, 16, v218
	v_and_b32_e32 v105, 0xffff0000, v218
	v_pk_add_f32 v[52:53], v[52:53], v[104:105]
	v_lshlrev_b32_e32 v104, 16, v220
	v_and_b32_e32 v105, 0xffff0000, v220
	v_pk_add_f32 v[104:105], v[44:45], v[104:105]
	v_lshlrev_b32_e32 v44, 16, v219
	v_and_b32_e32 v45, 0xffff0000, v219
	v_pk_add_f32 v[54:55], v[54:55], v[44:45]
	v_lshlrev_b32_e32 v44, 16, v221
	v_and_b32_e32 v45, 0xffff0000, v221
	v_pk_add_f32 v[106:107], v[46:47], v[44:45]
	v_lshlrev_b32_e32 v44, 16, v226
	v_and_b32_e32 v45, 0xffff0000, v226
	v_pk_add_f32 v[44:45], v[48:49], v[44:45]
	v_lshlrev_b32_e32 v48, 16, v229
	v_and_b32_e32 v49, 0xffff0000, v229
	v_pk_add_f32 v[42:43], v[42:43], v[48:49]
	v_lshlrev_b32_e32 v48, 16, v234
	v_and_b32_e32 v49, 0xffff0000, v234
	v_pk_add_f32 v[36:37], v[36:37], v[48:49]
	v_lshlrev_b32_e32 v48, 16, v236
	v_and_b32_e32 v49, 0xffff0000, v236
	v_lshlrev_b32_e32 v46, 16, v228
	v_and_b32_e32 v47, 0xffff0000, v228
	v_pk_add_f32 v[48:49], v[28:29], v[48:49]
	v_lshlrev_b32_e32 v28, 16, v235
	v_and_b32_e32 v29, 0xffff0000, v235
	v_pk_add_f32 v[40:41], v[40:41], v[46:47]
	v_lshlrev_b32_e32 v46, 16, v227
	v_and_b32_e32 v47, 0xffff0000, v227
	v_pk_add_f32 v[38:39], v[38:39], v[28:29]
	v_lshlrev_b32_e32 v28, 16, v237
	v_and_b32_e32 v29, 0xffff0000, v237
	v_pk_add_f32 v[46:47], v[50:51], v[46:47]
	v_pk_add_f32 v[50:51], v[30:31], v[28:29]
	v_lshlrev_b32_e32 v28, 16, v238
	v_and_b32_e32 v29, 0xffff0000, v238
	v_lshlrev_b32_e32 v180, 16, v64
	v_and_b32_e32 v181, 0xffff0000, v64
	v_pk_add_f32 v[28:29], v[32:33], v[28:29]
	v_lshlrev_b32_e32 v32, 16, v241
	v_and_b32_e32 v33, 0xffff0000, v241
	v_pk_add_f32 v[4:5], v[4:5], v[180:181]
	v_lshlrev_b32_e32 v180, 16, v66
	v_and_b32_e32 v181, 0xffff0000, v66
	v_pk_add_f32 v[26:27], v[26:27], v[32:33]
	v_lshlrev_b32_e32 v32, 16, v242
	v_and_b32_e32 v33, 0xffff0000, v242
	v_pk_add_f32 v[0:1], v[0:1], v[180:181]
	v_lshl_add_u64 v[180:181], s[28:29], 0, v[182:183]
	v_cvt_pk_bf16_f32 v112, v60, v61
	v_cvt_pk_bf16_f32 v113, v62, v63
	v_cvt_pk_bf16_f32 v114, v56, v57
	v_cvt_pk_bf16_f32 v115, v58, v59
	v_pk_add_f32 v[20:21], v[20:21], v[32:33]
	v_lshlrev_b32_e32 v32, 16, v244
	v_and_b32_e32 v33, 0xffff0000, v244
	v_lshl_add_u64 v[180:181], v[180:181], 0, v[170:171]
	v_cvt_pk_bf16_f32 v116, v52, v53
	v_cvt_pk_bf16_f32 v117, v54, v55
	v_cvt_pk_bf16_f32 v118, v104, v105
	v_cvt_pk_bf16_f32 v119, v106, v107
	v_lshlrev_b32_e32 v30, 16, v240
	v_and_b32_e32 v31, 0xffff0000, v240
	v_pk_add_f32 v[32:33], v[12:13], v[32:33]
	v_lshlrev_b32_e32 v12, 16, v243
	v_and_b32_e32 v13, 0xffff0000, v243
	global_store_dwordx4 v[180:181], v[112:115], off
	global_store_dwordx4 v[180:181], v[116:119], off offset:256
	v_cvt_pk_bf16_f32 v146, v44, v45
	v_lshl_add_u64 v[112:113], s[28:29], 0, v[132:133]
	v_cvt_pk_bf16_f32 v147, v46, v47
	v_cvt_pk_bf16_f32 v148, v40, v41
	v_cvt_pk_bf16_f32 v149, v42, v43
	v_pk_add_f32 v[24:25], v[24:25], v[30:31]
	v_lshlrev_b32_e32 v30, 16, v239
	v_and_b32_e32 v31, 0xffff0000, v239
	v_pk_add_f32 v[22:23], v[22:23], v[12:13]
	v_lshlrev_b32_e32 v12, 16, v245
	v_and_b32_e32 v13, 0xffff0000, v245
	v_lshl_add_u64 v[112:113], v[112:113], 0, v[170:171]
	v_cvt_pk_bf16_f32 v172, v36, v37
	v_cvt_pk_bf16_f32 v173, v38, v39
	v_cvt_pk_bf16_f32 v174, v48, v49
	v_cvt_pk_bf16_f32 v175, v50, v51
	v_pk_add_f32 v[30:31], v[34:35], v[30:31]
	v_pk_add_f32 v[34:35], v[14:15], v[12:13]
	v_lshlrev_b32_e32 v12, 16, v246
	v_and_b32_e32 v13, 0xffff0000, v246
	v_lshlrev_b32_e32 v14, 16, v248
	v_and_b32_e32 v15, 0xffff0000, v248
	global_store_dwordx4 v[112:113], v[146:149], off
	global_store_dwordx4 v[112:113], v[172:175], off offset:256
	v_lshl_add_u64 v[112:113], s[28:29], 0, v[134:135]
	v_cvt_pk_bf16_f32 v176, v28, v29
	v_cvt_pk_bf16_f32 v177, v30, v31
	v_cvt_pk_bf16_f32 v178, v24, v25
	v_cvt_pk_bf16_f32 v179, v26, v27
	v_pk_add_f32 v[12:13], v[16:17], v[12:13]
	v_pk_add_f32 v[8:9], v[8:9], v[14:15]
	v_lshlrev_b32_e32 v14, 16, v247
	v_and_b32_e32 v15, 0xffff0000, v247
	v_lshlrev_b32_e32 v16, 16, v249
	v_and_b32_e32 v17, 0xffff0000, v249
	v_lshlrev_b32_e32 v64, 16, v65
	v_and_b32_e32 v65, 0xffff0000, v65
	v_lshl_add_u64 v[112:113], v[112:113], 0, v[170:171]
	v_cvt_pk_bf16_f32 v194, v20, v21
	v_cvt_pk_bf16_f32 v195, v22, v23
	v_cvt_pk_bf16_f32 v196, v32, v33
	v_cvt_pk_bf16_f32 v197, v34, v35
	v_pk_add_f32 v[14:15], v[18:19], v[14:15]
	v_pk_add_f32 v[10:11], v[10:11], v[16:17]
	v_pk_add_f32 v[6:7], v[6:7], v[64:65]
	v_lshlrev_b32_e32 v64, 16, v67
	v_and_b32_e32 v65, 0xffff0000, v67
	global_store_dwordx4 v[112:113], v[176:179], off
	global_store_dwordx4 v[112:113], v[194:197], off offset:256
	v_lshl_add_u64 v[112:113], s[28:29], 0, v[184:185]
	v_cvt_pk_bf16_f32 v16, v12, v13
	v_cvt_pk_bf16_f32 v17, v14, v15
	v_cvt_pk_bf16_f32 v18, v8, v9
	v_cvt_pk_bf16_f32 v19, v10, v11
	v_pk_add_f32 v[2:3], v[2:3], v[64:65]
	v_lshl_add_u64 v[112:113], v[112:113], 0, v[170:171]
	v_cvt_pk_bf16_f32 v64, v4, v5
	v_cvt_pk_bf16_f32 v65, v6, v7
	v_cvt_pk_bf16_f32 v66, v0, v1
	v_cvt_pk_bf16_f32 v67, v2, v3
	global_store_dwordx4 v[112:113], v[16:19], off
	global_store_dwordx4 v[112:113], v[64:67], off offset:256
	s_lshl_b32 s10, s85, 2
	v_and_b32_e32 v17, 64, v188
	v_xor_b32_e32 v16, 16, v188
	v_add_u32_e32 v17, 64, v17
	v_cmp_lt_i32_e32 vcc, v16, v17
	v_xor_b32_e32 v18, 32, v188
	s_ashr_i32 s11, s10, 31
	v_cndmask_b32_e32 v16, v188, v16, vcc
	v_lshlrev_b32_e32 v16, 2, v16
	ds_bpermute_b32 v19, v16, v209
	v_cmp_lt_i32_e32 vcc, v18, v17
	s_lshl_b64 s[10:11], s[10:11], 2
	s_add_u32 s50, s83, s10
	v_cndmask_b32_e32 v17, v188, v18, vcc
	v_lshlrev_b32_e32 v17, 2, v17
	s_waitcnt lgkmcnt(0)
	v_add_f32_e32 v18, v209, v19
	ds_bpermute_b32 v19, v17, v18
	s_addc_u32 s51, s84, s11
	s_and_saveexec_b64 s[52:53], s[42:43]
	s_cbranch_execz .LBB0_106
	s_waitcnt lgkmcnt(0)
	v_add_f32_e32 v64, v18, v19
	v_lshlrev_b64 v[18:19], 6, v[168:169]
	v_lshl_add_u64 v[18:19], s[50:51], 0, v[18:19]
	global_store_dword v[18:19], v64, off

.Lm4ap_248:
	s_waitcnt lgkmcnt(0)
	s_barrier
	v_mfma_f32_16x16x32_bf16 v[124:127], v[128:131], v[162:165], 0
	v_mfma_f32_16x16x32_bf16 v[120:123], v[136:139], v[162:165], 0
	v_mfma_f32_16x16x32_bf16 v[108:111], v[128:131], v[170:173], 0
	v_mfma_f32_16x16x32_bf16 v[104:107], v[136:139], v[170:173], 0
	v_mfma_f32_16x16x32_bf16 v[96:99], v[128:131], v[178:181], 0
	v_mfma_f32_16x16x32_bf16 v[88:91], v[136:139], v[178:181], 0
	v_mfma_f32_16x16x32_bf16 v[84:87], v[128:131], v[194:197], 0
	v_mfma_f32_16x16x32_bf16 v[80:83], v[136:139], v[194:197], 0
	v_mfma_f32_16x16x32_bf16 v[124:127], v[132:135], v[166:169], v[124:127]
	v_mfma_f32_16x16x32_bf16 v[120:123], v[146:149], v[166:169], v[120:123]
	v_mfma_f32_16x16x32_bf16 v[108:111], v[132:135], v[174:177], v[108:111]
	v_mfma_f32_16x16x32_bf16 v[104:107], v[146:149], v[174:177], v[104:107]
	v_mfma_f32_16x16x32_bf16 v[96:99], v[132:135], v[182:185], v[96:99]
	v_mfma_f32_16x16x32_bf16 v[88:91], v[146:149], v[182:185], v[88:91]
	v_mfma_f32_16x16x32_bf16 v[84:87], v[132:135], v[210:213], v[84:87]
	v_mfma_f32_16x16x32_bf16 v[80:83], v[146:149], v[210:213], v[80:83]
	v_mfma_f32_16x16x32_bf16 v[116:119], v[214:217], v[162:165], 0
	v_mfma_f32_16x16x32_bf16 v[112:115], v[222:225], v[162:165], 0
	v_mfma_f32_16x16x32_bf16 v[100:103], v[214:217], v[170:173], 0
	v_mfma_f32_16x16x32_bf16 v[92:95], v[222:225], v[170:173], 0
	v_mfma_f32_16x16x32_bf16 v[76:79], v[214:217], v[178:181], 0
	v_mfma_f32_16x16x32_bf16 v[72:75], v[222:225], v[178:181], 0
	v_mfma_f32_16x16x32_bf16 v[68:71], v[214:217], v[194:197], 0
	v_mfma_f32_16x16x32_bf16 v[64:67], v[222:225], v[194:197], 0
	v_mfma_f32_16x16x32_bf16 v[116:119], v[218:221], v[166:169], v[116:119]
	v_mfma_f32_16x16x32_bf16 v[112:115], v[226:229], v[166:169], v[112:115]
	v_mfma_f32_16x16x32_bf16 v[100:103], v[218:221], v[174:177], v[100:103]
	v_mfma_f32_16x16x32_bf16 v[92:95], v[226:229], v[174:177], v[92:95]
	v_mfma_f32_16x16x32_bf16 v[76:79], v[218:221], v[182:185], v[76:79]
	v_mfma_f32_16x16x32_bf16 v[72:75], v[226:229], v[182:185], v[72:75]
	v_mfma_f32_16x16x32_bf16 v[68:71], v[218:221], v[210:213], v[68:71]
	v_mfma_f32_16x16x32_bf16 v[64:67], v[226:229], v[210:213], v[64:67]
	s_barrier
	s_add_i32 s19, s23, s57
	v_lshl_add_u64 v[230:231], s[54:55], 0, v[140:141]
	s_mov_b32 m0, s19
	s_nop 0
	global_load_lds_dwordx4 v[230:231], off
	v_lshl_add_u64 v[232:233], s[54:55], 0, v[150:151]
	s_add_i32 m0, s19, 0x2000
	s_nop 0
	global_load_lds_dwordx4 v[232:233], off
	s_mov_b32 m0, s68
	v_lshl_add_u64 v[234:235], s[58:59], 0, v[154:155]
	ds_read_b128 v[162:165], v208 offset:16384
	ds_read_b128 v[166:169], v208 offset:17408
	ds_read_b128 v[170:173], v208 offset:18432
	ds_read_b128 v[174:177], v208 offset:19456
	ds_read_b128 v[178:181], v208 offset:20480
	ds_read_b128 v[182:185], v208 offset:21504
	ds_read_b128 v[194:197], v208 offset:22528
	ds_read_b128 v[210:213], v208 offset:23552
	global_load_lds_dwordx4 v[234:235], off
	v_lshl_add_u64 v[236:237], s[58:59], 0, v[152:153]
	s_mov_b32 m0, s69
	s_nop 0
	global_load_lds_dwordx4 v[236:237], off
	s_add_u32 s84, s54, 0x40000
	s_addc_u32 s85, s55, 0
	s_add_i32 s6, s6, s57
	v_lshl_add_u64 v[250:251], s[84:85], 0, v[140:141]
	s_mov_b32 m0, s6
	s_nop 0
	global_load_lds_dwordx4 v[250:251], off
	v_lshl_add_u64 v[250:251], s[84:85], 0, v[150:151]
	s_add_i32 m0, s6, 0x2000
	s_nop 0
	global_load_lds_dwordx4 v[250:251], off
	s_waitcnt vmcnt(40)
	s_cmp_lg_u32 s100, 0
	s_cbranch_scc1 .Lm4bp_248
	s_waitcnt vmcnt(8)
.Lm4bp_248:
	s_waitcnt lgkmcnt(0)
	s_mov_b32 s100, 0
	s_barrier
	v_mfma_f32_16x16x32_bf16 v[60:63], v[128:131], v[162:165], 0
	v_mfma_f32_16x16x32_bf16 v[56:59], v[136:139], v[162:165], 0
	v_mfma_f32_16x16x32_bf16 v[48:51], v[128:131], v[170:173], 0
	v_mfma_f32_16x16x32_bf16 v[40:43], v[136:139], v[170:173], 0
	v_mfma_f32_16x16x32_bf16 v[32:35], v[128:131], v[178:181], 0
	v_mfma_f32_16x16x32_bf16 v[24:27], v[136:139], v[178:181], 0
	v_mfma_f32_16x16x32_bf16 v[16:19], v[128:131], v[194:197], 0
	v_mfma_f32_16x16x32_bf16 v[8:11], v[136:139], v[194:197], 0
	v_mfma_f32_16x16x32_bf16 v[60:63], v[132:135], v[166:169], v[60:63]
	v_mfma_f32_16x16x32_bf16 v[56:59], v[146:149], v[166:169], v[56:59]
	v_mfma_f32_16x16x32_bf16 v[48:51], v[132:135], v[174:177], v[48:51]
	v_mfma_f32_16x16x32_bf16 v[40:43], v[146:149], v[174:177], v[40:43]
	v_mfma_f32_16x16x32_bf16 v[32:35], v[132:135], v[182:185], v[32:35]
	v_mfma_f32_16x16x32_bf16 v[24:27], v[146:149], v[182:185], v[24:27]
	v_mfma_f32_16x16x32_bf16 v[16:19], v[132:135], v[210:213], v[16:19]
	v_mfma_f32_16x16x32_bf16 v[8:11], v[146:149], v[210:213], v[8:11]
	v_mfma_f32_16x16x32_bf16 v[52:55], v[214:217], v[162:165], 0
	v_mfma_f32_16x16x32_bf16 v[44:47], v[222:225], v[162:165], 0
	v_mfma_f32_16x16x32_bf16 v[36:39], v[214:217], v[170:173], 0
	v_mfma_f32_16x16x32_bf16 v[28:31], v[222:225], v[170:173], 0
	v_mfma_f32_16x16x32_bf16 v[20:23], v[214:217], v[178:181], 0
	v_mfma_f32_16x16x32_bf16 v[12:15], v[222:225], v[178:181], 0
	v_mfma_f32_16x16x32_bf16 v[4:7], v[214:217], v[194:197], 0
	v_mfma_f32_16x16x32_bf16 v[0:3], v[222:225], v[194:197], 0
	v_mfma_f32_16x16x32_bf16 v[52:55], v[218:221], v[166:169], v[52:55]
	v_mfma_f32_16x16x32_bf16 v[44:47], v[226:229], v[166:169], v[44:47]
	v_mfma_f32_16x16x32_bf16 v[36:39], v[218:221], v[174:177], v[36:39]
	v_mfma_f32_16x16x32_bf16 v[28:31], v[226:229], v[174:177], v[28:31]
	v_mfma_f32_16x16x32_bf16 v[20:23], v[218:221], v[182:185], v[20:23]
	v_mfma_f32_16x16x32_bf16 v[12:15], v[226:229], v[182:185], v[12:15]
	v_mfma_f32_16x16x32_bf16 v[4:7], v[218:221], v[210:213], v[4:7]
	v_mfma_f32_16x16x32_bf16 v[0:3], v[226:229], v[210:213], v[0:3]
	s_barrier
	s_add_i32 s6, 0, 0x18000
	v_add_u32_e32 v146, s6, v206
	ds_read_b128 v[128:131], v146
	ds_read_b128 v[132:135], v146 offset:1024
	ds_read_b128 v[136:139], v146 offset:2048
	ds_read_b128 v[146:149], v146 offset:3072
	s_add_u32 s58, s58, 0x40000
	s_addc_u32 s59, s59, 0
	s_mov_b32 m0, s70
	v_lshl_add_u64 v[214:215], s[58:59], 0, v[154:155]
	ds_read_b128 v[162:165], v208 offset:32768
	ds_read_b128 v[166:169], v208 offset:33792
	ds_read_b128 v[170:173], v208 offset:34816
	ds_read_b128 v[174:177], v208 offset:35840
	ds_read_b128 v[178:181], v208 offset:36864
	ds_read_b128 v[182:185], v208 offset:37888
	ds_read_b128 v[194:197], v208 offset:38912
	ds_read_b128 v[210:213], v208 offset:39936
	global_load_lds_dwordx4 v[214:215], off
	v_lshl_add_u64 v[214:215], s[58:59], 0, v[152:153]
	s_mov_b32 m0, s71
	s_nop 0
	global_load_lds_dwordx4 v[214:215], off
	s_add_i32 s19, 0, 0x1c000
	v_add_u32_e32 v192, s19, v206
	ds_read_b128 v[214:217], v192
	ds_read_b128 v[218:221], v192 offset:1024
	ds_read_b128 v[222:225], v192 offset:2048
	ds_read_b128 v[226:229], v192 offset:3072
	s_waitcnt vmcnt(8)
	s_waitcnt lgkmcnt(0)
	s_barrier
	v_mfma_f32_16x16x32_bf16 v[124:127], v[128:131], v[162:165], v[124:127]
	v_mfma_f32_16x16x32_bf16 v[120:123], v[136:139], v[162:165], v[120:123]
	v_mfma_f32_16x16x32_bf16 v[108:111], v[128:131], v[170:173], v[108:111]
	v_mfma_f32_16x16x32_bf16 v[104:107], v[136:139], v[170:173], v[104:107]
	v_mfma_f32_16x16x32_bf16 v[96:99], v[128:131], v[178:181], v[96:99]
	v_mfma_f32_16x16x32_bf16 v[88:91], v[136:139], v[178:181], v[88:91]
	v_mfma_f32_16x16x32_bf16 v[84:87], v[128:131], v[194:197], v[84:87]
	v_mfma_f32_16x16x32_bf16 v[80:83], v[136:139], v[194:197], v[80:83]
	v_mfma_f32_16x16x32_bf16 v[124:127], v[132:135], v[166:169], v[124:127]
	v_mfma_f32_16x16x32_bf16 v[120:123], v[146:149], v[166:169], v[120:123]
	v_mfma_f32_16x16x32_bf16 v[108:111], v[132:135], v[174:177], v[108:111]
	v_mfma_f32_16x16x32_bf16 v[104:107], v[146:149], v[174:177], v[104:107]
	v_mfma_f32_16x16x32_bf16 v[96:99], v[132:135], v[182:185], v[96:99]
	v_mfma_f32_16x16x32_bf16 v[88:91], v[146:149], v[182:185], v[88:91]
	v_mfma_f32_16x16x32_bf16 v[84:87], v[132:135], v[210:213], v[84:87]
	v_mfma_f32_16x16x32_bf16 v[80:83], v[146:149], v[210:213], v[80:83]
	v_mfma_f32_16x16x32_bf16 v[116:119], v[214:217], v[162:165], v[116:119]
	v_mfma_f32_16x16x32_bf16 v[112:115], v[222:225], v[162:165], v[112:115]
	v_mfma_f32_16x16x32_bf16 v[100:103], v[214:217], v[170:173], v[100:103]
	v_mfma_f32_16x16x32_bf16 v[92:95], v[222:225], v[170:173], v[92:95]
	v_mfma_f32_16x16x32_bf16 v[76:79], v[214:217], v[178:181], v[76:79]
	v_mfma_f32_16x16x32_bf16 v[72:75], v[222:225], v[178:181], v[72:75]
	v_mfma_f32_16x16x32_bf16 v[68:71], v[214:217], v[194:197], v[68:71]
	v_mfma_f32_16x16x32_bf16 v[64:67], v[222:225], v[194:197], v[64:67]
	v_mfma_f32_16x16x32_bf16 v[116:119], v[218:221], v[166:169], v[116:119]
	v_mfma_f32_16x16x32_bf16 v[112:115], v[226:229], v[166:169], v[112:115]
	v_mfma_f32_16x16x32_bf16 v[100:103], v[218:221], v[174:177], v[100:103]
	v_mfma_f32_16x16x32_bf16 v[92:95], v[226:229], v[174:177], v[92:95]
	v_mfma_f32_16x16x32_bf16 v[76:79], v[218:221], v[182:185], v[76:79]
	v_mfma_f32_16x16x32_bf16 v[72:75], v[226:229], v[182:185], v[72:75]
	v_mfma_f32_16x16x32_bf16 v[68:71], v[218:221], v[210:213], v[68:71]
	v_mfma_f32_16x16x32_bf16 v[64:67], v[226:229], v[210:213], v[64:67]
	s_barrier
	s_add_i32 s6, s6, s57
	v_lshl_add_u64 v[230:231], v[230:231], 0, s[36:37]
	s_mov_b32 m0, s6
	s_nop 0
	global_load_lds_dwordx4 v[230:231], off
	v_lshl_add_u64 v[230:231], v[232:233], 0, s[36:37]
	s_add_i32 m0, s6, 0x2000
	s_nop 0
	global_load_lds_dwordx4 v[230:231], off
	s_mov_b32 m0, s72
	v_lshl_add_u64 v[230:231], v[234:235], 0, s[36:37]
	ds_read_b128 v[162:165], v208 offset:49152
	ds_read_b128 v[166:169], v208 offset:50176
	ds_read_b128 v[170:173], v208 offset:51200
	ds_read_b128 v[174:177], v208 offset:52224
	ds_read_b128 v[178:181], v208 offset:53248
	ds_read_b128 v[182:185], v208 offset:54272
	ds_read_b128 v[194:197], v208 offset:55296
	ds_read_b128 v[210:213], v208 offset:56320
	global_load_lds_dwordx4 v[230:231], off
	v_lshl_add_u64 v[230:231], v[236:237], 0, s[36:37]
	s_mov_b32 m0, s73
	s_nop 0
	global_load_lds_dwordx4 v[230:231], off
	s_add_u32 s54, s54, 0x40080
	s_addc_u32 s55, s55, 0
	s_add_i32 s6, s19, s57
	v_lshl_add_u64 v[250:251], s[54:55], 0, v[140:141]
	s_mov_b32 m0, s6
	s_nop 0
	global_load_lds_dwordx4 v[250:251], off
	v_lshl_add_u64 v[250:251], s[54:55], 0, v[150:151]
	s_add_i32 m0, s6, 0x2000
	s_nop 0
	global_load_lds_dwordx4 v[250:251], off
	s_waitcnt vmcnt(8)
	s_waitcnt lgkmcnt(0)
	s_barrier
	v_mfma_f32_16x16x32_bf16 v[60:63], v[128:131], v[162:165], v[60:63]
	v_mfma_f32_16x16x32_bf16 v[56:59], v[136:139], v[162:165], v[56:59]
	v_mfma_f32_16x16x32_bf16 v[48:51], v[128:131], v[170:173], v[48:51]
	v_mfma_f32_16x16x32_bf16 v[40:43], v[136:139], v[170:173], v[40:43]
	v_mfma_f32_16x16x32_bf16 v[32:35], v[128:131], v[178:181], v[32:35]
	v_mfma_f32_16x16x32_bf16 v[24:27], v[136:139], v[178:181], v[24:27]
	v_mfma_f32_16x16x32_bf16 v[16:19], v[128:131], v[194:197], v[16:19]
	v_mfma_f32_16x16x32_bf16 v[8:11], v[136:139], v[194:197], v[8:11]
	v_mfma_f32_16x16x32_bf16 v[60:63], v[132:135], v[166:169], v[60:63]
	v_mfma_f32_16x16x32_bf16 v[56:59], v[146:149], v[166:169], v[56:59]
	v_mfma_f32_16x16x32_bf16 v[48:51], v[132:135], v[174:177], v[48:51]
	v_mfma_f32_16x16x32_bf16 v[40:43], v[146:149], v[174:177], v[40:43]
	v_mfma_f32_16x16x32_bf16 v[32:35], v[132:135], v[182:185], v[32:35]
	v_mfma_f32_16x16x32_bf16 v[24:27], v[146:149], v[182:185], v[24:27]
	v_mfma_f32_16x16x32_bf16 v[16:19], v[132:135], v[210:213], v[16:19]
	v_mfma_f32_16x16x32_bf16 v[8:11], v[146:149], v[210:213], v[8:11]
	v_mfma_f32_16x16x32_bf16 v[52:55], v[214:217], v[162:165], v[52:55]
	v_mfma_f32_16x16x32_bf16 v[44:47], v[222:225], v[162:165], v[44:47]
	v_mfma_f32_16x16x32_bf16 v[36:39], v[214:217], v[170:173], v[36:39]
	v_mfma_f32_16x16x32_bf16 v[28:31], v[222:225], v[170:173], v[28:31]
	v_mfma_f32_16x16x32_bf16 v[20:23], v[214:217], v[178:181], v[20:23]
	v_mfma_f32_16x16x32_bf16 v[12:15], v[222:225], v[178:181], v[12:15]
	v_mfma_f32_16x16x32_bf16 v[4:7], v[214:217], v[194:197], v[4:7]
	v_mfma_f32_16x16x32_bf16 v[0:3], v[222:225], v[194:197], v[0:3]
	v_mfma_f32_16x16x32_bf16 v[52:55], v[218:221], v[166:169], v[52:55]
	v_mfma_f32_16x16x32_bf16 v[44:47], v[226:229], v[166:169], v[44:47]
	v_mfma_f32_16x16x32_bf16 v[36:39], v[218:221], v[174:177], v[36:39]
	v_mfma_f32_16x16x32_bf16 v[28:31], v[226:229], v[174:177], v[28:31]
	v_mfma_f32_16x16x32_bf16 v[20:23], v[218:221], v[182:185], v[20:23]
	v_mfma_f32_16x16x32_bf16 v[12:15], v[226:229], v[182:185], v[12:15]
	v_mfma_f32_16x16x32_bf16 v[4:7], v[218:221], v[210:213], v[4:7]
	v_mfma_f32_16x16x32_bf16 v[0:3], v[226:229], v[210:213], v[0:3]
	s_add_i32 s82, s82, 2
	s_add_u32 s52, s52, 0x100
	s_addc_u32 s53, s53, 0
	s_add_u32 s39, s39, 0x100
	s_addc_u32 s51, s51, 0
	s_cmp_gt_u32 s82, 13
	s_barrier
.LBB0_248:
	s_add_u32 s6, s52, 0xfffc0080
	s_addc_u32 s19, s53, -1
	s_add_i32 s23, 0, 0x10000
	v_add_u32_e32 v146, s23, v206
	ds_read_b128 v[128:131], v146
	ds_read_b128 v[132:135], v146 offset:1024
	ds_read_b128 v[136:139], v146 offset:2048
	ds_read_b128 v[146:149], v146 offset:3072
	s_cmp_eq_u32 s82, 12
	s_cselect_b32 s59, s10, s19
	s_cselect_b32 s58, s11, s6
	s_cselect_b32 s55, s12, s51
	s_cselect_b32 s54, s35, s39
	v_lshl_add_u64 v[214:215], s[52:53], 0, v[158:159]
	s_add_i32 m0, s68, 0xc000
	ds_read_b128 v[162:165], v208
	ds_read_b128 v[166:169], v208 offset:1024
	ds_read_b128 v[170:173], v208 offset:2048
	ds_read_b128 v[174:177], v208 offset:3072
	ds_read_b128 v[178:181], v208 offset:4096
	ds_read_b128 v[182:185], v208 offset:5120
	ds_read_b128 v[194:197], v208 offset:6144
	ds_read_b128 v[210:213], v208 offset:7168
	global_load_lds_dwordx4 v[214:215], off
	v_lshl_add_u64 v[214:215], s[52:53], 0, v[160:161]
	s_add_i32 m0, s68, 0xe000
	s_nop 0
	global_load_lds_dwordx4 v[214:215], off
	s_add_i32 s6, 0, 0x14000
	v_add_u32_e32 v192, s6, v206
	ds_read_b128 v[214:217], v192
	ds_read_b128 v[218:221], v192 offset:1024
	ds_read_b128 v[222:225], v192 offset:2048
	ds_read_b128 v[226:229], v192 offset:3072
	s_waitcnt vmcnt(8)
	s_waitcnt lgkmcnt(0)
	s_barrier
	v_mfma_f32_16x16x32_bf16 v[124:127], v[128:131], v[162:165], v[124:127]
	v_mfma_f32_16x16x32_bf16 v[120:123], v[136:139], v[162:165], v[120:123]
	v_mfma_f32_16x16x32_bf16 v[108:111], v[128:131], v[170:173], v[108:111]
	v_mfma_f32_16x16x32_bf16 v[104:107], v[136:139], v[170:173], v[104:107]
	v_mfma_f32_16x16x32_bf16 v[96:99], v[128:131], v[178:181], v[96:99]
	v_mfma_f32_16x16x32_bf16 v[88:91], v[136:139], v[178:181], v[88:91]
	v_mfma_f32_16x16x32_bf16 v[84:87], v[128:131], v[194:197], v[84:87]
	v_mfma_f32_16x16x32_bf16 v[80:83], v[136:139], v[194:197], v[80:83]
	v_mfma_f32_16x16x32_bf16 v[124:127], v[132:135], v[166:169], v[124:127]
	v_mfma_f32_16x16x32_bf16 v[120:123], v[146:149], v[166:169], v[120:123]
	v_mfma_f32_16x16x32_bf16 v[108:111], v[132:135], v[174:177], v[108:111]
	v_mfma_f32_16x16x32_bf16 v[104:107], v[146:149], v[174:177], v[104:107]
	v_mfma_f32_16x16x32_bf16 v[96:99], v[132:135], v[182:185], v[96:99]
	v_mfma_f32_16x16x32_bf16 v[88:91], v[146:149], v[182:185], v[88:91]
	v_mfma_f32_16x16x32_bf16 v[84:87], v[132:135], v[210:213], v[84:87]
	v_mfma_f32_16x16x32_bf16 v[80:83], v[146:149], v[210:213], v[80:83]
	v_mfma_f32_16x16x32_bf16 v[116:119], v[214:217], v[162:165], v[116:119]
	v_mfma_f32_16x16x32_bf16 v[112:115], v[222:225], v[162:165], v[112:115]
	v_mfma_f32_16x16x32_bf16 v[100:103], v[214:217], v[170:173], v[100:103]
	v_mfma_f32_16x16x32_bf16 v[92:95], v[222:225], v[170:173], v[92:95]
	v_mfma_f32_16x16x32_bf16 v[76:79], v[214:217], v[178:181], v[76:79]
	v_mfma_f32_16x16x32_bf16 v[72:75], v[222:225], v[178:181], v[72:75]
	v_mfma_f32_16x16x32_bf16 v[68:71], v[214:217], v[194:197], v[68:71]
	v_mfma_f32_16x16x32_bf16 v[64:67], v[222:225], v[194:197], v[64:67]
	v_mfma_f32_16x16x32_bf16 v[116:119], v[218:221], v[166:169], v[116:119]
	v_mfma_f32_16x16x32_bf16 v[112:115], v[226:229], v[166:169], v[112:115]
	v_mfma_f32_16x16x32_bf16 v[100:103], v[218:221], v[174:177], v[100:103]
	v_mfma_f32_16x16x32_bf16 v[92:95], v[226:229], v[174:177], v[92:95]
	v_mfma_f32_16x16x32_bf16 v[76:79], v[218:221], v[182:185], v[76:79]
	v_mfma_f32_16x16x32_bf16 v[72:75], v[226:229], v[182:185], v[72:75]
	v_mfma_f32_16x16x32_bf16 v[68:71], v[218:221], v[210:213], v[68:71]
	v_mfma_f32_16x16x32_bf16 v[64:67], v[226:229], v[210:213], v[64:67]
	s_barrier
	s_add_i32 s19, s23, s57
	v_lshl_add_u64 v[230:231], s[54:55], 0, v[140:141]
	s_mov_b32 m0, s19
	s_nop 0
	global_load_lds_dwordx4 v[230:231], off
	v_lshl_add_u64 v[232:233], s[54:55], 0, v[150:151]
	s_add_i32 m0, s19, 0x2000
	s_nop 0
	global_load_lds_dwordx4 v[232:233], off
	s_mov_b32 m0, s68
	v_lshl_add_u64 v[234:235], s[58:59], 0, v[154:155]
	ds_read_b128 v[162:165], v208 offset:16384
	ds_read_b128 v[166:169], v208 offset:17408
	ds_read_b128 v[170:173], v208 offset:18432
	ds_read_b128 v[174:177], v208 offset:19456
	ds_read_b128 v[178:181], v208 offset:20480
	ds_read_b128 v[182:185], v208 offset:21504
	ds_read_b128 v[194:197], v208 offset:22528
	ds_read_b128 v[210:213], v208 offset:23552
	global_load_lds_dwordx4 v[234:235], off
	v_lshl_add_u64 v[236:237], s[58:59], 0, v[152:153]
	s_mov_b32 m0, s69
	s_nop 0
	global_load_lds_dwordx4 v[236:237], off
	s_add_u32 s84, s54, 0x40000
	s_addc_u32 s85, s55, 0
	s_add_i32 s6, s6, s57
	v_lshl_add_u64 v[250:251], s[84:85], 0, v[140:141]
	s_mov_b32 m0, s6
	s_nop 0
	global_load_lds_dwordx4 v[250:251], off
	v_lshl_add_u64 v[250:251], s[84:85], 0, v[150:151]
	s_add_i32 m0, s6, 0x2000
	s_nop 0
	global_load_lds_dwordx4 v[250:251], off
	s_waitcnt vmcnt(8)
	s_waitcnt lgkmcnt(0)
	s_barrier
	v_mfma_f32_16x16x32_bf16 v[60:63], v[128:131], v[162:165], v[60:63]
	v_mfma_f32_16x16x32_bf16 v[56:59], v[136:139], v[162:165], v[56:59]
	v_mfma_f32_16x16x32_bf16 v[48:51], v[128:131], v[170:173], v[48:51]
	v_mfma_f32_16x16x32_bf16 v[40:43], v[136:139], v[170:173], v[40:43]
	v_mfma_f32_16x16x32_bf16 v[32:35], v[128:131], v[178:181], v[32:35]
	v_mfma_f32_16x16x32_bf16 v[24:27], v[136:139], v[178:181], v[24:27]
	v_mfma_f32_16x16x32_bf16 v[16:19], v[128:131], v[194:197], v[16:19]
	v_mfma_f32_16x16x32_bf16 v[8:11], v[136:139], v[194:197], v[8:11]
	v_mfma_f32_16x16x32_bf16 v[60:63], v[132:135], v[166:169], v[60:63]
	v_mfma_f32_16x16x32_bf16 v[56:59], v[146:149], v[166:169], v[56:59]
	v_mfma_f32_16x16x32_bf16 v[48:51], v[132:135], v[174:177], v[48:51]
	v_mfma_f32_16x16x32_bf16 v[40:43], v[146:149], v[174:177], v[40:43]
	v_mfma_f32_16x16x32_bf16 v[32:35], v[132:135], v[182:185], v[32:35]
	v_mfma_f32_16x16x32_bf16 v[24:27], v[146:149], v[182:185], v[24:27]
	v_mfma_f32_16x16x32_bf16 v[16:19], v[132:135], v[210:213], v[16:19]
	v_mfma_f32_16x16x32_bf16 v[8:11], v[146:149], v[210:213], v[8:11]
	v_mfma_f32_16x16x32_bf16 v[52:55], v[214:217], v[162:165], v[52:55]
	v_mfma_f32_16x16x32_bf16 v[44:47], v[222:225], v[162:165], v[44:47]
	v_mfma_f32_16x16x32_bf16 v[36:39], v[214:217], v[170:173], v[36:39]
	v_mfma_f32_16x16x32_bf16 v[28:31], v[222:225], v[170:173], v[28:31]
	v_mfma_f32_16x16x32_bf16 v[20:23], v[214:217], v[178:181], v[20:23]
	v_mfma_f32_16x16x32_bf16 v[12:15], v[222:225], v[178:181], v[12:15]
	v_mfma_f32_16x16x32_bf16 v[4:7], v[214:217], v[194:197], v[4:7]
	v_mfma_f32_16x16x32_bf16 v[0:3], v[222:225], v[194:197], v[0:3]
	v_mfma_f32_16x16x32_bf16 v[52:55], v[218:221], v[166:169], v[52:55]
	v_mfma_f32_16x16x32_bf16 v[44:47], v[226:229], v[166:169], v[44:47]
	v_mfma_f32_16x16x32_bf16 v[36:39], v[218:221], v[174:177], v[36:39]
	v_mfma_f32_16x16x32_bf16 v[28:31], v[226:229], v[174:177], v[28:31]
	v_mfma_f32_16x16x32_bf16 v[20:23], v[218:221], v[182:185], v[20:23]
	v_mfma_f32_16x16x32_bf16 v[12:15], v[226:229], v[182:185], v[12:15]
	v_mfma_f32_16x16x32_bf16 v[4:7], v[218:221], v[210:213], v[4:7]
	v_mfma_f32_16x16x32_bf16 v[0:3], v[226:229], v[210:213], v[0:3]
	s_barrier
	s_add_i32 s6, 0, 0x18000
	v_add_u32_e32 v146, s6, v206
	ds_read_b128 v[128:131], v146
	ds_read_b128 v[132:135], v146 offset:1024
	ds_read_b128 v[136:139], v146 offset:2048
	ds_read_b128 v[146:149], v146 offset:3072
	s_add_u32 s58, s58, 0x40000
	s_addc_u32 s59, s59, 0
	s_mov_b32 m0, s70
	v_lshl_add_u64 v[214:215], s[58:59], 0, v[154:155]
	ds_read_b128 v[162:165], v208 offset:32768
	ds_read_b128 v[166:169], v208 offset:33792
	ds_read_b128 v[170:173], v208 offset:34816
	ds_read_b128 v[174:177], v208 offset:35840
	ds_read_b128 v[178:181], v208 offset:36864
	ds_read_b128 v[182:185], v208 offset:37888
	ds_read_b128 v[194:197], v208 offset:38912
	ds_read_b128 v[210:213], v208 offset:39936
	global_load_lds_dwordx4 v[214:215], off
	v_lshl_add_u64 v[214:215], s[58:59], 0, v[152:153]
	s_mov_b32 m0, s71
	s_nop 0
	global_load_lds_dwordx4 v[214:215], off
	s_add_i32 s19, 0, 0x1c000
	v_add_u32_e32 v192, s19, v206
	ds_read_b128 v[214:217], v192
	ds_read_b128 v[218:221], v192 offset:1024
	ds_read_b128 v[222:225], v192 offset:2048
	ds_read_b128 v[226:229], v192 offset:3072
	s_waitcnt vmcnt(8)
	s_waitcnt lgkmcnt(0)
	s_barrier
	v_mfma_f32_16x16x32_bf16 v[124:127], v[128:131], v[162:165], v[124:127]
	v_mfma_f32_16x16x32_bf16 v[120:123], v[136:139], v[162:165], v[120:123]
	v_mfma_f32_16x16x32_bf16 v[108:111], v[128:131], v[170:173], v[108:111]
	v_mfma_f32_16x16x32_bf16 v[104:107], v[136:139], v[170:173], v[104:107]
	v_mfma_f32_16x16x32_bf16 v[96:99], v[128:131], v[178:181], v[96:99]
	v_mfma_f32_16x16x32_bf16 v[88:91], v[136:139], v[178:181], v[88:91]
	v_mfma_f32_16x16x32_bf16 v[84:87], v[128:131], v[194:197], v[84:87]
	v_mfma_f32_16x16x32_bf16 v[80:83], v[136:139], v[194:197], v[80:83]
	v_mfma_f32_16x16x32_bf16 v[124:127], v[132:135], v[166:169], v[124:127]
	v_mfma_f32_16x16x32_bf16 v[120:123], v[146:149], v[166:169], v[120:123]
	v_mfma_f32_16x16x32_bf16 v[108:111], v[132:135], v[174:177], v[108:111]
	v_mfma_f32_16x16x32_bf16 v[104:107], v[146:149], v[174:177], v[104:107]
	v_mfma_f32_16x16x32_bf16 v[96:99], v[132:135], v[182:185], v[96:99]
	v_mfma_f32_16x16x32_bf16 v[88:91], v[146:149], v[182:185], v[88:91]
	v_mfma_f32_16x16x32_bf16 v[84:87], v[132:135], v[210:213], v[84:87]
	v_mfma_f32_16x16x32_bf16 v[80:83], v[146:149], v[210:213], v[80:83]
	v_mfma_f32_16x16x32_bf16 v[116:119], v[214:217], v[162:165], v[116:119]
	v_mfma_f32_16x16x32_bf16 v[112:115], v[222:225], v[162:165], v[112:115]
	v_mfma_f32_16x16x32_bf16 v[100:103], v[214:217], v[170:173], v[100:103]
	v_mfma_f32_16x16x32_bf16 v[92:95], v[222:225], v[170:173], v[92:95]
	v_mfma_f32_16x16x32_bf16 v[76:79], v[214:217], v[178:181], v[76:79]
	v_mfma_f32_16x16x32_bf16 v[72:75], v[222:225], v[178:181], v[72:75]
	v_mfma_f32_16x16x32_bf16 v[68:71], v[214:217], v[194:197], v[68:71]
	v_mfma_f32_16x16x32_bf16 v[64:67], v[222:225], v[194:197], v[64:67]
	v_mfma_f32_16x16x32_bf16 v[116:119], v[218:221], v[166:169], v[116:119]
	v_mfma_f32_16x16x32_bf16 v[112:115], v[226:229], v[166:169], v[112:115]
	v_mfma_f32_16x16x32_bf16 v[100:103], v[218:221], v[174:177], v[100:103]
	v_mfma_f32_16x16x32_bf16 v[92:95], v[226:229], v[174:177], v[92:95]
	v_mfma_f32_16x16x32_bf16 v[76:79], v[218:221], v[182:185], v[76:79]
	v_mfma_f32_16x16x32_bf16 v[72:75], v[226:229], v[182:185], v[72:75]
	v_mfma_f32_16x16x32_bf16 v[68:71], v[218:221], v[210:213], v[68:71]
	v_mfma_f32_16x16x32_bf16 v[64:67], v[226:229], v[210:213], v[64:67]
	s_barrier
	s_add_i32 s6, s6, s57
	v_lshl_add_u64 v[230:231], v[230:231], 0, s[36:37]
	s_mov_b32 m0, s6
	s_nop 0
	global_load_lds_dwordx4 v[230:231], off
	v_lshl_add_u64 v[230:231], v[232:233], 0, s[36:37]
	s_add_i32 m0, s6, 0x2000
	s_nop 0
	global_load_lds_dwordx4 v[230:231], off
	s_mov_b32 m0, s72
	v_lshl_add_u64 v[230:231], v[234:235], 0, s[36:37]
	ds_read_b128 v[162:165], v208 offset:49152
	ds_read_b128 v[166:169], v208 offset:50176
	ds_read_b128 v[170:173], v208 offset:51200
	ds_read_b128 v[174:177], v208 offset:52224
	ds_read_b128 v[178:181], v208 offset:53248
	ds_read_b128 v[182:185], v208 offset:54272
	ds_read_b128 v[194:197], v208 offset:55296
	ds_read_b128 v[210:213], v208 offset:56320
	global_load_lds_dwordx4 v[230:231], off
	v_lshl_add_u64 v[230:231], v[236:237], 0, s[36:37]
	s_mov_b32 m0, s73
	s_nop 0
	global_load_lds_dwordx4 v[230:231], off
	s_add_u32 s54, s54, 0x40080
	s_addc_u32 s55, s55, 0
	s_add_i32 s6, s19, s57
	v_lshl_add_u64 v[250:251], s[54:55], 0, v[140:141]
	s_mov_b32 m0, s6
	s_nop 0
	global_load_lds_dwordx4 v[250:251], off
	v_lshl_add_u64 v[250:251], s[54:55], 0, v[150:151]
	s_add_i32 m0, s6, 0x2000
	s_nop 0
	global_load_lds_dwordx4 v[250:251], off
	s_waitcnt vmcnt(8)
	s_waitcnt lgkmcnt(0)
	s_barrier
	v_mfma_f32_16x16x32_bf16 v[60:63], v[128:131], v[162:165], v[60:63]
	v_mfma_f32_16x16x32_bf16 v[56:59], v[136:139], v[162:165], v[56:59]
	v_mfma_f32_16x16x32_bf16 v[48:51], v[128:131], v[170:173], v[48:51]
	v_mfma_f32_16x16x32_bf16 v[40:43], v[136:139], v[170:173], v[40:43]
	v_mfma_f32_16x16x32_bf16 v[32:35], v[128:131], v[178:181], v[32:35]
	v_mfma_f32_16x16x32_bf16 v[24:27], v[136:139], v[178:181], v[24:27]
	v_mfma_f32_16x16x32_bf16 v[16:19], v[128:131], v[194:197], v[16:19]
	v_mfma_f32_16x16x32_bf16 v[8:11], v[136:139], v[194:197], v[8:11]
	v_mfma_f32_16x16x32_bf16 v[60:63], v[132:135], v[166:169], v[60:63]
	v_mfma_f32_16x16x32_bf16 v[56:59], v[146:149], v[166:169], v[56:59]
	v_mfma_f32_16x16x32_bf16 v[48:51], v[132:135], v[174:177], v[48:51]
	v_mfma_f32_16x16x32_bf16 v[40:43], v[146:149], v[174:177], v[40:43]
	v_mfma_f32_16x16x32_bf16 v[32:35], v[132:135], v[182:185], v[32:35]
	v_mfma_f32_16x16x32_bf16 v[24:27], v[146:149], v[182:185], v[24:27]
	v_mfma_f32_16x16x32_bf16 v[16:19], v[132:135], v[210:213], v[16:19]
	v_mfma_f32_16x16x32_bf16 v[8:11], v[146:149], v[210:213], v[8:11]
	v_mfma_f32_16x16x32_bf16 v[52:55], v[214:217], v[162:165], v[52:55]
	v_mfma_f32_16x16x32_bf16 v[44:47], v[222:225], v[162:165], v[44:47]
	v_mfma_f32_16x16x32_bf16 v[36:39], v[214:217], v[170:173], v[36:39]
	v_mfma_f32_16x16x32_bf16 v[28:31], v[222:225], v[170:173], v[28:31]
	v_mfma_f32_16x16x32_bf16 v[20:23], v[214:217], v[178:181], v[20:23]
	v_mfma_f32_16x16x32_bf16 v[12:15], v[222:225], v[178:181], v[12:15]
	v_mfma_f32_16x16x32_bf16 v[4:7], v[214:217], v[194:197], v[4:7]
	v_mfma_f32_16x16x32_bf16 v[0:3], v[222:225], v[194:197], v[0:3]
	v_mfma_f32_16x16x32_bf16 v[52:55], v[218:221], v[166:169], v[52:55]
	v_mfma_f32_16x16x32_bf16 v[44:47], v[226:229], v[166:169], v[44:47]
	v_mfma_f32_16x16x32_bf16 v[36:39], v[218:221], v[174:177], v[36:39]
	v_mfma_f32_16x16x32_bf16 v[28:31], v[226:229], v[174:177], v[28:31]
	v_mfma_f32_16x16x32_bf16 v[20:23], v[218:221], v[182:185], v[20:23]
	v_mfma_f32_16x16x32_bf16 v[12:15], v[226:229], v[182:185], v[12:15]
	v_mfma_f32_16x16x32_bf16 v[4:7], v[218:221], v[210:213], v[4:7]
	v_mfma_f32_16x16x32_bf16 v[0:3], v[226:229], v[210:213], v[0:3]
	s_add_i32 s82, s82, 2
	s_add_u32 s52, s52, 0x100
	s_addc_u32 s53, s53, 0
	s_add_u32 s39, s39, 0x100
	s_addc_u32 s51, s51, 0
	s_cmp_gt_u32 s82, 13
	s_barrier
	s_cbranch_scc0 .LBB0_248
	s_mov_b32 s100, 1
	s_ashr_i32 s51, s50, 31
	v_lshl_or_b32 v128, s81, 8, v207
	s_lshl_b64 s[10:11], s[50:51], 8
	v_ashrrev_i32_e32 v129, 31, v128
	v_lshl_add_u64 v[168:169], s[10:11], 0, v[156:157]
	v_lshlrev_b64 v[170:171], 1, v[128:129]
	v_lshl_add_u64 v[174:175], s[28:29], 0, v[170:171]
	v_lshlrev_b64 v[172:173], 11, v[168:169]
	v_lshl_add_u64 v[128:129], v[174:175], 0, v[172:173]
	global_load_dwordx4 v[146:149], v[128:129], off
	global_load_dwordx4 v[182:185], v[128:129], off offset:256
	v_or_b32_e32 v166, 16, v168
	v_mov_b32_e32 v167, v169
	v_lshlrev_b64 v[176:177], 11, v[166:167]
	v_lshl_add_u64 v[128:129], v[174:175], 0, v[176:177]
	global_load_dwordx4 v[194:197], v[128:129], off
	global_load_dwordx4 v[210:213], v[128:129], off offset:256
	v_or_b32_e32 v164, 32, v168
	v_mov_b32_e32 v165, v169
	v_or_b32_e32 v162, 48, v168
	v_mov_b32_e32 v163, v169
	v_lshlrev_b64 v[180:181], 11, v[164:165]
	v_lshlrev_b64 v[178:179], 11, v[162:163]
	v_lshl_add_u64 v[128:129], v[174:175], 0, v[180:181]
	v_lshl_add_u64 v[130:131], v[174:175], 0, v[178:179]
	global_load_dwordx4 v[214:217], v[128:129], off
	global_load_dwordx4 v[136:139], v[128:129], off offset:256
	global_load_dwordx4 v[132:135], v[130:131], off
	s_nop 0
	global_load_dwordx4 v[128:131], v[130:131], off offset:256
	s_mov_b64 s[10:11], 0x90
	v_lshl_add_u64 v[172:173], s[30:31], 0, v[172:173]
	v_lshl_add_u64 v[172:173], v[172:173], 0, v[170:171]
	s_waitcnt vmcnt(0)
	v_lshlrev_b32_e32 v218, 16, v146
	v_and_b32_e32 v219, 0xffff0000, v146
	v_lshlrev_b32_e32 v220, 16, v148
	v_and_b32_e32 v221, 0xffff0000, v148
	v_lshlrev_b32_e32 v146, 16, v147
	v_and_b32_e32 v147, 0xffff0000, v147
	v_lshlrev_b32_e32 v222, 16, v182
	v_and_b32_e32 v223, 0xffff0000, v182
	v_lshlrev_b32_e32 v224, 16, v184
	v_and_b32_e32 v225, 0xffff0000, v184
	v_lshlrev_b32_e32 v182, 16, v183
	v_and_b32_e32 v183, 0xffff0000, v183
	v_pk_add_f32 v[124:125], v[124:125], v[218:219]
	v_pk_add_f32 v[120:121], v[120:121], v[220:221]
	v_pk_add_f32 v[126:127], v[126:127], v[146:147]
	v_pk_add_f32 v[116:117], v[116:117], v[222:223]
	v_pk_add_f32 v[146:147], v[112:113], v[224:225]
	v_pk_add_f32 v[118:119], v[118:119], v[182:183]
	v_pk_mul_f32 v[220:221], v[124:125], v[124:125]
	v_pk_mul_f32 v[222:223], v[126:127], v[126:127]
	v_cvt_pk_bf16_f32 v112, v124, v125
	v_cvt_pk_bf16_f32 v113, v126, v127
	v_pk_mul_f32 v[124:125], v[116:117], v[116:117]
	v_pk_mul_f32 v[126:127], v[118:119], v[118:119]
	v_pk_mul_f32 v[228:229], v[146:147], v[146:147]
	v_cvt_pk_bf16_f32 v116, v116, v117
	v_cvt_pk_bf16_f32 v117, v118, v119
	v_cvt_pk_bf16_f32 v118, v146, v147
	v_add_f32_e32 v146, v220, v221
	v_add_f32_e32 v146, v222, v146
	v_lshlrev_b32_e32 v148, 16, v149
	v_and_b32_e32 v149, 0xffff0000, v149
	v_pk_mul_f32 v[224:225], v[120:121], v[120:121]
	v_add_f32_e32 v146, v223, v146
	v_pk_add_f32 v[122:123], v[122:123], v[148:149]
	v_add_f32_e32 v146, v224, v146
	v_pk_mul_f32 v[226:227], v[122:123], v[122:123]
	v_add_f32_e32 v146, v225, v146
	v_add_f32_e32 v146, v226, v146
	v_add_f32_e32 v146, v227, v146
	v_add_f32_e32 v124, v124, v146
	v_add_f32_e32 v124, v125, v124
	v_add_f32_e32 v124, v126, v124
	v_lshlrev_b32_e32 v184, 16, v185
	v_and_b32_e32 v185, 0xffff0000, v185
	v_add_f32_e32 v124, v127, v124
	v_pk_add_f32 v[148:149], v[114:115], v[184:185]
	v_add_f32_e32 v124, v228, v124
	v_pk_mul_f32 v[230:231], v[148:149], v[148:149]
	v_add_f32_e32 v124, v229, v124
	v_add_f32_e32 v124, v230, v124
	v_add_f32_e32 v209, v231, v124
	v_lshlrev_b32_e32 v124, 16, v212
	v_and_b32_e32 v125, 0xffff0000, v212
	v_pk_add_f32 v[124:125], v[92:93], v[124:125]
	v_lshlrev_b32_e32 v92, 16, v211
	v_and_b32_e32 v93, 0xffff0000, v211
	v_pk_add_f32 v[102:103], v[102:103], v[92:93]
	v_lshlrev_b32_e32 v92, 16, v213
	v_and_b32_e32 v93, 0xffff0000, v213
	v_pk_add_f32 v[126:127], v[94:95], v[92:93]
	v_lshlrev_b32_e32 v92, 16, v214
	v_and_b32_e32 v93, 0xffff0000, v214
	v_pk_add_f32 v[92:93], v[96:97], v[92:93]
	v_lshlrev_b32_e32 v96, 16, v217
	v_and_b32_e32 v97, 0xffff0000, v217
	v_lshlrev_b32_e32 v94, 16, v216
	v_and_b32_e32 v95, 0xffff0000, v216
	v_pk_add_f32 v[90:91], v[90:91], v[96:97]
	v_lshlrev_b32_e32 v96, 16, v136
	v_and_b32_e32 v97, 0xffff0000, v136
	v_lshlrev_b32_e32 v182, 16, v194
	v_and_b32_e32 v183, 0xffff0000, v194
	v_pk_add_f32 v[88:89], v[88:89], v[94:95]
	v_lshlrev_b32_e32 v94, 16, v215
	v_and_b32_e32 v95, 0xffff0000, v215
	v_pk_add_f32 v[96:97], v[76:77], v[96:97]
	v_lshl_add_u64 v[76:77], v[168:169], 0, s[36:37]
	v_lshlrev_b32_e32 v184, 16, v196
	v_and_b32_e32 v185, 0xffff0000, v196
	v_cvt_pk_bf16_f32 v114, v120, v121
	v_pk_add_f32 v[120:121], v[108:109], v[182:183]
	v_pk_add_f32 v[94:95], v[98:99], v[94:95]
	v_lshlrev_b64 v[182:183], 11, v[76:77]
	v_lshlrev_b32_e32 v98, 16, v138
	v_and_b32_e32 v99, 0xffff0000, v138
	v_pk_add_f32 v[108:109], v[104:105], v[184:185]
	v_lshl_add_u64 v[184:185], v[174:175], 0, v[182:183]
	v_pk_add_f32 v[98:99], v[72:73], v[98:99]
	v_lshlrev_b32_e32 v72, 16, v137
	v_and_b32_e32 v73, 0xffff0000, v137
	v_lshlrev_b32_e32 v218, 16, v210
	v_and_b32_e32 v219, 0xffff0000, v210
	global_load_dwordx4 v[210:213], v[184:185], off
	v_pk_add_f32 v[136:137], v[78:79], v[72:73]
	v_lshlrev_b32_e32 v72, 16, v139
	v_and_b32_e32 v73, 0xffff0000, v139
	v_pk_add_f32 v[138:139], v[74:75], v[72:73]
	v_lshlrev_b32_e32 v72, 16, v132
	v_and_b32_e32 v73, 0xffff0000, v132
	v_pk_add_f32 v[74:75], v[84:85], v[72:73]
	v_lshlrev_b32_e32 v72, 16, v134
	v_and_b32_e32 v73, 0xffff0000, v134
	v_pk_add_f32 v[78:79], v[80:81], v[72:73]
	v_lshlrev_b32_e32 v72, 16, v133
	v_and_b32_e32 v73, 0xffff0000, v133
	v_pk_add_f32 v[100:101], v[100:101], v[218:219]
	global_load_dwordx4 v[218:221], v[184:185], off offset:256
	v_pk_add_f32 v[80:81], v[86:87], v[72:73]
	v_lshlrev_b32_e32 v72, 16, v135
	v_and_b32_e32 v73, 0xffff0000, v135
	v_pk_add_f32 v[82:83], v[82:83], v[72:73]
	v_lshl_add_u64 v[72:73], v[168:169], 0, s[10:11]
	v_lshlrev_b64 v[132:133], 11, v[72:73]
	v_lshl_add_u64 v[134:135], v[174:175], 0, v[132:133]
	v_lshlrev_b32_e32 v84, 16, v128
	v_and_b32_e32 v85, 0xffff0000, v128
	global_load_dwordx4 v[226:229], v[134:135], off
	global_load_dwordx4 v[234:237], v[134:135], off offset:256
	v_pk_add_f32 v[84:85], v[68:69], v[84:85]
	v_lshlrev_b32_e32 v68, 16, v130
	v_and_b32_e32 v69, 0xffff0000, v130
	v_pk_add_f32 v[86:87], v[64:65], v[68:69]
	v_lshlrev_b32_e32 v64, 16, v129
	v_and_b32_e32 v65, 0xffff0000, v129
	s_mov_b64 s[10:11], 0xa0
	v_pk_add_f32 v[128:129], v[70:71], v[64:65]
	v_lshl_add_u64 v[70:71], v[168:169], 0, s[10:11]
	s_mov_b64 s[10:11], 0xb0
	v_lshlrev_b32_e32 v64, 16, v131
	v_and_b32_e32 v65, 0xffff0000, v131
	v_lshlrev_b64 v[134:135], 11, v[70:71]
	v_lshl_add_u64 v[68:69], v[168:169], 0, s[10:11]
	v_pk_add_f32 v[130:131], v[66:67], v[64:65]
	v_lshl_add_u64 v[64:65], v[174:175], 0, v[134:135]
	v_lshlrev_b64 v[184:185], 11, v[68:69]
	global_load_dwordx4 v[238:241], v[64:65], off
	global_load_dwordx4 v[242:245], v[64:65], off offset:256
	v_lshl_add_u64 v[64:65], v[174:175], 0, v[184:185]
	global_load_dwordx4 v[246:249], v[64:65], off
	s_nop 0
	global_load_dwordx4 v[64:67], v[64:65], off offset:256
	v_lshlrev_b32_e32 v194, 16, v195
	v_and_b32_e32 v195, 0xffff0000, v195
	v_lshlrev_b32_e32 v196, 16, v197
	v_and_b32_e32 v197, 0xffff0000, v197
	v_cvt_pk_bf16_f32 v115, v122, v123
	v_cvt_pk_bf16_f32 v119, v148, v149
	v_pk_add_f32 v[122:123], v[110:111], v[194:195]
	v_pk_add_f32 v[110:111], v[106:107], v[196:197]
	global_store_dwordx4 v[172:173], v[112:115], off
	global_store_dwordx4 v[172:173], v[116:119], off offset:256
	v_cvt_pk_bf16_f32 v104, v120, v121
	v_lshl_add_u64 v[112:113], s[30:31], 0, v[176:177]
	v_cvt_pk_bf16_f32 v105, v122, v123
	v_cvt_pk_bf16_f32 v106, v108, v109
	v_cvt_pk_bf16_f32 v107, v110, v111
	v_lshl_add_u64 v[112:113], v[112:113], 0, v[170:171]
	v_cvt_pk_bf16_f32 v146, v100, v101
	v_cvt_pk_bf16_f32 v147, v102, v103
	v_cvt_pk_bf16_f32 v148, v124, v125
	v_cvt_pk_bf16_f32 v149, v126, v127
	global_store_dwordx4 v[112:113], v[104:107], off
	global_store_dwordx4 v[112:113], v[146:149], off offset:256
	v_cvt_pk_bf16_f32 v194, v92, v93
	v_lshl_add_u64 v[104:105], s[30:31], 0, v[180:181]
	v_cvt_pk_bf16_f32 v195, v94, v95
	v_cvt_pk_bf16_f32 v196, v88, v89
	v_cvt_pk_bf16_f32 v197, v90, v91
	v_lshl_add_u64 v[104:105], v[104:105], 0, v[170:171]
	v_cvt_pk_bf16_f32 v214, v96, v97
	v_cvt_pk_bf16_f32 v215, v136, v137
	v_cvt_pk_bf16_f32 v216, v98, v99
	v_cvt_pk_bf16_f32 v217, v138, v139
	global_store_dwordx4 v[104:105], v[194:197], off
	global_store_dwordx4 v[104:105], v[214:217], off offset:256
	v_lshl_add_u64 v[104:105], s[30:31], 0, v[178:179]
	v_cvt_pk_bf16_f32 v222, v74, v75
	v_cvt_pk_bf16_f32 v223, v80, v81
	v_cvt_pk_bf16_f32 v224, v78, v79
	v_cvt_pk_bf16_f32 v225, v82, v83
	v_lshl_add_u64 v[104:105], v[104:105], 0, v[170:171]
	v_cvt_pk_bf16_f32 v230, v84, v85
	v_cvt_pk_bf16_f32 v231, v128, v129
	v_cvt_pk_bf16_f32 v232, v86, v87
	v_cvt_pk_bf16_f32 v233, v130, v131
	global_store_dwordx4 v[104:105], v[222:225], off
	global_store_dwordx4 v[104:105], v[230:233], off offset:256
	s_waitcnt vmcnt(0)
	v_lshlrev_b32_e32 v104, 16, v210
	v_and_b32_e32 v105, 0xffff0000, v210
	v_pk_add_f32 v[60:61], v[60:61], v[104:105]
	v_lshlrev_b32_e32 v104, 16, v212
	v_and_b32_e32 v105, 0xffff0000, v212
	v_pk_add_f32 v[56:57], v[56:57], v[104:105]
	v_lshlrev_b32_e32 v104, 16, v211
	v_and_b32_e32 v105, 0xffff0000, v211
	v_pk_add_f32 v[62:63], v[62:63], v[104:105]
	v_lshlrev_b32_e32 v104, 16, v213
	v_and_b32_e32 v105, 0xffff0000, v213
	v_pk_add_f32 v[58:59], v[58:59], v[104:105]
	v_lshlrev_b32_e32 v104, 16, v218
	v_and_b32_e32 v105, 0xffff0000, v218
	v_pk_add_f32 v[52:53], v[52:53], v[104:105]
	v_lshlrev_b32_e32 v104, 16, v220
	v_and_b32_e32 v105, 0xffff0000, v220
	v_pk_add_f32 v[104:105], v[44:45], v[104:105]
	v_lshlrev_b32_e32 v44, 16, v219
	v_and_b32_e32 v45, 0xffff0000, v219
	v_pk_add_f32 v[54:55], v[54:55], v[44:45]
	v_lshlrev_b32_e32 v44, 16, v221
	v_and_b32_e32 v45, 0xffff0000, v221
	v_pk_add_f32 v[106:107], v[46:47], v[44:45]
	v_lshlrev_b32_e32 v44, 16, v226
	v_and_b32_e32 v45, 0xffff0000, v226
	v_pk_add_f32 v[44:45], v[48:49], v[44:45]
	v_lshlrev_b32_e32 v48, 16, v229
	v_and_b32_e32 v49, 0xffff0000, v229
	v_pk_add_f32 v[42:43], v[42:43], v[48:49]
	v_lshlrev_b32_e32 v48, 16, v234
	v_and_b32_e32 v49, 0xffff0000, v234
	v_pk_add_f32 v[36:37], v[36:37], v[48:49]
	v_lshlrev_b32_e32 v48, 16, v236
	v_and_b32_e32 v49, 0xffff0000, v236
	v_lshlrev_b32_e32 v46, 16, v228
	v_and_b32_e32 v47, 0xffff0000, v228
	v_pk_add_f32 v[48:49], v[28:29], v[48:49]
	v_lshlrev_b32_e32 v28, 16, v235
	v_and_b32_e32 v29, 0xffff0000, v235
	v_pk_add_f32 v[40:41], v[40:41], v[46:47]
	v_lshlrev_b32_e32 v46, 16, v227
	v_and_b32_e32 v47, 0xffff0000, v227
	v_pk_add_f32 v[38:39], v[38:39], v[28:29]
	v_lshlrev_b32_e32 v28, 16, v237
	v_and_b32_e32 v29, 0xffff0000, v237
	v_pk_add_f32 v[46:47], v[50:51], v[46:47]
	v_pk_add_f32 v[50:51], v[30:31], v[28:29]
	v_lshlrev_b32_e32 v28, 16, v238
	v_and_b32_e32 v29, 0xffff0000, v238
	v_lshlrev_b32_e32 v180, 16, v64
	v_and_b32_e32 v181, 0xffff0000, v64
	v_pk_add_f32 v[28:29], v[32:33], v[28:29]
	v_lshlrev_b32_e32 v32, 16, v241
	v_and_b32_e32 v33, 0xffff0000, v241
	v_pk_add_f32 v[4:5], v[4:5], v[180:181]
	v_lshlrev_b32_e32 v180, 16, v66
	v_and_b32_e32 v181, 0xffff0000, v66
	v_pk_add_f32 v[26:27], v[26:27], v[32:33]
	v_lshlrev_b32_e32 v32, 16, v242
	v_and_b32_e32 v33, 0xffff0000, v242
	v_pk_add_f32 v[0:1], v[0:1], v[180:181]
	v_lshl_add_u64 v[180:181], s[30:31], 0, v[182:183]
	v_cvt_pk_bf16_f32 v112, v60, v61
	v_cvt_pk_bf16_f32 v113, v62, v63
	v_cvt_pk_bf16_f32 v114, v56, v57
	v_cvt_pk_bf16_f32 v115, v58, v59
	v_pk_add_f32 v[20:21], v[20:21], v[32:33]
	v_lshlrev_b32_e32 v32, 16, v244
	v_and_b32_e32 v33, 0xffff0000, v244
	v_lshl_add_u64 v[180:181], v[180:181], 0, v[170:171]
	v_cvt_pk_bf16_f32 v116, v52, v53
	v_cvt_pk_bf16_f32 v117, v54, v55
	v_cvt_pk_bf16_f32 v118, v104, v105
	v_cvt_pk_bf16_f32 v119, v106, v107
	v_lshlrev_b32_e32 v30, 16, v240
	v_and_b32_e32 v31, 0xffff0000, v240
	v_pk_add_f32 v[32:33], v[12:13], v[32:33]
	v_lshlrev_b32_e32 v12, 16, v243
	v_and_b32_e32 v13, 0xffff0000, v243
	global_store_dwordx4 v[180:181], v[112:115], off
	global_store_dwordx4 v[180:181], v[116:119], off offset:256
	v_cvt_pk_bf16_f32 v146, v44, v45
	v_lshl_add_u64 v[112:113], s[30:31], 0, v[132:133]
	v_cvt_pk_bf16_f32 v147, v46, v47
	v_cvt_pk_bf16_f32 v148, v40, v41
	v_cvt_pk_bf16_f32 v149, v42, v43
	v_pk_add_f32 v[24:25], v[24:25], v[30:31]
	v_lshlrev_b32_e32 v30, 16, v239
	v_and_b32_e32 v31, 0xffff0000, v239
	v_pk_add_f32 v[22:23], v[22:23], v[12:13]
	v_lshlrev_b32_e32 v12, 16, v245
	v_and_b32_e32 v13, 0xffff0000, v245
	v_lshl_add_u64 v[112:113], v[112:113], 0, v[170:171]
	v_cvt_pk_bf16_f32 v172, v36, v37
	v_cvt_pk_bf16_f32 v173, v38, v39
	v_cvt_pk_bf16_f32 v174, v48, v49
	v_cvt_pk_bf16_f32 v175, v50, v51
	v_pk_add_f32 v[30:31], v[34:35], v[30:31]
	v_pk_add_f32 v[34:35], v[14:15], v[12:13]
	v_lshlrev_b32_e32 v12, 16, v246
	v_and_b32_e32 v13, 0xffff0000, v246
	v_lshlrev_b32_e32 v14, 16, v248
	v_and_b32_e32 v15, 0xffff0000, v248
	global_store_dwordx4 v[112:113], v[146:149], off
	global_store_dwordx4 v[112:113], v[172:175], off offset:256
	v_lshl_add_u64 v[112:113], s[30:31], 0, v[134:135]
	v_cvt_pk_bf16_f32 v176, v28, v29
	v_cvt_pk_bf16_f32 v177, v30, v31
	v_cvt_pk_bf16_f32 v178, v24, v25
	v_cvt_pk_bf16_f32 v179, v26, v27
	v_pk_add_f32 v[12:13], v[16:17], v[12:13]
	v_pk_add_f32 v[8:9], v[8:9], v[14:15]
	v_lshlrev_b32_e32 v14, 16, v247
	v_and_b32_e32 v15, 0xffff0000, v247
	v_lshlrev_b32_e32 v16, 16, v249
	v_and_b32_e32 v17, 0xffff0000, v249
	v_lshlrev_b32_e32 v64, 16, v65
	v_and_b32_e32 v65, 0xffff0000, v65
	v_lshl_add_u64 v[112:113], v[112:113], 0, v[170:171]
	v_cvt_pk_bf16_f32 v194, v20, v21
	v_cvt_pk_bf16_f32 v195, v22, v23
	v_cvt_pk_bf16_f32 v196, v32, v33
	v_cvt_pk_bf16_f32 v197, v34, v35
	v_pk_add_f32 v[14:15], v[18:19], v[14:15]
	v_pk_add_f32 v[10:11], v[10:11], v[16:17]
	v_pk_add_f32 v[6:7], v[6:7], v[64:65]
	v_lshlrev_b32_e32 v64, 16, v67
	v_and_b32_e32 v65, 0xffff0000, v67
	global_store_dwordx4 v[112:113], v[176:179], off
	global_store_dwordx4 v[112:113], v[194:197], off offset:256
	v_lshl_add_u64 v[112:113], s[30:31], 0, v[184:185]
	v_cvt_pk_bf16_f32 v16, v12, v13
	v_cvt_pk_bf16_f32 v17, v14, v15
	v_cvt_pk_bf16_f32 v18, v8, v9
	v_cvt_pk_bf16_f32 v19, v10, v11
	v_pk_add_f32 v[2:3], v[2:3], v[64:65]
	v_lshl_add_u64 v[112:113], v[112:113], 0, v[170:171]
	v_cvt_pk_bf16_f32 v64, v4, v5
	v_cvt_pk_bf16_f32 v65, v6, v7
	v_cvt_pk_bf16_f32 v66, v0, v1
	v_cvt_pk_bf16_f32 v67, v2, v3
	global_store_dwordx4 v[112:113], v[16:19], off
	global_store_dwordx4 v[112:113], v[64:67], off offset:256
	s_lshl_b32 s10, s81, 2
	v_and_b32_e32 v17, 64, v188
	v_xor_b32_e32 v16, 16, v188
	v_add_u32_e32 v17, 64, v17
	v_cmp_lt_i32_e32 vcc, v16, v17
	v_xor_b32_e32 v18, 32, v188
	s_ashr_i32 s11, s10, 31
	v_cndmask_b32_e32 v16, v188, v16, vcc
	v_lshlrev_b32_e32 v16, 2, v16
	ds_bpermute_b32 v19, v16, v209
	v_cmp_lt_i32_e32 vcc, v18, v17
	s_lshl_b64 s[10:11], s[10:11], 2
	s_add_u32 s50, s75, s10
	v_cndmask_b32_e32 v17, v188, v18, vcc
	v_lshlrev_b32_e32 v17, 2, v17
	s_waitcnt lgkmcnt(0)
	v_add_f32_e32 v18, v209, v19
	ds_bpermute_b32 v19, v17, v18
	s_addc_u32 s51, s80, s11
	s_and_saveexec_b64 s[52:53], s[42:43]
	s_cbranch_execz .LBB0_251
	s_waitcnt lgkmcnt(0)
	v_add_f32_e32 v64, v18, v19
	v_lshlrev_b64 v[18:19], 6, v[168:169]
	v_lshl_add_u64 v[18:19], s[50:51], 0, v[18:19]
	global_store_dword v[18:19], v64, off

.Lm4ap_295:
	s_waitcnt lgkmcnt(0)
	s_barrier
	v_mfma_f32_16x16x32_bf16 v[124:127], v[146:149], v[170:173], 0
	v_mfma_f32_16x16x32_bf16 v[120:123], v[162:165], v[170:173], 0
	v_mfma_f32_16x16x32_bf16 v[116:119], v[146:149], v[178:181], 0
	v_mfma_f32_16x16x32_bf16 v[112:115], v[162:165], v[178:181], 0
	v_mfma_f32_16x16x32_bf16 v[108:111], v[146:149], v[194:197], 0
	v_mfma_f32_16x16x32_bf16 v[104:107], v[162:165], v[194:197], 0
	v_mfma_f32_16x16x32_bf16 v[100:103], v[146:149], v[210:213], 0
	v_mfma_f32_16x16x32_bf16 v[96:99], v[162:165], v[210:213], 0
	v_mfma_f32_16x16x32_bf16 v[124:127], v[158:161], v[174:177], v[124:127]
	v_mfma_f32_16x16x32_bf16 v[120:123], v[166:169], v[174:177], v[120:123]
	v_mfma_f32_16x16x32_bf16 v[116:119], v[158:161], v[182:185], v[116:119]
	v_mfma_f32_16x16x32_bf16 v[112:115], v[166:169], v[182:185], v[112:115]
	v_mfma_f32_16x16x32_bf16 v[108:111], v[158:161], v[206:209], v[108:111]
	v_mfma_f32_16x16x32_bf16 v[104:107], v[166:169], v[206:209], v[104:107]
	v_mfma_f32_16x16x32_bf16 v[100:103], v[158:161], v[214:217], v[100:103]
	v_mfma_f32_16x16x32_bf16 v[96:99], v[166:169], v[214:217], v[96:99]
	v_mfma_f32_16x16x32_bf16 v[92:95], v[218:221], v[170:173], 0
	v_mfma_f32_16x16x32_bf16 v[88:91], v[226:229], v[170:173], 0
	v_mfma_f32_16x16x32_bf16 v[84:87], v[218:221], v[178:181], 0
	v_mfma_f32_16x16x32_bf16 v[80:83], v[226:229], v[178:181], 0
	v_mfma_f32_16x16x32_bf16 v[76:79], v[218:221], v[194:197], 0
	v_mfma_f32_16x16x32_bf16 v[72:75], v[226:229], v[194:197], 0
	v_mfma_f32_16x16x32_bf16 v[68:71], v[218:221], v[210:213], 0
	v_mfma_f32_16x16x32_bf16 v[64:67], v[226:229], v[210:213], 0
	v_mfma_f32_16x16x32_bf16 v[92:95], v[222:225], v[174:177], v[92:95]
	v_mfma_f32_16x16x32_bf16 v[88:91], v[230:233], v[174:177], v[88:91]
	v_mfma_f32_16x16x32_bf16 v[84:87], v[222:225], v[182:185], v[84:87]
	v_mfma_f32_16x16x32_bf16 v[80:83], v[230:233], v[182:185], v[80:83]
	v_mfma_f32_16x16x32_bf16 v[76:79], v[222:225], v[206:209], v[76:79]
	v_mfma_f32_16x16x32_bf16 v[72:75], v[230:233], v[206:209], v[72:75]
	v_mfma_f32_16x16x32_bf16 v[68:71], v[222:225], v[214:217], v[68:71]
	v_mfma_f32_16x16x32_bf16 v[64:67], v[230:233], v[214:217], v[64:67]
	s_barrier
	s_add_i32 s19, s80, s57
	v_lshl_add_u64 v[234:235], s[50:51], 0, v[140:141]
	s_mov_b32 m0, s19
	s_nop 0
	global_load_lds_dwordx4 v[234:235], off
	v_lshl_add_u64 v[236:237], s[50:51], 0, v[132:133]
	s_add_i32 m0, s19, 0x2000
	s_nop 0
	global_load_lds_dwordx4 v[236:237], off
	s_mov_b32 m0, s58
	v_lshl_add_u64 v[238:239], s[52:53], 0, v[128:129]
	ds_read_b128 v[170:173], v157 offset:16384
	ds_read_b128 v[174:177], v157 offset:17408
	ds_read_b128 v[178:181], v157 offset:18432
	ds_read_b128 v[182:185], v157 offset:19456
	ds_read_b128 v[194:197], v157 offset:20480
	ds_read_b128 v[206:209], v157 offset:21504
	ds_read_b128 v[210:213], v157 offset:22528
	ds_read_b128 v[214:217], v157 offset:23552
	global_load_lds_dwordx4 v[238:239], off
	v_lshl_add_u64 v[240:241], s[52:53], 0, v[130:131]
	s_mov_b32 m0, s59
	s_nop 0
	global_load_lds_dwordx4 v[240:241], off
	s_add_u32 s80, s50, 0x40000
	s_addc_u32 s81, s51, 0
	s_add_i32 s6, s6, s57
	v_lshl_add_u64 v[250:251], s[80:81], 0, v[140:141]
	s_mov_b32 m0, s6
	s_nop 0
	global_load_lds_dwordx4 v[250:251], off
	v_lshl_add_u64 v[250:251], s[80:81], 0, v[132:133]
	s_add_i32 m0, s6, 0x2000
	s_nop 0
	global_load_lds_dwordx4 v[250:251], off
	s_waitcnt vmcnt(24)
	s_cmp_lg_u32 s100, 0
	s_cbranch_scc1 .Lm4bp_295
	s_waitcnt vmcnt(8)
.Lm4bp_295:
	s_waitcnt lgkmcnt(0)
	s_mov_b32 s100, 0
	s_barrier
	v_mfma_f32_16x16x32_bf16 v[60:63], v[146:149], v[170:173], 0
	v_mfma_f32_16x16x32_bf16 v[56:59], v[162:165], v[170:173], 0
	v_mfma_f32_16x16x32_bf16 v[52:55], v[146:149], v[178:181], 0
	v_mfma_f32_16x16x32_bf16 v[48:51], v[162:165], v[178:181], 0
	v_mfma_f32_16x16x32_bf16 v[44:47], v[146:149], v[194:197], 0
	v_mfma_f32_16x16x32_bf16 v[40:43], v[162:165], v[194:197], 0
	v_mfma_f32_16x16x32_bf16 v[36:39], v[146:149], v[210:213], 0
	v_mfma_f32_16x16x32_bf16 v[32:35], v[162:165], v[210:213], 0
	v_mfma_f32_16x16x32_bf16 v[60:63], v[158:161], v[174:177], v[60:63]
	v_mfma_f32_16x16x32_bf16 v[56:59], v[166:169], v[174:177], v[56:59]
	v_mfma_f32_16x16x32_bf16 v[52:55], v[158:161], v[182:185], v[52:55]
	v_mfma_f32_16x16x32_bf16 v[48:51], v[166:169], v[182:185], v[48:51]
	v_mfma_f32_16x16x32_bf16 v[44:47], v[158:161], v[206:209], v[44:47]
	v_mfma_f32_16x16x32_bf16 v[40:43], v[166:169], v[206:209], v[40:43]
	v_mfma_f32_16x16x32_bf16 v[36:39], v[158:161], v[214:217], v[36:39]
	v_mfma_f32_16x16x32_bf16 v[32:35], v[166:169], v[214:217], v[32:35]
	v_mfma_f32_16x16x32_bf16 v[28:31], v[218:221], v[170:173], 0
	v_mfma_f32_16x16x32_bf16 v[24:27], v[226:229], v[170:173], 0
	v_mfma_f32_16x16x32_bf16 v[20:23], v[218:221], v[178:181], 0
	v_mfma_f32_16x16x32_bf16 v[16:19], v[226:229], v[178:181], 0
	v_mfma_f32_16x16x32_bf16 v[12:15], v[218:221], v[194:197], 0
	v_mfma_f32_16x16x32_bf16 v[8:11], v[226:229], v[194:197], 0
	v_mfma_f32_16x16x32_bf16 v[4:7], v[218:221], v[210:213], 0
	v_mfma_f32_16x16x32_bf16 v[0:3], v[226:229], v[210:213], 0
	v_mfma_f32_16x16x32_bf16 v[28:31], v[222:225], v[174:177], v[28:31]
	v_mfma_f32_16x16x32_bf16 v[24:27], v[230:233], v[174:177], v[24:27]
	v_mfma_f32_16x16x32_bf16 v[20:23], v[222:225], v[182:185], v[20:23]
	v_mfma_f32_16x16x32_bf16 v[16:19], v[230:233], v[182:185], v[16:19]
	v_mfma_f32_16x16x32_bf16 v[12:15], v[222:225], v[206:209], v[12:15]
	v_mfma_f32_16x16x32_bf16 v[8:11], v[230:233], v[206:209], v[8:11]
	v_mfma_f32_16x16x32_bf16 v[4:7], v[222:225], v[214:217], v[4:7]
	v_mfma_f32_16x16x32_bf16 v[0:3], v[230:233], v[214:217], v[0:3]
	s_barrier
	s_add_i32 s6, 0, 0x18000
	v_add_u32_e32 v166, s6, v154
	ds_read_b128 v[146:149], v166
	ds_read_b128 v[158:161], v166 offset:1024
	ds_read_b128 v[162:165], v166 offset:2048
	ds_read_b128 v[166:169], v166 offset:3072
	s_add_u32 s52, s52, 0x40000
	s_addc_u32 s53, s53, 0
	s_mov_b32 m0, s68
	v_lshl_add_u64 v[218:219], s[52:53], 0, v[128:129]
	ds_read_b128 v[170:173], v157 offset:32768
	ds_read_b128 v[174:177], v157 offset:33792
	ds_read_b128 v[178:181], v157 offset:34816
	ds_read_b128 v[182:185], v157 offset:35840
	ds_read_b128 v[194:197], v157 offset:36864
	ds_read_b128 v[206:209], v157 offset:37888
	ds_read_b128 v[210:213], v157 offset:38912
	ds_read_b128 v[214:217], v157 offset:39936
	global_load_lds_dwordx4 v[218:219], off
	v_lshl_add_u64 v[218:219], s[52:53], 0, v[130:131]
	s_mov_b32 m0, s69
	s_nop 0
	global_load_lds_dwordx4 v[218:219], off
	s_add_i32 s19, 0, 0x1c000
	v_add_u32_e32 v192, s19, v154
	ds_read_b128 v[218:221], v192
	ds_read_b128 v[222:225], v192 offset:1024
	ds_read_b128 v[226:229], v192 offset:2048
	ds_read_b128 v[230:233], v192 offset:3072
	s_waitcnt vmcnt(8)
	s_waitcnt lgkmcnt(0)
	s_barrier
	v_mfma_f32_16x16x32_bf16 v[124:127], v[146:149], v[170:173], v[124:127]
	v_mfma_f32_16x16x32_bf16 v[120:123], v[162:165], v[170:173], v[120:123]
	v_mfma_f32_16x16x32_bf16 v[116:119], v[146:149], v[178:181], v[116:119]
	v_mfma_f32_16x16x32_bf16 v[112:115], v[162:165], v[178:181], v[112:115]
	v_mfma_f32_16x16x32_bf16 v[108:111], v[146:149], v[194:197], v[108:111]
	v_mfma_f32_16x16x32_bf16 v[104:107], v[162:165], v[194:197], v[104:107]
	v_mfma_f32_16x16x32_bf16 v[100:103], v[146:149], v[210:213], v[100:103]
	v_mfma_f32_16x16x32_bf16 v[96:99], v[162:165], v[210:213], v[96:99]
	v_mfma_f32_16x16x32_bf16 v[124:127], v[158:161], v[174:177], v[124:127]
	v_mfma_f32_16x16x32_bf16 v[120:123], v[166:169], v[174:177], v[120:123]
	v_mfma_f32_16x16x32_bf16 v[116:119], v[158:161], v[182:185], v[116:119]
	v_mfma_f32_16x16x32_bf16 v[112:115], v[166:169], v[182:185], v[112:115]
	v_mfma_f32_16x16x32_bf16 v[108:111], v[158:161], v[206:209], v[108:111]
	v_mfma_f32_16x16x32_bf16 v[104:107], v[166:169], v[206:209], v[104:107]
	v_mfma_f32_16x16x32_bf16 v[100:103], v[158:161], v[214:217], v[100:103]
	v_mfma_f32_16x16x32_bf16 v[96:99], v[166:169], v[214:217], v[96:99]
	v_mfma_f32_16x16x32_bf16 v[92:95], v[218:221], v[170:173], v[92:95]
	v_mfma_f32_16x16x32_bf16 v[88:91], v[226:229], v[170:173], v[88:91]
	v_mfma_f32_16x16x32_bf16 v[84:87], v[218:221], v[178:181], v[84:87]
	v_mfma_f32_16x16x32_bf16 v[80:83], v[226:229], v[178:181], v[80:83]
	v_mfma_f32_16x16x32_bf16 v[76:79], v[218:221], v[194:197], v[76:79]
	v_mfma_f32_16x16x32_bf16 v[72:75], v[226:229], v[194:197], v[72:75]
	v_mfma_f32_16x16x32_bf16 v[68:71], v[218:221], v[210:213], v[68:71]
	v_mfma_f32_16x16x32_bf16 v[64:67], v[226:229], v[210:213], v[64:67]
	v_mfma_f32_16x16x32_bf16 v[92:95], v[222:225], v[174:177], v[92:95]
	v_mfma_f32_16x16x32_bf16 v[88:91], v[230:233], v[174:177], v[88:91]
	v_mfma_f32_16x16x32_bf16 v[84:87], v[222:225], v[182:185], v[84:87]
	v_mfma_f32_16x16x32_bf16 v[80:83], v[230:233], v[182:185], v[80:83]
	v_mfma_f32_16x16x32_bf16 v[76:79], v[222:225], v[206:209], v[76:79]
	v_mfma_f32_16x16x32_bf16 v[72:75], v[230:233], v[206:209], v[72:75]
	v_mfma_f32_16x16x32_bf16 v[68:71], v[222:225], v[214:217], v[68:71]
	v_mfma_f32_16x16x32_bf16 v[64:67], v[230:233], v[214:217], v[64:67]
	s_barrier
	s_add_i32 s6, s6, s57
	v_lshl_add_u64 v[234:235], v[234:235], 0, s[36:37]
	s_mov_b32 m0, s6
	s_nop 0
	global_load_lds_dwordx4 v[234:235], off
	v_lshl_add_u64 v[234:235], v[236:237], 0, s[36:37]
	s_add_i32 m0, s6, 0x2000
	s_nop 0
	global_load_lds_dwordx4 v[234:235], off
	s_mov_b32 m0, s70
	v_lshl_add_u64 v[234:235], v[238:239], 0, s[36:37]
	ds_read_b128 v[170:173], v157 offset:49152
	ds_read_b128 v[174:177], v157 offset:50176
	ds_read_b128 v[178:181], v157 offset:51200
	ds_read_b128 v[182:185], v157 offset:52224
	ds_read_b128 v[194:197], v157 offset:53248
	ds_read_b128 v[206:209], v157 offset:54272
	ds_read_b128 v[210:213], v157 offset:55296
	ds_read_b128 v[214:217], v157 offset:56320
	global_load_lds_dwordx4 v[234:235], off
	v_lshl_add_u64 v[234:235], v[240:241], 0, s[36:37]
	s_mov_b32 m0, s71
	s_nop 0
	global_load_lds_dwordx4 v[234:235], off
	s_add_u32 s50, s50, 0x40080
	s_addc_u32 s51, s51, 0
	s_add_i32 s6, s19, s57
	v_lshl_add_u64 v[250:251], s[50:51], 0, v[140:141]
	s_mov_b32 m0, s6
	s_nop 0
	global_load_lds_dwordx4 v[250:251], off
	v_lshl_add_u64 v[250:251], s[50:51], 0, v[132:133]
	s_add_i32 m0, s6, 0x2000
	s_nop 0
	global_load_lds_dwordx4 v[250:251], off
	s_waitcnt vmcnt(8)
	s_waitcnt lgkmcnt(0)
	s_barrier
	v_mfma_f32_16x16x32_bf16 v[60:63], v[146:149], v[170:173], v[60:63]
	v_mfma_f32_16x16x32_bf16 v[56:59], v[162:165], v[170:173], v[56:59]
	v_mfma_f32_16x16x32_bf16 v[52:55], v[146:149], v[178:181], v[52:55]
	v_mfma_f32_16x16x32_bf16 v[48:51], v[162:165], v[178:181], v[48:51]
	v_mfma_f32_16x16x32_bf16 v[44:47], v[146:149], v[194:197], v[44:47]
	v_mfma_f32_16x16x32_bf16 v[40:43], v[162:165], v[194:197], v[40:43]
	v_mfma_f32_16x16x32_bf16 v[36:39], v[146:149], v[210:213], v[36:39]
	v_mfma_f32_16x16x32_bf16 v[32:35], v[162:165], v[210:213], v[32:35]
	v_mfma_f32_16x16x32_bf16 v[60:63], v[158:161], v[174:177], v[60:63]
	v_mfma_f32_16x16x32_bf16 v[56:59], v[166:169], v[174:177], v[56:59]
	v_mfma_f32_16x16x32_bf16 v[52:55], v[158:161], v[182:185], v[52:55]
	v_mfma_f32_16x16x32_bf16 v[48:51], v[166:169], v[182:185], v[48:51]
	v_mfma_f32_16x16x32_bf16 v[44:47], v[158:161], v[206:209], v[44:47]
	v_mfma_f32_16x16x32_bf16 v[40:43], v[166:169], v[206:209], v[40:43]
	v_mfma_f32_16x16x32_bf16 v[36:39], v[158:161], v[214:217], v[36:39]
	v_mfma_f32_16x16x32_bf16 v[32:35], v[166:169], v[214:217], v[32:35]
	v_mfma_f32_16x16x32_bf16 v[28:31], v[218:221], v[170:173], v[28:31]
	v_mfma_f32_16x16x32_bf16 v[24:27], v[226:229], v[170:173], v[24:27]
	v_mfma_f32_16x16x32_bf16 v[20:23], v[218:221], v[178:181], v[20:23]
	v_mfma_f32_16x16x32_bf16 v[16:19], v[226:229], v[178:181], v[16:19]
	v_mfma_f32_16x16x32_bf16 v[12:15], v[218:221], v[194:197], v[12:15]
	v_mfma_f32_16x16x32_bf16 v[8:11], v[226:229], v[194:197], v[8:11]
	v_mfma_f32_16x16x32_bf16 v[4:7], v[218:221], v[210:213], v[4:7]
	v_mfma_f32_16x16x32_bf16 v[0:3], v[226:229], v[210:213], v[0:3]
	v_mfma_f32_16x16x32_bf16 v[28:31], v[222:225], v[174:177], v[28:31]
	v_mfma_f32_16x16x32_bf16 v[24:27], v[230:233], v[174:177], v[24:27]
	v_mfma_f32_16x16x32_bf16 v[20:23], v[222:225], v[182:185], v[20:23]
	v_mfma_f32_16x16x32_bf16 v[16:19], v[230:233], v[182:185], v[16:19]
	v_mfma_f32_16x16x32_bf16 v[12:15], v[222:225], v[206:209], v[12:15]
	v_mfma_f32_16x16x32_bf16 v[8:11], v[230:233], v[206:209], v[8:11]
	v_mfma_f32_16x16x32_bf16 v[4:7], v[222:225], v[214:217], v[4:7]
	v_mfma_f32_16x16x32_bf16 v[0:3], v[230:233], v[214:217], v[0:3]
	s_add_i32 s75, s75, 2
	s_add_u32 s48, s48, 0x100
	s_addc_u32 s49, s49, 0
	s_cmp_gt_u32 s75, 13
	s_barrier
.LBB0_295:
	s_add_u32 s6, s4, s48
	s_addc_u32 s19, s5, s49
	s_add_u32 s6, s6, 0x100
	s_addc_u32 s19, s19, 0
	s_add_u32 s23, s10, s48
	s_addc_u32 s50, s11, s49
	s_add_i32 s80, 0, 0x10000
	v_add_u32_e32 v166, s80, v154
	ds_read_b128 v[146:149], v166
	ds_read_b128 v[158:161], v166 offset:1024
	ds_read_b128 v[162:165], v166 offset:2048
	ds_read_b128 v[166:169], v166 offset:3072
	s_cmpk_eq_i32 s48, 0x700
	s_cselect_b32 s53, s12, s19
	s_cselect_b32 s52, s29, s6
	s_cselect_b32 s51, s31, s50
	s_cselect_b32 s50, s35, s23
	v_lshl_add_u64 v[218:219], v[150:151], 0, s[48:49]
	s_add_i32 m0, s58, 0xc000
	ds_read_b128 v[170:173], v157
	ds_read_b128 v[174:177], v157 offset:1024
	ds_read_b128 v[178:181], v157 offset:2048
	ds_read_b128 v[182:185], v157 offset:3072
	ds_read_b128 v[194:197], v157 offset:4096
	ds_read_b128 v[206:209], v157 offset:5120
	ds_read_b128 v[210:213], v157 offset:6144
	ds_read_b128 v[214:217], v157 offset:7168
	global_load_lds_dwordx4 v[218:219], off
	v_lshl_add_u64 v[218:219], v[152:153], 0, s[48:49]
	s_add_i32 m0, s58, 0xe000
	s_nop 0
	global_load_lds_dwordx4 v[218:219], off
	s_add_i32 s6, 0, 0x14000
	v_add_u32_e32 v192, s6, v154
	ds_read_b128 v[218:221], v192
	ds_read_b128 v[222:225], v192 offset:1024
	ds_read_b128 v[226:229], v192 offset:2048
	ds_read_b128 v[230:233], v192 offset:3072
	s_waitcnt vmcnt(8)
	s_waitcnt lgkmcnt(0)
	s_barrier
	v_mfma_f32_16x16x32_bf16 v[124:127], v[146:149], v[170:173], v[124:127]
	v_mfma_f32_16x16x32_bf16 v[120:123], v[162:165], v[170:173], v[120:123]
	v_mfma_f32_16x16x32_bf16 v[116:119], v[146:149], v[178:181], v[116:119]
	v_mfma_f32_16x16x32_bf16 v[112:115], v[162:165], v[178:181], v[112:115]
	v_mfma_f32_16x16x32_bf16 v[108:111], v[146:149], v[194:197], v[108:111]
	v_mfma_f32_16x16x32_bf16 v[104:107], v[162:165], v[194:197], v[104:107]
	v_mfma_f32_16x16x32_bf16 v[100:103], v[146:149], v[210:213], v[100:103]
	v_mfma_f32_16x16x32_bf16 v[96:99], v[162:165], v[210:213], v[96:99]
	v_mfma_f32_16x16x32_bf16 v[124:127], v[158:161], v[174:177], v[124:127]
	v_mfma_f32_16x16x32_bf16 v[120:123], v[166:169], v[174:177], v[120:123]
	v_mfma_f32_16x16x32_bf16 v[116:119], v[158:161], v[182:185], v[116:119]
	v_mfma_f32_16x16x32_bf16 v[112:115], v[166:169], v[182:185], v[112:115]
	v_mfma_f32_16x16x32_bf16 v[108:111], v[158:161], v[206:209], v[108:111]
	v_mfma_f32_16x16x32_bf16 v[104:107], v[166:169], v[206:209], v[104:107]
	v_mfma_f32_16x16x32_bf16 v[100:103], v[158:161], v[214:217], v[100:103]
	v_mfma_f32_16x16x32_bf16 v[96:99], v[166:169], v[214:217], v[96:99]
	v_mfma_f32_16x16x32_bf16 v[92:95], v[218:221], v[170:173], v[92:95]
	v_mfma_f32_16x16x32_bf16 v[88:91], v[226:229], v[170:173], v[88:91]
	v_mfma_f32_16x16x32_bf16 v[84:87], v[218:221], v[178:181], v[84:87]
	v_mfma_f32_16x16x32_bf16 v[80:83], v[226:229], v[178:181], v[80:83]
	v_mfma_f32_16x16x32_bf16 v[76:79], v[218:221], v[194:197], v[76:79]
	v_mfma_f32_16x16x32_bf16 v[72:75], v[226:229], v[194:197], v[72:75]
	v_mfma_f32_16x16x32_bf16 v[68:71], v[218:221], v[210:213], v[68:71]
	v_mfma_f32_16x16x32_bf16 v[64:67], v[226:229], v[210:213], v[64:67]
	v_mfma_f32_16x16x32_bf16 v[92:95], v[222:225], v[174:177], v[92:95]
	v_mfma_f32_16x16x32_bf16 v[88:91], v[230:233], v[174:177], v[88:91]
	v_mfma_f32_16x16x32_bf16 v[84:87], v[222:225], v[182:185], v[84:87]
	v_mfma_f32_16x16x32_bf16 v[80:83], v[230:233], v[182:185], v[80:83]
	v_mfma_f32_16x16x32_bf16 v[76:79], v[222:225], v[206:209], v[76:79]
	v_mfma_f32_16x16x32_bf16 v[72:75], v[230:233], v[206:209], v[72:75]
	v_mfma_f32_16x16x32_bf16 v[68:71], v[222:225], v[214:217], v[68:71]
	v_mfma_f32_16x16x32_bf16 v[64:67], v[230:233], v[214:217], v[64:67]
	s_barrier
	s_add_i32 s19, s80, s57
	v_lshl_add_u64 v[234:235], s[50:51], 0, v[140:141]
	s_mov_b32 m0, s19
	s_nop 0
	global_load_lds_dwordx4 v[234:235], off
	v_lshl_add_u64 v[236:237], s[50:51], 0, v[132:133]
	s_add_i32 m0, s19, 0x2000
	s_nop 0
	global_load_lds_dwordx4 v[236:237], off
	s_mov_b32 m0, s58
	v_lshl_add_u64 v[238:239], s[52:53], 0, v[128:129]
	ds_read_b128 v[170:173], v157 offset:16384
	ds_read_b128 v[174:177], v157 offset:17408
	ds_read_b128 v[178:181], v157 offset:18432
	ds_read_b128 v[182:185], v157 offset:19456
	ds_read_b128 v[194:197], v157 offset:20480
	ds_read_b128 v[206:209], v157 offset:21504
	ds_read_b128 v[210:213], v157 offset:22528
	ds_read_b128 v[214:217], v157 offset:23552
	global_load_lds_dwordx4 v[238:239], off
	v_lshl_add_u64 v[240:241], s[52:53], 0, v[130:131]
	s_mov_b32 m0, s59
	s_nop 0
	global_load_lds_dwordx4 v[240:241], off
	s_add_u32 s80, s50, 0x40000
	s_addc_u32 s81, s51, 0
	s_add_i32 s6, s6, s57
	v_lshl_add_u64 v[250:251], s[80:81], 0, v[140:141]
	s_mov_b32 m0, s6
	s_nop 0
	global_load_lds_dwordx4 v[250:251], off
	v_lshl_add_u64 v[250:251], s[80:81], 0, v[132:133]
	s_add_i32 m0, s6, 0x2000
	s_nop 0
	global_load_lds_dwordx4 v[250:251], off
	s_waitcnt vmcnt(8)
	s_waitcnt lgkmcnt(0)
	s_barrier
	v_mfma_f32_16x16x32_bf16 v[60:63], v[146:149], v[170:173], v[60:63]
	v_mfma_f32_16x16x32_bf16 v[56:59], v[162:165], v[170:173], v[56:59]
	v_mfma_f32_16x16x32_bf16 v[52:55], v[146:149], v[178:181], v[52:55]
	v_mfma_f32_16x16x32_bf16 v[48:51], v[162:165], v[178:181], v[48:51]
	v_mfma_f32_16x16x32_bf16 v[44:47], v[146:149], v[194:197], v[44:47]
	v_mfma_f32_16x16x32_bf16 v[40:43], v[162:165], v[194:197], v[40:43]
	v_mfma_f32_16x16x32_bf16 v[36:39], v[146:149], v[210:213], v[36:39]
	v_mfma_f32_16x16x32_bf16 v[32:35], v[162:165], v[210:213], v[32:35]
	v_mfma_f32_16x16x32_bf16 v[60:63], v[158:161], v[174:177], v[60:63]
	v_mfma_f32_16x16x32_bf16 v[56:59], v[166:169], v[174:177], v[56:59]
	v_mfma_f32_16x16x32_bf16 v[52:55], v[158:161], v[182:185], v[52:55]
	v_mfma_f32_16x16x32_bf16 v[48:51], v[166:169], v[182:185], v[48:51]
	v_mfma_f32_16x16x32_bf16 v[44:47], v[158:161], v[206:209], v[44:47]
	v_mfma_f32_16x16x32_bf16 v[40:43], v[166:169], v[206:209], v[40:43]
	v_mfma_f32_16x16x32_bf16 v[36:39], v[158:161], v[214:217], v[36:39]
	v_mfma_f32_16x16x32_bf16 v[32:35], v[166:169], v[214:217], v[32:35]
	v_mfma_f32_16x16x32_bf16 v[28:31], v[218:221], v[170:173], v[28:31]
	v_mfma_f32_16x16x32_bf16 v[24:27], v[226:229], v[170:173], v[24:27]
	v_mfma_f32_16x16x32_bf16 v[20:23], v[218:221], v[178:181], v[20:23]
	v_mfma_f32_16x16x32_bf16 v[16:19], v[226:229], v[178:181], v[16:19]
	v_mfma_f32_16x16x32_bf16 v[12:15], v[218:221], v[194:197], v[12:15]
	v_mfma_f32_16x16x32_bf16 v[8:11], v[226:229], v[194:197], v[8:11]
	v_mfma_f32_16x16x32_bf16 v[4:7], v[218:221], v[210:213], v[4:7]
	v_mfma_f32_16x16x32_bf16 v[0:3], v[226:229], v[210:213], v[0:3]
	v_mfma_f32_16x16x32_bf16 v[28:31], v[222:225], v[174:177], v[28:31]
	v_mfma_f32_16x16x32_bf16 v[24:27], v[230:233], v[174:177], v[24:27]
	v_mfma_f32_16x16x32_bf16 v[20:23], v[222:225], v[182:185], v[20:23]
	v_mfma_f32_16x16x32_bf16 v[16:19], v[230:233], v[182:185], v[16:19]
	v_mfma_f32_16x16x32_bf16 v[12:15], v[222:225], v[206:209], v[12:15]
	v_mfma_f32_16x16x32_bf16 v[8:11], v[230:233], v[206:209], v[8:11]
	v_mfma_f32_16x16x32_bf16 v[4:7], v[222:225], v[214:217], v[4:7]
	v_mfma_f32_16x16x32_bf16 v[0:3], v[230:233], v[214:217], v[0:3]
	s_barrier
	s_add_i32 s6, 0, 0x18000
	v_add_u32_e32 v166, s6, v154
	ds_read_b128 v[146:149], v166
	ds_read_b128 v[158:161], v166 offset:1024
	ds_read_b128 v[162:165], v166 offset:2048
	ds_read_b128 v[166:169], v166 offset:3072
	s_add_u32 s52, s52, 0x40000
	s_addc_u32 s53, s53, 0
	s_mov_b32 m0, s68
	v_lshl_add_u64 v[218:219], s[52:53], 0, v[128:129]
	ds_read_b128 v[170:173], v157 offset:32768
	ds_read_b128 v[174:177], v157 offset:33792
	ds_read_b128 v[178:181], v157 offset:34816
	ds_read_b128 v[182:185], v157 offset:35840
	ds_read_b128 v[194:197], v157 offset:36864
	ds_read_b128 v[206:209], v157 offset:37888
	ds_read_b128 v[210:213], v157 offset:38912
	ds_read_b128 v[214:217], v157 offset:39936
	global_load_lds_dwordx4 v[218:219], off
	v_lshl_add_u64 v[218:219], s[52:53], 0, v[130:131]
	s_mov_b32 m0, s69
	s_nop 0
	global_load_lds_dwordx4 v[218:219], off
	s_add_i32 s19, 0, 0x1c000
	v_add_u32_e32 v192, s19, v154
	ds_read_b128 v[218:221], v192
	ds_read_b128 v[222:225], v192 offset:1024
	ds_read_b128 v[226:229], v192 offset:2048
	ds_read_b128 v[230:233], v192 offset:3072
	s_waitcnt vmcnt(8)
	s_waitcnt lgkmcnt(0)
	s_barrier
	v_mfma_f32_16x16x32_bf16 v[124:127], v[146:149], v[170:173], v[124:127]
	v_mfma_f32_16x16x32_bf16 v[120:123], v[162:165], v[170:173], v[120:123]
	v_mfma_f32_16x16x32_bf16 v[116:119], v[146:149], v[178:181], v[116:119]
	v_mfma_f32_16x16x32_bf16 v[112:115], v[162:165], v[178:181], v[112:115]
	v_mfma_f32_16x16x32_bf16 v[108:111], v[146:149], v[194:197], v[108:111]
	v_mfma_f32_16x16x32_bf16 v[104:107], v[162:165], v[194:197], v[104:107]
	v_mfma_f32_16x16x32_bf16 v[100:103], v[146:149], v[210:213], v[100:103]
	v_mfma_f32_16x16x32_bf16 v[96:99], v[162:165], v[210:213], v[96:99]
	v_mfma_f32_16x16x32_bf16 v[124:127], v[158:161], v[174:177], v[124:127]
	v_mfma_f32_16x16x32_bf16 v[120:123], v[166:169], v[174:177], v[120:123]
	v_mfma_f32_16x16x32_bf16 v[116:119], v[158:161], v[182:185], v[116:119]
	v_mfma_f32_16x16x32_bf16 v[112:115], v[166:169], v[182:185], v[112:115]
	v_mfma_f32_16x16x32_bf16 v[108:111], v[158:161], v[206:209], v[108:111]
	v_mfma_f32_16x16x32_bf16 v[104:107], v[166:169], v[206:209], v[104:107]
	v_mfma_f32_16x16x32_bf16 v[100:103], v[158:161], v[214:217], v[100:103]
	v_mfma_f32_16x16x32_bf16 v[96:99], v[166:169], v[214:217], v[96:99]
	v_mfma_f32_16x16x32_bf16 v[92:95], v[218:221], v[170:173], v[92:95]
	v_mfma_f32_16x16x32_bf16 v[88:91], v[226:229], v[170:173], v[88:91]
	v_mfma_f32_16x16x32_bf16 v[84:87], v[218:221], v[178:181], v[84:87]
	v_mfma_f32_16x16x32_bf16 v[80:83], v[226:229], v[178:181], v[80:83]
	v_mfma_f32_16x16x32_bf16 v[76:79], v[218:221], v[194:197], v[76:79]
	v_mfma_f32_16x16x32_bf16 v[72:75], v[226:229], v[194:197], v[72:75]
	v_mfma_f32_16x16x32_bf16 v[68:71], v[218:221], v[210:213], v[68:71]
	v_mfma_f32_16x16x32_bf16 v[64:67], v[226:229], v[210:213], v[64:67]
	v_mfma_f32_16x16x32_bf16 v[92:95], v[222:225], v[174:177], v[92:95]
	v_mfma_f32_16x16x32_bf16 v[88:91], v[230:233], v[174:177], v[88:91]
	v_mfma_f32_16x16x32_bf16 v[84:87], v[222:225], v[182:185], v[84:87]
	v_mfma_f32_16x16x32_bf16 v[80:83], v[230:233], v[182:185], v[80:83]
	v_mfma_f32_16x16x32_bf16 v[76:79], v[222:225], v[206:209], v[76:79]
	v_mfma_f32_16x16x32_bf16 v[72:75], v[230:233], v[206:209], v[72:75]
	v_mfma_f32_16x16x32_bf16 v[68:71], v[222:225], v[214:217], v[68:71]
	v_mfma_f32_16x16x32_bf16 v[64:67], v[230:233], v[214:217], v[64:67]
	s_barrier
	s_add_i32 s6, s6, s57
	v_lshl_add_u64 v[234:235], v[234:235], 0, s[36:37]
	s_mov_b32 m0, s6
	s_nop 0
	global_load_lds_dwordx4 v[234:235], off
	v_lshl_add_u64 v[234:235], v[236:237], 0, s[36:37]
	s_add_i32 m0, s6, 0x2000
	s_nop 0
	global_load_lds_dwordx4 v[234:235], off
	s_mov_b32 m0, s70
	v_lshl_add_u64 v[234:235], v[238:239], 0, s[36:37]
	ds_read_b128 v[170:173], v157 offset:49152
	ds_read_b128 v[174:177], v157 offset:50176
	ds_read_b128 v[178:181], v157 offset:51200
	ds_read_b128 v[182:185], v157 offset:52224
	ds_read_b128 v[194:197], v157 offset:53248
	ds_read_b128 v[206:209], v157 offset:54272
	ds_read_b128 v[210:213], v157 offset:55296
	ds_read_b128 v[214:217], v157 offset:56320
	global_load_lds_dwordx4 v[234:235], off
	v_lshl_add_u64 v[234:235], v[240:241], 0, s[36:37]
	s_mov_b32 m0, s71
	s_nop 0
	global_load_lds_dwordx4 v[234:235], off
	s_add_u32 s50, s50, 0x40080
	s_addc_u32 s51, s51, 0
	s_add_i32 s6, s19, s57
	v_lshl_add_u64 v[250:251], s[50:51], 0, v[140:141]
	s_mov_b32 m0, s6
	s_nop 0
	global_load_lds_dwordx4 v[250:251], off
	v_lshl_add_u64 v[250:251], s[50:51], 0, v[132:133]
	s_add_i32 m0, s6, 0x2000
	s_nop 0
	global_load_lds_dwordx4 v[250:251], off
	s_waitcnt vmcnt(8)
	s_waitcnt lgkmcnt(0)
	s_barrier
	v_mfma_f32_16x16x32_bf16 v[60:63], v[146:149], v[170:173], v[60:63]
	v_mfma_f32_16x16x32_bf16 v[56:59], v[162:165], v[170:173], v[56:59]
	v_mfma_f32_16x16x32_bf16 v[52:55], v[146:149], v[178:181], v[52:55]
	v_mfma_f32_16x16x32_bf16 v[48:51], v[162:165], v[178:181], v[48:51]
	v_mfma_f32_16x16x32_bf16 v[44:47], v[146:149], v[194:197], v[44:47]
	v_mfma_f32_16x16x32_bf16 v[40:43], v[162:165], v[194:197], v[40:43]
	v_mfma_f32_16x16x32_bf16 v[36:39], v[146:149], v[210:213], v[36:39]
	v_mfma_f32_16x16x32_bf16 v[32:35], v[162:165], v[210:213], v[32:35]
	v_mfma_f32_16x16x32_bf16 v[60:63], v[158:161], v[174:177], v[60:63]
	v_mfma_f32_16x16x32_bf16 v[56:59], v[166:169], v[174:177], v[56:59]
	v_mfma_f32_16x16x32_bf16 v[52:55], v[158:161], v[182:185], v[52:55]
	v_mfma_f32_16x16x32_bf16 v[48:51], v[166:169], v[182:185], v[48:51]
	v_mfma_f32_16x16x32_bf16 v[44:47], v[158:161], v[206:209], v[44:47]
	v_mfma_f32_16x16x32_bf16 v[40:43], v[166:169], v[206:209], v[40:43]
	v_mfma_f32_16x16x32_bf16 v[36:39], v[158:161], v[214:217], v[36:39]
	v_mfma_f32_16x16x32_bf16 v[32:35], v[166:169], v[214:217], v[32:35]
	v_mfma_f32_16x16x32_bf16 v[28:31], v[218:221], v[170:173], v[28:31]
	v_mfma_f32_16x16x32_bf16 v[24:27], v[226:229], v[170:173], v[24:27]
	v_mfma_f32_16x16x32_bf16 v[20:23], v[218:221], v[178:181], v[20:23]
	v_mfma_f32_16x16x32_bf16 v[16:19], v[226:229], v[178:181], v[16:19]
	v_mfma_f32_16x16x32_bf16 v[12:15], v[218:221], v[194:197], v[12:15]
	v_mfma_f32_16x16x32_bf16 v[8:11], v[226:229], v[194:197], v[8:11]
	v_mfma_f32_16x16x32_bf16 v[4:7], v[218:221], v[210:213], v[4:7]
	v_mfma_f32_16x16x32_bf16 v[0:3], v[226:229], v[210:213], v[0:3]
	v_mfma_f32_16x16x32_bf16 v[28:31], v[222:225], v[174:177], v[28:31]
	v_mfma_f32_16x16x32_bf16 v[24:27], v[230:233], v[174:177], v[24:27]
	v_mfma_f32_16x16x32_bf16 v[20:23], v[222:225], v[182:185], v[20:23]
	v_mfma_f32_16x16x32_bf16 v[16:19], v[230:233], v[182:185], v[16:19]
	v_mfma_f32_16x16x32_bf16 v[12:15], v[222:225], v[206:209], v[12:15]
	v_mfma_f32_16x16x32_bf16 v[8:11], v[230:233], v[206:209], v[8:11]
	v_mfma_f32_16x16x32_bf16 v[4:7], v[222:225], v[214:217], v[4:7]
	v_mfma_f32_16x16x32_bf16 v[0:3], v[230:233], v[214:217], v[0:3]
	s_add_i32 s75, s75, 2
	s_add_u32 s48, s48, 0x100
	s_addc_u32 s49, s49, 0
	s_cmp_gt_u32 s75, 13
	s_barrier
	s_cbranch_scc0 .LBB0_295
	s_mov_b32 s100, 1
	s_add_u32 s48, s10, 0xffffff00
	v_lshl_add_u32 v166, s73, 10, v155
	s_addc_u32 s49, s11, -1
	s_ashr_i32 s29, s28, 31
	v_lshl_or_b32 v146, s72, 8, v156
	ds_read2_b32 v[158:159], v166 offset1:16
	s_lshl_b64 s[10:11], s[28:29], 8
	v_ashrrev_i32_e32 v147, 31, v146
	v_lshl_add_u64 v[148:149], s[10:11], 0, v[134:135]
	v_lshl_add_u64 v[146:147], v[146:147], 1, s[26:27]
	v_mad_u64_u32 v[150:151], s[10:11], v148, s13, v[146:147]
	v_mov_b32_e32 v146, v151
	v_mad_u64_u32 v[152:153], s[10:11], v149, s13, v[146:147]
	s_waitcnt lgkmcnt(0)
	v_pk_mul_f32 v[148:149], v[126:127], v[158:159] op_sel_hi:[1,0]
	v_pk_mul_f32 v[146:147], v[124:125], v[158:159] op_sel_hi:[1,0]
	v_pk_mul_f32 v[160:161], v[122:123], v[158:159] op_sel_hi:[1,0]
	v_pk_mul_f32 v[162:163], v[120:121], v[158:159] op_sel_hi:[1,0]
	v_mov_b32_e32 v151, v152
	v_cvt_pk_bf16_f32 v146, v146, v147
	v_cvt_pk_bf16_f32 v147, v148, v149
	v_cvt_pk_bf16_f32 v148, v162, v163
	v_cvt_pk_bf16_f32 v149, v160, v161
	global_store_dwordx4 v[150:151], v[146:149], off
	v_pk_mul_f32 v[160:161], v[90:91], v[158:159] op_sel_hi:[1,0]
	v_pk_mul_f32 v[162:163], v[88:89], v[158:159] op_sel_hi:[1,0]
	v_pk_mul_f32 v[148:149], v[94:95], v[158:159] op_sel_hi:[1,0]
	v_pk_mul_f32 v[146:147], v[92:93], v[158:159] op_sel_hi:[1,0]
	v_mov_b32_e32 v158, v159
	v_cvt_pk_bf16_f32 v146, v146, v147
	v_cvt_pk_bf16_f32 v147, v148, v149
	v_cvt_pk_bf16_f32 v148, v162, v163
	v_cvt_pk_bf16_f32 v149, v160, v161
	global_store_dwordx4 v[150:151], v[146:149], off offset:256
	v_pk_mul_f32 v[160:161], v[114:115], v[158:159] op_sel_hi:[1,0]
	s_mov_b32 s6, 0x1e000
	v_pk_mul_f32 v[148:149], v[118:119], v[158:159] op_sel_hi:[1,0]
	v_pk_mul_f32 v[146:147], v[116:117], v[158:159] op_sel_hi:[1,0]
	ds_read2_b32 v[164:165], v166 offset0:32 offset1:48
	v_pk_mul_f32 v[162:163], v[112:113], v[158:159] op_sel_hi:[1,0]
	v_cvt_pk_bf16_f32 v146, v146, v147
	v_cvt_pk_bf16_f32 v147, v148, v149
	v_cvt_pk_bf16_f32 v149, v160, v161
	v_add_co_u32_e32 v160, vcc, s6, v150
	v_cvt_pk_bf16_f32 v148, v162, v163
	s_nop 0
	v_addc_co_u32_e32 v161, vcc, 0, v152, vcc
	global_store_dwordx4 v[160:161], v[146:149], off
	v_pk_mul_f32 v[162:163], v[82:83], v[158:159] op_sel_hi:[1,0]
	s_mov_b32 s6, 0x3c000
	v_pk_mul_f32 v[148:149], v[86:87], v[158:159] op_sel_hi:[1,0]
	v_pk_mul_f32 v[146:147], v[84:85], v[158:159] op_sel_hi:[1,0]
	v_pk_mul_f32 v[158:159], v[80:81], v[158:159] op_sel_hi:[1,0]
	v_cvt_pk_bf16_f32 v146, v146, v147
	v_cvt_pk_bf16_f32 v147, v148, v149
	v_cvt_pk_bf16_f32 v148, v158, v159
	v_cvt_pk_bf16_f32 v149, v162, v163
	global_store_dwordx4 v[160:161], v[146:149], off offset:256
	s_waitcnt lgkmcnt(0)
	v_pk_mul_f32 v[158:159], v[106:107], v[164:165] op_sel_hi:[1,0]
	v_pk_mul_f32 v[160:161], v[104:105], v[164:165] op_sel_hi:[1,0]
	v_pk_mul_f32 v[148:149], v[110:111], v[164:165] op_sel_hi:[1,0]
	v_pk_mul_f32 v[146:147], v[108:109], v[164:165] op_sel_hi:[1,0]
	v_pk_mul_f32 v[162:163], v[72:73], v[164:165] op_sel_hi:[1,0]
	v_cvt_pk_bf16_f32 v146, v146, v147
	v_cvt_pk_bf16_f32 v147, v148, v149
	v_cvt_pk_bf16_f32 v149, v158, v159
	v_add_co_u32_e32 v158, vcc, s6, v150
	v_cvt_pk_bf16_f32 v148, v160, v161
	s_nop 0
	v_addc_co_u32_e32 v159, vcc, 0, v152, vcc
	global_store_dwordx4 v[158:159], v[146:149], off
	v_pk_mul_f32 v[160:161], v[74:75], v[164:165] op_sel_hi:[1,0]
	s_mov_b32 s6, 0x5a000
	v_pk_mul_f32 v[148:149], v[78:79], v[164:165] op_sel_hi:[1,0]
	v_pk_mul_f32 v[146:147], v[76:77], v[164:165] op_sel_hi:[1,0]
	s_nop 0
	v_cvt_pk_bf16_f32 v146, v146, v147
	v_cvt_pk_bf16_f32 v147, v148, v149
	v_cvt_pk_bf16_f32 v148, v162, v163
	v_cvt_pk_bf16_f32 v149, v160, v161
	global_store_dwordx4 v[158:159], v[146:149], off offset:256
	v_mov_b32_e32 v158, v165
	v_pk_mul_f32 v[160:161], v[98:99], v[158:159] op_sel_hi:[1,0]
	v_pk_mul_f32 v[148:149], v[102:103], v[158:159] op_sel_hi:[1,0]
	v_pk_mul_f32 v[146:147], v[100:101], v[158:159] op_sel_hi:[1,0]
	ds_read2_b32 v[164:165], v166 offset0:128 offset1:144
	v_pk_mul_f32 v[162:163], v[96:97], v[158:159] op_sel_hi:[1,0]
	v_cvt_pk_bf16_f32 v146, v146, v147
	v_cvt_pk_bf16_f32 v147, v148, v149
	v_cvt_pk_bf16_f32 v149, v160, v161
	v_add_co_u32_e32 v160, vcc, s6, v150
	v_cvt_pk_bf16_f32 v148, v162, v163
	s_nop 0
	v_addc_co_u32_e32 v161, vcc, 0, v152, vcc
	global_store_dwordx4 v[160:161], v[146:149], off
	v_pk_mul_f32 v[162:163], v[66:67], v[158:159] op_sel_hi:[1,0]
	s_mov_b32 s6, 0xf0000
	v_pk_mul_f32 v[148:149], v[70:71], v[158:159] op_sel_hi:[1,0]
	v_pk_mul_f32 v[146:147], v[68:69], v[158:159] op_sel_hi:[1,0]
	v_pk_mul_f32 v[158:159], v[64:65], v[158:159] op_sel_hi:[1,0]
	v_cvt_pk_bf16_f32 v146, v146, v147
	v_cvt_pk_bf16_f32 v147, v148, v149
	v_cvt_pk_bf16_f32 v148, v158, v159
	v_cvt_pk_bf16_f32 v149, v162, v163
	global_store_dwordx4 v[160:161], v[146:149], off offset:256
	s_waitcnt lgkmcnt(0)
	v_pk_mul_f32 v[158:159], v[58:59], v[164:165] op_sel_hi:[1,0]
	v_pk_mul_f32 v[160:161], v[56:57], v[164:165] op_sel_hi:[1,0]
	v_pk_mul_f32 v[148:149], v[62:63], v[164:165] op_sel_hi:[1,0]
	v_pk_mul_f32 v[146:147], v[60:61], v[164:165] op_sel_hi:[1,0]
	v_pk_mul_f32 v[162:163], v[24:25], v[164:165] op_sel_hi:[1,0]
	v_cvt_pk_bf16_f32 v146, v146, v147
	v_cvt_pk_bf16_f32 v147, v148, v149
	v_cvt_pk_bf16_f32 v149, v158, v159
	v_add_co_u32_e32 v158, vcc, s6, v150
	v_cvt_pk_bf16_f32 v148, v160, v161
	s_nop 0
	v_addc_co_u32_e32 v159, vcc, 0, v152, vcc
	global_store_dwordx4 v[158:159], v[146:149], off
	v_pk_mul_f32 v[160:161], v[26:27], v[164:165] op_sel_hi:[1,0]
	s_mov_b32 s6, 0x10e000
	v_pk_mul_f32 v[148:149], v[30:31], v[164:165] op_sel_hi:[1,0]
	v_pk_mul_f32 v[146:147], v[28:29], v[164:165] op_sel_hi:[1,0]
	s_nop 0
	v_cvt_pk_bf16_f32 v146, v146, v147
	v_cvt_pk_bf16_f32 v147, v148, v149
	v_cvt_pk_bf16_f32 v148, v162, v163
	v_cvt_pk_bf16_f32 v149, v160, v161
	global_store_dwordx4 v[158:159], v[146:149], off offset:256
	v_mov_b32_e32 v158, v165
	v_pk_mul_f32 v[160:161], v[50:51], v[158:159] op_sel_hi:[1,0]
	v_pk_mul_f32 v[148:149], v[54:55], v[158:159] op_sel_hi:[1,0]
	v_pk_mul_f32 v[146:147], v[52:53], v[158:159] op_sel_hi:[1,0]
	ds_read2_b32 v[164:165], v166 offset0:160 offset1:176
	v_pk_mul_f32 v[162:163], v[48:49], v[158:159] op_sel_hi:[1,0]
	v_cvt_pk_bf16_f32 v146, v146, v147
	v_cvt_pk_bf16_f32 v147, v148, v149
	v_cvt_pk_bf16_f32 v149, v160, v161
	v_add_co_u32_e32 v160, vcc, s6, v150
	v_cvt_pk_bf16_f32 v148, v162, v163
	s_nop 0
	v_addc_co_u32_e32 v161, vcc, 0, v152, vcc
	global_store_dwordx4 v[160:161], v[146:149], off
	v_pk_mul_f32 v[162:163], v[18:19], v[158:159] op_sel_hi:[1,0]
	s_mov_b32 s6, 0x12c000
	v_pk_mul_f32 v[148:149], v[22:23], v[158:159] op_sel_hi:[1,0]
	v_pk_mul_f32 v[146:147], v[20:21], v[158:159] op_sel_hi:[1,0]
	v_pk_mul_f32 v[158:159], v[16:17], v[158:159] op_sel_hi:[1,0]
	v_cvt_pk_bf16_f32 v146, v146, v147
	v_cvt_pk_bf16_f32 v147, v148, v149
	v_cvt_pk_bf16_f32 v148, v158, v159
	v_cvt_pk_bf16_f32 v149, v162, v163
	global_store_dwordx4 v[160:161], v[146:149], off offset:256
	s_waitcnt lgkmcnt(0)
	v_pk_mul_f32 v[158:159], v[42:43], v[164:165] op_sel_hi:[1,0]
	v_pk_mul_f32 v[160:161], v[40:41], v[164:165] op_sel_hi:[1,0]
	v_pk_mul_f32 v[148:149], v[46:47], v[164:165] op_sel_hi:[1,0]
	v_pk_mul_f32 v[146:147], v[44:45], v[164:165] op_sel_hi:[1,0]
	v_pk_mul_f32 v[162:163], v[8:9], v[164:165] op_sel_hi:[1,0]
	v_cvt_pk_bf16_f32 v146, v146, v147
	v_cvt_pk_bf16_f32 v147, v148, v149
	v_cvt_pk_bf16_f32 v149, v158, v159
	v_add_co_u32_e32 v158, vcc, s6, v150
	v_cvt_pk_bf16_f32 v148, v160, v161
	s_nop 0
	v_addc_co_u32_e32 v159, vcc, 0, v152, vcc
	global_store_dwordx4 v[158:159], v[146:149], off
	v_pk_mul_f32 v[160:161], v[10:11], v[164:165] op_sel_hi:[1,0]
	s_mov_b32 s6, 0x14a000
	v_pk_mul_f32 v[148:149], v[14:15], v[164:165] op_sel_hi:[1,0]
	v_pk_mul_f32 v[146:147], v[12:13], v[164:165] op_sel_hi:[1,0]
	v_add_co_u32_e32 v150, vcc, s6, v150
	v_cvt_pk_bf16_f32 v146, v146, v147
	v_cvt_pk_bf16_f32 v147, v148, v149
	v_cvt_pk_bf16_f32 v148, v162, v163
	v_cvt_pk_bf16_f32 v149, v160, v161
	global_store_dwordx4 v[158:159], v[146:149], off offset:256
	v_mov_b32_e32 v158, v165
	v_pk_mul_f32 v[160:161], v[34:35], v[158:159] op_sel_hi:[1,0]
	v_pk_mul_f32 v[148:149], v[38:39], v[158:159] op_sel_hi:[1,0]
	v_pk_mul_f32 v[146:147], v[36:37], v[158:159] op_sel_hi:[1,0]
	v_pk_mul_f32 v[162:163], v[32:33], v[158:159] op_sel_hi:[1,0]
	v_cvt_pk_bf16_f32 v146, v146, v147
	v_cvt_pk_bf16_f32 v147, v148, v149
	v_cvt_pk_bf16_f32 v148, v162, v163
	v_cvt_pk_bf16_f32 v149, v160, v161
	v_addc_co_u32_e32 v151, vcc, 0, v152, vcc
	global_store_dwordx4 v[150:151], v[146:149], off
	v_pk_mul_f32 v[152:153], v[2:3], v[158:159] op_sel_hi:[1,0]
	s_andn2_b64 vcc, exec, s[44:45]
	v_pk_mul_f32 v[148:149], v[6:7], v[158:159] op_sel_hi:[1,0]
	v_pk_mul_f32 v[146:147], v[4:5], v[158:159] op_sel_hi:[1,0]
	v_pk_mul_f32 v[158:159], v[0:1], v[158:159] op_sel_hi:[1,0]
	v_cvt_pk_bf16_f32 v146, v146, v147
	v_cvt_pk_bf16_f32 v147, v148, v149
	v_cvt_pk_bf16_f32 v148, v158, v159
	v_cvt_pk_bf16_f32 v149, v152, v153
	global_store_dwordx4 v[150:151], v[146:149], off offset:256
	s_cbranch_vccz .LBB0_291
	s_mov_b64 s[38:39], s[48:49]
	s_andn2_b64 vcc, exec, s[42:43]
	s_mov_b64 s[48:49], s[38:39]
	s_cbranch_vccnz .LBB0_292

.Lm4ap_315:
	s_waitcnt lgkmcnt(0)
	s_barrier
	v_mfma_f32_16x16x32_bf16 v[124:127], v[146:149], v[170:173], 0
	v_mfma_f32_16x16x32_bf16 v[120:123], v[162:165], v[170:173], 0
	v_mfma_f32_16x16x32_bf16 v[116:119], v[146:149], v[178:181], 0
	v_mfma_f32_16x16x32_bf16 v[112:115], v[162:165], v[178:181], 0
	v_mfma_f32_16x16x32_bf16 v[108:111], v[146:149], v[194:197], 0
	v_mfma_f32_16x16x32_bf16 v[104:107], v[162:165], v[194:197], 0
	v_mfma_f32_16x16x32_bf16 v[100:103], v[146:149], v[210:213], 0
	v_mfma_f32_16x16x32_bf16 v[96:99], v[162:165], v[210:213], 0
	v_mfma_f32_16x16x32_bf16 v[124:127], v[158:161], v[174:177], v[124:127]
	v_mfma_f32_16x16x32_bf16 v[120:123], v[166:169], v[174:177], v[120:123]
	v_mfma_f32_16x16x32_bf16 v[116:119], v[158:161], v[182:185], v[116:119]
	v_mfma_f32_16x16x32_bf16 v[112:115], v[166:169], v[182:185], v[112:115]
	v_mfma_f32_16x16x32_bf16 v[108:111], v[158:161], v[206:209], v[108:111]
	v_mfma_f32_16x16x32_bf16 v[104:107], v[166:169], v[206:209], v[104:107]
	v_mfma_f32_16x16x32_bf16 v[100:103], v[158:161], v[214:217], v[100:103]
	v_mfma_f32_16x16x32_bf16 v[96:99], v[166:169], v[214:217], v[96:99]
	v_mfma_f32_16x16x32_bf16 v[92:95], v[218:221], v[170:173], 0
	v_mfma_f32_16x16x32_bf16 v[88:91], v[226:229], v[170:173], 0
	v_mfma_f32_16x16x32_bf16 v[84:87], v[218:221], v[178:181], 0
	v_mfma_f32_16x16x32_bf16 v[80:83], v[226:229], v[178:181], 0
	v_mfma_f32_16x16x32_bf16 v[76:79], v[218:221], v[194:197], 0
	v_mfma_f32_16x16x32_bf16 v[72:75], v[226:229], v[194:197], 0
	v_mfma_f32_16x16x32_bf16 v[68:71], v[218:221], v[210:213], 0
	v_mfma_f32_16x16x32_bf16 v[64:67], v[226:229], v[210:213], 0
	v_mfma_f32_16x16x32_bf16 v[92:95], v[222:225], v[174:177], v[92:95]
	v_mfma_f32_16x16x32_bf16 v[88:91], v[230:233], v[174:177], v[88:91]
	v_mfma_f32_16x16x32_bf16 v[84:87], v[222:225], v[182:185], v[84:87]
	v_mfma_f32_16x16x32_bf16 v[80:83], v[230:233], v[182:185], v[80:83]
	v_mfma_f32_16x16x32_bf16 v[76:79], v[222:225], v[206:209], v[76:79]
	v_mfma_f32_16x16x32_bf16 v[72:75], v[230:233], v[206:209], v[72:75]
	v_mfma_f32_16x16x32_bf16 v[68:71], v[222:225], v[214:217], v[68:71]
	v_mfma_f32_16x16x32_bf16 v[64:67], v[230:233], v[214:217], v[64:67]
	s_barrier
	s_add_i32 s19, s80, s57
	v_lshl_add_u64 v[234:235], s[50:51], 0, v[140:141]
	s_mov_b32 m0, s19
	s_nop 0
	global_load_lds_dwordx4 v[234:235], off
	v_lshl_add_u64 v[236:237], s[50:51], 0, v[132:133]
	s_add_i32 m0, s19, 0x2000
	s_nop 0
	global_load_lds_dwordx4 v[236:237], off
	s_mov_b32 m0, s58
	v_lshl_add_u64 v[238:239], s[52:53], 0, v[128:129]
	ds_read_b128 v[170:173], v156 offset:16384
	ds_read_b128 v[174:177], v156 offset:17408
	ds_read_b128 v[178:181], v156 offset:18432
	ds_read_b128 v[182:185], v156 offset:19456
	ds_read_b128 v[194:197], v156 offset:20480
	ds_read_b128 v[206:209], v156 offset:21504
	ds_read_b128 v[210:213], v156 offset:22528
	ds_read_b128 v[214:217], v156 offset:23552
	global_load_lds_dwordx4 v[238:239], off
	v_lshl_add_u64 v[240:241], s[52:53], 0, v[130:131]
	s_mov_b32 m0, s59
	s_nop 0
	global_load_lds_dwordx4 v[240:241], off
	s_add_u32 s80, s50, 0x40000
	s_addc_u32 s81, s51, 0
	s_add_i32 s6, s6, s57
	v_lshl_add_u64 v[250:251], s[80:81], 0, v[140:141]
	s_mov_b32 m0, s6
	s_nop 0
	global_load_lds_dwordx4 v[250:251], off
	v_lshl_add_u64 v[250:251], s[80:81], 0, v[132:133]
	s_add_i32 m0, s6, 0x2000
	s_nop 0
	global_load_lds_dwordx4 v[250:251], off
	s_waitcnt vmcnt(24)
	s_cmp_lg_u32 s100, 0
	s_cbranch_scc1 .Lm4bp_315
	s_waitcnt vmcnt(8)
.Lm4bp_315:
	s_waitcnt lgkmcnt(0)
	s_mov_b32 s100, 0
	s_barrier
	v_mfma_f32_16x16x32_bf16 v[60:63], v[146:149], v[170:173], 0
	v_mfma_f32_16x16x32_bf16 v[56:59], v[162:165], v[170:173], 0
	v_mfma_f32_16x16x32_bf16 v[52:55], v[146:149], v[178:181], 0
	v_mfma_f32_16x16x32_bf16 v[48:51], v[162:165], v[178:181], 0
	v_mfma_f32_16x16x32_bf16 v[44:47], v[146:149], v[194:197], 0
	v_mfma_f32_16x16x32_bf16 v[40:43], v[162:165], v[194:197], 0
	v_mfma_f32_16x16x32_bf16 v[36:39], v[146:149], v[210:213], 0
	v_mfma_f32_16x16x32_bf16 v[32:35], v[162:165], v[210:213], 0
	v_mfma_f32_16x16x32_bf16 v[60:63], v[158:161], v[174:177], v[60:63]
	v_mfma_f32_16x16x32_bf16 v[56:59], v[166:169], v[174:177], v[56:59]
	v_mfma_f32_16x16x32_bf16 v[52:55], v[158:161], v[182:185], v[52:55]
	v_mfma_f32_16x16x32_bf16 v[48:51], v[166:169], v[182:185], v[48:51]
	v_mfma_f32_16x16x32_bf16 v[44:47], v[158:161], v[206:209], v[44:47]
	v_mfma_f32_16x16x32_bf16 v[40:43], v[166:169], v[206:209], v[40:43]
	v_mfma_f32_16x16x32_bf16 v[36:39], v[158:161], v[214:217], v[36:39]
	v_mfma_f32_16x16x32_bf16 v[32:35], v[166:169], v[214:217], v[32:35]
	v_mfma_f32_16x16x32_bf16 v[28:31], v[218:221], v[170:173], 0
	v_mfma_f32_16x16x32_bf16 v[24:27], v[226:229], v[170:173], 0
	v_mfma_f32_16x16x32_bf16 v[20:23], v[218:221], v[178:181], 0
	v_mfma_f32_16x16x32_bf16 v[16:19], v[226:229], v[178:181], 0
	v_mfma_f32_16x16x32_bf16 v[12:15], v[218:221], v[194:197], 0
	v_mfma_f32_16x16x32_bf16 v[8:11], v[226:229], v[194:197], 0
	v_mfma_f32_16x16x32_bf16 v[4:7], v[218:221], v[210:213], 0
	v_mfma_f32_16x16x32_bf16 v[0:3], v[226:229], v[210:213], 0
	v_mfma_f32_16x16x32_bf16 v[28:31], v[222:225], v[174:177], v[28:31]
	v_mfma_f32_16x16x32_bf16 v[24:27], v[230:233], v[174:177], v[24:27]
	v_mfma_f32_16x16x32_bf16 v[20:23], v[222:225], v[182:185], v[20:23]
	v_mfma_f32_16x16x32_bf16 v[16:19], v[230:233], v[182:185], v[16:19]
	v_mfma_f32_16x16x32_bf16 v[12:15], v[222:225], v[206:209], v[12:15]
	v_mfma_f32_16x16x32_bf16 v[8:11], v[230:233], v[206:209], v[8:11]
	v_mfma_f32_16x16x32_bf16 v[4:7], v[222:225], v[214:217], v[4:7]
	v_mfma_f32_16x16x32_bf16 v[0:3], v[230:233], v[214:217], v[0:3]
	s_barrier
	s_add_i32 s6, 0, 0x18000
	v_add_u32_e32 v157, s6, v154
	ds_read_b128 v[146:149], v157
	ds_read_b128 v[158:161], v157 offset:1024
	ds_read_b128 v[162:165], v157 offset:2048
	ds_read_b128 v[166:169], v157 offset:3072
	s_add_u32 s52, s52, 0x40000
	s_addc_u32 s53, s53, 0
	s_mov_b32 m0, s68
	v_lshl_add_u64 v[218:219], s[52:53], 0, v[128:129]
	ds_read_b128 v[170:173], v156 offset:32768
	ds_read_b128 v[174:177], v156 offset:33792
	ds_read_b128 v[178:181], v156 offset:34816
	ds_read_b128 v[182:185], v156 offset:35840
	ds_read_b128 v[194:197], v156 offset:36864
	ds_read_b128 v[206:209], v156 offset:37888
	ds_read_b128 v[210:213], v156 offset:38912
	ds_read_b128 v[214:217], v156 offset:39936
	global_load_lds_dwordx4 v[218:219], off
	v_lshl_add_u64 v[218:219], s[52:53], 0, v[130:131]
	s_mov_b32 m0, s69
	s_nop 0
	global_load_lds_dwordx4 v[218:219], off
	s_add_i32 s19, 0, 0x1c000
	v_add_u32_e32 v157, s19, v154
	ds_read_b128 v[218:221], v157
	ds_read_b128 v[222:225], v157 offset:1024
	ds_read_b128 v[226:229], v157 offset:2048
	ds_read_b128 v[230:233], v157 offset:3072
	s_waitcnt vmcnt(8)
	s_waitcnt lgkmcnt(0)
	s_barrier
	v_mfma_f32_16x16x32_bf16 v[124:127], v[146:149], v[170:173], v[124:127]
	v_mfma_f32_16x16x32_bf16 v[120:123], v[162:165], v[170:173], v[120:123]
	v_mfma_f32_16x16x32_bf16 v[116:119], v[146:149], v[178:181], v[116:119]
	v_mfma_f32_16x16x32_bf16 v[112:115], v[162:165], v[178:181], v[112:115]
	v_mfma_f32_16x16x32_bf16 v[108:111], v[146:149], v[194:197], v[108:111]
	v_mfma_f32_16x16x32_bf16 v[104:107], v[162:165], v[194:197], v[104:107]
	v_mfma_f32_16x16x32_bf16 v[100:103], v[146:149], v[210:213], v[100:103]
	v_mfma_f32_16x16x32_bf16 v[96:99], v[162:165], v[210:213], v[96:99]
	v_mfma_f32_16x16x32_bf16 v[124:127], v[158:161], v[174:177], v[124:127]
	v_mfma_f32_16x16x32_bf16 v[120:123], v[166:169], v[174:177], v[120:123]
	v_mfma_f32_16x16x32_bf16 v[116:119], v[158:161], v[182:185], v[116:119]
	v_mfma_f32_16x16x32_bf16 v[112:115], v[166:169], v[182:185], v[112:115]
	v_mfma_f32_16x16x32_bf16 v[108:111], v[158:161], v[206:209], v[108:111]
	v_mfma_f32_16x16x32_bf16 v[104:107], v[166:169], v[206:209], v[104:107]
	v_mfma_f32_16x16x32_bf16 v[100:103], v[158:161], v[214:217], v[100:103]
	v_mfma_f32_16x16x32_bf16 v[96:99], v[166:169], v[214:217], v[96:99]
	v_mfma_f32_16x16x32_bf16 v[92:95], v[218:221], v[170:173], v[92:95]
	v_mfma_f32_16x16x32_bf16 v[88:91], v[226:229], v[170:173], v[88:91]
	v_mfma_f32_16x16x32_bf16 v[84:87], v[218:221], v[178:181], v[84:87]
	v_mfma_f32_16x16x32_bf16 v[80:83], v[226:229], v[178:181], v[80:83]
	v_mfma_f32_16x16x32_bf16 v[76:79], v[218:221], v[194:197], v[76:79]
	v_mfma_f32_16x16x32_bf16 v[72:75], v[226:229], v[194:197], v[72:75]
	v_mfma_f32_16x16x32_bf16 v[68:71], v[218:221], v[210:213], v[68:71]
	v_mfma_f32_16x16x32_bf16 v[64:67], v[226:229], v[210:213], v[64:67]
	v_mfma_f32_16x16x32_bf16 v[92:95], v[222:225], v[174:177], v[92:95]
	v_mfma_f32_16x16x32_bf16 v[88:91], v[230:233], v[174:177], v[88:91]
	v_mfma_f32_16x16x32_bf16 v[84:87], v[222:225], v[182:185], v[84:87]
	v_mfma_f32_16x16x32_bf16 v[80:83], v[230:233], v[182:185], v[80:83]
	v_mfma_f32_16x16x32_bf16 v[76:79], v[222:225], v[206:209], v[76:79]
	v_mfma_f32_16x16x32_bf16 v[72:75], v[230:233], v[206:209], v[72:75]
	v_mfma_f32_16x16x32_bf16 v[68:71], v[222:225], v[214:217], v[68:71]
	v_mfma_f32_16x16x32_bf16 v[64:67], v[230:233], v[214:217], v[64:67]
	s_barrier
	s_add_i32 s6, s6, s57
	v_lshl_add_u64 v[234:235], v[234:235], 0, s[36:37]
	s_mov_b32 m0, s6
	s_nop 0
	global_load_lds_dwordx4 v[234:235], off
	v_lshl_add_u64 v[234:235], v[236:237], 0, s[36:37]
	s_add_i32 m0, s6, 0x2000
	s_nop 0
	global_load_lds_dwordx4 v[234:235], off
	s_mov_b32 m0, s71
	v_lshl_add_u64 v[234:235], v[238:239], 0, s[36:37]
	ds_read_b128 v[170:173], v156 offset:49152
	ds_read_b128 v[174:177], v156 offset:50176
	ds_read_b128 v[178:181], v156 offset:51200
	ds_read_b128 v[182:185], v156 offset:52224
	ds_read_b128 v[194:197], v156 offset:53248
	ds_read_b128 v[206:209], v156 offset:54272
	ds_read_b128 v[210:213], v156 offset:55296
	ds_read_b128 v[214:217], v156 offset:56320
	global_load_lds_dwordx4 v[234:235], off
	v_lshl_add_u64 v[234:235], v[240:241], 0, s[36:37]
	s_mov_b32 m0, s72
	s_nop 0
	global_load_lds_dwordx4 v[234:235], off
	s_add_u32 s50, s50, 0x40080
	s_addc_u32 s51, s51, 0
	s_add_i32 s6, s19, s57
	v_lshl_add_u64 v[250:251], s[50:51], 0, v[140:141]
	s_mov_b32 m0, s6
	s_nop 0
	global_load_lds_dwordx4 v[250:251], off
	v_lshl_add_u64 v[250:251], s[50:51], 0, v[132:133]
	s_add_i32 m0, s6, 0x2000
	s_nop 0
	global_load_lds_dwordx4 v[250:251], off
	s_waitcnt vmcnt(8)
	s_waitcnt lgkmcnt(0)
	s_barrier
	v_mfma_f32_16x16x32_bf16 v[60:63], v[146:149], v[170:173], v[60:63]
	v_mfma_f32_16x16x32_bf16 v[56:59], v[162:165], v[170:173], v[56:59]
	v_mfma_f32_16x16x32_bf16 v[52:55], v[146:149], v[178:181], v[52:55]
	v_mfma_f32_16x16x32_bf16 v[48:51], v[162:165], v[178:181], v[48:51]
	v_mfma_f32_16x16x32_bf16 v[44:47], v[146:149], v[194:197], v[44:47]
	v_mfma_f32_16x16x32_bf16 v[40:43], v[162:165], v[194:197], v[40:43]
	v_mfma_f32_16x16x32_bf16 v[36:39], v[146:149], v[210:213], v[36:39]
	v_mfma_f32_16x16x32_bf16 v[32:35], v[162:165], v[210:213], v[32:35]
	v_mfma_f32_16x16x32_bf16 v[60:63], v[158:161], v[174:177], v[60:63]
	v_mfma_f32_16x16x32_bf16 v[56:59], v[166:169], v[174:177], v[56:59]
	v_mfma_f32_16x16x32_bf16 v[52:55], v[158:161], v[182:185], v[52:55]
	v_mfma_f32_16x16x32_bf16 v[48:51], v[166:169], v[182:185], v[48:51]
	v_mfma_f32_16x16x32_bf16 v[44:47], v[158:161], v[206:209], v[44:47]
	v_mfma_f32_16x16x32_bf16 v[40:43], v[166:169], v[206:209], v[40:43]
	v_mfma_f32_16x16x32_bf16 v[36:39], v[158:161], v[214:217], v[36:39]
	v_mfma_f32_16x16x32_bf16 v[32:35], v[166:169], v[214:217], v[32:35]
	v_mfma_f32_16x16x32_bf16 v[28:31], v[218:221], v[170:173], v[28:31]
	v_mfma_f32_16x16x32_bf16 v[24:27], v[226:229], v[170:173], v[24:27]
	v_mfma_f32_16x16x32_bf16 v[20:23], v[218:221], v[178:181], v[20:23]
	v_mfma_f32_16x16x32_bf16 v[16:19], v[226:229], v[178:181], v[16:19]
	v_mfma_f32_16x16x32_bf16 v[12:15], v[218:221], v[194:197], v[12:15]
	v_mfma_f32_16x16x32_bf16 v[8:11], v[226:229], v[194:197], v[8:11]
	v_mfma_f32_16x16x32_bf16 v[4:7], v[218:221], v[210:213], v[4:7]
	v_mfma_f32_16x16x32_bf16 v[0:3], v[226:229], v[210:213], v[0:3]
	v_mfma_f32_16x16x32_bf16 v[28:31], v[222:225], v[174:177], v[28:31]
	v_mfma_f32_16x16x32_bf16 v[24:27], v[230:233], v[174:177], v[24:27]
	v_mfma_f32_16x16x32_bf16 v[20:23], v[222:225], v[182:185], v[20:23]
	v_mfma_f32_16x16x32_bf16 v[16:19], v[230:233], v[182:185], v[16:19]
	v_mfma_f32_16x16x32_bf16 v[12:15], v[222:225], v[206:209], v[12:15]
	v_mfma_f32_16x16x32_bf16 v[8:11], v[230:233], v[206:209], v[8:11]
	v_mfma_f32_16x16x32_bf16 v[4:7], v[222:225], v[214:217], v[4:7]
	v_mfma_f32_16x16x32_bf16 v[0:3], v[230:233], v[214:217], v[0:3]
	s_add_i32 s75, s75, 2
	s_add_u32 s48, s48, 0x100
	s_addc_u32 s49, s49, 0
	s_cmp_gt_u32 s75, 13
	s_barrier
.LBB0_315:
	s_add_u32 s6, s4, s48
	s_addc_u32 s19, s5, s49
	s_add_u32 s6, s6, 0x100
	s_addc_u32 s19, s19, 0
	s_add_u32 s23, s11, s48
	s_addc_u32 s50, s12, s49
	s_add_i32 s80, 0, 0x10000
	v_add_u32_e32 v157, s80, v154
	ds_read_b128 v[146:149], v157
	ds_read_b128 v[158:161], v157 offset:1024
	ds_read_b128 v[162:165], v157 offset:2048
	ds_read_b128 v[166:169], v157 offset:3072
	s_cmpk_eq_i32 s48, 0x700
	s_cselect_b32 s53, s29, s19
	s_cselect_b32 s52, s31, s6
	s_cselect_b32 s51, s35, s50
	s_cselect_b32 s50, s74, s23
	v_lshl_add_u64 v[218:219], v[150:151], 0, s[48:49]
	s_add_i32 m0, s58, 0xc000
	ds_read_b128 v[170:173], v156
	ds_read_b128 v[174:177], v156 offset:1024
	ds_read_b128 v[178:181], v156 offset:2048
	ds_read_b128 v[182:185], v156 offset:3072
	ds_read_b128 v[194:197], v156 offset:4096
	ds_read_b128 v[206:209], v156 offset:5120
	ds_read_b128 v[210:213], v156 offset:6144
	ds_read_b128 v[214:217], v156 offset:7168
	global_load_lds_dwordx4 v[218:219], off
	v_lshl_add_u64 v[218:219], v[152:153], 0, s[48:49]
	s_add_i32 m0, s58, 0xe000
	s_nop 0
	global_load_lds_dwordx4 v[218:219], off
	s_add_i32 s6, 0, 0x14000
	v_add_u32_e32 v157, s6, v154
	ds_read_b128 v[218:221], v157
	ds_read_b128 v[222:225], v157 offset:1024
	ds_read_b128 v[226:229], v157 offset:2048
	ds_read_b128 v[230:233], v157 offset:3072
	s_waitcnt vmcnt(8)
	s_waitcnt lgkmcnt(0)
	s_barrier
	v_mfma_f32_16x16x32_bf16 v[124:127], v[146:149], v[170:173], v[124:127]
	v_mfma_f32_16x16x32_bf16 v[120:123], v[162:165], v[170:173], v[120:123]
	v_mfma_f32_16x16x32_bf16 v[116:119], v[146:149], v[178:181], v[116:119]
	v_mfma_f32_16x16x32_bf16 v[112:115], v[162:165], v[178:181], v[112:115]
	v_mfma_f32_16x16x32_bf16 v[108:111], v[146:149], v[194:197], v[108:111]
	v_mfma_f32_16x16x32_bf16 v[104:107], v[162:165], v[194:197], v[104:107]
	v_mfma_f32_16x16x32_bf16 v[100:103], v[146:149], v[210:213], v[100:103]
	v_mfma_f32_16x16x32_bf16 v[96:99], v[162:165], v[210:213], v[96:99]
	v_mfma_f32_16x16x32_bf16 v[124:127], v[158:161], v[174:177], v[124:127]
	v_mfma_f32_16x16x32_bf16 v[120:123], v[166:169], v[174:177], v[120:123]
	v_mfma_f32_16x16x32_bf16 v[116:119], v[158:161], v[182:185], v[116:119]
	v_mfma_f32_16x16x32_bf16 v[112:115], v[166:169], v[182:185], v[112:115]
	v_mfma_f32_16x16x32_bf16 v[108:111], v[158:161], v[206:209], v[108:111]
	v_mfma_f32_16x16x32_bf16 v[104:107], v[166:169], v[206:209], v[104:107]
	v_mfma_f32_16x16x32_bf16 v[100:103], v[158:161], v[214:217], v[100:103]
	v_mfma_f32_16x16x32_bf16 v[96:99], v[166:169], v[214:217], v[96:99]
	v_mfma_f32_16x16x32_bf16 v[92:95], v[218:221], v[170:173], v[92:95]
	v_mfma_f32_16x16x32_bf16 v[88:91], v[226:229], v[170:173], v[88:91]
	v_mfma_f32_16x16x32_bf16 v[84:87], v[218:221], v[178:181], v[84:87]
	v_mfma_f32_16x16x32_bf16 v[80:83], v[226:229], v[178:181], v[80:83]
	v_mfma_f32_16x16x32_bf16 v[76:79], v[218:221], v[194:197], v[76:79]
	v_mfma_f32_16x16x32_bf16 v[72:75], v[226:229], v[194:197], v[72:75]
	v_mfma_f32_16x16x32_bf16 v[68:71], v[218:221], v[210:213], v[68:71]
	v_mfma_f32_16x16x32_bf16 v[64:67], v[226:229], v[210:213], v[64:67]
	v_mfma_f32_16x16x32_bf16 v[92:95], v[222:225], v[174:177], v[92:95]
	v_mfma_f32_16x16x32_bf16 v[88:91], v[230:233], v[174:177], v[88:91]
	v_mfma_f32_16x16x32_bf16 v[84:87], v[222:225], v[182:185], v[84:87]
	v_mfma_f32_16x16x32_bf16 v[80:83], v[230:233], v[182:185], v[80:83]
	v_mfma_f32_16x16x32_bf16 v[76:79], v[222:225], v[206:209], v[76:79]
	v_mfma_f32_16x16x32_bf16 v[72:75], v[230:233], v[206:209], v[72:75]
	v_mfma_f32_16x16x32_bf16 v[68:71], v[222:225], v[214:217], v[68:71]
	v_mfma_f32_16x16x32_bf16 v[64:67], v[230:233], v[214:217], v[64:67]
	s_barrier
	s_add_i32 s19, s80, s57
	v_lshl_add_u64 v[234:235], s[50:51], 0, v[140:141]
	s_mov_b32 m0, s19
	s_nop 0
	global_load_lds_dwordx4 v[234:235], off
	v_lshl_add_u64 v[236:237], s[50:51], 0, v[132:133]
	s_add_i32 m0, s19, 0x2000
	s_nop 0
	global_load_lds_dwordx4 v[236:237], off
	s_mov_b32 m0, s58
	v_lshl_add_u64 v[238:239], s[52:53], 0, v[128:129]
	ds_read_b128 v[170:173], v156 offset:16384
	ds_read_b128 v[174:177], v156 offset:17408
	ds_read_b128 v[178:181], v156 offset:18432
	ds_read_b128 v[182:185], v156 offset:19456
	ds_read_b128 v[194:197], v156 offset:20480
	ds_read_b128 v[206:209], v156 offset:21504
	ds_read_b128 v[210:213], v156 offset:22528
	ds_read_b128 v[214:217], v156 offset:23552
	global_load_lds_dwordx4 v[238:239], off
	v_lshl_add_u64 v[240:241], s[52:53], 0, v[130:131]
	s_mov_b32 m0, s59
	s_nop 0
	global_load_lds_dwordx4 v[240:241], off
	s_add_u32 s80, s50, 0x40000
	s_addc_u32 s81, s51, 0
	s_add_i32 s6, s6, s57
	v_lshl_add_u64 v[250:251], s[80:81], 0, v[140:141]
	s_mov_b32 m0, s6
	s_nop 0
	global_load_lds_dwordx4 v[250:251], off
	v_lshl_add_u64 v[250:251], s[80:81], 0, v[132:133]
	s_add_i32 m0, s6, 0x2000
	s_nop 0
	global_load_lds_dwordx4 v[250:251], off
	s_waitcnt vmcnt(8)
	s_waitcnt lgkmcnt(0)
	s_barrier
	v_mfma_f32_16x16x32_bf16 v[60:63], v[146:149], v[170:173], v[60:63]
	v_mfma_f32_16x16x32_bf16 v[56:59], v[162:165], v[170:173], v[56:59]
	v_mfma_f32_16x16x32_bf16 v[52:55], v[146:149], v[178:181], v[52:55]
	v_mfma_f32_16x16x32_bf16 v[48:51], v[162:165], v[178:181], v[48:51]
	v_mfma_f32_16x16x32_bf16 v[44:47], v[146:149], v[194:197], v[44:47]
	v_mfma_f32_16x16x32_bf16 v[40:43], v[162:165], v[194:197], v[40:43]
	v_mfma_f32_16x16x32_bf16 v[36:39], v[146:149], v[210:213], v[36:39]
	v_mfma_f32_16x16x32_bf16 v[32:35], v[162:165], v[210:213], v[32:35]
	v_mfma_f32_16x16x32_bf16 v[60:63], v[158:161], v[174:177], v[60:63]
	v_mfma_f32_16x16x32_bf16 v[56:59], v[166:169], v[174:177], v[56:59]
	v_mfma_f32_16x16x32_bf16 v[52:55], v[158:161], v[182:185], v[52:55]
	v_mfma_f32_16x16x32_bf16 v[48:51], v[166:169], v[182:185], v[48:51]
	v_mfma_f32_16x16x32_bf16 v[44:47], v[158:161], v[206:209], v[44:47]
	v_mfma_f32_16x16x32_bf16 v[40:43], v[166:169], v[206:209], v[40:43]
	v_mfma_f32_16x16x32_bf16 v[36:39], v[158:161], v[214:217], v[36:39]
	v_mfma_f32_16x16x32_bf16 v[32:35], v[166:169], v[214:217], v[32:35]
	v_mfma_f32_16x16x32_bf16 v[28:31], v[218:221], v[170:173], v[28:31]
	v_mfma_f32_16x16x32_bf16 v[24:27], v[226:229], v[170:173], v[24:27]
	v_mfma_f32_16x16x32_bf16 v[20:23], v[218:221], v[178:181], v[20:23]
	v_mfma_f32_16x16x32_bf16 v[16:19], v[226:229], v[178:181], v[16:19]
	v_mfma_f32_16x16x32_bf16 v[12:15], v[218:221], v[194:197], v[12:15]
	v_mfma_f32_16x16x32_bf16 v[8:11], v[226:229], v[194:197], v[8:11]
	v_mfma_f32_16x16x32_bf16 v[4:7], v[218:221], v[210:213], v[4:7]
	v_mfma_f32_16x16x32_bf16 v[0:3], v[226:229], v[210:213], v[0:3]
	v_mfma_f32_16x16x32_bf16 v[28:31], v[222:225], v[174:177], v[28:31]
	v_mfma_f32_16x16x32_bf16 v[24:27], v[230:233], v[174:177], v[24:27]
	v_mfma_f32_16x16x32_bf16 v[20:23], v[222:225], v[182:185], v[20:23]
	v_mfma_f32_16x16x32_bf16 v[16:19], v[230:233], v[182:185], v[16:19]
	v_mfma_f32_16x16x32_bf16 v[12:15], v[222:225], v[206:209], v[12:15]
	v_mfma_f32_16x16x32_bf16 v[8:11], v[230:233], v[206:209], v[8:11]
	v_mfma_f32_16x16x32_bf16 v[4:7], v[222:225], v[214:217], v[4:7]
	v_mfma_f32_16x16x32_bf16 v[0:3], v[230:233], v[214:217], v[0:3]
	s_barrier
	s_add_i32 s6, 0, 0x18000
	v_add_u32_e32 v157, s6, v154
	ds_read_b128 v[146:149], v157
	ds_read_b128 v[158:161], v157 offset:1024
	ds_read_b128 v[162:165], v157 offset:2048
	ds_read_b128 v[166:169], v157 offset:3072
	s_add_u32 s52, s52, 0x40000
	s_addc_u32 s53, s53, 0
	s_mov_b32 m0, s68
	v_lshl_add_u64 v[218:219], s[52:53], 0, v[128:129]
	ds_read_b128 v[170:173], v156 offset:32768
	ds_read_b128 v[174:177], v156 offset:33792
	ds_read_b128 v[178:181], v156 offset:34816
	ds_read_b128 v[182:185], v156 offset:35840
	ds_read_b128 v[194:197], v156 offset:36864
	ds_read_b128 v[206:209], v156 offset:37888
	ds_read_b128 v[210:213], v156 offset:38912
	ds_read_b128 v[214:217], v156 offset:39936
	global_load_lds_dwordx4 v[218:219], off
	v_lshl_add_u64 v[218:219], s[52:53], 0, v[130:131]
	s_mov_b32 m0, s69
	s_nop 0
	global_load_lds_dwordx4 v[218:219], off
	s_add_i32 s19, 0, 0x1c000
	v_add_u32_e32 v157, s19, v154
	ds_read_b128 v[218:221], v157
	ds_read_b128 v[222:225], v157 offset:1024
	ds_read_b128 v[226:229], v157 offset:2048
	ds_read_b128 v[230:233], v157 offset:3072
	s_waitcnt vmcnt(8)
	s_waitcnt lgkmcnt(0)
	s_barrier
	v_mfma_f32_16x16x32_bf16 v[124:127], v[146:149], v[170:173], v[124:127]
	v_mfma_f32_16x16x32_bf16 v[120:123], v[162:165], v[170:173], v[120:123]
	v_mfma_f32_16x16x32_bf16 v[116:119], v[146:149], v[178:181], v[116:119]
	v_mfma_f32_16x16x32_bf16 v[112:115], v[162:165], v[178:181], v[112:115]
	v_mfma_f32_16x16x32_bf16 v[108:111], v[146:149], v[194:197], v[108:111]
	v_mfma_f32_16x16x32_bf16 v[104:107], v[162:165], v[194:197], v[104:107]
	v_mfma_f32_16x16x32_bf16 v[100:103], v[146:149], v[210:213], v[100:103]
	v_mfma_f32_16x16x32_bf16 v[96:99], v[162:165], v[210:213], v[96:99]
	v_mfma_f32_16x16x32_bf16 v[124:127], v[158:161], v[174:177], v[124:127]
	v_mfma_f32_16x16x32_bf16 v[120:123], v[166:169], v[174:177], v[120:123]
	v_mfma_f32_16x16x32_bf16 v[116:119], v[158:161], v[182:185], v[116:119]
	v_mfma_f32_16x16x32_bf16 v[112:115], v[166:169], v[182:185], v[112:115]
	v_mfma_f32_16x16x32_bf16 v[108:111], v[158:161], v[206:209], v[108:111]
	v_mfma_f32_16x16x32_bf16 v[104:107], v[166:169], v[206:209], v[104:107]
	v_mfma_f32_16x16x32_bf16 v[100:103], v[158:161], v[214:217], v[100:103]
	v_mfma_f32_16x16x32_bf16 v[96:99], v[166:169], v[214:217], v[96:99]
	v_mfma_f32_16x16x32_bf16 v[92:95], v[218:221], v[170:173], v[92:95]
	v_mfma_f32_16x16x32_bf16 v[88:91], v[226:229], v[170:173], v[88:91]
	v_mfma_f32_16x16x32_bf16 v[84:87], v[218:221], v[178:181], v[84:87]
	v_mfma_f32_16x16x32_bf16 v[80:83], v[226:229], v[178:181], v[80:83]
	v_mfma_f32_16x16x32_bf16 v[76:79], v[218:221], v[194:197], v[76:79]
	v_mfma_f32_16x16x32_bf16 v[72:75], v[226:229], v[194:197], v[72:75]
	v_mfma_f32_16x16x32_bf16 v[68:71], v[218:221], v[210:213], v[68:71]
	v_mfma_f32_16x16x32_bf16 v[64:67], v[226:229], v[210:213], v[64:67]
	v_mfma_f32_16x16x32_bf16 v[92:95], v[222:225], v[174:177], v[92:95]
	v_mfma_f32_16x16x32_bf16 v[88:91], v[230:233], v[174:177], v[88:91]
	v_mfma_f32_16x16x32_bf16 v[84:87], v[222:225], v[182:185], v[84:87]
	v_mfma_f32_16x16x32_bf16 v[80:83], v[230:233], v[182:185], v[80:83]
	v_mfma_f32_16x16x32_bf16 v[76:79], v[222:225], v[206:209], v[76:79]
	v_mfma_f32_16x16x32_bf16 v[72:75], v[230:233], v[206:209], v[72:75]
	v_mfma_f32_16x16x32_bf16 v[68:71], v[222:225], v[214:217], v[68:71]
	v_mfma_f32_16x16x32_bf16 v[64:67], v[230:233], v[214:217], v[64:67]
	s_barrier
	s_add_i32 s6, s6, s57
	v_lshl_add_u64 v[234:235], v[234:235], 0, s[36:37]
	s_mov_b32 m0, s6
	s_nop 0
	global_load_lds_dwordx4 v[234:235], off
	v_lshl_add_u64 v[234:235], v[236:237], 0, s[36:37]
	s_add_i32 m0, s6, 0x2000
	s_nop 0
	global_load_lds_dwordx4 v[234:235], off
	s_mov_b32 m0, s71
	v_lshl_add_u64 v[234:235], v[238:239], 0, s[36:37]
	ds_read_b128 v[170:173], v156 offset:49152
	ds_read_b128 v[174:177], v156 offset:50176
	ds_read_b128 v[178:181], v156 offset:51200
	ds_read_b128 v[182:185], v156 offset:52224
	ds_read_b128 v[194:197], v156 offset:53248
	ds_read_b128 v[206:209], v156 offset:54272
	ds_read_b128 v[210:213], v156 offset:55296
	ds_read_b128 v[214:217], v156 offset:56320
	global_load_lds_dwordx4 v[234:235], off
	v_lshl_add_u64 v[234:235], v[240:241], 0, s[36:37]
	s_mov_b32 m0, s72
	s_nop 0
	global_load_lds_dwordx4 v[234:235], off
	s_add_u32 s50, s50, 0x40080
	s_addc_u32 s51, s51, 0
	s_add_i32 s6, s19, s57
	v_lshl_add_u64 v[250:251], s[50:51], 0, v[140:141]
	s_mov_b32 m0, s6
	s_nop 0
	global_load_lds_dwordx4 v[250:251], off
	v_lshl_add_u64 v[250:251], s[50:51], 0, v[132:133]
	s_add_i32 m0, s6, 0x2000
	s_nop 0
	global_load_lds_dwordx4 v[250:251], off
	s_waitcnt vmcnt(8)
	s_waitcnt lgkmcnt(0)
	s_barrier
	v_mfma_f32_16x16x32_bf16 v[60:63], v[146:149], v[170:173], v[60:63]
	v_mfma_f32_16x16x32_bf16 v[56:59], v[162:165], v[170:173], v[56:59]
	v_mfma_f32_16x16x32_bf16 v[52:55], v[146:149], v[178:181], v[52:55]
	v_mfma_f32_16x16x32_bf16 v[48:51], v[162:165], v[178:181], v[48:51]
	v_mfma_f32_16x16x32_bf16 v[44:47], v[146:149], v[194:197], v[44:47]
	v_mfma_f32_16x16x32_bf16 v[40:43], v[162:165], v[194:197], v[40:43]
	v_mfma_f32_16x16x32_bf16 v[36:39], v[146:149], v[210:213], v[36:39]
	v_mfma_f32_16x16x32_bf16 v[32:35], v[162:165], v[210:213], v[32:35]
	v_mfma_f32_16x16x32_bf16 v[60:63], v[158:161], v[174:177], v[60:63]
	v_mfma_f32_16x16x32_bf16 v[56:59], v[166:169], v[174:177], v[56:59]
	v_mfma_f32_16x16x32_bf16 v[52:55], v[158:161], v[182:185], v[52:55]
	v_mfma_f32_16x16x32_bf16 v[48:51], v[166:169], v[182:185], v[48:51]
	v_mfma_f32_16x16x32_bf16 v[44:47], v[158:161], v[206:209], v[44:47]
	v_mfma_f32_16x16x32_bf16 v[40:43], v[166:169], v[206:209], v[40:43]
	v_mfma_f32_16x16x32_bf16 v[36:39], v[158:161], v[214:217], v[36:39]
	v_mfma_f32_16x16x32_bf16 v[32:35], v[166:169], v[214:217], v[32:35]
	v_mfma_f32_16x16x32_bf16 v[28:31], v[218:221], v[170:173], v[28:31]
	v_mfma_f32_16x16x32_bf16 v[24:27], v[226:229], v[170:173], v[24:27]
	v_mfma_f32_16x16x32_bf16 v[20:23], v[218:221], v[178:181], v[20:23]
	v_mfma_f32_16x16x32_bf16 v[16:19], v[226:229], v[178:181], v[16:19]
	v_mfma_f32_16x16x32_bf16 v[12:15], v[218:221], v[194:197], v[12:15]
	v_mfma_f32_16x16x32_bf16 v[8:11], v[226:229], v[194:197], v[8:11]
	v_mfma_f32_16x16x32_bf16 v[4:7], v[218:221], v[210:213], v[4:7]
	v_mfma_f32_16x16x32_bf16 v[0:3], v[226:229], v[210:213], v[0:3]
	v_mfma_f32_16x16x32_bf16 v[28:31], v[222:225], v[174:177], v[28:31]
	v_mfma_f32_16x16x32_bf16 v[24:27], v[230:233], v[174:177], v[24:27]
	v_mfma_f32_16x16x32_bf16 v[20:23], v[222:225], v[182:185], v[20:23]
	v_mfma_f32_16x16x32_bf16 v[16:19], v[230:233], v[182:185], v[16:19]
	v_mfma_f32_16x16x32_bf16 v[12:15], v[222:225], v[206:209], v[12:15]
	v_mfma_f32_16x16x32_bf16 v[8:11], v[230:233], v[206:209], v[8:11]
	v_mfma_f32_16x16x32_bf16 v[4:7], v[222:225], v[214:217], v[4:7]
	v_mfma_f32_16x16x32_bf16 v[0:3], v[230:233], v[214:217], v[0:3]
	s_add_i32 s75, s75, 2
	s_add_u32 s48, s48, 0x100
	s_addc_u32 s49, s49, 0
	s_cmp_gt_u32 s75, 13
	s_barrier
	s_cbranch_scc0 .LBB0_315
	s_mov_b32 s100, 1
	s_add_u32 s48, s11, 0xffffff00
	v_lshl_or_b32 v146, s70, 8, v155
	s_addc_u32 s49, s12, -1
	s_ashr_i32 s29, s28, 31
	v_ashrrev_i32_e32 v147, 31, v146
	v_lshl_add_u64 v[146:147], v[146:147], 1, s[26:27]
	s_lshl_b64 s[50:51], s[28:29], 20
	v_lshl_add_u64 v[146:147], v[146:147], 0, s[50:51]
	v_lshl_add_u64 v[150:151], v[146:147], 0, v[134:135]
	v_cvt_pk_bf16_f32 v146, v124, v125
	v_cvt_pk_bf16_f32 v147, v126, v127
	v_cvt_pk_bf16_f32 v148, v120, v121
	v_cvt_pk_bf16_f32 v149, v122, v123
	global_store_dwordx4 v[150:151], v[146:149], off
	v_add_co_u32_e32 v152, vcc, s66, v150
	s_nop 0
	v_cvt_pk_bf16_f32 v146, v92, v93
	v_cvt_pk_bf16_f32 v147, v94, v95
	v_cvt_pk_bf16_f32 v148, v88, v89
	v_cvt_pk_bf16_f32 v149, v90, v91
	global_store_dwordx4 v[150:151], v[146:149], off offset:256
	v_addc_co_u32_e32 v153, vcc, 0, v151, vcc
	s_nop 0
	v_cvt_pk_bf16_f32 v146, v116, v117
	v_cvt_pk_bf16_f32 v147, v118, v119
	v_cvt_pk_bf16_f32 v148, v112, v113
	v_cvt_pk_bf16_f32 v149, v114, v115
	global_store_dwordx4 v[152:153], v[146:149], off
	s_mov_b32 s6, 0x20000
	s_nop 0
	v_cvt_pk_bf16_f32 v146, v84, v85
	v_cvt_pk_bf16_f32 v147, v86, v87
	v_cvt_pk_bf16_f32 v148, v80, v81
	v_cvt_pk_bf16_f32 v149, v82, v83
	global_store_dwordx4 v[152:153], v[146:149], off offset:256
	v_add_co_u32_e32 v152, vcc, s6, v150
	s_nop 0
	v_cvt_pk_bf16_f32 v146, v108, v109
	v_cvt_pk_bf16_f32 v147, v110, v111
	v_cvt_pk_bf16_f32 v148, v104, v105
	v_cvt_pk_bf16_f32 v149, v106, v107
	v_addc_co_u32_e32 v153, vcc, 0, v151, vcc
	global_store_dwordx4 v[152:153], v[146:149], off
	s_mov_b32 s6, 0x30000
	s_nop 0
	v_cvt_pk_bf16_f32 v146, v76, v77
	v_cvt_pk_bf16_f32 v147, v78, v79
	v_cvt_pk_bf16_f32 v148, v72, v73
	v_cvt_pk_bf16_f32 v149, v74, v75
	global_store_dwordx4 v[152:153], v[146:149], off offset:256
	v_add_co_u32_e32 v152, vcc, s6, v150
	s_nop 0
	v_cvt_pk_bf16_f32 v146, v100, v101
	v_cvt_pk_bf16_f32 v147, v102, v103
	v_cvt_pk_bf16_f32 v148, v96, v97
	v_cvt_pk_bf16_f32 v149, v98, v99
	v_addc_co_u32_e32 v153, vcc, 0, v151, vcc
	global_store_dwordx4 v[152:153], v[146:149], off
	s_mov_b32 s6, 0x80000
	s_nop 0
	v_cvt_pk_bf16_f32 v146, v68, v69
	v_cvt_pk_bf16_f32 v147, v70, v71
	v_cvt_pk_bf16_f32 v148, v64, v65
	v_cvt_pk_bf16_f32 v149, v66, v67
	global_store_dwordx4 v[152:153], v[146:149], off offset:256
	v_add_co_u32_e32 v152, vcc, s6, v150
	s_nop 0
	v_cvt_pk_bf16_f32 v146, v60, v61
	v_cvt_pk_bf16_f32 v147, v62, v63
	v_cvt_pk_bf16_f32 v148, v56, v57
	v_cvt_pk_bf16_f32 v149, v58, v59
	v_addc_co_u32_e32 v153, vcc, 0, v151, vcc
	global_store_dwordx4 v[152:153], v[146:149], off
	s_mov_b32 s6, 0x90000
	s_nop 0
	v_cvt_pk_bf16_f32 v146, v28, v29
	v_cvt_pk_bf16_f32 v147, v30, v31
	v_cvt_pk_bf16_f32 v148, v24, v25
	v_cvt_pk_bf16_f32 v149, v26, v27
	global_store_dwordx4 v[152:153], v[146:149], off offset:256
	v_add_co_u32_e32 v152, vcc, s6, v150
	s_nop 0
	v_cvt_pk_bf16_f32 v146, v52, v53
	v_cvt_pk_bf16_f32 v147, v54, v55
	v_cvt_pk_bf16_f32 v148, v48, v49
	v_cvt_pk_bf16_f32 v149, v50, v51
	v_addc_co_u32_e32 v153, vcc, 0, v151, vcc
	global_store_dwordx4 v[152:153], v[146:149], off
	s_mov_b32 s6, 0xa0000
	s_nop 0
	v_cvt_pk_bf16_f32 v146, v20, v21
	v_cvt_pk_bf16_f32 v147, v22, v23
	v_cvt_pk_bf16_f32 v148, v16, v17
	v_cvt_pk_bf16_f32 v149, v18, v19
	global_store_dwordx4 v[152:153], v[146:149], off offset:256
	v_add_co_u32_e32 v152, vcc, s6, v150
	s_nop 0
	v_cvt_pk_bf16_f32 v146, v44, v45
	v_cvt_pk_bf16_f32 v147, v46, v47
	v_cvt_pk_bf16_f32 v148, v40, v41
	v_cvt_pk_bf16_f32 v149, v42, v43
	v_addc_co_u32_e32 v153, vcc, 0, v151, vcc
	s_mov_b32 s6, 0xb0000
	global_store_dwordx4 v[152:153], v[146:149], off
	v_add_co_u32_e32 v150, vcc, s6, v150
	s_nop 0
	v_cvt_pk_bf16_f32 v146, v12, v13
	v_cvt_pk_bf16_f32 v147, v14, v15
	v_cvt_pk_bf16_f32 v148, v8, v9
	v_cvt_pk_bf16_f32 v149, v10, v11
	global_store_dwordx4 v[152:153], v[146:149], off offset:256
	v_addc_co_u32_e32 v151, vcc, 0, v151, vcc
	s_nop 0
	v_cvt_pk_bf16_f32 v146, v36, v37
	v_cvt_pk_bf16_f32 v147, v38, v39
	v_cvt_pk_bf16_f32 v148, v32, v33
	v_cvt_pk_bf16_f32 v149, v34, v35
	global_store_dwordx4 v[150:151], v[146:149], off
	s_andn2_b64 vcc, exec, s[44:45]
	s_nop 0
	v_cvt_pk_bf16_f32 v146, v4, v5
	v_cvt_pk_bf16_f32 v147, v6, v7
	v_cvt_pk_bf16_f32 v148, v0, v1
	v_cvt_pk_bf16_f32 v149, v2, v3
	global_store_dwordx4 v[150:151], v[146:149], off offset:256
	s_cbranch_vccz .LBB0_307
	s_mov_b64 s[42:43], s[48:49]
	s_andn2_b64 vcc, exec, s[38:39]
	s_mov_b64 s[48:49], s[42:43]
	s_cbranch_vccnz .LBB0_308

.LBB0_341:
	s_add_u32 s46, s50, 0x100
	s_addc_u32 s47, s51, 0
	s_add_i32 s6, 0, 0x10000
	v_add_u32_e32 v146, s6, v206
	ds_read_b128 v[128:131], v146
	ds_read_b128 v[132:135], v146 offset:1024
	ds_read_b128 v[136:139], v146 offset:2048
	ds_read_b128 v[146:149], v146 offset:3072
	s_cmp_eq_u32 s12, 40
	s_cselect_b32 s53, s31, s47
	s_cselect_b32 s52, s30, s46
	s_cselect_b32 s49, s35, s11
	s_cselect_b32 s48, s34, s10
	v_lshl_add_u64 v[214:215], s[50:51], 0, v[158:159]
	s_add_i32 m0, s58, 0xc000
	ds_read_b128 v[162:165], v208
	ds_read_b128 v[166:169], v208 offset:1024
	ds_read_b128 v[170:173], v208 offset:2048
	ds_read_b128 v[174:177], v208 offset:3072
	ds_read_b128 v[178:181], v208 offset:4096
	ds_read_b128 v[182:185], v208 offset:5120
	ds_read_b128 v[194:197], v208 offset:6144
	ds_read_b128 v[210:213], v208 offset:7168
	global_load_lds_dwordx4 v[214:215], off
	v_lshl_add_u64 v[214:215], s[50:51], 0, v[160:161]
	s_add_i32 m0, s58, 0xe000
	s_nop 0
	global_load_lds_dwordx4 v[214:215], off
	s_add_i32 s19, 0, 0x14000
	v_add_u32_e32 v192, s19, v206
	ds_read_b128 v[214:217], v192
	ds_read_b128 v[218:221], v192 offset:1024
	ds_read_b128 v[222:225], v192 offset:2048
	ds_read_b128 v[226:229], v192 offset:3072
	s_waitcnt vmcnt(8)
	s_waitcnt lgkmcnt(0)
	s_barrier
	v_mfma_f32_16x16x32_bf16 v[124:127], v[128:131], v[162:165], v[124:127]
	v_mfma_f32_16x16x32_bf16 v[120:123], v[136:139], v[162:165], v[120:123]
	v_mfma_f32_16x16x32_bf16 v[108:111], v[128:131], v[170:173], v[108:111]
	v_mfma_f32_16x16x32_bf16 v[104:107], v[136:139], v[170:173], v[104:107]
	v_mfma_f32_16x16x32_bf16 v[96:99], v[128:131], v[178:181], v[96:99]
	v_mfma_f32_16x16x32_bf16 v[88:91], v[136:139], v[178:181], v[88:91]
	v_mfma_f32_16x16x32_bf16 v[84:87], v[128:131], v[194:197], v[84:87]
	v_mfma_f32_16x16x32_bf16 v[80:83], v[136:139], v[194:197], v[80:83]
	v_mfma_f32_16x16x32_bf16 v[124:127], v[132:135], v[166:169], v[124:127]
	v_mfma_f32_16x16x32_bf16 v[120:123], v[146:149], v[166:169], v[120:123]
	v_mfma_f32_16x16x32_bf16 v[108:111], v[132:135], v[174:177], v[108:111]
	v_mfma_f32_16x16x32_bf16 v[104:107], v[146:149], v[174:177], v[104:107]
	v_mfma_f32_16x16x32_bf16 v[96:99], v[132:135], v[182:185], v[96:99]
	v_mfma_f32_16x16x32_bf16 v[88:91], v[146:149], v[182:185], v[88:91]
	v_mfma_f32_16x16x32_bf16 v[84:87], v[132:135], v[210:213], v[84:87]
	v_mfma_f32_16x16x32_bf16 v[80:83], v[146:149], v[210:213], v[80:83]
	v_mfma_f32_16x16x32_bf16 v[116:119], v[214:217], v[162:165], v[116:119]
	v_mfma_f32_16x16x32_bf16 v[112:115], v[222:225], v[162:165], v[112:115]
	v_mfma_f32_16x16x32_bf16 v[100:103], v[214:217], v[170:173], v[100:103]
	v_mfma_f32_16x16x32_bf16 v[92:95], v[222:225], v[170:173], v[92:95]
	v_mfma_f32_16x16x32_bf16 v[76:79], v[214:217], v[178:181], v[76:79]
	v_mfma_f32_16x16x32_bf16 v[72:75], v[222:225], v[178:181], v[72:75]
	v_mfma_f32_16x16x32_bf16 v[68:71], v[214:217], v[194:197], v[68:71]
	v_mfma_f32_16x16x32_bf16 v[64:67], v[222:225], v[194:197], v[64:67]
	v_mfma_f32_16x16x32_bf16 v[116:119], v[218:221], v[166:169], v[116:119]
	v_mfma_f32_16x16x32_bf16 v[112:115], v[226:229], v[166:169], v[112:115]
	v_mfma_f32_16x16x32_bf16 v[100:103], v[218:221], v[174:177], v[100:103]
	v_mfma_f32_16x16x32_bf16 v[92:95], v[226:229], v[174:177], v[92:95]
	v_mfma_f32_16x16x32_bf16 v[76:79], v[218:221], v[182:185], v[76:79]
	v_mfma_f32_16x16x32_bf16 v[72:75], v[226:229], v[182:185], v[72:75]
	v_mfma_f32_16x16x32_bf16 v[68:71], v[218:221], v[210:213], v[68:71]
	v_mfma_f32_16x16x32_bf16 v[64:67], v[226:229], v[210:213], v[64:67]
	s_barrier
	s_add_i32 s6, s6, s57
	v_lshl_add_u64 v[230:231], s[48:49], 0, v[140:141]
	s_mov_b32 m0, s6
	s_nop 0
	global_load_lds_dwordx4 v[230:231], off
	v_lshl_add_u64 v[232:233], s[48:49], 0, v[150:151]
	s_add_i32 m0, s6, 0x2000
	s_nop 0
	global_load_lds_dwordx4 v[232:233], off
	s_mov_b32 m0, s58
	v_lshl_add_u64 v[234:235], s[52:53], 0, v[154:155]
	ds_read_b128 v[162:165], v208 offset:16384
	ds_read_b128 v[166:169], v208 offset:17408
	ds_read_b128 v[170:173], v208 offset:18432
	ds_read_b128 v[174:177], v208 offset:19456
	ds_read_b128 v[178:181], v208 offset:20480
	ds_read_b128 v[182:185], v208 offset:21504
	ds_read_b128 v[194:197], v208 offset:22528
	ds_read_b128 v[210:213], v208 offset:23552
	global_load_lds_dwordx4 v[234:235], off
	v_lshl_add_u64 v[236:237], s[52:53], 0, v[152:153]
	s_mov_b32 m0, s59
	s_nop 0
	global_load_lds_dwordx4 v[236:237], off
	s_add_u32 s50, s48, 0xb0000
	s_addc_u32 s51, s49, 0
	s_add_i32 s6, s19, s57
	v_lshl_add_u64 v[250:251], s[50:51], 0, v[140:141]
	s_mov_b32 m0, s6
	s_nop 0
	global_load_lds_dwordx4 v[250:251], off
	v_lshl_add_u64 v[250:251], s[50:51], 0, v[150:151]
	s_add_i32 m0, s6, 0x2000
	s_nop 0
	global_load_lds_dwordx4 v[250:251], off
	s_waitcnt vmcnt(8)
	s_waitcnt lgkmcnt(0)
	s_barrier
	v_mfma_f32_16x16x32_bf16 v[60:63], v[128:131], v[162:165], v[60:63]
	v_mfma_f32_16x16x32_bf16 v[56:59], v[136:139], v[162:165], v[56:59]
	v_mfma_f32_16x16x32_bf16 v[48:51], v[128:131], v[170:173], v[48:51]
	v_mfma_f32_16x16x32_bf16 v[40:43], v[136:139], v[170:173], v[40:43]
	v_mfma_f32_16x16x32_bf16 v[32:35], v[128:131], v[178:181], v[32:35]
	v_mfma_f32_16x16x32_bf16 v[24:27], v[136:139], v[178:181], v[24:27]
	v_mfma_f32_16x16x32_bf16 v[16:19], v[128:131], v[194:197], v[16:19]
	v_mfma_f32_16x16x32_bf16 v[8:11], v[136:139], v[194:197], v[8:11]
	v_mfma_f32_16x16x32_bf16 v[60:63], v[132:135], v[166:169], v[60:63]
	v_mfma_f32_16x16x32_bf16 v[56:59], v[146:149], v[166:169], v[56:59]
	v_mfma_f32_16x16x32_bf16 v[48:51], v[132:135], v[174:177], v[48:51]
	v_mfma_f32_16x16x32_bf16 v[40:43], v[146:149], v[174:177], v[40:43]
	v_mfma_f32_16x16x32_bf16 v[32:35], v[132:135], v[182:185], v[32:35]
	v_mfma_f32_16x16x32_bf16 v[24:27], v[146:149], v[182:185], v[24:27]
	v_mfma_f32_16x16x32_bf16 v[16:19], v[132:135], v[210:213], v[16:19]
	v_mfma_f32_16x16x32_bf16 v[8:11], v[146:149], v[210:213], v[8:11]
	v_mfma_f32_16x16x32_bf16 v[52:55], v[214:217], v[162:165], v[52:55]
	v_mfma_f32_16x16x32_bf16 v[44:47], v[222:225], v[162:165], v[44:47]
	v_mfma_f32_16x16x32_bf16 v[36:39], v[214:217], v[170:173], v[36:39]
	v_mfma_f32_16x16x32_bf16 v[28:31], v[222:225], v[170:173], v[28:31]
	v_mfma_f32_16x16x32_bf16 v[20:23], v[214:217], v[178:181], v[20:23]
	v_mfma_f32_16x16x32_bf16 v[12:15], v[222:225], v[178:181], v[12:15]
	v_mfma_f32_16x16x32_bf16 v[4:7], v[214:217], v[194:197], v[4:7]
	v_mfma_f32_16x16x32_bf16 v[0:3], v[222:225], v[194:197], v[0:3]
	v_mfma_f32_16x16x32_bf16 v[52:55], v[218:221], v[166:169], v[52:55]
	v_mfma_f32_16x16x32_bf16 v[44:47], v[226:229], v[166:169], v[44:47]
	v_mfma_f32_16x16x32_bf16 v[36:39], v[218:221], v[174:177], v[36:39]
	v_mfma_f32_16x16x32_bf16 v[28:31], v[226:229], v[174:177], v[28:31]
	v_mfma_f32_16x16x32_bf16 v[20:23], v[218:221], v[182:185], v[20:23]
	v_mfma_f32_16x16x32_bf16 v[12:15], v[226:229], v[182:185], v[12:15]
	v_mfma_f32_16x16x32_bf16 v[4:7], v[218:221], v[210:213], v[4:7]
	v_mfma_f32_16x16x32_bf16 v[0:3], v[226:229], v[210:213], v[0:3]
	s_barrier
	s_add_i32 s6, 0, 0x18000
	v_add_u32_e32 v146, s6, v206
	ds_read_b128 v[128:131], v146
	ds_read_b128 v[132:135], v146 offset:1024
	ds_read_b128 v[136:139], v146 offset:2048
	ds_read_b128 v[146:149], v146 offset:3072
	s_add_u32 s50, s52, 0xb0000
	s_addc_u32 s51, s53, 0
	s_mov_b32 m0, s68
	v_lshl_add_u64 v[214:215], s[50:51], 0, v[154:155]
	ds_read_b128 v[162:165], v208 offset:32768
	ds_read_b128 v[166:169], v208 offset:33792
	ds_read_b128 v[170:173], v208 offset:34816
	ds_read_b128 v[174:177], v208 offset:35840
	ds_read_b128 v[178:181], v208 offset:36864
	ds_read_b128 v[182:185], v208 offset:37888
	ds_read_b128 v[194:197], v208 offset:38912
	ds_read_b128 v[210:213], v208 offset:39936
	global_load_lds_dwordx4 v[214:215], off
	v_lshl_add_u64 v[214:215], s[50:51], 0, v[152:153]
	s_mov_b32 m0, s69
	s_nop 0
	global_load_lds_dwordx4 v[214:215], off
	s_add_i32 s19, 0, 0x1c000
	v_add_u32_e32 v192, s19, v206
	ds_read_b128 v[214:217], v192
	ds_read_b128 v[218:221], v192 offset:1024
	ds_read_b128 v[222:225], v192 offset:2048
	ds_read_b128 v[226:229], v192 offset:3072
	s_waitcnt vmcnt(8)
	s_waitcnt lgkmcnt(0)
	s_barrier
	v_mfma_f32_16x16x32_bf16 v[124:127], v[128:131], v[162:165], v[124:127]
	v_mfma_f32_16x16x32_bf16 v[120:123], v[136:139], v[162:165], v[120:123]
	v_mfma_f32_16x16x32_bf16 v[108:111], v[128:131], v[170:173], v[108:111]
	v_mfma_f32_16x16x32_bf16 v[104:107], v[136:139], v[170:173], v[104:107]
	v_mfma_f32_16x16x32_bf16 v[96:99], v[128:131], v[178:181], v[96:99]
	v_mfma_f32_16x16x32_bf16 v[88:91], v[136:139], v[178:181], v[88:91]
	v_mfma_f32_16x16x32_bf16 v[84:87], v[128:131], v[194:197], v[84:87]
	v_mfma_f32_16x16x32_bf16 v[80:83], v[136:139], v[194:197], v[80:83]
	v_mfma_f32_16x16x32_bf16 v[124:127], v[132:135], v[166:169], v[124:127]
	v_mfma_f32_16x16x32_bf16 v[120:123], v[146:149], v[166:169], v[120:123]
	v_mfma_f32_16x16x32_bf16 v[108:111], v[132:135], v[174:177], v[108:111]
	v_mfma_f32_16x16x32_bf16 v[104:107], v[146:149], v[174:177], v[104:107]
	v_mfma_f32_16x16x32_bf16 v[96:99], v[132:135], v[182:185], v[96:99]
	v_mfma_f32_16x16x32_bf16 v[88:91], v[146:149], v[182:185], v[88:91]
	v_mfma_f32_16x16x32_bf16 v[84:87], v[132:135], v[210:213], v[84:87]
	v_mfma_f32_16x16x32_bf16 v[80:83], v[146:149], v[210:213], v[80:83]
	v_mfma_f32_16x16x32_bf16 v[116:119], v[214:217], v[162:165], v[116:119]
	v_mfma_f32_16x16x32_bf16 v[112:115], v[222:225], v[162:165], v[112:115]
	v_mfma_f32_16x16x32_bf16 v[100:103], v[214:217], v[170:173], v[100:103]
	v_mfma_f32_16x16x32_bf16 v[92:95], v[222:225], v[170:173], v[92:95]
	v_mfma_f32_16x16x32_bf16 v[76:79], v[214:217], v[178:181], v[76:79]
	v_mfma_f32_16x16x32_bf16 v[72:75], v[222:225], v[178:181], v[72:75]
	v_mfma_f32_16x16x32_bf16 v[68:71], v[214:217], v[194:197], v[68:71]
	v_mfma_f32_16x16x32_bf16 v[64:67], v[222:225], v[194:197], v[64:67]
	v_mfma_f32_16x16x32_bf16 v[116:119], v[218:221], v[166:169], v[116:119]
	v_mfma_f32_16x16x32_bf16 v[112:115], v[226:229], v[166:169], v[112:115]
	v_mfma_f32_16x16x32_bf16 v[100:103], v[218:221], v[174:177], v[100:103]
	v_mfma_f32_16x16x32_bf16 v[92:95], v[226:229], v[174:177], v[92:95]
	v_mfma_f32_16x16x32_bf16 v[76:79], v[218:221], v[182:185], v[76:79]
	v_mfma_f32_16x16x32_bf16 v[72:75], v[226:229], v[182:185], v[72:75]
	v_mfma_f32_16x16x32_bf16 v[68:71], v[218:221], v[210:213], v[68:71]
	v_mfma_f32_16x16x32_bf16 v[64:67], v[226:229], v[210:213], v[64:67]
	s_barrier
	s_add_i32 s6, s6, s57
	v_lshl_add_u64 v[230:231], v[230:231], 0, s[36:37]
	s_mov_b32 m0, s6
	s_nop 0
	global_load_lds_dwordx4 v[230:231], off
	v_lshl_add_u64 v[230:231], v[232:233], 0, s[36:37]
	s_add_i32 m0, s6, 0x2000
	s_nop 0
	global_load_lds_dwordx4 v[230:231], off
	s_mov_b32 m0, s70
	v_lshl_add_u64 v[230:231], v[234:235], 0, s[36:37]
	ds_read_b128 v[162:165], v208 offset:49152
	ds_read_b128 v[166:169], v208 offset:50176
	ds_read_b128 v[170:173], v208 offset:51200
	ds_read_b128 v[174:177], v208 offset:52224
	ds_read_b128 v[178:181], v208 offset:53248
	ds_read_b128 v[182:185], v208 offset:54272
	ds_read_b128 v[194:197], v208 offset:55296
	ds_read_b128 v[210:213], v208 offset:56320
	global_load_lds_dwordx4 v[230:231], off
	v_lshl_add_u64 v[230:231], v[236:237], 0, s[36:37]
	s_mov_b32 m0, s71
	s_nop 0
	global_load_lds_dwordx4 v[230:231], off
	s_add_u32 s48, s48, 0xb0080
	s_addc_u32 s49, s49, 0
	s_add_i32 s6, s19, s57
	v_lshl_add_u64 v[250:251], s[48:49], 0, v[140:141]
	s_mov_b32 m0, s6
	s_nop 0
	global_load_lds_dwordx4 v[250:251], off
	v_lshl_add_u64 v[250:251], s[48:49], 0, v[150:151]
	s_add_i32 m0, s6, 0x2000
	s_nop 0
	global_load_lds_dwordx4 v[250:251], off
	s_waitcnt vmcnt(8)
	s_waitcnt lgkmcnt(0)
	s_barrier
	v_mfma_f32_16x16x32_bf16 v[60:63], v[128:131], v[162:165], v[60:63]
	v_mfma_f32_16x16x32_bf16 v[56:59], v[136:139], v[162:165], v[56:59]
	v_mfma_f32_16x16x32_bf16 v[48:51], v[128:131], v[170:173], v[48:51]
	v_mfma_f32_16x16x32_bf16 v[40:43], v[136:139], v[170:173], v[40:43]
	v_mfma_f32_16x16x32_bf16 v[32:35], v[128:131], v[178:181], v[32:35]
	v_mfma_f32_16x16x32_bf16 v[24:27], v[136:139], v[178:181], v[24:27]
	v_mfma_f32_16x16x32_bf16 v[16:19], v[128:131], v[194:197], v[16:19]
	v_mfma_f32_16x16x32_bf16 v[8:11], v[136:139], v[194:197], v[8:11]
	v_mfma_f32_16x16x32_bf16 v[60:63], v[132:135], v[166:169], v[60:63]
	v_mfma_f32_16x16x32_bf16 v[56:59], v[146:149], v[166:169], v[56:59]
	v_mfma_f32_16x16x32_bf16 v[48:51], v[132:135], v[174:177], v[48:51]
	v_mfma_f32_16x16x32_bf16 v[40:43], v[146:149], v[174:177], v[40:43]
	v_mfma_f32_16x16x32_bf16 v[32:35], v[132:135], v[182:185], v[32:35]
	v_mfma_f32_16x16x32_bf16 v[24:27], v[146:149], v[182:185], v[24:27]
	v_mfma_f32_16x16x32_bf16 v[16:19], v[132:135], v[210:213], v[16:19]
	v_mfma_f32_16x16x32_bf16 v[8:11], v[146:149], v[210:213], v[8:11]
	v_mfma_f32_16x16x32_bf16 v[52:55], v[214:217], v[162:165], v[52:55]
	v_mfma_f32_16x16x32_bf16 v[44:47], v[222:225], v[162:165], v[44:47]
	v_mfma_f32_16x16x32_bf16 v[36:39], v[214:217], v[170:173], v[36:39]
	v_mfma_f32_16x16x32_bf16 v[28:31], v[222:225], v[170:173], v[28:31]
	v_mfma_f32_16x16x32_bf16 v[20:23], v[214:217], v[178:181], v[20:23]
	v_mfma_f32_16x16x32_bf16 v[12:15], v[222:225], v[178:181], v[12:15]
	v_mfma_f32_16x16x32_bf16 v[4:7], v[214:217], v[194:197], v[4:7]
	v_mfma_f32_16x16x32_bf16 v[0:3], v[222:225], v[194:197], v[0:3]
	v_mfma_f32_16x16x32_bf16 v[52:55], v[218:221], v[166:169], v[52:55]
	v_mfma_f32_16x16x32_bf16 v[44:47], v[226:229], v[166:169], v[44:47]
	v_mfma_f32_16x16x32_bf16 v[36:39], v[218:221], v[174:177], v[36:39]
	v_mfma_f32_16x16x32_bf16 v[28:31], v[226:229], v[174:177], v[28:31]
	v_mfma_f32_16x16x32_bf16 v[20:23], v[218:221], v[182:185], v[20:23]
	v_mfma_f32_16x16x32_bf16 v[12:15], v[226:229], v[182:185], v[12:15]
	v_mfma_f32_16x16x32_bf16 v[4:7], v[218:221], v[210:213], v[4:7]
	v_mfma_f32_16x16x32_bf16 v[0:3], v[226:229], v[210:213], v[0:3]
	s_add_i32 s12, s12, 2
	s_add_u32 s10, s10, 0x100
	s_addc_u32 s11, s11, 0
	s_cmp_gt_u32 s12, 41
	s_mov_b64 s[50:51], s[46:47]
	s_barrier
	s_cbranch_scc0 .LBB0_341
	s_mov_b32 s100, 1
	s_ashr_i32 s39, s38, 31
	v_lshl_or_b32 v128, s81, 8, v207
	s_lshl_b64 s[10:11], s[38:39], 8
	v_ashrrev_i32_e32 v129, 31, v128
	v_lshl_add_u64 v[168:169], s[10:11], 0, v[156:157]
	v_lshlrev_b64 v[170:171], 1, v[128:129]
	v_lshl_add_u64 v[174:175], s[26:27], 0, v[170:171]
	v_lshlrev_b64 v[172:173], 11, v[168:169]
	v_lshl_add_u64 v[128:129], v[174:175], 0, v[172:173]
	global_load_dwordx4 v[182:185], v[128:129], off
	global_load_dwordx4 v[210:213], v[128:129], off offset:256
	v_or_b32_e32 v166, 16, v168
	v_mov_b32_e32 v167, v169
	v_lshlrev_b64 v[176:177], 11, v[166:167]
	v_lshl_add_u64 v[128:129], v[174:175], 0, v[176:177]
	global_load_dwordx4 v[214:217], v[128:129], off
	global_load_dwordx4 v[218:221], v[128:129], off offset:256
	v_or_b32_e32 v164, 32, v168
	v_mov_b32_e32 v165, v169
	v_or_b32_e32 v162, 48, v168
	v_mov_b32_e32 v163, v169
	v_lshlrev_b64 v[180:181], 11, v[164:165]
	v_lshlrev_b64 v[178:179], 11, v[162:163]
	v_lshl_add_u64 v[128:129], v[174:175], 0, v[180:181]
	v_lshl_add_u64 v[130:131], v[174:175], 0, v[178:179]
	global_load_dwordx4 v[222:225], v[128:129], off
	global_load_dwordx4 v[136:139], v[128:129], off offset:256
	global_load_dwordx4 v[132:135], v[130:131], off
	s_nop 0
	global_load_dwordx4 v[128:131], v[130:131], off offset:256
	s_mov_b64 s[10:11], 0x90
	v_lshl_add_u64 v[172:173], s[28:29], 0, v[172:173]
	v_lshl_add_u64 v[172:173], v[172:173], 0, v[170:171]
	s_waitcnt vmcnt(0)
	v_lshlrev_b32_e32 v146, 16, v182
	v_and_b32_e32 v147, 0xffff0000, v182
	v_lshlrev_b32_e32 v148, 16, v184
	v_and_b32_e32 v149, 0xffff0000, v184
	v_lshlrev_b32_e32 v182, 16, v183
	v_and_b32_e32 v183, 0xffff0000, v183
	v_lshlrev_b32_e32 v194, 16, v210
	v_and_b32_e32 v195, 0xffff0000, v210
	v_lshlrev_b32_e32 v196, 16, v212
	v_and_b32_e32 v197, 0xffff0000, v212
	v_lshlrev_b32_e32 v210, 16, v211
	v_and_b32_e32 v211, 0xffff0000, v211
	v_lshlrev_b32_e32 v212, 16, v213
	v_and_b32_e32 v213, 0xffff0000, v213
	v_pk_fma_f32 v[124:125], v[124:125], 0.5, v[146:147] op_sel_hi:[1,0,1]
	v_pk_fma_f32 v[120:121], v[120:121], 0.5, v[148:149] op_sel_hi:[1,0,1]
	v_pk_fma_f32 v[126:127], v[126:127], 0.5, v[182:183] op_sel_hi:[1,0,1]
	v_pk_fma_f32 v[116:117], v[116:117], 0.5, v[194:195] op_sel_hi:[1,0,1]
	v_pk_fma_f32 v[146:147], v[112:113], 0.5, v[196:197] op_sel_hi:[1,0,1]
	v_pk_fma_f32 v[118:119], v[118:119], 0.5, v[210:211] op_sel_hi:[1,0,1]
	v_pk_fma_f32 v[148:149], v[114:115], 0.5, v[212:213] op_sel_hi:[1,0,1]
	v_pk_mul_f32 v[212:213], v[124:125], v[124:125]
	v_lshlrev_b32_e32 v182, 16, v214
	v_and_b32_e32 v183, 0xffff0000, v214
	v_lshlrev_b32_e32 v194, 16, v215
	v_and_b32_e32 v195, 0xffff0000, v215
	v_pk_mul_f32 v[214:215], v[126:127], v[126:127]
	v_cvt_pk_bf16_f32 v112, v124, v125
	v_cvt_pk_bf16_f32 v113, v126, v127
	v_pk_mul_f32 v[124:125], v[116:117], v[116:117]
	v_pk_mul_f32 v[126:127], v[118:119], v[118:119]
	v_pk_mul_f32 v[228:229], v[146:147], v[146:147]
	v_cvt_pk_bf16_f32 v116, v116, v117
	v_cvt_pk_bf16_f32 v117, v118, v119
	v_cvt_pk_bf16_f32 v118, v146, v147
	v_add_f32_e32 v146, v212, v213
	v_lshlrev_b32_e32 v184, 16, v185
	v_and_b32_e32 v185, 0xffff0000, v185
	v_add_f32_e32 v146, v214, v146
	v_pk_fma_f32 v[122:123], v[122:123], 0.5, v[184:185] op_sel_hi:[1,0,1]
	v_lshlrev_b32_e32 v184, 16, v216
	v_and_b32_e32 v185, 0xffff0000, v216
	v_lshlrev_b32_e32 v196, 16, v217
	v_and_b32_e32 v197, 0xffff0000, v217
	v_pk_mul_f32 v[216:217], v[120:121], v[120:121]
	v_add_f32_e32 v146, v215, v146
	v_add_f32_e32 v146, v216, v146
	v_pk_mul_f32 v[226:227], v[122:123], v[122:123]
	v_add_f32_e32 v146, v217, v146
	v_add_f32_e32 v146, v226, v146
	v_add_f32_e32 v146, v227, v146
	v_add_f32_e32 v124, v124, v146
	v_add_f32_e32 v124, v125, v124
	v_add_f32_e32 v124, v126, v124
	v_add_f32_e32 v124, v127, v124
	v_add_f32_e32 v124, v228, v124
	v_pk_mul_f32 v[230:231], v[148:149], v[148:149]
	v_add_f32_e32 v124, v229, v124
	v_add_f32_e32 v124, v230, v124
	v_add_f32_e32 v209, v231, v124
	v_lshlrev_b32_e32 v124, 16, v220
	v_and_b32_e32 v125, 0xffff0000, v220
	v_pk_fma_f32 v[124:125], v[92:93], 0.5, v[124:125] op_sel_hi:[1,0,1]
	v_lshlrev_b32_e32 v92, 16, v219
	v_and_b32_e32 v93, 0xffff0000, v219
	v_pk_fma_f32 v[102:103], v[102:103], 0.5, v[92:93] op_sel_hi:[1,0,1]
	v_lshlrev_b32_e32 v92, 16, v221
	v_and_b32_e32 v93, 0xffff0000, v221
	v_pk_fma_f32 v[126:127], v[94:95], 0.5, v[92:93] op_sel_hi:[1,0,1]
	v_lshlrev_b32_e32 v92, 16, v222
	v_and_b32_e32 v93, 0xffff0000, v222
	v_pk_fma_f32 v[92:93], v[96:97], 0.5, v[92:93] op_sel_hi:[1,0,1]
	v_lshlrev_b32_e32 v96, 16, v225
	v_and_b32_e32 v97, 0xffff0000, v225
	v_lshlrev_b32_e32 v94, 16, v224
	v_and_b32_e32 v95, 0xffff0000, v224
	v_pk_fma_f32 v[90:91], v[90:91], 0.5, v[96:97] op_sel_hi:[1,0,1]
	v_lshlrev_b32_e32 v96, 16, v136
	v_and_b32_e32 v97, 0xffff0000, v136
	v_pk_fma_f32 v[88:89], v[88:89], 0.5, v[94:95] op_sel_hi:[1,0,1]
	v_lshlrev_b32_e32 v94, 16, v223
	v_and_b32_e32 v95, 0xffff0000, v223
	v_pk_fma_f32 v[96:97], v[76:77], 0.5, v[96:97] op_sel_hi:[1,0,1]
	v_lshl_add_u64 v[76:77], v[168:169], 0, s[36:37]
	v_cvt_pk_bf16_f32 v114, v120, v121
	v_pk_fma_f32 v[120:121], v[108:109], 0.5, v[182:183] op_sel_hi:[1,0,1]
	v_pk_fma_f32 v[94:95], v[98:99], 0.5, v[94:95] op_sel_hi:[1,0,1]
	v_lshlrev_b64 v[182:183], 11, v[76:77]
	v_lshlrev_b32_e32 v98, 16, v138
	v_and_b32_e32 v99, 0xffff0000, v138
	v_lshl_add_u64 v[146:147], v[174:175], 0, v[182:183]
	v_pk_fma_f32 v[98:99], v[72:73], 0.5, v[98:99] op_sel_hi:[1,0,1]
	v_lshlrev_b32_e32 v72, 16, v137
	v_and_b32_e32 v73, 0xffff0000, v137
	v_lshlrev_b32_e32 v210, 16, v218
	v_and_b32_e32 v211, 0xffff0000, v218
	global_load_dwordx4 v[218:221], v[146:147], off
	global_load_dwordx4 v[226:229], v[146:147], off offset:256
	v_pk_fma_f32 v[136:137], v[78:79], 0.5, v[72:73] op_sel_hi:[1,0,1]
	v_lshlrev_b32_e32 v72, 16, v139
	v_and_b32_e32 v73, 0xffff0000, v139
	v_pk_fma_f32 v[138:139], v[74:75], 0.5, v[72:73] op_sel_hi:[1,0,1]
	v_lshlrev_b32_e32 v72, 16, v132
	v_and_b32_e32 v73, 0xffff0000, v132
	v_pk_fma_f32 v[74:75], v[84:85], 0.5, v[72:73] op_sel_hi:[1,0,1]
	v_lshlrev_b32_e32 v72, 16, v134
	v_and_b32_e32 v73, 0xffff0000, v134
	v_pk_fma_f32 v[78:79], v[80:81], 0.5, v[72:73] op_sel_hi:[1,0,1]
	v_lshlrev_b32_e32 v72, 16, v133
	v_and_b32_e32 v73, 0xffff0000, v133
	v_pk_fma_f32 v[80:81], v[86:87], 0.5, v[72:73] op_sel_hi:[1,0,1]
	v_lshlrev_b32_e32 v72, 16, v135
	v_and_b32_e32 v73, 0xffff0000, v135
	v_pk_fma_f32 v[82:83], v[82:83], 0.5, v[72:73] op_sel_hi:[1,0,1]
	v_lshl_add_u64 v[72:73], v[168:169], 0, s[10:11]
	v_lshlrev_b64 v[132:133], 11, v[72:73]
	v_lshl_add_u64 v[134:135], v[174:175], 0, v[132:133]
	global_load_dwordx4 v[234:237], v[134:135], off
	global_load_dwordx4 v[242:245], v[134:135], off offset:256
	v_lshlrev_b32_e32 v84, 16, v128
	v_and_b32_e32 v85, 0xffff0000, v128
	v_pk_fma_f32 v[84:85], v[68:69], 0.5, v[84:85] op_sel_hi:[1,0,1]
	v_lshlrev_b32_e32 v68, 16, v130
	v_and_b32_e32 v69, 0xffff0000, v130
	v_pk_fma_f32 v[86:87], v[64:65], 0.5, v[68:69] op_sel_hi:[1,0,1]
	v_lshlrev_b32_e32 v64, 16, v129
	v_and_b32_e32 v65, 0xffff0000, v129
	s_mov_b64 s[10:11], 0xa0
	v_pk_fma_f32 v[128:129], v[70:71], 0.5, v[64:65] op_sel_hi:[1,0,1]
	v_lshl_add_u64 v[70:71], v[168:169], 0, s[10:11]
	v_lshlrev_b32_e32 v64, 16, v131
	v_and_b32_e32 v65, 0xffff0000, v131
	v_lshlrev_b64 v[134:135], 11, v[70:71]
	v_pk_fma_f32 v[130:131], v[66:67], 0.5, v[64:65] op_sel_hi:[1,0,1]
	v_lshl_add_u64 v[64:65], v[174:175], 0, v[134:135]
	v_cvt_pk_bf16_f32 v115, v122, v123
	v_pk_fma_f32 v[122:123], v[110:111], 0.5, v[194:195] op_sel_hi:[1,0,1]
	v_pk_fma_f32 v[110:111], v[106:107], 0.5, v[196:197] op_sel_hi:[1,0,1]
	global_load_dwordx4 v[246:249], v[64:65], off
	global_load_dwordx4 v[194:197], v[64:65], off offset:256
	s_mov_b64 s[10:11], 0xb0
	v_lshl_add_u64 v[68:69], v[168:169], 0, s[10:11]
	v_pk_fma_f32 v[108:109], v[104:105], 0.5, v[184:185] op_sel_hi:[1,0,1]
	v_lshlrev_b64 v[184:185], 11, v[68:69]
	v_lshl_add_u64 v[64:65], v[174:175], 0, v[184:185]
	v_cvt_pk_bf16_f32 v119, v148, v149
	global_load_dwordx4 v[146:149], v[64:65], off
	s_nop 0
	global_load_dwordx4 v[64:67], v[64:65], off offset:256
	global_store_dwordx4 v[172:173], v[112:115], off
	global_store_dwordx4 v[172:173], v[116:119], off offset:256
	v_cvt_pk_bf16_f32 v104, v120, v121
	v_lshl_add_u64 v[112:113], s[28:29], 0, v[176:177]
	v_cvt_pk_bf16_f32 v105, v122, v123
	v_cvt_pk_bf16_f32 v106, v108, v109
	v_cvt_pk_bf16_f32 v107, v110, v111
	v_pk_fma_f32 v[100:101], v[100:101], 0.5, v[210:211] op_sel_hi:[1,0,1]
	v_lshl_add_u64 v[112:113], v[112:113], 0, v[170:171]
	v_cvt_pk_bf16_f32 v210, v100, v101
	v_cvt_pk_bf16_f32 v211, v102, v103
	v_cvt_pk_bf16_f32 v212, v124, v125
	v_cvt_pk_bf16_f32 v213, v126, v127
	global_store_dwordx4 v[112:113], v[104:107], off
	global_store_dwordx4 v[112:113], v[210:213], off offset:256
	v_cvt_pk_bf16_f32 v214, v92, v93
	v_lshl_add_u64 v[104:105], s[28:29], 0, v[180:181]
	v_cvt_pk_bf16_f32 v215, v94, v95
	v_cvt_pk_bf16_f32 v216, v88, v89
	v_cvt_pk_bf16_f32 v217, v90, v91
	v_lshl_add_u64 v[104:105], v[104:105], 0, v[170:171]
	v_cvt_pk_bf16_f32 v222, v96, v97
	v_cvt_pk_bf16_f32 v223, v136, v137
	v_cvt_pk_bf16_f32 v224, v98, v99
	v_cvt_pk_bf16_f32 v225, v138, v139
	global_store_dwordx4 v[104:105], v[214:217], off
	global_store_dwordx4 v[104:105], v[222:225], off offset:256
	v_lshl_add_u64 v[104:105], s[28:29], 0, v[178:179]
	v_cvt_pk_bf16_f32 v230, v74, v75
	v_cvt_pk_bf16_f32 v231, v80, v81
	v_cvt_pk_bf16_f32 v232, v78, v79
	v_cvt_pk_bf16_f32 v233, v82, v83
	v_lshl_add_u64 v[104:105], v[104:105], 0, v[170:171]
	v_cvt_pk_bf16_f32 v238, v84, v85
	v_cvt_pk_bf16_f32 v239, v128, v129
	v_cvt_pk_bf16_f32 v240, v86, v87
	v_cvt_pk_bf16_f32 v241, v130, v131
	global_store_dwordx4 v[104:105], v[230:233], off
	global_store_dwordx4 v[104:105], v[238:241], off offset:256
	s_waitcnt vmcnt(0)
	v_lshlrev_b32_e32 v104, 16, v218
	v_and_b32_e32 v105, 0xffff0000, v218
	v_pk_fma_f32 v[60:61], v[60:61], 0.5, v[104:105] op_sel_hi:[1,0,1]
	v_lshlrev_b32_e32 v104, 16, v220
	v_and_b32_e32 v105, 0xffff0000, v220
	v_pk_fma_f32 v[56:57], v[56:57], 0.5, v[104:105] op_sel_hi:[1,0,1]
	v_lshlrev_b32_e32 v104, 16, v219
	v_and_b32_e32 v105, 0xffff0000, v219
	v_pk_fma_f32 v[62:63], v[62:63], 0.5, v[104:105] op_sel_hi:[1,0,1]
	v_lshlrev_b32_e32 v104, 16, v221
	v_and_b32_e32 v105, 0xffff0000, v221
	v_pk_fma_f32 v[58:59], v[58:59], 0.5, v[104:105] op_sel_hi:[1,0,1]
	v_lshlrev_b32_e32 v104, 16, v226
	v_and_b32_e32 v105, 0xffff0000, v226
	v_pk_fma_f32 v[52:53], v[52:53], 0.5, v[104:105] op_sel_hi:[1,0,1]
	v_lshlrev_b32_e32 v104, 16, v228
	v_and_b32_e32 v105, 0xffff0000, v228
	v_pk_fma_f32 v[104:105], v[44:45], 0.5, v[104:105] op_sel_hi:[1,0,1]
	v_lshlrev_b32_e32 v44, 16, v227
	v_and_b32_e32 v45, 0xffff0000, v227
	v_pk_fma_f32 v[54:55], v[54:55], 0.5, v[44:45] op_sel_hi:[1,0,1]
	v_lshlrev_b32_e32 v44, 16, v229
	v_and_b32_e32 v45, 0xffff0000, v229
	v_pk_fma_f32 v[106:107], v[46:47], 0.5, v[44:45] op_sel_hi:[1,0,1]
	v_lshlrev_b32_e32 v44, 16, v234
	v_and_b32_e32 v45, 0xffff0000, v234
	v_pk_fma_f32 v[44:45], v[48:49], 0.5, v[44:45] op_sel_hi:[1,0,1]
	v_lshlrev_b32_e32 v48, 16, v237
	v_and_b32_e32 v49, 0xffff0000, v237
	v_pk_fma_f32 v[42:43], v[42:43], 0.5, v[48:49] op_sel_hi:[1,0,1]
	v_lshlrev_b32_e32 v48, 16, v242
	v_and_b32_e32 v49, 0xffff0000, v242
	v_pk_fma_f32 v[36:37], v[36:37], 0.5, v[48:49] op_sel_hi:[1,0,1]
	v_lshlrev_b32_e32 v48, 16, v244
	v_and_b32_e32 v49, 0xffff0000, v244
	v_lshlrev_b32_e32 v46, 16, v236
	v_and_b32_e32 v47, 0xffff0000, v236
	v_pk_fma_f32 v[48:49], v[28:29], 0.5, v[48:49] op_sel_hi:[1,0,1]
	v_lshlrev_b32_e32 v28, 16, v243
	v_and_b32_e32 v29, 0xffff0000, v243
	v_pk_fma_f32 v[40:41], v[40:41], 0.5, v[46:47] op_sel_hi:[1,0,1]
	v_lshlrev_b32_e32 v46, 16, v235
	v_and_b32_e32 v47, 0xffff0000, v235
	v_pk_fma_f32 v[38:39], v[38:39], 0.5, v[28:29] op_sel_hi:[1,0,1]
	v_lshlrev_b32_e32 v28, 16, v245
	v_and_b32_e32 v29, 0xffff0000, v245
	v_pk_fma_f32 v[46:47], v[50:51], 0.5, v[46:47] op_sel_hi:[1,0,1]
	v_pk_fma_f32 v[50:51], v[30:31], 0.5, v[28:29] op_sel_hi:[1,0,1]
	v_lshlrev_b32_e32 v28, 16, v246
	v_and_b32_e32 v29, 0xffff0000, v246
	v_pk_fma_f32 v[28:29], v[32:33], 0.5, v[28:29] op_sel_hi:[1,0,1]
	v_lshlrev_b32_e32 v32, 16, v249
	v_and_b32_e32 v33, 0xffff0000, v249
	v_pk_fma_f32 v[26:27], v[26:27], 0.5, v[32:33] op_sel_hi:[1,0,1]
	v_lshlrev_b32_e32 v32, 16, v194
	v_and_b32_e32 v33, 0xffff0000, v194
	v_pk_fma_f32 v[20:21], v[20:21], 0.5, v[32:33] op_sel_hi:[1,0,1]
	v_lshlrev_b32_e32 v32, 16, v196
	v_and_b32_e32 v33, 0xffff0000, v196
	v_lshlrev_b32_e32 v30, 16, v248
	v_and_b32_e32 v31, 0xffff0000, v248
	v_pk_fma_f32 v[32:33], v[12:13], 0.5, v[32:33] op_sel_hi:[1,0,1]
	v_lshlrev_b32_e32 v12, 16, v195
	v_and_b32_e32 v13, 0xffff0000, v195
	v_pk_fma_f32 v[24:25], v[24:25], 0.5, v[30:31] op_sel_hi:[1,0,1]
	v_lshlrev_b32_e32 v30, 16, v247
	v_and_b32_e32 v31, 0xffff0000, v247
	v_pk_fma_f32 v[22:23], v[22:23], 0.5, v[12:13] op_sel_hi:[1,0,1]
	v_lshlrev_b32_e32 v12, 16, v197
	v_and_b32_e32 v13, 0xffff0000, v197
	v_pk_fma_f32 v[30:31], v[34:35], 0.5, v[30:31] op_sel_hi:[1,0,1]
	v_pk_fma_f32 v[34:35], v[14:15], 0.5, v[12:13] op_sel_hi:[1,0,1]
	v_lshlrev_b32_e32 v14, 16, v148
	v_and_b32_e32 v15, 0xffff0000, v148
	v_lshlrev_b32_e32 v12, 16, v146
	v_and_b32_e32 v13, 0xffff0000, v146
	v_pk_fma_f32 v[8:9], v[8:9], 0.5, v[14:15] op_sel_hi:[1,0,1]
	v_lshlrev_b32_e32 v14, 16, v147
	v_and_b32_e32 v15, 0xffff0000, v147
	v_lshlrev_b32_e32 v146, 16, v64
	v_and_b32_e32 v147, 0xffff0000, v64
	v_pk_fma_f32 v[4:5], v[4:5], 0.5, v[146:147] op_sel_hi:[1,0,1]
	v_lshlrev_b32_e32 v146, 16, v66
	v_and_b32_e32 v147, 0xffff0000, v66
	v_pk_fma_f32 v[0:1], v[0:1], 0.5, v[146:147] op_sel_hi:[1,0,1]
	v_lshl_add_u64 v[146:147], s[28:29], 0, v[182:183]
	v_cvt_pk_bf16_f32 v112, v60, v61
	v_cvt_pk_bf16_f32 v113, v62, v63
	v_cvt_pk_bf16_f32 v114, v56, v57
	v_cvt_pk_bf16_f32 v115, v58, v59
	v_lshl_add_u64 v[146:147], v[146:147], 0, v[170:171]
	v_cvt_pk_bf16_f32 v116, v52, v53
	v_cvt_pk_bf16_f32 v117, v54, v55
	v_cvt_pk_bf16_f32 v118, v104, v105
	v_cvt_pk_bf16_f32 v119, v106, v107
	global_store_dwordx4 v[146:147], v[112:115], off
	global_store_dwordx4 v[146:147], v[116:119], off offset:256
	v_cvt_pk_bf16_f32 v172, v44, v45
	v_lshl_add_u64 v[112:113], s[28:29], 0, v[132:133]
	v_cvt_pk_bf16_f32 v173, v46, v47
	v_cvt_pk_bf16_f32 v174, v40, v41
	v_cvt_pk_bf16_f32 v175, v42, v43
	v_lshl_add_u64 v[112:113], v[112:113], 0, v[170:171]
	v_cvt_pk_bf16_f32 v176, v36, v37
	v_cvt_pk_bf16_f32 v177, v38, v39
	v_cvt_pk_bf16_f32 v178, v48, v49
	v_cvt_pk_bf16_f32 v179, v50, v51
	global_store_dwordx4 v[112:113], v[172:175], off
	global_store_dwordx4 v[112:113], v[176:179], off offset:256
	v_lshl_add_u64 v[112:113], s[28:29], 0, v[134:135]
	v_cvt_pk_bf16_f32 v210, v28, v29
	v_cvt_pk_bf16_f32 v211, v30, v31
	v_cvt_pk_bf16_f32 v212, v24, v25
	v_cvt_pk_bf16_f32 v213, v26, v27
	v_pk_fma_f32 v[12:13], v[16:17], 0.5, v[12:13] op_sel_hi:[1,0,1]
	v_lshlrev_b32_e32 v16, 16, v149
	v_and_b32_e32 v17, 0xffff0000, v149
	v_lshlrev_b32_e32 v64, 16, v65
	v_and_b32_e32 v65, 0xffff0000, v65
	v_lshl_add_u64 v[112:113], v[112:113], 0, v[170:171]
	v_cvt_pk_bf16_f32 v194, v20, v21
	v_cvt_pk_bf16_f32 v195, v22, v23
	v_cvt_pk_bf16_f32 v196, v32, v33
	v_cvt_pk_bf16_f32 v197, v34, v35
	v_pk_fma_f32 v[14:15], v[18:19], 0.5, v[14:15] op_sel_hi:[1,0,1]
	v_pk_fma_f32 v[10:11], v[10:11], 0.5, v[16:17] op_sel_hi:[1,0,1]
	v_pk_fma_f32 v[6:7], v[6:7], 0.5, v[64:65] op_sel_hi:[1,0,1]
	v_lshlrev_b32_e32 v64, 16, v67
	v_and_b32_e32 v65, 0xffff0000, v67
	global_store_dwordx4 v[112:113], v[210:213], off
	global_store_dwordx4 v[112:113], v[194:197], off offset:256
	v_lshl_add_u64 v[112:113], s[28:29], 0, v[184:185]
	v_cvt_pk_bf16_f32 v16, v12, v13
	v_cvt_pk_bf16_f32 v17, v14, v15
	v_cvt_pk_bf16_f32 v18, v8, v9
	v_cvt_pk_bf16_f32 v19, v10, v11
	v_pk_fma_f32 v[2:3], v[2:3], 0.5, v[64:65] op_sel_hi:[1,0,1]
	v_lshl_add_u64 v[112:113], v[112:113], 0, v[170:171]
	v_cvt_pk_bf16_f32 v64, v4, v5
	v_cvt_pk_bf16_f32 v65, v6, v7
	v_cvt_pk_bf16_f32 v66, v0, v1
	v_cvt_pk_bf16_f32 v67, v2, v3
	global_store_dwordx4 v[112:113], v[16:19], off
	global_store_dwordx4 v[112:113], v[64:67], off offset:256
	s_lshl_b32 s10, s81, 2
	v_and_b32_e32 v17, 64, v188
	v_xor_b32_e32 v16, 16, v188
	v_add_u32_e32 v17, 64, v17
	v_cmp_lt_i32_e32 vcc, v16, v17
	v_xor_b32_e32 v18, 32, v188
	s_ashr_i32 s11, s10, 31
	v_cndmask_b32_e32 v16, v188, v16, vcc
	v_lshlrev_b32_e32 v16, 2, v16
	ds_bpermute_b32 v19, v16, v209
	v_cmp_lt_i32_e32 vcc, v18, v17
	s_lshl_b64 s[10:11], s[10:11], 2
	s_add_u32 s38, s73, s10
	v_cndmask_b32_e32 v17, v188, v18, vcc
	v_lshlrev_b32_e32 v17, 2, v17
	s_waitcnt lgkmcnt(0)
	v_add_f32_e32 v18, v209, v19
	ds_bpermute_b32 v19, v17, v18
	s_addc_u32 s39, s74, s11
	s_and_saveexec_b64 s[46:47], s[42:43]
	s_cbranch_execz .LBB0_344
	s_waitcnt lgkmcnt(0)
	v_add_f32_e32 v64, v18, v19
	v_lshlrev_b64 v[18:19], 6, v[168:169]
	v_lshl_add_u64 v[18:19], s[38:39], 0, v[18:19]
	global_store_dword v[18:19], v64, off

.Lm4ap_386:
	s_waitcnt lgkmcnt(0)
	s_barrier
	v_mfma_f32_16x16x32_bf16 v[124:127], v[158:161], v[174:177], 0
	v_mfma_f32_16x16x32_bf16 v[120:123], v[166:169], v[174:177], 0
	v_mfma_f32_16x16x32_bf16 v[116:119], v[158:161], v[182:185], 0
	v_mfma_f32_16x16x32_bf16 v[112:115], v[166:169], v[182:185], 0
	v_mfma_f32_16x16x32_bf16 v[108:111], v[158:161], v[210:213], 0
	v_mfma_f32_16x16x32_bf16 v[104:107], v[166:169], v[210:213], 0
	v_mfma_f32_16x16x32_bf16 v[100:103], v[158:161], v[218:221], 0
	v_mfma_f32_16x16x32_bf16 v[96:99], v[166:169], v[218:221], 0
	v_mfma_f32_16x16x32_bf16 v[124:127], v[162:165], v[178:181], v[124:127]
	v_mfma_f32_16x16x32_bf16 v[120:123], v[170:173], v[178:181], v[120:123]
	v_mfma_f32_16x16x32_bf16 v[116:119], v[162:165], v[206:209], v[116:119]
	v_mfma_f32_16x16x32_bf16 v[112:115], v[170:173], v[206:209], v[112:115]
	v_mfma_f32_16x16x32_bf16 v[108:111], v[162:165], v[214:217], v[108:111]
	v_mfma_f32_16x16x32_bf16 v[104:107], v[170:173], v[214:217], v[104:107]
	v_mfma_f32_16x16x32_bf16 v[100:103], v[162:165], v[222:225], v[100:103]
	v_mfma_f32_16x16x32_bf16 v[96:99], v[170:173], v[222:225], v[96:99]
	v_mfma_f32_16x16x32_bf16 v[92:95], v[226:229], v[174:177], 0
	v_mfma_f32_16x16x32_bf16 v[88:91], v[234:237], v[174:177], 0
	v_mfma_f32_16x16x32_bf16 v[84:87], v[226:229], v[182:185], 0
	v_mfma_f32_16x16x32_bf16 v[80:83], v[234:237], v[182:185], 0
	v_mfma_f32_16x16x32_bf16 v[76:79], v[226:229], v[210:213], 0
	v_mfma_f32_16x16x32_bf16 v[72:75], v[234:237], v[210:213], 0
	v_mfma_f32_16x16x32_bf16 v[68:71], v[226:229], v[218:221], 0
	v_mfma_f32_16x16x32_bf16 v[64:67], v[234:237], v[218:221], 0
	v_mfma_f32_16x16x32_bf16 v[92:95], v[230:233], v[178:181], v[92:95]
	v_mfma_f32_16x16x32_bf16 v[88:91], v[238:241], v[178:181], v[88:91]
	v_mfma_f32_16x16x32_bf16 v[84:87], v[230:233], v[206:209], v[84:87]
	v_mfma_f32_16x16x32_bf16 v[80:83], v[238:241], v[206:209], v[80:83]
	v_mfma_f32_16x16x32_bf16 v[76:79], v[230:233], v[214:217], v[76:79]
	v_mfma_f32_16x16x32_bf16 v[72:75], v[238:241], v[214:217], v[72:75]
	v_mfma_f32_16x16x32_bf16 v[68:71], v[230:233], v[222:225], v[68:71]
	v_mfma_f32_16x16x32_bf16 v[64:67], v[238:241], v[222:225], v[64:67]
	s_barrier
	s_add_i32 s19, s82, s57
	v_lshl_add_u64 v[146:147], s[54:55], 0, v[140:141]
	s_mov_b32 m0, s19
	v_lshl_add_u64 v[148:149], s[54:55], 0, v[132:133]
	global_load_lds_dwordx4 v[146:147], off
	s_add_i32 m0, s19, 0x2000
	s_nop 0
	global_load_lds_dwordx4 v[148:149], off
	s_mov_b32 m0, s68
	v_lshl_add_u64 v[194:195], s[58:59], 0, v[128:129]
	ds_read_b128 v[174:177], v157 offset:16384
	ds_read_b128 v[178:181], v157 offset:17408
	ds_read_b128 v[182:185], v157 offset:18432
	ds_read_b128 v[206:209], v157 offset:19456
	ds_read_b128 v[210:213], v157 offset:20480
	ds_read_b128 v[214:217], v157 offset:21504
	ds_read_b128 v[218:221], v157 offset:22528
	ds_read_b128 v[222:225], v157 offset:23552
	global_load_lds_dwordx4 v[194:195], off
	v_lshl_add_u64 v[196:197], s[58:59], 0, v[130:131]
	s_mov_b32 m0, s69
	s_nop 0
	global_load_lds_dwordx4 v[196:197], off
	s_add_u32 s82, s54, 0x40000
	s_addc_u32 s83, s55, 0
	s_add_i32 s6, s6, s57
	v_lshl_add_u64 v[250:251], s[82:83], 0, v[140:141]
	s_mov_b32 m0, s6
	s_nop 0
	global_load_lds_dwordx4 v[250:251], off
	v_lshl_add_u64 v[250:251], s[82:83], 0, v[132:133]
	s_add_i32 m0, s6, 0x2000
	s_nop 0
	global_load_lds_dwordx4 v[250:251], off
	s_waitcnt vmcnt(16)
	s_cmp_lg_u32 s100, 0
	s_cbranch_scc1 .Lm4bp_386
	s_waitcnt vmcnt(8)
.Lm4bp_386:
	s_waitcnt lgkmcnt(0)
	s_mov_b32 s100, 0
	s_barrier
	v_mfma_f32_16x16x32_bf16 v[60:63], v[158:161], v[174:177], 0
	v_mfma_f32_16x16x32_bf16 v[56:59], v[166:169], v[174:177], 0
	v_mfma_f32_16x16x32_bf16 v[52:55], v[158:161], v[182:185], 0
	v_mfma_f32_16x16x32_bf16 v[48:51], v[166:169], v[182:185], 0
	v_mfma_f32_16x16x32_bf16 v[44:47], v[158:161], v[210:213], 0
	v_mfma_f32_16x16x32_bf16 v[40:43], v[166:169], v[210:213], 0
	v_mfma_f32_16x16x32_bf16 v[36:39], v[158:161], v[218:221], 0
	v_mfma_f32_16x16x32_bf16 v[32:35], v[166:169], v[218:221], 0
	v_mfma_f32_16x16x32_bf16 v[60:63], v[162:165], v[178:181], v[60:63]
	v_mfma_f32_16x16x32_bf16 v[56:59], v[170:173], v[178:181], v[56:59]
	v_mfma_f32_16x16x32_bf16 v[52:55], v[162:165], v[206:209], v[52:55]
	v_mfma_f32_16x16x32_bf16 v[48:51], v[170:173], v[206:209], v[48:51]
	v_mfma_f32_16x16x32_bf16 v[44:47], v[162:165], v[214:217], v[44:47]
	v_mfma_f32_16x16x32_bf16 v[40:43], v[170:173], v[214:217], v[40:43]
	v_mfma_f32_16x16x32_bf16 v[36:39], v[162:165], v[222:225], v[36:39]
	v_mfma_f32_16x16x32_bf16 v[32:35], v[170:173], v[222:225], v[32:35]
	v_mfma_f32_16x16x32_bf16 v[28:31], v[226:229], v[174:177], 0
	v_mfma_f32_16x16x32_bf16 v[24:27], v[234:237], v[174:177], 0
	v_mfma_f32_16x16x32_bf16 v[20:23], v[226:229], v[182:185], 0
	v_mfma_f32_16x16x32_bf16 v[16:19], v[234:237], v[182:185], 0
	v_mfma_f32_16x16x32_bf16 v[12:15], v[226:229], v[210:213], 0
	v_mfma_f32_16x16x32_bf16 v[8:11], v[234:237], v[210:213], 0
	v_mfma_f32_16x16x32_bf16 v[4:7], v[226:229], v[218:221], 0
	v_mfma_f32_16x16x32_bf16 v[0:3], v[234:237], v[218:221], 0
	v_mfma_f32_16x16x32_bf16 v[28:31], v[230:233], v[178:181], v[28:31]
	v_mfma_f32_16x16x32_bf16 v[24:27], v[238:241], v[178:181], v[24:27]
	v_mfma_f32_16x16x32_bf16 v[20:23], v[230:233], v[206:209], v[20:23]
	v_mfma_f32_16x16x32_bf16 v[16:19], v[238:241], v[206:209], v[16:19]
	v_mfma_f32_16x16x32_bf16 v[12:15], v[230:233], v[214:217], v[12:15]
	v_mfma_f32_16x16x32_bf16 v[8:11], v[238:241], v[214:217], v[8:11]
	v_mfma_f32_16x16x32_bf16 v[4:7], v[230:233], v[222:225], v[4:7]
	v_mfma_f32_16x16x32_bf16 v[0:3], v[238:241], v[222:225], v[0:3]
	s_barrier
	s_add_i32 s6, 0, 0x18000
	v_add_u32_e32 v170, s6, v154
	ds_read_b128 v[158:161], v170
	ds_read_b128 v[162:165], v170 offset:1024
	ds_read_b128 v[166:169], v170 offset:2048
	ds_read_b128 v[170:173], v170 offset:3072
	s_add_u32 s58, s58, 0x40000
	s_addc_u32 s59, s59, 0
	s_mov_b32 m0, s70
	v_lshl_add_u64 v[226:227], s[58:59], 0, v[128:129]
	ds_read_b128 v[174:177], v157 offset:32768
	ds_read_b128 v[178:181], v157 offset:33792
	ds_read_b128 v[182:185], v157 offset:34816
	ds_read_b128 v[206:209], v157 offset:35840
	ds_read_b128 v[210:213], v157 offset:36864
	ds_read_b128 v[214:217], v157 offset:37888
	ds_read_b128 v[218:221], v157 offset:38912
	ds_read_b128 v[222:225], v157 offset:39936
	global_load_lds_dwordx4 v[226:227], off
	v_lshl_add_u64 v[226:227], s[58:59], 0, v[130:131]
	s_mov_b32 m0, s71
	s_nop 0
	global_load_lds_dwordx4 v[226:227], off
	s_add_i32 s19, 0, 0x1c000
	v_add_u32_e32 v192, s19, v154
	ds_read_b128 v[226:229], v192
	ds_read_b128 v[230:233], v192 offset:1024
	ds_read_b128 v[234:237], v192 offset:2048
	ds_read_b128 v[238:241], v192 offset:3072
	s_waitcnt vmcnt(8)
	s_waitcnt lgkmcnt(0)
	s_barrier
	v_mfma_f32_16x16x32_bf16 v[124:127], v[158:161], v[174:177], v[124:127]
	v_mfma_f32_16x16x32_bf16 v[120:123], v[166:169], v[174:177], v[120:123]
	v_mfma_f32_16x16x32_bf16 v[116:119], v[158:161], v[182:185], v[116:119]
	v_mfma_f32_16x16x32_bf16 v[112:115], v[166:169], v[182:185], v[112:115]
	v_mfma_f32_16x16x32_bf16 v[108:111], v[158:161], v[210:213], v[108:111]
	v_mfma_f32_16x16x32_bf16 v[104:107], v[166:169], v[210:213], v[104:107]
	v_mfma_f32_16x16x32_bf16 v[100:103], v[158:161], v[218:221], v[100:103]
	v_mfma_f32_16x16x32_bf16 v[96:99], v[166:169], v[218:221], v[96:99]
	v_mfma_f32_16x16x32_bf16 v[124:127], v[162:165], v[178:181], v[124:127]
	v_mfma_f32_16x16x32_bf16 v[120:123], v[170:173], v[178:181], v[120:123]
	v_mfma_f32_16x16x32_bf16 v[116:119], v[162:165], v[206:209], v[116:119]
	v_mfma_f32_16x16x32_bf16 v[112:115], v[170:173], v[206:209], v[112:115]
	v_mfma_f32_16x16x32_bf16 v[108:111], v[162:165], v[214:217], v[108:111]
	v_mfma_f32_16x16x32_bf16 v[104:107], v[170:173], v[214:217], v[104:107]
	v_mfma_f32_16x16x32_bf16 v[100:103], v[162:165], v[222:225], v[100:103]
	v_mfma_f32_16x16x32_bf16 v[96:99], v[170:173], v[222:225], v[96:99]
	v_mfma_f32_16x16x32_bf16 v[92:95], v[226:229], v[174:177], v[92:95]
	v_mfma_f32_16x16x32_bf16 v[88:91], v[234:237], v[174:177], v[88:91]
	v_mfma_f32_16x16x32_bf16 v[84:87], v[226:229], v[182:185], v[84:87]
	v_mfma_f32_16x16x32_bf16 v[80:83], v[234:237], v[182:185], v[80:83]
	v_mfma_f32_16x16x32_bf16 v[76:79], v[226:229], v[210:213], v[76:79]
	v_mfma_f32_16x16x32_bf16 v[72:75], v[234:237], v[210:213], v[72:75]
	v_mfma_f32_16x16x32_bf16 v[68:71], v[226:229], v[218:221], v[68:71]
	v_mfma_f32_16x16x32_bf16 v[64:67], v[234:237], v[218:221], v[64:67]
	v_mfma_f32_16x16x32_bf16 v[92:95], v[230:233], v[178:181], v[92:95]
	v_mfma_f32_16x16x32_bf16 v[88:91], v[238:241], v[178:181], v[88:91]
	v_mfma_f32_16x16x32_bf16 v[84:87], v[230:233], v[206:209], v[84:87]
	v_mfma_f32_16x16x32_bf16 v[80:83], v[238:241], v[206:209], v[80:83]
	v_mfma_f32_16x16x32_bf16 v[76:79], v[230:233], v[214:217], v[76:79]
	v_mfma_f32_16x16x32_bf16 v[72:75], v[238:241], v[214:217], v[72:75]
	v_mfma_f32_16x16x32_bf16 v[68:71], v[230:233], v[222:225], v[68:71]
	v_mfma_f32_16x16x32_bf16 v[64:67], v[238:241], v[222:225], v[64:67]
	s_barrier
	s_add_i32 s6, s6, s57
	v_lshl_add_u64 v[146:147], v[146:147], 0, s[36:37]
	s_mov_b32 m0, s6
	s_nop 0
	global_load_lds_dwordx4 v[146:147], off
	v_lshl_add_u64 v[146:147], v[148:149], 0, s[36:37]
	s_add_i32 m0, s6, 0x2000
	s_nop 0
	global_load_lds_dwordx4 v[146:147], off
	s_mov_b32 m0, s72
	v_lshl_add_u64 v[146:147], v[194:195], 0, s[36:37]
	ds_read_b128 v[174:177], v157 offset:49152
	ds_read_b128 v[178:181], v157 offset:50176
	ds_read_b128 v[182:185], v157 offset:51200
	ds_read_b128 v[206:209], v157 offset:52224
	ds_read_b128 v[210:213], v157 offset:53248
	ds_read_b128 v[214:217], v157 offset:54272
	ds_read_b128 v[218:221], v157 offset:55296
	ds_read_b128 v[222:225], v157 offset:56320
	global_load_lds_dwordx4 v[146:147], off
	v_lshl_add_u64 v[146:147], v[196:197], 0, s[36:37]
	s_mov_b32 m0, s73
	s_nop 0
	global_load_lds_dwordx4 v[146:147], off
	s_add_u32 s54, s54, 0x40080
	s_addc_u32 s55, s55, 0
	s_add_i32 s6, s19, s57
	v_lshl_add_u64 v[146:147], s[54:55], 0, v[140:141]
	s_mov_b32 m0, s6
	s_nop 0
	global_load_lds_dwordx4 v[146:147], off
	v_lshl_add_u64 v[146:147], s[54:55], 0, v[132:133]
	s_add_i32 m0, s6, 0x2000
	s_nop 0
	global_load_lds_dwordx4 v[146:147], off
	s_waitcnt vmcnt(8)
	s_waitcnt lgkmcnt(0)
	s_barrier
	v_mfma_f32_16x16x32_bf16 v[60:63], v[158:161], v[174:177], v[60:63]
	v_mfma_f32_16x16x32_bf16 v[56:59], v[166:169], v[174:177], v[56:59]
	v_mfma_f32_16x16x32_bf16 v[52:55], v[158:161], v[182:185], v[52:55]
	v_mfma_f32_16x16x32_bf16 v[48:51], v[166:169], v[182:185], v[48:51]
	v_mfma_f32_16x16x32_bf16 v[44:47], v[158:161], v[210:213], v[44:47]
	v_mfma_f32_16x16x32_bf16 v[40:43], v[166:169], v[210:213], v[40:43]
	v_mfma_f32_16x16x32_bf16 v[36:39], v[158:161], v[218:221], v[36:39]
	v_mfma_f32_16x16x32_bf16 v[32:35], v[166:169], v[218:221], v[32:35]
	v_mfma_f32_16x16x32_bf16 v[60:63], v[162:165], v[178:181], v[60:63]
	v_mfma_f32_16x16x32_bf16 v[56:59], v[170:173], v[178:181], v[56:59]
	v_mfma_f32_16x16x32_bf16 v[52:55], v[162:165], v[206:209], v[52:55]
	v_mfma_f32_16x16x32_bf16 v[48:51], v[170:173], v[206:209], v[48:51]
	v_mfma_f32_16x16x32_bf16 v[44:47], v[162:165], v[214:217], v[44:47]
	v_mfma_f32_16x16x32_bf16 v[40:43], v[170:173], v[214:217], v[40:43]
	v_mfma_f32_16x16x32_bf16 v[36:39], v[162:165], v[222:225], v[36:39]
	v_mfma_f32_16x16x32_bf16 v[32:35], v[170:173], v[222:225], v[32:35]
	v_mfma_f32_16x16x32_bf16 v[28:31], v[226:229], v[174:177], v[28:31]
	v_mfma_f32_16x16x32_bf16 v[24:27], v[234:237], v[174:177], v[24:27]
	v_mfma_f32_16x16x32_bf16 v[20:23], v[226:229], v[182:185], v[20:23]
	v_mfma_f32_16x16x32_bf16 v[16:19], v[234:237], v[182:185], v[16:19]
	v_mfma_f32_16x16x32_bf16 v[12:15], v[226:229], v[210:213], v[12:15]
	v_mfma_f32_16x16x32_bf16 v[8:11], v[234:237], v[210:213], v[8:11]
	v_mfma_f32_16x16x32_bf16 v[4:7], v[226:229], v[218:221], v[4:7]
	v_mfma_f32_16x16x32_bf16 v[0:3], v[234:237], v[218:221], v[0:3]
	v_mfma_f32_16x16x32_bf16 v[28:31], v[230:233], v[178:181], v[28:31]
	v_mfma_f32_16x16x32_bf16 v[24:27], v[238:241], v[178:181], v[24:27]
	v_mfma_f32_16x16x32_bf16 v[20:23], v[230:233], v[206:209], v[20:23]
	v_mfma_f32_16x16x32_bf16 v[16:19], v[238:241], v[206:209], v[16:19]
	v_mfma_f32_16x16x32_bf16 v[12:15], v[230:233], v[214:217], v[12:15]
	v_mfma_f32_16x16x32_bf16 v[8:11], v[238:241], v[214:217], v[8:11]
	v_mfma_f32_16x16x32_bf16 v[4:7], v[230:233], v[222:225], v[4:7]
	v_mfma_f32_16x16x32_bf16 v[0:3], v[238:241], v[222:225], v[0:3]
	s_add_i32 s81, s81, 2
	s_add_u32 s52, s52, 0x100
	s_addc_u32 s53, s53, 0
	s_cmp_gt_u32 s81, 13
	s_barrier
.LBB0_386:
	s_add_u32 s6, s28, s52
	s_addc_u32 s19, s29, s53
	s_add_u32 s6, s6, 0x100
	s_addc_u32 s19, s19, 0
	s_add_u32 s23, s10, s52
	s_addc_u32 s54, s11, s53
	s_add_i32 s82, 0, 0x10000
	v_add_u32_e32 v146, s82, v154
	ds_read_b128 v[158:161], v146
	ds_read_b128 v[162:165], v146 offset:1024
	ds_read_b128 v[166:169], v146 offset:2048
	ds_read_b128 v[170:173], v146 offset:3072
	s_cmpk_eq_i32 s52, 0x700
	s_cselect_b32 s59, s12, s19
	s_cselect_b32 s58, s35, s6
	s_cselect_b32 s55, s39, s54
	s_cselect_b32 s54, s47, s23
	v_lshl_add_u64 v[146:147], v[150:151], 0, s[52:53]
	s_add_i32 m0, s68, 0xc000
	ds_read_b128 v[174:177], v157
	ds_read_b128 v[178:181], v157 offset:1024
	ds_read_b128 v[182:185], v157 offset:2048
	ds_read_b128 v[206:209], v157 offset:3072
	ds_read_b128 v[210:213], v157 offset:4096
	ds_read_b128 v[214:217], v157 offset:5120
	ds_read_b128 v[218:221], v157 offset:6144
	ds_read_b128 v[222:225], v157 offset:7168
	global_load_lds_dwordx4 v[146:147], off
	v_lshl_add_u64 v[146:147], v[152:153], 0, s[52:53]
	s_add_i32 m0, s68, 0xe000
	s_nop 0
	global_load_lds_dwordx4 v[146:147], off
	s_add_i32 s6, 0, 0x14000
	v_add_u32_e32 v146, s6, v154
	ds_read_b128 v[226:229], v146
	ds_read_b128 v[230:233], v146 offset:1024
	ds_read_b128 v[234:237], v146 offset:2048
	ds_read_b128 v[238:241], v146 offset:3072
	s_waitcnt vmcnt(8)
	s_waitcnt lgkmcnt(0)
	s_barrier
	v_mfma_f32_16x16x32_bf16 v[124:127], v[158:161], v[174:177], v[124:127]
	v_mfma_f32_16x16x32_bf16 v[120:123], v[166:169], v[174:177], v[120:123]
	v_mfma_f32_16x16x32_bf16 v[116:119], v[158:161], v[182:185], v[116:119]
	v_mfma_f32_16x16x32_bf16 v[112:115], v[166:169], v[182:185], v[112:115]
	v_mfma_f32_16x16x32_bf16 v[108:111], v[158:161], v[210:213], v[108:111]
	v_mfma_f32_16x16x32_bf16 v[104:107], v[166:169], v[210:213], v[104:107]
	v_mfma_f32_16x16x32_bf16 v[100:103], v[158:161], v[218:221], v[100:103]
	v_mfma_f32_16x16x32_bf16 v[96:99], v[166:169], v[218:221], v[96:99]
	v_mfma_f32_16x16x32_bf16 v[124:127], v[162:165], v[178:181], v[124:127]
	v_mfma_f32_16x16x32_bf16 v[120:123], v[170:173], v[178:181], v[120:123]
	v_mfma_f32_16x16x32_bf16 v[116:119], v[162:165], v[206:209], v[116:119]
	v_mfma_f32_16x16x32_bf16 v[112:115], v[170:173], v[206:209], v[112:115]
	v_mfma_f32_16x16x32_bf16 v[108:111], v[162:165], v[214:217], v[108:111]
	v_mfma_f32_16x16x32_bf16 v[104:107], v[170:173], v[214:217], v[104:107]
	v_mfma_f32_16x16x32_bf16 v[100:103], v[162:165], v[222:225], v[100:103]
	v_mfma_f32_16x16x32_bf16 v[96:99], v[170:173], v[222:225], v[96:99]
	v_mfma_f32_16x16x32_bf16 v[92:95], v[226:229], v[174:177], v[92:95]
	v_mfma_f32_16x16x32_bf16 v[88:91], v[234:237], v[174:177], v[88:91]
	v_mfma_f32_16x16x32_bf16 v[84:87], v[226:229], v[182:185], v[84:87]
	v_mfma_f32_16x16x32_bf16 v[80:83], v[234:237], v[182:185], v[80:83]
	v_mfma_f32_16x16x32_bf16 v[76:79], v[226:229], v[210:213], v[76:79]
	v_mfma_f32_16x16x32_bf16 v[72:75], v[234:237], v[210:213], v[72:75]
	v_mfma_f32_16x16x32_bf16 v[68:71], v[226:229], v[218:221], v[68:71]
	v_mfma_f32_16x16x32_bf16 v[64:67], v[234:237], v[218:221], v[64:67]
	v_mfma_f32_16x16x32_bf16 v[92:95], v[230:233], v[178:181], v[92:95]
	v_mfma_f32_16x16x32_bf16 v[88:91], v[238:241], v[178:181], v[88:91]
	v_mfma_f32_16x16x32_bf16 v[84:87], v[230:233], v[206:209], v[84:87]
	v_mfma_f32_16x16x32_bf16 v[80:83], v[238:241], v[206:209], v[80:83]
	v_mfma_f32_16x16x32_bf16 v[76:79], v[230:233], v[214:217], v[76:79]
	v_mfma_f32_16x16x32_bf16 v[72:75], v[238:241], v[214:217], v[72:75]
	v_mfma_f32_16x16x32_bf16 v[68:71], v[230:233], v[222:225], v[68:71]
	v_mfma_f32_16x16x32_bf16 v[64:67], v[238:241], v[222:225], v[64:67]
	s_barrier
	s_add_i32 s19, s82, s57
	v_lshl_add_u64 v[146:147], s[54:55], 0, v[140:141]
	s_mov_b32 m0, s19
	v_lshl_add_u64 v[148:149], s[54:55], 0, v[132:133]
	global_load_lds_dwordx4 v[146:147], off
	s_add_i32 m0, s19, 0x2000
	s_nop 0
	global_load_lds_dwordx4 v[148:149], off
	s_mov_b32 m0, s68
	v_lshl_add_u64 v[194:195], s[58:59], 0, v[128:129]
	ds_read_b128 v[174:177], v157 offset:16384
	ds_read_b128 v[178:181], v157 offset:17408
	ds_read_b128 v[182:185], v157 offset:18432
	ds_read_b128 v[206:209], v157 offset:19456
	ds_read_b128 v[210:213], v157 offset:20480
	ds_read_b128 v[214:217], v157 offset:21504
	ds_read_b128 v[218:221], v157 offset:22528
	ds_read_b128 v[222:225], v157 offset:23552
	global_load_lds_dwordx4 v[194:195], off
	v_lshl_add_u64 v[196:197], s[58:59], 0, v[130:131]
	s_mov_b32 m0, s69
	s_nop 0
	global_load_lds_dwordx4 v[196:197], off
	s_add_u32 s82, s54, 0x40000
	s_addc_u32 s83, s55, 0
	s_add_i32 s6, s6, s57
	v_lshl_add_u64 v[250:251], s[82:83], 0, v[140:141]
	s_mov_b32 m0, s6
	s_nop 0
	global_load_lds_dwordx4 v[250:251], off
	v_lshl_add_u64 v[250:251], s[82:83], 0, v[132:133]
	s_add_i32 m0, s6, 0x2000
	s_nop 0
	global_load_lds_dwordx4 v[250:251], off
	s_waitcnt vmcnt(8)
	s_waitcnt lgkmcnt(0)
	s_barrier
	v_mfma_f32_16x16x32_bf16 v[60:63], v[158:161], v[174:177], v[60:63]
	v_mfma_f32_16x16x32_bf16 v[56:59], v[166:169], v[174:177], v[56:59]
	v_mfma_f32_16x16x32_bf16 v[52:55], v[158:161], v[182:185], v[52:55]
	v_mfma_f32_16x16x32_bf16 v[48:51], v[166:169], v[182:185], v[48:51]
	v_mfma_f32_16x16x32_bf16 v[44:47], v[158:161], v[210:213], v[44:47]
	v_mfma_f32_16x16x32_bf16 v[40:43], v[166:169], v[210:213], v[40:43]
	v_mfma_f32_16x16x32_bf16 v[36:39], v[158:161], v[218:221], v[36:39]
	v_mfma_f32_16x16x32_bf16 v[32:35], v[166:169], v[218:221], v[32:35]
	v_mfma_f32_16x16x32_bf16 v[60:63], v[162:165], v[178:181], v[60:63]
	v_mfma_f32_16x16x32_bf16 v[56:59], v[170:173], v[178:181], v[56:59]
	v_mfma_f32_16x16x32_bf16 v[52:55], v[162:165], v[206:209], v[52:55]
	v_mfma_f32_16x16x32_bf16 v[48:51], v[170:173], v[206:209], v[48:51]
	v_mfma_f32_16x16x32_bf16 v[44:47], v[162:165], v[214:217], v[44:47]
	v_mfma_f32_16x16x32_bf16 v[40:43], v[170:173], v[214:217], v[40:43]
	v_mfma_f32_16x16x32_bf16 v[36:39], v[162:165], v[222:225], v[36:39]
	v_mfma_f32_16x16x32_bf16 v[32:35], v[170:173], v[222:225], v[32:35]
	v_mfma_f32_16x16x32_bf16 v[28:31], v[226:229], v[174:177], v[28:31]
	v_mfma_f32_16x16x32_bf16 v[24:27], v[234:237], v[174:177], v[24:27]
	v_mfma_f32_16x16x32_bf16 v[20:23], v[226:229], v[182:185], v[20:23]
	v_mfma_f32_16x16x32_bf16 v[16:19], v[234:237], v[182:185], v[16:19]
	v_mfma_f32_16x16x32_bf16 v[12:15], v[226:229], v[210:213], v[12:15]
	v_mfma_f32_16x16x32_bf16 v[8:11], v[234:237], v[210:213], v[8:11]
	v_mfma_f32_16x16x32_bf16 v[4:7], v[226:229], v[218:221], v[4:7]
	v_mfma_f32_16x16x32_bf16 v[0:3], v[234:237], v[218:221], v[0:3]
	v_mfma_f32_16x16x32_bf16 v[28:31], v[230:233], v[178:181], v[28:31]
	v_mfma_f32_16x16x32_bf16 v[24:27], v[238:241], v[178:181], v[24:27]
	v_mfma_f32_16x16x32_bf16 v[20:23], v[230:233], v[206:209], v[20:23]
	v_mfma_f32_16x16x32_bf16 v[16:19], v[238:241], v[206:209], v[16:19]
	v_mfma_f32_16x16x32_bf16 v[12:15], v[230:233], v[214:217], v[12:15]
	v_mfma_f32_16x16x32_bf16 v[8:11], v[238:241], v[214:217], v[8:11]
	v_mfma_f32_16x16x32_bf16 v[4:7], v[230:233], v[222:225], v[4:7]
	v_mfma_f32_16x16x32_bf16 v[0:3], v[238:241], v[222:225], v[0:3]
	s_barrier
	s_add_i32 s6, 0, 0x18000
	v_add_u32_e32 v170, s6, v154
	ds_read_b128 v[158:161], v170
	ds_read_b128 v[162:165], v170 offset:1024
	ds_read_b128 v[166:169], v170 offset:2048
	ds_read_b128 v[170:173], v170 offset:3072
	s_add_u32 s58, s58, 0x40000
	s_addc_u32 s59, s59, 0
	s_mov_b32 m0, s70
	v_lshl_add_u64 v[226:227], s[58:59], 0, v[128:129]
	ds_read_b128 v[174:177], v157 offset:32768
	ds_read_b128 v[178:181], v157 offset:33792
	ds_read_b128 v[182:185], v157 offset:34816
	ds_read_b128 v[206:209], v157 offset:35840
	ds_read_b128 v[210:213], v157 offset:36864
	ds_read_b128 v[214:217], v157 offset:37888
	ds_read_b128 v[218:221], v157 offset:38912
	ds_read_b128 v[222:225], v157 offset:39936
	global_load_lds_dwordx4 v[226:227], off
	v_lshl_add_u64 v[226:227], s[58:59], 0, v[130:131]
	s_mov_b32 m0, s71
	s_nop 0
	global_load_lds_dwordx4 v[226:227], off
	s_add_i32 s19, 0, 0x1c000
	v_add_u32_e32 v192, s19, v154
	ds_read_b128 v[226:229], v192
	ds_read_b128 v[230:233], v192 offset:1024
	ds_read_b128 v[234:237], v192 offset:2048
	ds_read_b128 v[238:241], v192 offset:3072
	s_waitcnt vmcnt(8)
	s_waitcnt lgkmcnt(0)
	s_barrier
	v_mfma_f32_16x16x32_bf16 v[124:127], v[158:161], v[174:177], v[124:127]
	v_mfma_f32_16x16x32_bf16 v[120:123], v[166:169], v[174:177], v[120:123]
	v_mfma_f32_16x16x32_bf16 v[116:119], v[158:161], v[182:185], v[116:119]
	v_mfma_f32_16x16x32_bf16 v[112:115], v[166:169], v[182:185], v[112:115]
	v_mfma_f32_16x16x32_bf16 v[108:111], v[158:161], v[210:213], v[108:111]
	v_mfma_f32_16x16x32_bf16 v[104:107], v[166:169], v[210:213], v[104:107]
	v_mfma_f32_16x16x32_bf16 v[100:103], v[158:161], v[218:221], v[100:103]
	v_mfma_f32_16x16x32_bf16 v[96:99], v[166:169], v[218:221], v[96:99]
	v_mfma_f32_16x16x32_bf16 v[124:127], v[162:165], v[178:181], v[124:127]
	v_mfma_f32_16x16x32_bf16 v[120:123], v[170:173], v[178:181], v[120:123]
	v_mfma_f32_16x16x32_bf16 v[116:119], v[162:165], v[206:209], v[116:119]
	v_mfma_f32_16x16x32_bf16 v[112:115], v[170:173], v[206:209], v[112:115]
	v_mfma_f32_16x16x32_bf16 v[108:111], v[162:165], v[214:217], v[108:111]
	v_mfma_f32_16x16x32_bf16 v[104:107], v[170:173], v[214:217], v[104:107]
	v_mfma_f32_16x16x32_bf16 v[100:103], v[162:165], v[222:225], v[100:103]
	v_mfma_f32_16x16x32_bf16 v[96:99], v[170:173], v[222:225], v[96:99]
	v_mfma_f32_16x16x32_bf16 v[92:95], v[226:229], v[174:177], v[92:95]
	v_mfma_f32_16x16x32_bf16 v[88:91], v[234:237], v[174:177], v[88:91]
	v_mfma_f32_16x16x32_bf16 v[84:87], v[226:229], v[182:185], v[84:87]
	v_mfma_f32_16x16x32_bf16 v[80:83], v[234:237], v[182:185], v[80:83]
	v_mfma_f32_16x16x32_bf16 v[76:79], v[226:229], v[210:213], v[76:79]
	v_mfma_f32_16x16x32_bf16 v[72:75], v[234:237], v[210:213], v[72:75]
	v_mfma_f32_16x16x32_bf16 v[68:71], v[226:229], v[218:221], v[68:71]
	v_mfma_f32_16x16x32_bf16 v[64:67], v[234:237], v[218:221], v[64:67]
	v_mfma_f32_16x16x32_bf16 v[92:95], v[230:233], v[178:181], v[92:95]
	v_mfma_f32_16x16x32_bf16 v[88:91], v[238:241], v[178:181], v[88:91]
	v_mfma_f32_16x16x32_bf16 v[84:87], v[230:233], v[206:209], v[84:87]
	v_mfma_f32_16x16x32_bf16 v[80:83], v[238:241], v[206:209], v[80:83]
	v_mfma_f32_16x16x32_bf16 v[76:79], v[230:233], v[214:217], v[76:79]
	v_mfma_f32_16x16x32_bf16 v[72:75], v[238:241], v[214:217], v[72:75]
	v_mfma_f32_16x16x32_bf16 v[68:71], v[230:233], v[222:225], v[68:71]
	v_mfma_f32_16x16x32_bf16 v[64:67], v[238:241], v[222:225], v[64:67]
	s_barrier
	s_add_i32 s6, s6, s57
	v_lshl_add_u64 v[146:147], v[146:147], 0, s[36:37]
	s_mov_b32 m0, s6
	s_nop 0
	global_load_lds_dwordx4 v[146:147], off
	v_lshl_add_u64 v[146:147], v[148:149], 0, s[36:37]
	s_add_i32 m0, s6, 0x2000
	s_nop 0
	global_load_lds_dwordx4 v[146:147], off
	s_mov_b32 m0, s72
	v_lshl_add_u64 v[146:147], v[194:195], 0, s[36:37]
	ds_read_b128 v[174:177], v157 offset:49152
	ds_read_b128 v[178:181], v157 offset:50176
	ds_read_b128 v[182:185], v157 offset:51200
	ds_read_b128 v[206:209], v157 offset:52224
	ds_read_b128 v[210:213], v157 offset:53248
	ds_read_b128 v[214:217], v157 offset:54272
	ds_read_b128 v[218:221], v157 offset:55296
	ds_read_b128 v[222:225], v157 offset:56320
	global_load_lds_dwordx4 v[146:147], off
	v_lshl_add_u64 v[146:147], v[196:197], 0, s[36:37]
	s_mov_b32 m0, s73
	s_nop 0
	global_load_lds_dwordx4 v[146:147], off
	s_add_u32 s54, s54, 0x40080
	s_addc_u32 s55, s55, 0
	s_add_i32 s6, s19, s57
	v_lshl_add_u64 v[146:147], s[54:55], 0, v[140:141]
	s_mov_b32 m0, s6
	s_nop 0
	global_load_lds_dwordx4 v[146:147], off
	v_lshl_add_u64 v[146:147], s[54:55], 0, v[132:133]
	s_add_i32 m0, s6, 0x2000
	s_nop 0
	global_load_lds_dwordx4 v[146:147], off
	s_waitcnt vmcnt(8)
	s_waitcnt lgkmcnt(0)
	s_barrier
	v_mfma_f32_16x16x32_bf16 v[60:63], v[158:161], v[174:177], v[60:63]
	v_mfma_f32_16x16x32_bf16 v[56:59], v[166:169], v[174:177], v[56:59]
	v_mfma_f32_16x16x32_bf16 v[52:55], v[158:161], v[182:185], v[52:55]
	v_mfma_f32_16x16x32_bf16 v[48:51], v[166:169], v[182:185], v[48:51]
	v_mfma_f32_16x16x32_bf16 v[44:47], v[158:161], v[210:213], v[44:47]
	v_mfma_f32_16x16x32_bf16 v[40:43], v[166:169], v[210:213], v[40:43]
	v_mfma_f32_16x16x32_bf16 v[36:39], v[158:161], v[218:221], v[36:39]
	v_mfma_f32_16x16x32_bf16 v[32:35], v[166:169], v[218:221], v[32:35]
	v_mfma_f32_16x16x32_bf16 v[60:63], v[162:165], v[178:181], v[60:63]
	v_mfma_f32_16x16x32_bf16 v[56:59], v[170:173], v[178:181], v[56:59]
	v_mfma_f32_16x16x32_bf16 v[52:55], v[162:165], v[206:209], v[52:55]
	v_mfma_f32_16x16x32_bf16 v[48:51], v[170:173], v[206:209], v[48:51]
	v_mfma_f32_16x16x32_bf16 v[44:47], v[162:165], v[214:217], v[44:47]
	v_mfma_f32_16x16x32_bf16 v[40:43], v[170:173], v[214:217], v[40:43]
	v_mfma_f32_16x16x32_bf16 v[36:39], v[162:165], v[222:225], v[36:39]
	v_mfma_f32_16x16x32_bf16 v[32:35], v[170:173], v[222:225], v[32:35]
	v_mfma_f32_16x16x32_bf16 v[28:31], v[226:229], v[174:177], v[28:31]
	v_mfma_f32_16x16x32_bf16 v[24:27], v[234:237], v[174:177], v[24:27]
	v_mfma_f32_16x16x32_bf16 v[20:23], v[226:229], v[182:185], v[20:23]
	v_mfma_f32_16x16x32_bf16 v[16:19], v[234:237], v[182:185], v[16:19]
	v_mfma_f32_16x16x32_bf16 v[12:15], v[226:229], v[210:213], v[12:15]
	v_mfma_f32_16x16x32_bf16 v[8:11], v[234:237], v[210:213], v[8:11]
	v_mfma_f32_16x16x32_bf16 v[4:7], v[226:229], v[218:221], v[4:7]
	v_mfma_f32_16x16x32_bf16 v[0:3], v[234:237], v[218:221], v[0:3]
	v_mfma_f32_16x16x32_bf16 v[28:31], v[230:233], v[178:181], v[28:31]
	v_mfma_f32_16x16x32_bf16 v[24:27], v[238:241], v[178:181], v[24:27]
	v_mfma_f32_16x16x32_bf16 v[20:23], v[230:233], v[206:209], v[20:23]
	v_mfma_f32_16x16x32_bf16 v[16:19], v[238:241], v[206:209], v[16:19]
	v_mfma_f32_16x16x32_bf16 v[12:15], v[230:233], v[214:217], v[12:15]
	v_mfma_f32_16x16x32_bf16 v[8:11], v[238:241], v[214:217], v[8:11]
	v_mfma_f32_16x16x32_bf16 v[4:7], v[230:233], v[222:225], v[4:7]
	v_mfma_f32_16x16x32_bf16 v[0:3], v[238:241], v[222:225], v[0:3]
	s_add_i32 s81, s81, 2
	s_add_u32 s52, s52, 0x100
	s_addc_u32 s53, s53, 0
	s_cmp_gt_u32 s81, 13
	s_barrier
	s_cbranch_scc0 .LBB0_386
	s_mov_b32 s100, 1
	v_lshl_add_u32 v158, s75, 10, v155
	ds_read2_b32 v[146:147], v158 offset1:16
	s_add_u32 s52, s10, 0xffffff00
	s_addc_u32 s53, s11, -1
	s_ashr_i32 s35, s34, 31
	s_lshl_b64 s[10:11], s[34:35], 8
	s_waitcnt lgkmcnt(0)
	v_mul_f32_e32 v184, 0xbfb8aa3b, v146
	v_mul_f32_e32 v206, v146, v146
	v_pk_mul_f32 v[168:169], v[124:125], v[184:185] op_sel_hi:[1,0]
	v_pk_mul_f32 v[170:171], v[126:127], v[184:185] op_sel_hi:[1,0]
	v_pk_mul_f32 v[172:173], v[120:121], v[184:185] op_sel_hi:[1,0]
	v_pk_mul_f32 v[174:175], v[122:123], v[184:185] op_sel_hi:[1,0]
	v_exp_f32_e32 v168, v168
	v_exp_f32_e32 v169, v169
	v_exp_f32_e32 v170, v170
	v_exp_f32_e32 v171, v171
	v_exp_f32_e32 v172, v172
	v_exp_f32_e32 v173, v173
	v_exp_f32_e32 v174, v174
	v_exp_f32_e32 v175, v175
	v_pk_mul_f32 v[176:177], v[124:125], v[92:93]
	v_pk_mul_f32 v[178:179], v[126:127], v[94:95]
	v_pk_mul_f32 v[180:181], v[120:121], v[88:89]
	v_pk_mul_f32 v[182:183], v[122:123], v[90:91]
	v_pk_add_f32 v[168:169], v[168:169], 1.0 op_sel_hi:[1,0]
	v_pk_add_f32 v[170:171], v[170:171], 1.0 op_sel_hi:[1,0]
	v_pk_add_f32 v[172:173], v[172:173], 1.0 op_sel_hi:[1,0]
	v_pk_add_f32 v[174:175], v[174:175], 1.0 op_sel_hi:[1,0]
	v_rcp_f32_e32 v168, v168
	v_rcp_f32_e32 v169, v169
	v_rcp_f32_e32 v170, v170
	v_rcp_f32_e32 v171, v171
	v_rcp_f32_e32 v172, v172
	v_rcp_f32_e32 v173, v173
	v_rcp_f32_e32 v174, v174
	v_rcp_f32_e32 v175, v175
	v_pk_mul_f32 v[176:177], v[176:177], v[206:207] op_sel_hi:[1,0]
	v_pk_mul_f32 v[178:179], v[178:179], v[206:207] op_sel_hi:[1,0]
	v_pk_mul_f32 v[180:181], v[180:181], v[206:207] op_sel_hi:[1,0]
	v_pk_mul_f32 v[182:183], v[182:183], v[206:207] op_sel_hi:[1,0]
	v_pk_mul_f32 v[176:177], v[176:177], v[168:169]
	v_pk_mul_f32 v[178:179], v[178:179], v[170:171]
	v_pk_mul_f32 v[180:181], v[180:181], v[172:173]
	v_pk_mul_f32 v[182:183], v[182:183], v[174:175]
	v_cvt_pk_bf16_f32 v160, v176, v177
	v_cvt_pk_bf16_f32 v161, v178, v179
	v_cvt_pk_bf16_f32 v162, v180, v181
	v_cvt_pk_bf16_f32 v163, v182, v183
	v_lshl_add_u64 v[152:153], v[134:135], 0, s[10:11]
	s_movk_i32 s6, 0x1600
	v_lshl_or_b32 v150, s74, 7, v156
	v_ashrrev_i32_e32 v151, 31, v150
	s_nop 1
	v_mov_b64_e32 v[148:149], s[30:31]
	v_mad_u64_u32 v[148:149], s[10:11], v152, s6, v[148:149]
	v_mov_b32_e32 v146, v149
	v_mad_u64_u32 v[152:153], s[10:11], v153, s6, v[146:147]
	v_mov_b32_e32 v149, v152
	v_mov_b32_e32 v146, v147
	v_lshl_add_u64 v[150:151], v[150:151], 1, v[148:149]
	global_store_dwordx4 v[150:151], v[160:163], off
	v_mul_f32_e32 v184, 0xbfb8aa3b, v146
	v_mul_f32_e32 v206, v146, v146
	v_pk_mul_f32 v[168:169], v[116:117], v[184:185] op_sel_hi:[1,0]
	v_pk_mul_f32 v[170:171], v[118:119], v[184:185] op_sel_hi:[1,0]
	v_pk_mul_f32 v[172:173], v[112:113], v[184:185] op_sel_hi:[1,0]
	v_pk_mul_f32 v[174:175], v[114:115], v[184:185] op_sel_hi:[1,0]
	v_exp_f32_e32 v168, v168
	v_exp_f32_e32 v169, v169
	v_exp_f32_e32 v170, v170
	v_exp_f32_e32 v171, v171
	v_exp_f32_e32 v172, v172
	v_exp_f32_e32 v173, v173
	v_exp_f32_e32 v174, v174
	v_exp_f32_e32 v175, v175
	v_pk_mul_f32 v[176:177], v[116:117], v[84:85]
	v_pk_mul_f32 v[178:179], v[118:119], v[86:87]
	v_pk_mul_f32 v[180:181], v[112:113], v[80:81]
	v_pk_mul_f32 v[182:183], v[114:115], v[82:83]
	v_pk_add_f32 v[168:169], v[168:169], 1.0 op_sel_hi:[1,0]
	v_pk_add_f32 v[170:171], v[170:171], 1.0 op_sel_hi:[1,0]
	v_pk_add_f32 v[172:173], v[172:173], 1.0 op_sel_hi:[1,0]
	v_pk_add_f32 v[174:175], v[174:175], 1.0 op_sel_hi:[1,0]
	v_rcp_f32_e32 v168, v168
	v_rcp_f32_e32 v169, v169
	v_rcp_f32_e32 v170, v170
	v_rcp_f32_e32 v171, v171
	v_rcp_f32_e32 v172, v172
	v_rcp_f32_e32 v173, v173
	v_rcp_f32_e32 v174, v174
	v_rcp_f32_e32 v175, v175
	v_pk_mul_f32 v[176:177], v[176:177], v[206:207] op_sel_hi:[1,0]
	v_pk_mul_f32 v[178:179], v[178:179], v[206:207] op_sel_hi:[1,0]
	v_pk_mul_f32 v[180:181], v[180:181], v[206:207] op_sel_hi:[1,0]
	v_pk_mul_f32 v[182:183], v[182:183], v[206:207] op_sel_hi:[1,0]
	v_pk_mul_f32 v[176:177], v[176:177], v[168:169]
	v_pk_mul_f32 v[178:179], v[178:179], v[170:171]
	v_pk_mul_f32 v[180:181], v[180:181], v[172:173]
	v_pk_mul_f32 v[182:183], v[182:183], v[174:175]
	v_cvt_pk_bf16_f32 v160, v176, v177
	v_cvt_pk_bf16_f32 v161, v178, v179
	v_cvt_pk_bf16_f32 v162, v180, v181
	v_cvt_pk_bf16_f32 v163, v182, v183
	s_mov_b32 s6, 0x16000
	s_nop 1
	v_add_co_u32_e32 v146, vcc, s6, v150
	s_nop 0
	v_addc_co_u32_e32 v147, vcc, 0, v151, vcc
	global_store_dwordx4 v[146:147], v[160:163], off
	ds_read2_b32 v[146:147], v158 offset0:32 offset1:48
	s_mov_b32 s6, 0x2c000
	s_waitcnt lgkmcnt(0)
	v_mul_f32_e32 v184, 0xbfb8aa3b, v146
	v_mul_f32_e32 v206, v146, v146
	v_pk_mul_f32 v[168:169], v[108:109], v[184:185] op_sel_hi:[1,0]
	v_pk_mul_f32 v[170:171], v[110:111], v[184:185] op_sel_hi:[1,0]
	v_pk_mul_f32 v[172:173], v[104:105], v[184:185] op_sel_hi:[1,0]
	v_pk_mul_f32 v[174:175], v[106:107], v[184:185] op_sel_hi:[1,0]
	v_exp_f32_e32 v168, v168
	v_exp_f32_e32 v169, v169
	v_exp_f32_e32 v170, v170
	v_exp_f32_e32 v171, v171
	v_exp_f32_e32 v172, v172
	v_exp_f32_e32 v173, v173
	v_exp_f32_e32 v174, v174
	v_exp_f32_e32 v175, v175
	v_pk_mul_f32 v[176:177], v[108:109], v[76:77]
	v_pk_mul_f32 v[178:179], v[110:111], v[78:79]
	v_pk_mul_f32 v[180:181], v[104:105], v[72:73]
	v_pk_mul_f32 v[182:183], v[106:107], v[74:75]
	v_pk_add_f32 v[168:169], v[168:169], 1.0 op_sel_hi:[1,0]
	v_pk_add_f32 v[170:171], v[170:171], 1.0 op_sel_hi:[1,0]
	v_pk_add_f32 v[172:173], v[172:173], 1.0 op_sel_hi:[1,0]
	v_pk_add_f32 v[174:175], v[174:175], 1.0 op_sel_hi:[1,0]
	v_rcp_f32_e32 v168, v168
	v_rcp_f32_e32 v169, v169
	v_rcp_f32_e32 v170, v170
	v_rcp_f32_e32 v171, v171
	v_rcp_f32_e32 v172, v172
	v_rcp_f32_e32 v173, v173
	v_rcp_f32_e32 v174, v174
	v_rcp_f32_e32 v175, v175
	v_pk_mul_f32 v[176:177], v[176:177], v[206:207] op_sel_hi:[1,0]
	v_pk_mul_f32 v[178:179], v[178:179], v[206:207] op_sel_hi:[1,0]
	v_pk_mul_f32 v[180:181], v[180:181], v[206:207] op_sel_hi:[1,0]
	v_pk_mul_f32 v[182:183], v[182:183], v[206:207] op_sel_hi:[1,0]
	v_pk_mul_f32 v[176:177], v[176:177], v[168:169]
	v_pk_mul_f32 v[178:179], v[178:179], v[170:171]
	v_pk_mul_f32 v[180:181], v[180:181], v[172:173]
	v_pk_mul_f32 v[182:183], v[182:183], v[174:175]
	v_cvt_pk_bf16_f32 v160, v176, v177
	v_cvt_pk_bf16_f32 v161, v178, v179
	v_cvt_pk_bf16_f32 v162, v180, v181
	v_cvt_pk_bf16_f32 v163, v182, v183
	s_nop 1
	v_mov_b32_e32 v146, v147
	v_add_co_u32_e32 v148, vcc, s6, v150
	v_addc_co_u32_e32 v149, vcc, 0, v151, vcc
	global_store_dwordx4 v[148:149], v[160:163], off
	v_mul_f32_e32 v184, 0xbfb8aa3b, v146
	v_mul_f32_e32 v206, v146, v146
	v_pk_mul_f32 v[168:169], v[100:101], v[184:185] op_sel_hi:[1,0]
	v_pk_mul_f32 v[170:171], v[102:103], v[184:185] op_sel_hi:[1,0]
	v_pk_mul_f32 v[172:173], v[96:97], v[184:185] op_sel_hi:[1,0]
	v_pk_mul_f32 v[174:175], v[98:99], v[184:185] op_sel_hi:[1,0]
	v_exp_f32_e32 v168, v168
	v_exp_f32_e32 v169, v169
	v_exp_f32_e32 v170, v170
	v_exp_f32_e32 v171, v171
	v_exp_f32_e32 v172, v172
	v_exp_f32_e32 v173, v173
	v_exp_f32_e32 v174, v174
	v_exp_f32_e32 v175, v175
	v_pk_mul_f32 v[176:177], v[100:101], v[68:69]
	v_pk_mul_f32 v[178:179], v[102:103], v[70:71]
	v_pk_mul_f32 v[180:181], v[96:97], v[64:65]
	v_pk_mul_f32 v[182:183], v[98:99], v[66:67]
	v_pk_add_f32 v[168:169], v[168:169], 1.0 op_sel_hi:[1,0]
	v_pk_add_f32 v[170:171], v[170:171], 1.0 op_sel_hi:[1,0]
	v_pk_add_f32 v[172:173], v[172:173], 1.0 op_sel_hi:[1,0]
	v_pk_add_f32 v[174:175], v[174:175], 1.0 op_sel_hi:[1,0]
	v_rcp_f32_e32 v168, v168
	v_rcp_f32_e32 v169, v169
	v_rcp_f32_e32 v170, v170
	v_rcp_f32_e32 v171, v171
	v_rcp_f32_e32 v172, v172
	v_rcp_f32_e32 v173, v173
	v_rcp_f32_e32 v174, v174
	v_rcp_f32_e32 v175, v175
	v_pk_mul_f32 v[176:177], v[176:177], v[206:207] op_sel_hi:[1,0]
	v_pk_mul_f32 v[178:179], v[178:179], v[206:207] op_sel_hi:[1,0]
	v_pk_mul_f32 v[180:181], v[180:181], v[206:207] op_sel_hi:[1,0]
	v_pk_mul_f32 v[182:183], v[182:183], v[206:207] op_sel_hi:[1,0]
	v_pk_mul_f32 v[176:177], v[176:177], v[168:169]
	v_pk_mul_f32 v[178:179], v[178:179], v[170:171]
	v_pk_mul_f32 v[180:181], v[180:181], v[172:173]
	v_pk_mul_f32 v[182:183], v[182:183], v[174:175]
	v_cvt_pk_bf16_f32 v160, v176, v177
	v_cvt_pk_bf16_f32 v161, v178, v179
	v_cvt_pk_bf16_f32 v162, v180, v181
	v_cvt_pk_bf16_f32 v163, v182, v183
	s_mov_b32 s6, 0x42000
	s_nop 1
	v_add_co_u32_e32 v146, vcc, s6, v150
	s_nop 0
	v_addc_co_u32_e32 v147, vcc, 0, v151, vcc
	global_store_dwordx4 v[146:147], v[160:163], off
	ds_read2_b32 v[146:147], v158 offset0:128 offset1:144
	s_mov_b32 s6, 0xb0000
	s_waitcnt lgkmcnt(0)
	v_mul_f32_e32 v184, 0xbfb8aa3b, v146
	v_mul_f32_e32 v206, v146, v146
	v_pk_mul_f32 v[168:169], v[60:61], v[184:185] op_sel_hi:[1,0]
	v_pk_mul_f32 v[170:171], v[62:63], v[184:185] op_sel_hi:[1,0]
	v_pk_mul_f32 v[172:173], v[56:57], v[184:185] op_sel_hi:[1,0]
	v_pk_mul_f32 v[174:175], v[58:59], v[184:185] op_sel_hi:[1,0]
	v_exp_f32_e32 v168, v168
	v_exp_f32_e32 v169, v169
	v_exp_f32_e32 v170, v170
	v_exp_f32_e32 v171, v171
	v_exp_f32_e32 v172, v172
	v_exp_f32_e32 v173, v173
	v_exp_f32_e32 v174, v174
	v_exp_f32_e32 v175, v175
	v_pk_mul_f32 v[176:177], v[60:61], v[28:29]
	v_pk_mul_f32 v[178:179], v[62:63], v[30:31]
	v_pk_mul_f32 v[180:181], v[56:57], v[24:25]
	v_pk_mul_f32 v[182:183], v[58:59], v[26:27]
	v_pk_add_f32 v[168:169], v[168:169], 1.0 op_sel_hi:[1,0]
	v_pk_add_f32 v[170:171], v[170:171], 1.0 op_sel_hi:[1,0]
	v_pk_add_f32 v[172:173], v[172:173], 1.0 op_sel_hi:[1,0]
	v_pk_add_f32 v[174:175], v[174:175], 1.0 op_sel_hi:[1,0]
	v_rcp_f32_e32 v168, v168
	v_rcp_f32_e32 v169, v169
	v_rcp_f32_e32 v170, v170
	v_rcp_f32_e32 v171, v171
	v_rcp_f32_e32 v172, v172
	v_rcp_f32_e32 v173, v173
	v_rcp_f32_e32 v174, v174
	v_rcp_f32_e32 v175, v175
	v_pk_mul_f32 v[176:177], v[176:177], v[206:207] op_sel_hi:[1,0]
	v_pk_mul_f32 v[178:179], v[178:179], v[206:207] op_sel_hi:[1,0]
	v_pk_mul_f32 v[180:181], v[180:181], v[206:207] op_sel_hi:[1,0]
	v_pk_mul_f32 v[182:183], v[182:183], v[206:207] op_sel_hi:[1,0]
	v_pk_mul_f32 v[176:177], v[176:177], v[168:169]
	v_pk_mul_f32 v[178:179], v[178:179], v[170:171]
	v_pk_mul_f32 v[180:181], v[180:181], v[172:173]
	v_pk_mul_f32 v[182:183], v[182:183], v[174:175]
	v_cvt_pk_bf16_f32 v160, v176, v177
	v_cvt_pk_bf16_f32 v161, v178, v179
	v_cvt_pk_bf16_f32 v162, v180, v181
	v_cvt_pk_bf16_f32 v163, v182, v183
	s_nop 1
	v_mov_b32_e32 v146, v147
	v_add_co_u32_e32 v148, vcc, s6, v150
	v_addc_co_u32_e32 v149, vcc, 0, v151, vcc
	global_store_dwordx4 v[148:149], v[160:163], off
	v_mul_f32_e32 v184, 0xbfb8aa3b, v146
	v_mul_f32_e32 v206, v146, v146
	v_pk_mul_f32 v[168:169], v[52:53], v[184:185] op_sel_hi:[1,0]
	v_pk_mul_f32 v[170:171], v[54:55], v[184:185] op_sel_hi:[1,0]
	v_pk_mul_f32 v[172:173], v[48:49], v[184:185] op_sel_hi:[1,0]
	v_pk_mul_f32 v[174:175], v[50:51], v[184:185] op_sel_hi:[1,0]
	v_exp_f32_e32 v168, v168
	v_exp_f32_e32 v169, v169
	v_exp_f32_e32 v170, v170
	v_exp_f32_e32 v171, v171
	v_exp_f32_e32 v172, v172
	v_exp_f32_e32 v173, v173
	v_exp_f32_e32 v174, v174
	v_exp_f32_e32 v175, v175
	v_pk_mul_f32 v[176:177], v[52:53], v[20:21]
	v_pk_mul_f32 v[178:179], v[54:55], v[22:23]
	v_pk_mul_f32 v[180:181], v[48:49], v[16:17]
	v_pk_mul_f32 v[182:183], v[50:51], v[18:19]
	v_pk_add_f32 v[168:169], v[168:169], 1.0 op_sel_hi:[1,0]
	v_pk_add_f32 v[170:171], v[170:171], 1.0 op_sel_hi:[1,0]
	v_pk_add_f32 v[172:173], v[172:173], 1.0 op_sel_hi:[1,0]
	v_pk_add_f32 v[174:175], v[174:175], 1.0 op_sel_hi:[1,0]
	v_rcp_f32_e32 v168, v168
	v_rcp_f32_e32 v169, v169
	v_rcp_f32_e32 v170, v170
	v_rcp_f32_e32 v171, v171
	v_rcp_f32_e32 v172, v172
	v_rcp_f32_e32 v173, v173
	v_rcp_f32_e32 v174, v174
	v_rcp_f32_e32 v175, v175
	v_pk_mul_f32 v[176:177], v[176:177], v[206:207] op_sel_hi:[1,0]
	v_pk_mul_f32 v[178:179], v[178:179], v[206:207] op_sel_hi:[1,0]
	v_pk_mul_f32 v[180:181], v[180:181], v[206:207] op_sel_hi:[1,0]
	v_pk_mul_f32 v[182:183], v[182:183], v[206:207] op_sel_hi:[1,0]
	v_pk_mul_f32 v[176:177], v[176:177], v[168:169]
	v_pk_mul_f32 v[178:179], v[178:179], v[170:171]
	v_pk_mul_f32 v[180:181], v[180:181], v[172:173]
	v_pk_mul_f32 v[182:183], v[182:183], v[174:175]
	v_cvt_pk_bf16_f32 v160, v176, v177
	v_cvt_pk_bf16_f32 v161, v178, v179
	v_cvt_pk_bf16_f32 v162, v180, v181
	v_cvt_pk_bf16_f32 v163, v182, v183
	s_mov_b32 s6, 0xc6000
	s_nop 1
	v_add_co_u32_e32 v146, vcc, s6, v150
	s_nop 0
	v_addc_co_u32_e32 v147, vcc, 0, v151, vcc
	global_store_dwordx4 v[146:147], v[160:163], off
	ds_read2_b32 v[146:147], v158 offset0:160 offset1:176
	s_mov_b32 s6, 0xdc000
	s_waitcnt lgkmcnt(0)
	v_mul_f32_e32 v184, 0xbfb8aa3b, v146
	v_mul_f32_e32 v206, v146, v146
	v_pk_mul_f32 v[168:169], v[44:45], v[184:185] op_sel_hi:[1,0]
	v_pk_mul_f32 v[170:171], v[46:47], v[184:185] op_sel_hi:[1,0]
	v_pk_mul_f32 v[172:173], v[40:41], v[184:185] op_sel_hi:[1,0]
	v_pk_mul_f32 v[174:175], v[42:43], v[184:185] op_sel_hi:[1,0]
	v_exp_f32_e32 v168, v168
	v_exp_f32_e32 v169, v169
	v_exp_f32_e32 v170, v170
	v_exp_f32_e32 v171, v171
	v_exp_f32_e32 v172, v172
	v_exp_f32_e32 v173, v173
	v_exp_f32_e32 v174, v174
	v_exp_f32_e32 v175, v175
	v_pk_mul_f32 v[176:177], v[44:45], v[12:13]
	v_pk_mul_f32 v[178:179], v[46:47], v[14:15]
	v_pk_mul_f32 v[180:181], v[40:41], v[8:9]
	v_pk_mul_f32 v[182:183], v[42:43], v[10:11]
	v_pk_add_f32 v[168:169], v[168:169], 1.0 op_sel_hi:[1,0]
	v_pk_add_f32 v[170:171], v[170:171], 1.0 op_sel_hi:[1,0]
	v_pk_add_f32 v[172:173], v[172:173], 1.0 op_sel_hi:[1,0]
	v_pk_add_f32 v[174:175], v[174:175], 1.0 op_sel_hi:[1,0]
	v_rcp_f32_e32 v168, v168
	v_rcp_f32_e32 v169, v169
	v_rcp_f32_e32 v170, v170
	v_rcp_f32_e32 v171, v171
	v_rcp_f32_e32 v172, v172
	v_rcp_f32_e32 v173, v173
	v_rcp_f32_e32 v174, v174
	v_rcp_f32_e32 v175, v175
	v_pk_mul_f32 v[176:177], v[176:177], v[206:207] op_sel_hi:[1,0]
	v_pk_mul_f32 v[178:179], v[178:179], v[206:207] op_sel_hi:[1,0]
	v_pk_mul_f32 v[180:181], v[180:181], v[206:207] op_sel_hi:[1,0]
	v_pk_mul_f32 v[182:183], v[182:183], v[206:207] op_sel_hi:[1,0]
	v_pk_mul_f32 v[176:177], v[176:177], v[168:169]
	v_pk_mul_f32 v[178:179], v[178:179], v[170:171]
	v_pk_mul_f32 v[180:181], v[180:181], v[172:173]
	v_pk_mul_f32 v[182:183], v[182:183], v[174:175]
	v_cvt_pk_bf16_f32 v158, v176, v177
	v_cvt_pk_bf16_f32 v159, v178, v179
	v_cvt_pk_bf16_f32 v160, v180, v181
	v_cvt_pk_bf16_f32 v161, v182, v183
	s_nop 1
	v_mov_b32_e32 v146, v147
	v_add_co_u32_e32 v148, vcc, s6, v150
	v_addc_co_u32_e32 v149, vcc, 0, v151, vcc
	global_store_dwordx4 v[148:149], v[158:161], off
	v_mul_f32_e32 v184, 0xbfb8aa3b, v146
	v_mul_f32_e32 v206, v146, v146
	v_pk_mul_f32 v[168:169], v[36:37], v[184:185] op_sel_hi:[1,0]
	v_pk_mul_f32 v[170:171], v[38:39], v[184:185] op_sel_hi:[1,0]
	v_pk_mul_f32 v[172:173], v[32:33], v[184:185] op_sel_hi:[1,0]
	v_pk_mul_f32 v[174:175], v[34:35], v[184:185] op_sel_hi:[1,0]
	v_exp_f32_e32 v168, v168
	v_exp_f32_e32 v169, v169
	v_exp_f32_e32 v170, v170
	v_exp_f32_e32 v171, v171
	v_exp_f32_e32 v172, v172
	v_exp_f32_e32 v173, v173
	v_exp_f32_e32 v174, v174
	v_exp_f32_e32 v175, v175
	v_pk_mul_f32 v[176:177], v[36:37], v[4:5]
	v_pk_mul_f32 v[178:179], v[38:39], v[6:7]
	v_pk_mul_f32 v[180:181], v[32:33], v[0:1]
	v_pk_mul_f32 v[182:183], v[34:35], v[2:3]
	v_pk_add_f32 v[168:169], v[168:169], 1.0 op_sel_hi:[1,0]
	v_pk_add_f32 v[170:171], v[170:171], 1.0 op_sel_hi:[1,0]
	v_pk_add_f32 v[172:173], v[172:173], 1.0 op_sel_hi:[1,0]
	v_pk_add_f32 v[174:175], v[174:175], 1.0 op_sel_hi:[1,0]
	v_rcp_f32_e32 v168, v168
	v_rcp_f32_e32 v169, v169
	v_rcp_f32_e32 v170, v170
	v_rcp_f32_e32 v171, v171
	v_rcp_f32_e32 v172, v172
	v_rcp_f32_e32 v173, v173
	v_rcp_f32_e32 v174, v174
	v_rcp_f32_e32 v175, v175
	v_pk_mul_f32 v[176:177], v[176:177], v[206:207] op_sel_hi:[1,0]
	v_pk_mul_f32 v[178:179], v[178:179], v[206:207] op_sel_hi:[1,0]
	v_pk_mul_f32 v[180:181], v[180:181], v[206:207] op_sel_hi:[1,0]
	v_pk_mul_f32 v[182:183], v[182:183], v[206:207] op_sel_hi:[1,0]
	v_pk_mul_f32 v[176:177], v[176:177], v[168:169]
	v_pk_mul_f32 v[178:179], v[178:179], v[170:171]
	v_pk_mul_f32 v[180:181], v[180:181], v[172:173]
	v_pk_mul_f32 v[182:183], v[182:183], v[174:175]
	v_cvt_pk_bf16_f32 v158, v176, v177
	v_cvt_pk_bf16_f32 v159, v178, v179
	v_cvt_pk_bf16_f32 v160, v180, v181
	v_cvt_pk_bf16_f32 v161, v182, v183
	s_nop 1
	v_add_co_u32_e32 v146, vcc, 0xf2000, v150
	s_nop 0
	v_addc_co_u32_e32 v147, vcc, 0, v151, vcc
	s_andn2_b64 vcc, exec, s[44:45]
	global_store_dwordx4 v[146:147], v[158:161], off
	s_cbranch_vccz .LBB0_382
	s_mov_b64 s[48:49], s[52:53]
	s_andn2_b64 vcc, exec, s[42:43]
	s_mov_b64 s[52:53], s[48:49]
	s_cbranch_vccnz .LBB0_383
